# GEMM K-loops: barrier hand-off tightened around every 16-MFMA segment (s_setprio 1 moved before the entry barrier, duplicate lgkmcnt wait dropped, exit barrier placed right after the last MFMA ahead o
# speedup vs baseline: 1.0183x; 1.0055x over previous
.LBB0_287:
	s_add_u32 s0, s22, 0xfffc0080
	s_addc_u32 s1, s23, -1
	s_add_i32 s72, 0, 0x10000
	v_add_u32_e32 v80, s72, v163
	ds_read_b128 v[68:71], v80
	ds_read_b128 v[72:75], v80 offset:1024
	ds_read_b128 v[76:79], v80 offset:2048
	ds_read_b128 v[80:83], v80 offset:3072
	s_cmp_eq_u32 s69, 12
	s_cselect_b32 s27, s18, s1
	s_cselect_b32 s26, s19, s0
	s_cselect_b32 s25, s45, s68
	s_cselect_b32 s24, s47, s59
	v_lshl_add_u64 v[202:203], s[22:23], 0, v[154:155]
	s_add_i32 m0, s53, 0xc000
	ds_read_b128 v[158:161], v165
	ds_read_b128 v[174:177], v165 offset:1024
	ds_read_b128 v[178:181], v165 offset:2048
	ds_read_b128 v[182:185], v165 offset:3072
	ds_read_b128 v[186:189], v165 offset:4096
	ds_read_b128 v[190:193], v165 offset:5120
	ds_read_b128 v[194:197], v165 offset:6144
	ds_read_b128 v[198:201], v165 offset:7168
	global_load_lds_dwordx4 v[202:203], off
	v_lshl_add_u64 v[202:203], s[22:23], 0, v[156:157]
	s_add_i32 m0, s53, 0xe000
	s_nop 0
	global_load_lds_dwordx4 v[202:203], off
	s_waitcnt lgkmcnt(8)
	s_setprio 1
	s_barrier
	s_waitcnt lgkmcnt(0)
	v_mfma_f32_16x16x32_bf16 v[144:147], v[68:71], v[158:161], v[144:147]
	v_mfma_f32_16x16x32_bf16 v[140:143], v[76:79], v[158:161], v[140:143]
	v_mfma_f32_16x16x32_bf16 v[128:131], v[68:71], v[178:181], v[128:131]
	v_mfma_f32_16x16x32_bf16 v[124:127], v[76:79], v[178:181], v[124:127]
	v_mfma_f32_16x16x32_bf16 v[112:115], v[68:71], v[186:189], v[112:115]
	v_mfma_f32_16x16x32_bf16 v[108:111], v[76:79], v[186:189], v[108:111]
	v_mfma_f32_16x16x32_bf16 v[96:99], v[68:71], v[194:197], v[96:99]
	v_mfma_f32_16x16x32_bf16 v[92:95], v[76:79], v[194:197], v[92:95]
	v_mfma_f32_16x16x32_bf16 v[144:147], v[72:75], v[174:177], v[144:147]
	v_mfma_f32_16x16x32_bf16 v[140:143], v[80:83], v[174:177], v[140:143]
	v_mfma_f32_16x16x32_bf16 v[128:131], v[72:75], v[182:185], v[128:131]
	v_mfma_f32_16x16x32_bf16 v[124:127], v[80:83], v[182:185], v[124:127]
	v_mfma_f32_16x16x32_bf16 v[112:115], v[72:75], v[190:193], v[112:115]
	v_mfma_f32_16x16x32_bf16 v[108:111], v[80:83], v[190:193], v[108:111]
	v_mfma_f32_16x16x32_bf16 v[96:99], v[72:75], v[198:201], v[96:99]
	v_mfma_f32_16x16x32_bf16 v[92:95], v[80:83], v[198:201], v[92:95]
	s_barrier
	s_setprio 0
	s_add_i32 s73, 0, 0x14000
	s_add_i32 s0, s72, s52
	v_add_u32_e32 v166, s73, v163
	v_lshl_add_u64 v[218:219], s[24:25], 0, v[26:27]
	s_mov_b32 m0, s0
	ds_read_b128 v[202:205], v166
	ds_read_b128 v[206:209], v166 offset:1024
	ds_read_b128 v[210:213], v166 offset:2048
	ds_read_b128 v[214:217], v166 offset:3072
	global_load_lds_dwordx4 v[218:219], off
	v_lshl_add_u64 v[220:221], s[24:25], 0, v[148:149]
	s_add_i32 m0, s0, 0x2000
	s_nop 0
	global_load_lds_dwordx4 v[220:221], off
	s_setprio 1
	s_barrier
	s_waitcnt lgkmcnt(0)
	v_mfma_f32_16x16x32_bf16 v[136:139], v[202:205], v[158:161], v[136:139]
	v_mfma_f32_16x16x32_bf16 v[132:135], v[210:213], v[158:161], v[132:135]
	v_mfma_f32_16x16x32_bf16 v[120:123], v[202:205], v[178:181], v[120:123]
	v_mfma_f32_16x16x32_bf16 v[116:119], v[210:213], v[178:181], v[116:119]
	v_mfma_f32_16x16x32_bf16 v[104:107], v[202:205], v[186:189], v[104:107]
	v_mfma_f32_16x16x32_bf16 v[100:103], v[210:213], v[186:189], v[100:103]
	v_mfma_f32_16x16x32_bf16 v[88:91], v[202:205], v[194:197], v[88:91]
	v_mfma_f32_16x16x32_bf16 v[84:87], v[210:213], v[194:197], v[84:87]
	v_mfma_f32_16x16x32_bf16 v[136:139], v[206:209], v[174:177], v[136:139]
	v_mfma_f32_16x16x32_bf16 v[132:135], v[214:217], v[174:177], v[132:135]
	v_mfma_f32_16x16x32_bf16 v[120:123], v[206:209], v[182:185], v[120:123]
	v_mfma_f32_16x16x32_bf16 v[116:119], v[214:217], v[182:185], v[116:119]
	v_mfma_f32_16x16x32_bf16 v[104:107], v[206:209], v[190:193], v[104:107]
	v_mfma_f32_16x16x32_bf16 v[100:103], v[214:217], v[190:193], v[100:103]
	v_mfma_f32_16x16x32_bf16 v[88:91], v[206:209], v[198:201], v[88:91]
	v_mfma_f32_16x16x32_bf16 v[84:87], v[214:217], v[198:201], v[84:87]
	s_barrier
	s_setprio 0
	s_mov_b32 m0, s53
	v_lshl_add_u64 v[222:223], s[26:27], 0, v[152:153]
	ds_read_b128 v[158:161], v165 offset:16384
	ds_read_b128 v[174:177], v165 offset:17408
	ds_read_b128 v[178:181], v165 offset:18432
	ds_read_b128 v[182:185], v165 offset:19456
	ds_read_b128 v[186:189], v165 offset:20480
	ds_read_b128 v[190:193], v165 offset:21504
	ds_read_b128 v[194:197], v165 offset:22528
	ds_read_b128 v[198:201], v165 offset:23552
	global_load_lds_dwordx4 v[222:223], off
	v_lshl_add_u64 v[224:225], s[26:27], 0, v[150:151]
	s_mov_b32 m0, s54
	s_nop 0
	global_load_lds_dwordx4 v[224:225], off
	s_setprio 1
	s_barrier
	s_waitcnt lgkmcnt(0)
	v_mfma_f32_16x16x32_bf16 v[64:67], v[68:71], v[158:161], v[64:67]
	v_mfma_f32_16x16x32_bf16 v[60:63], v[76:79], v[158:161], v[60:63]
	v_mfma_f32_16x16x32_bf16 v[48:51], v[68:71], v[178:181], v[48:51]
	v_mfma_f32_16x16x32_bf16 v[44:47], v[76:79], v[178:181], v[44:47]
	v_mfma_f32_16x16x32_bf16 v[32:35], v[68:71], v[186:189], v[32:35]
	v_mfma_f32_16x16x32_bf16 v[28:31], v[76:79], v[186:189], v[28:31]
	v_mfma_f32_16x16x32_bf16 v[14:17], v[68:71], v[194:197], v[14:17]
	v_mfma_f32_16x16x32_bf16 v[10:13], v[76:79], v[194:197], v[10:13]
	v_mfma_f32_16x16x32_bf16 v[64:67], v[72:75], v[174:177], v[64:67]
	v_mfma_f32_16x16x32_bf16 v[60:63], v[80:83], v[174:177], v[60:63]
	v_mfma_f32_16x16x32_bf16 v[48:51], v[72:75], v[182:185], v[48:51]
	v_mfma_f32_16x16x32_bf16 v[44:47], v[80:83], v[182:185], v[44:47]
	v_mfma_f32_16x16x32_bf16 v[32:35], v[72:75], v[190:193], v[32:35]
	v_mfma_f32_16x16x32_bf16 v[28:31], v[80:83], v[190:193], v[28:31]
	v_mfma_f32_16x16x32_bf16 v[14:17], v[72:75], v[198:201], v[14:17]
	v_mfma_f32_16x16x32_bf16 v[10:13], v[80:83], v[198:201], v[10:13]
	s_barrier
	s_setprio 0
	s_add_u32 s0, s24, 0x40000
	s_addc_u32 s1, s25, 0
	s_add_i32 s72, s73, s52
	v_lshl_add_u64 v[68:69], s[0:1], 0, v[26:27]
	s_mov_b32 m0, s72
	s_nop 0
	global_load_lds_dwordx4 v[68:69], off
	v_lshl_add_u64 v[68:69], s[0:1], 0, v[148:149]
	s_add_i32 m0, s72, 0x2000
	s_nop 0
	global_load_lds_dwordx4 v[68:69], off
	s_waitcnt vmcnt(6)
	s_setprio 1
	s_barrier
	v_mfma_f32_16x16x32_bf16 v[56:59], v[202:205], v[158:161], v[56:59]
	v_mfma_f32_16x16x32_bf16 v[52:55], v[210:213], v[158:161], v[52:55]
	v_mfma_f32_16x16x32_bf16 v[40:43], v[202:205], v[178:181], v[40:43]
	v_mfma_f32_16x16x32_bf16 v[36:39], v[210:213], v[178:181], v[36:39]
	v_mfma_f32_16x16x32_bf16 v[22:25], v[202:205], v[186:189], v[22:25]
	v_mfma_f32_16x16x32_bf16 v[18:21], v[210:213], v[186:189], v[18:21]
	v_mfma_f32_16x16x32_bf16 v[6:9], v[202:205], v[194:197], v[6:9]
	v_mfma_f32_16x16x32_bf16 v[2:5], v[210:213], v[194:197], v[2:5]
	v_mfma_f32_16x16x32_bf16 v[56:59], v[206:209], v[174:177], v[56:59]
	v_mfma_f32_16x16x32_bf16 v[52:55], v[214:217], v[174:177], v[52:55]
	v_mfma_f32_16x16x32_bf16 v[40:43], v[206:209], v[182:185], v[40:43]
	v_mfma_f32_16x16x32_bf16 v[36:39], v[214:217], v[182:185], v[36:39]
	v_mfma_f32_16x16x32_bf16 v[22:25], v[206:209], v[190:193], v[22:25]
	v_mfma_f32_16x16x32_bf16 v[18:21], v[214:217], v[190:193], v[18:21]
	v_mfma_f32_16x16x32_bf16 v[6:9], v[206:209], v[198:201], v[6:9]
	v_mfma_f32_16x16x32_bf16 v[2:5], v[214:217], v[198:201], v[2:5]
	s_barrier
	s_setprio 0
	s_add_i32 s72, 0, 0x18000
	v_add_u32_e32 v80, s72, v163
	ds_read_b128 v[68:71], v80
	ds_read_b128 v[72:75], v80 offset:1024
	ds_read_b128 v[76:79], v80 offset:2048
	ds_read_b128 v[80:83], v80 offset:3072
	s_add_u32 s0, s26, 0x40000
	s_addc_u32 s1, s27, 0
	s_mov_b32 m0, s55
	v_lshl_add_u64 v[202:203], s[0:1], 0, v[152:153]
	ds_read_b128 v[158:161], v165 offset:32768
	ds_read_b128 v[174:177], v165 offset:33792
	ds_read_b128 v[178:181], v165 offset:34816
	ds_read_b128 v[182:185], v165 offset:35840
	ds_read_b128 v[186:189], v165 offset:36864
	ds_read_b128 v[190:193], v165 offset:37888
	ds_read_b128 v[194:197], v165 offset:38912
	ds_read_b128 v[198:201], v165 offset:39936
	global_load_lds_dwordx4 v[202:203], off
	v_lshl_add_u64 v[202:203], s[0:1], 0, v[150:151]
	s_mov_b32 m0, s56
	s_nop 0
	global_load_lds_dwordx4 v[202:203], off
	s_waitcnt lgkmcnt(8)
	s_setprio 1
	s_barrier
	s_waitcnt lgkmcnt(0)
	v_mfma_f32_16x16x32_bf16 v[144:147], v[68:71], v[158:161], v[144:147]
	v_mfma_f32_16x16x32_bf16 v[140:143], v[76:79], v[158:161], v[140:143]
	v_mfma_f32_16x16x32_bf16 v[128:131], v[68:71], v[178:181], v[128:131]
	v_mfma_f32_16x16x32_bf16 v[124:127], v[76:79], v[178:181], v[124:127]
	v_mfma_f32_16x16x32_bf16 v[112:115], v[68:71], v[186:189], v[112:115]
	v_mfma_f32_16x16x32_bf16 v[108:111], v[76:79], v[186:189], v[108:111]
	v_mfma_f32_16x16x32_bf16 v[96:99], v[68:71], v[194:197], v[96:99]
	v_mfma_f32_16x16x32_bf16 v[92:95], v[76:79], v[194:197], v[92:95]
	v_mfma_f32_16x16x32_bf16 v[144:147], v[72:75], v[174:177], v[144:147]
	v_mfma_f32_16x16x32_bf16 v[140:143], v[80:83], v[174:177], v[140:143]
	v_mfma_f32_16x16x32_bf16 v[128:131], v[72:75], v[182:185], v[128:131]
	v_mfma_f32_16x16x32_bf16 v[124:127], v[80:83], v[182:185], v[124:127]
	v_mfma_f32_16x16x32_bf16 v[112:115], v[72:75], v[190:193], v[112:115]
	v_mfma_f32_16x16x32_bf16 v[108:111], v[80:83], v[190:193], v[108:111]
	v_mfma_f32_16x16x32_bf16 v[96:99], v[72:75], v[198:201], v[96:99]
	v_mfma_f32_16x16x32_bf16 v[92:95], v[80:83], v[198:201], v[92:95]
	s_barrier
	s_setprio 0
	s_add_i32 s26, 0, 0x1c000
	s_add_i32 s0, s72, s52
	v_add_u32_e32 v166, s26, v163
	v_lshl_add_u64 v[218:219], v[218:219], 0, s[12:13]
	s_mov_b32 m0, s0
	ds_read_b128 v[202:205], v166
	ds_read_b128 v[206:209], v166 offset:1024
	ds_read_b128 v[210:213], v166 offset:2048
	ds_read_b128 v[214:217], v166 offset:3072
	global_load_lds_dwordx4 v[218:219], off
	v_lshl_add_u64 v[218:219], v[220:221], 0, s[12:13]
	s_add_i32 m0, s0, 0x2000
	s_nop 0
	global_load_lds_dwordx4 v[218:219], off
	s_setprio 1
	s_barrier
	s_waitcnt lgkmcnt(0)
	v_mfma_f32_16x16x32_bf16 v[136:139], v[202:205], v[158:161], v[136:139]
	v_mfma_f32_16x16x32_bf16 v[132:135], v[210:213], v[158:161], v[132:135]
	v_mfma_f32_16x16x32_bf16 v[120:123], v[202:205], v[178:181], v[120:123]
	v_mfma_f32_16x16x32_bf16 v[116:119], v[210:213], v[178:181], v[116:119]
	v_mfma_f32_16x16x32_bf16 v[104:107], v[202:205], v[186:189], v[104:107]
	v_mfma_f32_16x16x32_bf16 v[100:103], v[210:213], v[186:189], v[100:103]
	v_mfma_f32_16x16x32_bf16 v[88:91], v[202:205], v[194:197], v[88:91]
	v_mfma_f32_16x16x32_bf16 v[84:87], v[210:213], v[194:197], v[84:87]
	v_mfma_f32_16x16x32_bf16 v[136:139], v[206:209], v[174:177], v[136:139]
	v_mfma_f32_16x16x32_bf16 v[132:135], v[214:217], v[174:177], v[132:135]
	v_mfma_f32_16x16x32_bf16 v[120:123], v[206:209], v[182:185], v[120:123]
	v_mfma_f32_16x16x32_bf16 v[116:119], v[214:217], v[182:185], v[116:119]
	v_mfma_f32_16x16x32_bf16 v[104:107], v[206:209], v[190:193], v[104:107]
	v_mfma_f32_16x16x32_bf16 v[100:103], v[214:217], v[190:193], v[100:103]
	v_mfma_f32_16x16x32_bf16 v[88:91], v[206:209], v[198:201], v[88:91]
	v_mfma_f32_16x16x32_bf16 v[84:87], v[214:217], v[198:201], v[84:87]
	s_barrier
	s_setprio 0
	s_mov_b32 m0, s30
	v_lshl_add_u64 v[218:219], v[222:223], 0, s[12:13]
	ds_read_b128 v[158:161], v165 offset:49152
	ds_read_b128 v[174:177], v165 offset:50176
	ds_read_b128 v[178:181], v165 offset:51200
	ds_read_b128 v[182:185], v165 offset:52224
	ds_read_b128 v[186:189], v165 offset:53248
	ds_read_b128 v[190:193], v165 offset:54272
	ds_read_b128 v[194:197], v165 offset:55296
	ds_read_b128 v[198:201], v165 offset:56320
	global_load_lds_dwordx4 v[218:219], off
	v_lshl_add_u64 v[218:219], v[224:225], 0, s[12:13]
	s_mov_b32 m0, s31
	s_nop 0
	global_load_lds_dwordx4 v[218:219], off
	s_setprio 1
	s_barrier
	s_waitcnt lgkmcnt(0)
	v_mfma_f32_16x16x32_bf16 v[64:67], v[68:71], v[158:161], v[64:67]
	v_mfma_f32_16x16x32_bf16 v[60:63], v[76:79], v[158:161], v[60:63]
	v_mfma_f32_16x16x32_bf16 v[48:51], v[68:71], v[178:181], v[48:51]
	v_mfma_f32_16x16x32_bf16 v[44:47], v[76:79], v[178:181], v[44:47]
	v_mfma_f32_16x16x32_bf16 v[32:35], v[68:71], v[186:189], v[32:35]
	v_mfma_f32_16x16x32_bf16 v[28:31], v[76:79], v[186:189], v[28:31]
	v_mfma_f32_16x16x32_bf16 v[14:17], v[68:71], v[194:197], v[14:17]
	v_mfma_f32_16x16x32_bf16 v[10:13], v[76:79], v[194:197], v[10:13]
	v_mfma_f32_16x16x32_bf16 v[64:67], v[72:75], v[174:177], v[64:67]
	v_mfma_f32_16x16x32_bf16 v[60:63], v[80:83], v[174:177], v[60:63]
	v_mfma_f32_16x16x32_bf16 v[48:51], v[72:75], v[182:185], v[48:51]
	v_mfma_f32_16x16x32_bf16 v[44:47], v[80:83], v[182:185], v[44:47]
	v_mfma_f32_16x16x32_bf16 v[32:35], v[72:75], v[190:193], v[32:35]
	v_mfma_f32_16x16x32_bf16 v[28:31], v[80:83], v[190:193], v[28:31]
	v_mfma_f32_16x16x32_bf16 v[14:17], v[72:75], v[198:201], v[14:17]
	v_mfma_f32_16x16x32_bf16 v[10:13], v[80:83], v[198:201], v[10:13]
	s_barrier
	s_setprio 0
	s_add_u32 s0, s24, 0x40080
	s_addc_u32 s1, s25, 0
	s_add_i32 s24, s26, s52
	v_lshl_add_u64 v[68:69], s[0:1], 0, v[26:27]
	s_mov_b32 m0, s24
	s_nop 0
	global_load_lds_dwordx4 v[68:69], off
	v_lshl_add_u64 v[68:69], s[0:1], 0, v[148:149]
	s_add_i32 m0, s24, 0x2000
	s_nop 0
	global_load_lds_dwordx4 v[68:69], off
	s_waitcnt vmcnt(6)
	s_setprio 1
	s_barrier
	v_mfma_f32_16x16x32_bf16 v[56:59], v[202:205], v[158:161], v[56:59]
	v_mfma_f32_16x16x32_bf16 v[52:55], v[210:213], v[158:161], v[52:55]
	v_mfma_f32_16x16x32_bf16 v[40:43], v[202:205], v[178:181], v[40:43]
	v_mfma_f32_16x16x32_bf16 v[36:39], v[210:213], v[178:181], v[36:39]
	v_mfma_f32_16x16x32_bf16 v[22:25], v[202:205], v[186:189], v[22:25]
	v_mfma_f32_16x16x32_bf16 v[18:21], v[210:213], v[186:189], v[18:21]
	v_mfma_f32_16x16x32_bf16 v[6:9], v[202:205], v[194:197], v[6:9]
	v_mfma_f32_16x16x32_bf16 v[2:5], v[210:213], v[194:197], v[2:5]
	v_mfma_f32_16x16x32_bf16 v[56:59], v[206:209], v[174:177], v[56:59]
	v_mfma_f32_16x16x32_bf16 v[52:55], v[214:217], v[174:177], v[52:55]
	v_mfma_f32_16x16x32_bf16 v[40:43], v[206:209], v[182:185], v[40:43]
	v_mfma_f32_16x16x32_bf16 v[36:39], v[214:217], v[182:185], v[36:39]
	v_mfma_f32_16x16x32_bf16 v[22:25], v[206:209], v[190:193], v[22:25]
	v_mfma_f32_16x16x32_bf16 v[18:21], v[214:217], v[190:193], v[18:21]
	v_mfma_f32_16x16x32_bf16 v[6:9], v[206:209], v[198:201], v[6:9]
	v_mfma_f32_16x16x32_bf16 v[2:5], v[214:217], v[198:201], v[2:5]
	s_barrier
	s_setprio 0
	s_add_i32 s69, s69, 2
	s_add_u32 s22, s22, 0x100
	s_addc_u32 s23, s23, 0
	s_add_u32 s59, s59, 0x100
	s_addc_u32 s68, s68, 0
	s_cmp_gt_u32 s69, 13
	s_cbranch_scc0 .LBB0_287
	s_cmpk_gt_i32 s58, 0xff
	s_mov_b64 s[18:19], 0xb000
	s_cbranch_scc1 .LBB0_283
	s_ashr_i32 s0, s58, 5
	s_mul_hi_i32 s19, s0, 0x1600
	s_mul_i32 s18, s0, 0x1600
	s_branch .LBB0_283

.LBB0_361:
	s_add_u32 s28, s26, 0x100
	s_addc_u32 s29, s27, 0
	s_add_i32 s0, 0, 0x10000
	v_add_u32_e32 v160, s0, v222
	ds_read_b128 v[132:135], v160
	ds_read_b128 v[136:139], v160 offset:1024
	ds_read_b128 v[156:159], v160 offset:2048
	ds_read_b128 v[160:163], v160 offset:3072
	s_cmp_eq_u32 s46, 40
	s_cselect_b32 s35, s45, s29
	s_cselect_b32 s34, s44, s28
	s_cselect_b32 s31, s23, s19
	s_cselect_b32 s30, s22, s18
	v_lshl_add_u64 v[164:165], s[26:27], 0, v[152:153]
	s_add_i32 m0, s20, 0xc000
	ds_read_b128 v[172:175], v224
	ds_read_b128 v[176:179], v224 offset:1024
	ds_read_b128 v[180:183], v224 offset:2048
	ds_read_b128 v[184:187], v224 offset:3072
	ds_read_b128 v[188:191], v224 offset:4096
	ds_read_b128 v[192:195], v224 offset:5120
	ds_read_b128 v[196:199], v224 offset:6144
	ds_read_b128 v[200:203], v224 offset:7168
	global_load_lds_dwordx4 v[164:165], off
	v_lshl_add_u64 v[164:165], s[26:27], 0, v[154:155]
	s_add_i32 m0, s20, 0xe000
	s_nop 0
	global_load_lds_dwordx4 v[164:165], off
	s_waitcnt lgkmcnt(8)
	s_setprio 1
	s_barrier
	s_waitcnt lgkmcnt(0)
	v_mfma_f32_16x16x32_bf16 v[128:131], v[132:135], v[172:175], v[128:131]
	v_mfma_f32_16x16x32_bf16 v[124:127], v[156:159], v[172:175], v[124:127]
	v_mfma_f32_16x16x32_bf16 v[120:123], v[132:135], v[180:183], v[120:123]
	v_mfma_f32_16x16x32_bf16 v[116:119], v[156:159], v[180:183], v[116:119]
	v_mfma_f32_16x16x32_bf16 v[112:115], v[132:135], v[188:191], v[112:115]
	v_mfma_f32_16x16x32_bf16 v[108:111], v[156:159], v[188:191], v[108:111]
	v_mfma_f32_16x16x32_bf16 v[104:107], v[132:135], v[196:199], v[104:107]
	v_mfma_f32_16x16x32_bf16 v[100:103], v[156:159], v[196:199], v[100:103]
	v_mfma_f32_16x16x32_bf16 v[128:131], v[136:139], v[176:179], v[128:131]
	v_mfma_f32_16x16x32_bf16 v[124:127], v[160:163], v[176:179], v[124:127]
	v_mfma_f32_16x16x32_bf16 v[120:123], v[136:139], v[184:187], v[120:123]
	v_mfma_f32_16x16x32_bf16 v[116:119], v[160:163], v[184:187], v[116:119]
	v_mfma_f32_16x16x32_bf16 v[112:115], v[136:139], v[192:195], v[112:115]
	v_mfma_f32_16x16x32_bf16 v[108:111], v[160:163], v[192:195], v[108:111]
	v_mfma_f32_16x16x32_bf16 v[104:107], v[136:139], v[200:203], v[104:107]
	v_mfma_f32_16x16x32_bf16 v[100:103], v[160:163], v[200:203], v[100:103]
	s_barrier
	s_setprio 0
	s_add_i32 s26, 0, 0x14000
	v_add_u32_e32 v164, s26, v222
	s_add_i32 s0, s0, s17
	ds_read_b128 v[204:207], v164
	ds_read_b128 v[208:211], v164 offset:1024
	ds_read_b128 v[212:215], v164 offset:2048
	ds_read_b128 v[216:219], v164 offset:3072
	v_lshl_add_u64 v[164:165], s[30:31], 0, v[26:27]
	s_mov_b32 m0, s0
	v_lshl_add_u64 v[166:167], s[30:31], 0, v[140:141]
	global_load_lds_dwordx4 v[164:165], off
	s_add_i32 m0, s0, 0x2000
	s_nop 0
	global_load_lds_dwordx4 v[166:167], off
	s_setprio 1
	s_barrier
	s_waitcnt lgkmcnt(0)
	v_mfma_f32_16x16x32_bf16 v[64:67], v[204:207], v[172:175], v[64:67]
	v_mfma_f32_16x16x32_bf16 v[60:63], v[212:215], v[172:175], v[60:63]
	v_mfma_f32_16x16x32_bf16 v[56:59], v[204:207], v[180:183], v[56:59]
	v_mfma_f32_16x16x32_bf16 v[52:55], v[212:215], v[180:183], v[52:55]
	v_mfma_f32_16x16x32_bf16 v[48:51], v[204:207], v[188:191], v[48:51]
	v_mfma_f32_16x16x32_bf16 v[44:47], v[212:215], v[188:191], v[44:47]
	v_mfma_f32_16x16x32_bf16 v[40:43], v[204:207], v[196:199], v[40:43]
	v_mfma_f32_16x16x32_bf16 v[36:39], v[212:215], v[196:199], v[36:39]
	v_mfma_f32_16x16x32_bf16 v[64:67], v[208:211], v[176:179], v[64:67]
	v_mfma_f32_16x16x32_bf16 v[60:63], v[216:219], v[176:179], v[60:63]
	v_mfma_f32_16x16x32_bf16 v[56:59], v[208:211], v[184:187], v[56:59]
	v_mfma_f32_16x16x32_bf16 v[52:55], v[216:219], v[184:187], v[52:55]
	v_mfma_f32_16x16x32_bf16 v[48:51], v[208:211], v[192:195], v[48:51]
	v_mfma_f32_16x16x32_bf16 v[44:47], v[216:219], v[192:195], v[44:47]
	v_mfma_f32_16x16x32_bf16 v[40:43], v[208:211], v[200:203], v[40:43]
	v_mfma_f32_16x16x32_bf16 v[36:39], v[216:219], v[200:203], v[36:39]
	s_barrier
	s_setprio 0
	s_mov_b32 m0, s20
	v_lshl_add_u64 v[168:169], s[34:35], 0, v[144:145]
	ds_read_b128 v[172:175], v224 offset:16384
	ds_read_b128 v[176:179], v224 offset:17408
	ds_read_b128 v[180:183], v224 offset:18432
	ds_read_b128 v[184:187], v224 offset:19456
	ds_read_b128 v[188:191], v224 offset:20480
	ds_read_b128 v[192:195], v224 offset:21504
	ds_read_b128 v[196:199], v224 offset:22528
	ds_read_b128 v[200:203], v224 offset:23552
	global_load_lds_dwordx4 v[168:169], off
	v_lshl_add_u64 v[220:221], s[34:35], 0, v[142:143]
	s_mov_b32 m0, s21
	s_nop 0
	global_load_lds_dwordx4 v[220:221], off
	s_setprio 1
	s_barrier
	s_waitcnt lgkmcnt(0)
	v_mfma_f32_16x16x32_bf16 v[96:99], v[132:135], v[172:175], v[96:99]
	v_mfma_f32_16x16x32_bf16 v[92:95], v[156:159], v[172:175], v[92:95]
	v_mfma_f32_16x16x32_bf16 v[88:91], v[132:135], v[180:183], v[88:91]
	v_mfma_f32_16x16x32_bf16 v[84:87], v[156:159], v[180:183], v[84:87]
	v_mfma_f32_16x16x32_bf16 v[80:83], v[132:135], v[188:191], v[80:83]
	v_mfma_f32_16x16x32_bf16 v[76:79], v[156:159], v[188:191], v[76:79]
	v_mfma_f32_16x16x32_bf16 v[72:75], v[132:135], v[196:199], v[72:75]
	v_mfma_f32_16x16x32_bf16 v[68:71], v[156:159], v[196:199], v[68:71]
	v_mfma_f32_16x16x32_bf16 v[96:99], v[136:139], v[176:179], v[96:99]
	v_mfma_f32_16x16x32_bf16 v[92:95], v[160:163], v[176:179], v[92:95]
	v_mfma_f32_16x16x32_bf16 v[88:91], v[136:139], v[184:187], v[88:91]
	v_mfma_f32_16x16x32_bf16 v[84:87], v[160:163], v[184:187], v[84:87]
	v_mfma_f32_16x16x32_bf16 v[80:83], v[136:139], v[192:195], v[80:83]
	v_mfma_f32_16x16x32_bf16 v[76:79], v[160:163], v[192:195], v[76:79]
	v_mfma_f32_16x16x32_bf16 v[72:75], v[136:139], v[200:203], v[72:75]
	v_mfma_f32_16x16x32_bf16 v[68:71], v[160:163], v[200:203], v[68:71]
	s_barrier
	s_setprio 0
	s_add_u32 s0, s30, 0xb0000
	s_addc_u32 s1, s31, 0
	s_add_i32 s26, s26, s17
	v_lshl_add_u64 v[132:133], s[0:1], 0, v[26:27]
	s_mov_b32 m0, s26
	s_nop 0
	global_load_lds_dwordx4 v[132:133], off
	v_lshl_add_u64 v[132:133], s[0:1], 0, v[140:141]
	s_add_i32 m0, s26, 0x2000
	s_nop 0
	global_load_lds_dwordx4 v[132:133], off
	s_waitcnt vmcnt(6)
	s_setprio 1
	s_barrier
	v_mfma_f32_16x16x32_bf16 v[32:35], v[204:207], v[172:175], v[32:35]
	v_mfma_f32_16x16x32_bf16 v[28:31], v[212:215], v[172:175], v[28:31]
	v_mfma_f32_16x16x32_bf16 v[22:25], v[204:207], v[180:183], v[22:25]
	v_mfma_f32_16x16x32_bf16 v[18:21], v[212:215], v[180:183], v[18:21]
	v_mfma_f32_16x16x32_bf16 v[14:17], v[204:207], v[188:191], v[14:17]
	v_mfma_f32_16x16x32_bf16 v[10:13], v[212:215], v[188:191], v[10:13]
	v_mfma_f32_16x16x32_bf16 v[6:9], v[204:207], v[196:199], v[6:9]
	v_mfma_f32_16x16x32_bf16 v[2:5], v[212:215], v[196:199], v[2:5]
	v_mfma_f32_16x16x32_bf16 v[32:35], v[208:211], v[176:179], v[32:35]
	v_mfma_f32_16x16x32_bf16 v[28:31], v[216:219], v[176:179], v[28:31]
	v_mfma_f32_16x16x32_bf16 v[22:25], v[208:211], v[184:187], v[22:25]
	v_mfma_f32_16x16x32_bf16 v[18:21], v[216:219], v[184:187], v[18:21]
	v_mfma_f32_16x16x32_bf16 v[14:17], v[208:211], v[192:195], v[14:17]
	v_mfma_f32_16x16x32_bf16 v[10:13], v[216:219], v[192:195], v[10:13]
	v_mfma_f32_16x16x32_bf16 v[6:9], v[208:211], v[200:203], v[6:9]
	v_mfma_f32_16x16x32_bf16 v[2:5], v[216:219], v[200:203], v[2:5]
	s_barrier
	s_setprio 0
	s_add_i32 s26, 0, 0x18000
	v_add_u32_e32 v160, s26, v222
	ds_read_b128 v[132:135], v160
	ds_read_b128 v[136:139], v160 offset:1024
	ds_read_b128 v[156:159], v160 offset:2048
	ds_read_b128 v[160:163], v160 offset:3072
	s_add_u32 s0, s34, 0xb0000
	s_addc_u32 s1, s35, 0
	s_mov_b32 m0, s36
	v_lshl_add_u64 v[204:205], s[0:1], 0, v[144:145]
	ds_read_b128 v[172:175], v224 offset:32768
	ds_read_b128 v[176:179], v224 offset:33792
	ds_read_b128 v[180:183], v224 offset:34816
	ds_read_b128 v[184:187], v224 offset:35840
	ds_read_b128 v[188:191], v224 offset:36864
	ds_read_b128 v[192:195], v224 offset:37888
	ds_read_b128 v[196:199], v224 offset:38912
	ds_read_b128 v[200:203], v224 offset:39936
	global_load_lds_dwordx4 v[204:205], off
	v_lshl_add_u64 v[204:205], s[0:1], 0, v[142:143]
	s_mov_b32 m0, s37
	s_nop 0
	global_load_lds_dwordx4 v[204:205], off
	s_waitcnt lgkmcnt(8)
	s_setprio 1
	s_barrier
	s_waitcnt lgkmcnt(0)
	v_mfma_f32_16x16x32_bf16 v[128:131], v[132:135], v[172:175], v[128:131]
	v_mfma_f32_16x16x32_bf16 v[124:127], v[156:159], v[172:175], v[124:127]
	v_mfma_f32_16x16x32_bf16 v[120:123], v[132:135], v[180:183], v[120:123]
	v_mfma_f32_16x16x32_bf16 v[116:119], v[156:159], v[180:183], v[116:119]
	v_mfma_f32_16x16x32_bf16 v[112:115], v[132:135], v[188:191], v[112:115]
	v_mfma_f32_16x16x32_bf16 v[108:111], v[156:159], v[188:191], v[108:111]
	v_mfma_f32_16x16x32_bf16 v[104:107], v[132:135], v[196:199], v[104:107]
	v_mfma_f32_16x16x32_bf16 v[100:103], v[156:159], v[196:199], v[100:103]
	v_mfma_f32_16x16x32_bf16 v[128:131], v[136:139], v[176:179], v[128:131]
	v_mfma_f32_16x16x32_bf16 v[124:127], v[160:163], v[176:179], v[124:127]
	v_mfma_f32_16x16x32_bf16 v[120:123], v[136:139], v[184:187], v[120:123]
	v_mfma_f32_16x16x32_bf16 v[116:119], v[160:163], v[184:187], v[116:119]
	v_mfma_f32_16x16x32_bf16 v[112:115], v[136:139], v[192:195], v[112:115]
	v_mfma_f32_16x16x32_bf16 v[108:111], v[160:163], v[192:195], v[108:111]
	v_mfma_f32_16x16x32_bf16 v[104:107], v[136:139], v[200:203], v[104:107]
	v_mfma_f32_16x16x32_bf16 v[100:103], v[160:163], v[200:203], v[100:103]
	s_barrier
	s_setprio 0
	s_add_i32 s27, 0, 0x1c000
	s_add_i32 s0, s26, s17
	v_add_u32_e32 v216, s27, v222
	v_lshl_add_u64 v[164:165], v[164:165], 0, s[12:13]
	s_mov_b32 m0, s0
	ds_read_b128 v[204:207], v216
	ds_read_b128 v[208:211], v216 offset:1024
	ds_read_b128 v[212:215], v216 offset:2048
	ds_read_b128 v[216:219], v216 offset:3072
	global_load_lds_dwordx4 v[164:165], off
	v_lshl_add_u64 v[164:165], v[166:167], 0, s[12:13]
	s_add_i32 m0, s0, 0x2000
	s_nop 0
	global_load_lds_dwordx4 v[164:165], off
	s_setprio 1
	s_barrier
	s_waitcnt lgkmcnt(0)
	v_mfma_f32_16x16x32_bf16 v[64:67], v[204:207], v[172:175], v[64:67]
	v_mfma_f32_16x16x32_bf16 v[60:63], v[212:215], v[172:175], v[60:63]
	v_mfma_f32_16x16x32_bf16 v[56:59], v[204:207], v[180:183], v[56:59]
	v_mfma_f32_16x16x32_bf16 v[52:55], v[212:215], v[180:183], v[52:55]
	v_mfma_f32_16x16x32_bf16 v[48:51], v[204:207], v[188:191], v[48:51]
	v_mfma_f32_16x16x32_bf16 v[44:47], v[212:215], v[188:191], v[44:47]
	v_mfma_f32_16x16x32_bf16 v[40:43], v[204:207], v[196:199], v[40:43]
	v_mfma_f32_16x16x32_bf16 v[36:39], v[212:215], v[196:199], v[36:39]
	v_mfma_f32_16x16x32_bf16 v[64:67], v[208:211], v[176:179], v[64:67]
	v_mfma_f32_16x16x32_bf16 v[60:63], v[216:219], v[176:179], v[60:63]
	v_mfma_f32_16x16x32_bf16 v[56:59], v[208:211], v[184:187], v[56:59]
	v_mfma_f32_16x16x32_bf16 v[52:55], v[216:219], v[184:187], v[52:55]
	v_mfma_f32_16x16x32_bf16 v[48:51], v[208:211], v[192:195], v[48:51]
	v_mfma_f32_16x16x32_bf16 v[44:47], v[216:219], v[192:195], v[44:47]
	v_mfma_f32_16x16x32_bf16 v[40:43], v[208:211], v[200:203], v[40:43]
	v_mfma_f32_16x16x32_bf16 v[36:39], v[216:219], v[200:203], v[36:39]
	s_barrier
	s_setprio 0
	s_mov_b32 m0, s59
	v_lshl_add_u64 v[164:165], v[168:169], 0, s[12:13]
	ds_read_b128 v[172:175], v224 offset:49152
	ds_read_b128 v[176:179], v224 offset:50176
	ds_read_b128 v[180:183], v224 offset:51200
	ds_read_b128 v[184:187], v224 offset:52224
	ds_read_b128 v[188:191], v224 offset:53248
	ds_read_b128 v[192:195], v224 offset:54272
	ds_read_b128 v[196:199], v224 offset:55296
	ds_read_b128 v[200:203], v224 offset:56320
	global_load_lds_dwordx4 v[164:165], off
	v_lshl_add_u64 v[164:165], v[220:221], 0, s[12:13]
	s_mov_b32 m0, s68
	s_nop 0
	global_load_lds_dwordx4 v[164:165], off
	s_setprio 1
	s_barrier
	s_waitcnt lgkmcnt(0)
	v_mfma_f32_16x16x32_bf16 v[96:99], v[132:135], v[172:175], v[96:99]
	v_mfma_f32_16x16x32_bf16 v[92:95], v[156:159], v[172:175], v[92:95]
	v_mfma_f32_16x16x32_bf16 v[88:91], v[132:135], v[180:183], v[88:91]
	v_mfma_f32_16x16x32_bf16 v[84:87], v[156:159], v[180:183], v[84:87]
	v_mfma_f32_16x16x32_bf16 v[80:83], v[132:135], v[188:191], v[80:83]
	v_mfma_f32_16x16x32_bf16 v[76:79], v[156:159], v[188:191], v[76:79]
	v_mfma_f32_16x16x32_bf16 v[72:75], v[132:135], v[196:199], v[72:75]
	v_mfma_f32_16x16x32_bf16 v[68:71], v[156:159], v[196:199], v[68:71]
	v_mfma_f32_16x16x32_bf16 v[96:99], v[136:139], v[176:179], v[96:99]
	v_mfma_f32_16x16x32_bf16 v[92:95], v[160:163], v[176:179], v[92:95]
	v_mfma_f32_16x16x32_bf16 v[88:91], v[136:139], v[184:187], v[88:91]
	v_mfma_f32_16x16x32_bf16 v[84:87], v[160:163], v[184:187], v[84:87]
	v_mfma_f32_16x16x32_bf16 v[80:83], v[136:139], v[192:195], v[80:83]
	v_mfma_f32_16x16x32_bf16 v[76:79], v[160:163], v[192:195], v[76:79]
	v_mfma_f32_16x16x32_bf16 v[72:75], v[136:139], v[200:203], v[72:75]
	v_mfma_f32_16x16x32_bf16 v[68:71], v[160:163], v[200:203], v[68:71]
	s_barrier
	s_setprio 0
	s_add_u32 s0, s30, 0xb0080
	s_addc_u32 s1, s31, 0
	s_add_i32 s26, s27, s17
	v_lshl_add_u64 v[132:133], s[0:1], 0, v[26:27]
	s_mov_b32 m0, s26
	s_nop 0
	global_load_lds_dwordx4 v[132:133], off
	v_lshl_add_u64 v[132:133], s[0:1], 0, v[140:141]
	s_add_i32 m0, s26, 0x2000
	s_nop 0
	global_load_lds_dwordx4 v[132:133], off
	s_waitcnt vmcnt(6)
	s_setprio 1
	s_barrier
	v_mfma_f32_16x16x32_bf16 v[32:35], v[204:207], v[172:175], v[32:35]
	v_mfma_f32_16x16x32_bf16 v[28:31], v[212:215], v[172:175], v[28:31]
	v_mfma_f32_16x16x32_bf16 v[22:25], v[204:207], v[180:183], v[22:25]
	v_mfma_f32_16x16x32_bf16 v[18:21], v[212:215], v[180:183], v[18:21]
	v_mfma_f32_16x16x32_bf16 v[14:17], v[204:207], v[188:191], v[14:17]
	v_mfma_f32_16x16x32_bf16 v[10:13], v[212:215], v[188:191], v[10:13]
	v_mfma_f32_16x16x32_bf16 v[6:9], v[204:207], v[196:199], v[6:9]
	v_mfma_f32_16x16x32_bf16 v[2:5], v[212:215], v[196:199], v[2:5]
	v_mfma_f32_16x16x32_bf16 v[32:35], v[208:211], v[176:179], v[32:35]
	v_mfma_f32_16x16x32_bf16 v[28:31], v[216:219], v[176:179], v[28:31]
	v_mfma_f32_16x16x32_bf16 v[22:25], v[208:211], v[184:187], v[22:25]
	v_mfma_f32_16x16x32_bf16 v[18:21], v[216:219], v[184:187], v[18:21]
	v_mfma_f32_16x16x32_bf16 v[14:17], v[208:211], v[192:195], v[14:17]
	v_mfma_f32_16x16x32_bf16 v[10:13], v[216:219], v[192:195], v[10:13]
	v_mfma_f32_16x16x32_bf16 v[6:9], v[208:211], v[200:203], v[6:9]
	v_mfma_f32_16x16x32_bf16 v[2:5], v[216:219], v[200:203], v[2:5]
	s_barrier
	s_setprio 0
	s_add_i32 s46, s46, 2
	s_add_u32 s18, s18, 0x100
	s_addc_u32 s19, s19, 0
	s_cmp_gt_u32 s46, 41
	s_mov_b64 s[26:27], s[28:29]
	s_cbranch_scc0 .LBB0_361
	s_min_i32 s0, s24, 0x100
	s_ashr_i32 s0, s0, 5
	s_ashr_i32 s1, s0, 31
	s_add_i32 s18, s24, 0xffffff00
	s_cmpk_lt_i32 s24, 0x100
	s_cselect_b32 s18, s24, s18
	s_cselect_b32 s27, 0, s58
	s_cselect_b32 s26, 0, s57
	s_ashr_i32 s19, s18, 31
	s_lshl_b64 s[18:19], s[18:19], 19
	s_add_u32 s26, s50, s26
	v_lshl_or_b32 v178, s25, 8, v223
	s_addc_u32 s27, s51, s27
	s_ashr_i32 s25, s24, 31
	v_lshl_add_u64 v[132:133], s[18:19], 0, v[146:147]
	s_lshl_b64 s[18:19], s[24:25], 19
	v_lshl_add_u64 v[184:185], v[148:149], 0, s[18:19]
	s_lshl_b64 s[24:25], s[24:25], 10
	s_mul_i32 s18, s0, 0x9000
	v_ashrrev_i32_e32 v179, 31, v178
	s_mul_hi_i32 s19, s0, 0x9000
	s_add_u32 s18, s48, s18
	s_addc_u32 s19, s49, s19
	v_lshlrev_b64 v[186:187], 2, v[178:179]
	v_lshl_add_u64 v[156:157], s[18:19], 0, v[186:187]
	v_lshl_add_u64 v[180:181], v[132:133], 0, v[178:179]
	v_lshl_add_u64 v[182:183], v[132:133], 1, s[26:27]
	global_load_dwordx4 v[132:135], v[156:157], off offset:16
	global_load_dwordx4 v[136:139], v[156:157], off
	s_lshl_b64 s[0:1], s[0:1], 12
	s_add_u32 s28, s52, s0
	s_addc_u32 s29, s53, s1
	v_lshl_add_u64 v[196:197], v[180:181], 1, s[26:27]
	v_lshl_add_u64 v[180:181], s[28:29], 0, v[186:187]
	v_add_co_u32_e32 v210, vcc, s65, v196
	v_lshlrev_b64 v[188:189], 1, v[178:179]
	s_nop 0
	v_addc_co_u32_e32 v211, vcc, 0, v197, vcc
	s_mov_b32 s1, 0x20000
	v_lshl_add_u64 v[178:179], v[184:185], 0, v[188:189]
	v_add_co_u32_e32 v184, vcc, s1, v196
	s_mov_b32 s18, 0x30000
	s_nop 0
	v_addc_co_u32_e32 v185, vcc, 0, v197, vcc
	v_lshl_add_u64 v[182:183], v[182:183], 0, v[188:189]
	v_add_co_u32_e32 v188, vcc, s18, v196
	s_mov_b32 s0, 0x8000
	s_nop 0
	v_addc_co_u32_e32 v189, vcc, 0, v197, vcc
	s_mov_b32 s19, 0x80000
	s_mov_b32 s26, 0x90000
	s_waitcnt vmcnt(0)
	v_pk_mul_f32 v[172:173], v[134:135], 0.5 op_sel_hi:[1,0]
	v_pk_mul_f32 v[176:177], v[138:139], 0.5 op_sel_hi:[1,0]
	v_pk_mul_f32 v[174:175], v[136:137], 0.5 op_sel_hi:[1,0]
	v_pk_mul_f32 v[164:165], v[132:133], 0.5 op_sel_hi:[1,0]
	global_load_dwordx4 v[132:135], v[156:157], off offset:528
	global_load_dwordx4 v[136:139], v[156:157], off offset:512
	s_waitcnt vmcnt(0)
	v_pk_mul_f32 v[158:159], v[134:135], 0.5 op_sel_hi:[1,0]
	v_pk_mul_f32 v[162:163], v[138:139], 0.5 op_sel_hi:[1,0]
	v_pk_mul_f32 v[160:161], v[136:137], 0.5 op_sel_hi:[1,0]
	v_pk_mul_f32 v[156:157], v[132:133], 0.5 op_sel_hi:[1,0]
	global_load_dwordx4 v[132:135], v[180:181], off offset:16
	global_load_dwordx4 v[136:139], v[180:181], off
	global_load_dwordx4 v[190:193], v[196:197], off offset:2048
	global_load_dwordx4 v[198:201], v[210:211], off offset:2048
	global_load_dwordx4 v[202:205], v[184:185], off offset:2048
	global_load_dwordx4 v[206:209], v[188:189], off offset:2048
	s_waitcnt vmcnt(0)
	v_lshlrev_b32_e32 v186, 16, v190
	v_and_b32_e32 v187, 0xffff0000, v190
	v_lshlrev_b32_e32 v190, 16, v191
	v_and_b32_e32 v191, 0xffff0000, v191
	v_lshlrev_b32_e32 v194, 16, v192
	v_and_b32_e32 v195, 0xffff0000, v192
	v_lshlrev_b32_e32 v192, 16, v193
	v_and_b32_e32 v193, 0xffff0000, v193
	v_pk_fma_f32 v[130:131], v[130:131], v[176:177], v[190:191]
	v_pk_fma_f32 v[128:129], v[128:129], v[174:175], v[186:187]
	v_pk_fma_f32 v[126:127], v[126:127], v[172:173], v[192:193]
	v_pk_fma_f32 v[124:125], v[124:125], v[164:165], v[194:195]
	v_cvt_pk_bf16_f32 v190, v128, v129
	v_cvt_pk_bf16_f32 v191, v130, v131
	v_cvt_pk_bf16_f32 v192, v124, v125
	v_cvt_pk_bf16_f32 v193, v126, v127
	v_lshlrev_b32_e32 v130, 16, v190
	v_and_b32_e32 v131, 0xffff0000, v190
	v_lshlrev_b32_e32 v128, 16, v191
	v_and_b32_e32 v129, 0xffff0000, v191
	v_lshlrev_b32_e32 v126, 16, v192
	v_and_b32_e32 v127, 0xffff0000, v192
	v_lshlrev_b32_e32 v124, 16, v193
	v_and_b32_e32 v125, 0xffff0000, v193
	v_lshlrev_b32_e32 v212, 16, v198
	v_and_b32_e32 v213, 0xffff0000, v198
	v_lshlrev_b32_e32 v198, 16, v199
	v_and_b32_e32 v199, 0xffff0000, v199
	global_store_dwordx4 v[182:183], v[190:193], off offset:2048
	v_pk_mul_f32 v[186:187], v[138:139], v[128:129]
	v_pk_mul_f32 v[194:195], v[134:135], v[124:125]
	v_pk_mul_f32 v[190:191], v[136:137], v[130:131]
	v_pk_mul_f32 v[192:193], v[132:133], v[126:127]
	v_lshlrev_b32_e32 v214, 16, v200
	v_and_b32_e32 v215, 0xffff0000, v200
	v_lshlrev_b32_e32 v200, 16, v201
	v_and_b32_e32 v201, 0xffff0000, v201
	v_cvt_pk_bf16_f32 v190, v190, v191
	v_cvt_pk_bf16_f32 v191, v186, v187
	v_cvt_pk_bf16_f32 v192, v192, v193
	v_cvt_pk_bf16_f32 v193, v194, v195
	v_pk_fma_f32 v[122:123], v[122:123], v[176:177], v[198:199]
	v_pk_fma_f32 v[120:121], v[120:121], v[174:175], v[212:213]
	global_store_dwordx4 v[178:179], v[190:193], off
	v_pk_fma_f32 v[118:119], v[118:119], v[172:173], v[200:201]
	v_pk_fma_f32 v[116:117], v[116:117], v[164:165], v[214:215]
	v_cvt_pk_bf16_f32 v190, v120, v121
	v_cvt_pk_bf16_f32 v191, v122, v123
	v_add_co_u32_e32 v186, vcc, s65, v182
	v_cvt_pk_bf16_f32 v192, v116, v117
	v_cvt_pk_bf16_f32 v193, v118, v119
	v_addc_co_u32_e32 v187, vcc, 0, v183, vcc
	v_lshlrev_b32_e32 v122, 16, v190
	v_and_b32_e32 v123, 0xffff0000, v190
	v_lshlrev_b32_e32 v120, 16, v191
	v_and_b32_e32 v121, 0xffff0000, v191
	global_store_dwordx4 v[186:187], v[190:193], off offset:2048
	v_lshlrev_b32_e32 v118, 16, v192
	v_and_b32_e32 v119, 0xffff0000, v192
	v_lshlrev_b32_e32 v116, 16, v193
	v_and_b32_e32 v117, 0xffff0000, v193
	v_pk_mul_f32 v[190:191], v[138:139], v[120:121]
	v_pk_mul_f32 v[192:193], v[136:137], v[122:123]
	v_pk_mul_f32 v[198:199], v[134:135], v[116:117]
	v_pk_mul_f32 v[194:195], v[132:133], v[118:119]
	v_cvt_pk_bf16_f32 v192, v192, v193
	v_cvt_pk_bf16_f32 v193, v190, v191
	v_add_co_u32_e32 v190, vcc, s0, v178
	v_cvt_pk_bf16_f32 v194, v194, v195
	v_cvt_pk_bf16_f32 v195, v198, v199
	v_addc_co_u32_e32 v191, vcc, 0, v179, vcc
	global_store_dwordx4 v[190:191], v[192:195], off
	v_lshlrev_b32_e32 v198, 16, v202
	v_and_b32_e32 v199, 0xffff0000, v202
	v_add_co_u32_e32 v192, vcc, s19, v196
	v_lshlrev_b32_e32 v200, 16, v203
	s_nop 0
	v_addc_co_u32_e32 v193, vcc, 0, v197, vcc
	v_add_co_u32_e32 v194, vcc, s26, v196
	v_and_b32_e32 v201, 0xffff0000, v203
	global_load_dwordx4 v[212:215], v[192:193], off offset:2048
	v_addc_co_u32_e32 v195, vcc, 0, v197, vcc
	v_lshlrev_b32_e32 v202, 16, v204
	v_and_b32_e32 v203, 0xffff0000, v204
	v_lshlrev_b32_e32 v204, 16, v205
	v_and_b32_e32 v205, 0xffff0000, v205
	v_pk_fma_f32 v[114:115], v[114:115], v[176:177], v[200:201]
	v_pk_fma_f32 v[112:113], v[112:113], v[174:175], v[198:199]
	v_pk_fma_f32 v[110:111], v[110:111], v[172:173], v[204:205]
	v_pk_fma_f32 v[108:109], v[108:109], v[164:165], v[202:203]
	v_cvt_pk_bf16_f32 v200, v112, v113
	v_cvt_pk_bf16_f32 v201, v114, v115
	v_add_co_u32_e32 v198, vcc, s1, v182
	v_cvt_pk_bf16_f32 v202, v108, v109
	v_cvt_pk_bf16_f32 v203, v110, v111
	v_addc_co_u32_e32 v199, vcc, 0, v183, vcc
	v_lshlrev_b32_e32 v114, 16, v200
	v_and_b32_e32 v115, 0xffff0000, v200
	v_lshlrev_b32_e32 v112, 16, v201
	v_and_b32_e32 v113, 0xffff0000, v201
	global_load_dwordx4 v[216:219], v[194:195], off offset:2048
	v_lshlrev_b32_e32 v110, 16, v202
	global_store_dwordx4 v[198:199], v[200:203], off offset:2048
	v_and_b32_e32 v111, 0xffff0000, v202
	v_lshlrev_b32_e32 v108, 16, v203
	v_and_b32_e32 v109, 0xffff0000, v203
	v_pk_mul_f32 v[200:201], v[138:139], v[112:113]
	v_pk_mul_f32 v[202:203], v[136:137], v[114:115]
	v_lshlrev_b32_e32 v220, 16, v206
	v_and_b32_e32 v221, 0xffff0000, v206
	v_lshlrev_b32_e32 v206, 16, v207
	v_and_b32_e32 v207, 0xffff0000, v207
	v_pk_mul_f32 v[238:239], v[134:135], v[108:109]
	v_pk_mul_f32 v[204:205], v[132:133], v[110:111]
	v_cvt_pk_bf16_f32 v202, v202, v203
	v_cvt_pk_bf16_f32 v203, v200, v201
	v_add_co_u32_e32 v200, vcc, s65, v178
	v_lshlrev_b32_e32 v234, 16, v208
	v_and_b32_e32 v235, 0xffff0000, v208
	v_lshlrev_b32_e32 v208, 16, v209
	v_and_b32_e32 v209, 0xffff0000, v209
	v_cvt_pk_bf16_f32 v204, v204, v205
	v_cvt_pk_bf16_f32 v205, v238, v239
	v_addc_co_u32_e32 v201, vcc, 0, v179, vcc
	v_pk_fma_f32 v[106:107], v[106:107], v[176:177], v[206:207]
	v_pk_fma_f32 v[104:105], v[104:105], v[174:175], v[220:221]
	global_store_dwordx4 v[200:201], v[202:205], off
	v_pk_fma_f32 v[102:103], v[102:103], v[172:173], v[208:209]
	v_pk_fma_f32 v[100:101], v[100:101], v[164:165], v[234:235]
	v_cvt_pk_bf16_f32 v204, v104, v105
	v_cvt_pk_bf16_f32 v205, v106, v107
	v_add_co_u32_e32 v202, vcc, s18, v182
	v_cvt_pk_bf16_f32 v206, v100, v101
	v_cvt_pk_bf16_f32 v207, v102, v103
	v_addc_co_u32_e32 v203, vcc, 0, v183, vcc
	v_lshlrev_b32_e32 v106, 16, v204
	v_and_b32_e32 v107, 0xffff0000, v204
	v_lshlrev_b32_e32 v104, 16, v205
	v_and_b32_e32 v105, 0xffff0000, v205
	global_store_dwordx4 v[202:203], v[204:207], off offset:2048
	v_lshlrev_b32_e32 v102, 16, v206
	v_and_b32_e32 v103, 0xffff0000, v206
	v_lshlrev_b32_e32 v100, 16, v207
	v_and_b32_e32 v101, 0xffff0000, v207
	v_pk_mul_f32 v[204:205], v[138:139], v[104:105]
	v_pk_mul_f32 v[206:207], v[136:137], v[106:107]
	s_mov_b32 s0, 0x18000
	v_pk_mul_f32 v[220:221], v[134:135], v[100:101]
	v_pk_mul_f32 v[208:209], v[132:133], v[102:103]
	v_cvt_pk_bf16_f32 v206, v206, v207
	v_cvt_pk_bf16_f32 v207, v204, v205
	v_add_co_u32_e32 v204, vcc, s0, v178
	v_cvt_pk_bf16_f32 v208, v208, v209
	v_cvt_pk_bf16_f32 v209, v220, v221
	v_addc_co_u32_e32 v205, vcc, 0, v179, vcc
	global_store_dwordx4 v[204:205], v[206:209], off
	s_mov_b32 s0, 0xb0000
	s_waitcnt vmcnt(0)
	v_lshlrev_b32_e32 v220, 16, v212
	v_add_co_u32_e32 v206, vcc, s76, v196
	v_and_b32_e32 v221, 0xffff0000, v212
	s_nop 0
	v_addc_co_u32_e32 v207, vcc, 0, v197, vcc
	global_load_dwordx4 v[238:241], v[206:207], off offset:2048
	v_add_co_u32_e32 v208, vcc, s0, v196
	v_lshlrev_b32_e32 v212, 16, v213
	s_nop 0
	v_addc_co_u32_e32 v209, vcc, 0, v197, vcc
	global_load_dwordx4 v[242:245], v[208:209], off offset:2048
	v_and_b32_e32 v213, 0xffff0000, v213
	v_lshlrev_b32_e32 v234, 16, v214
	v_and_b32_e32 v235, 0xffff0000, v214
	v_lshlrev_b32_e32 v214, 16, v215
	v_and_b32_e32 v215, 0xffff0000, v215
	v_pk_fma_f32 v[98:99], v[98:99], v[176:177], v[212:213]
	v_pk_fma_f32 v[96:97], v[96:97], v[174:175], v[220:221]
	v_pk_fma_f32 v[94:95], v[94:95], v[172:173], v[214:215]
	v_pk_fma_f32 v[92:93], v[92:93], v[164:165], v[234:235]
	v_cvt_pk_bf16_f32 v214, v96, v97
	v_cvt_pk_bf16_f32 v215, v98, v99
	v_add_co_u32_e32 v212, vcc, s19, v182
	v_lshlrev_b32_e32 v246, 16, v216
	v_and_b32_e32 v247, 0xffff0000, v216
	v_lshlrev_b32_e32 v248, 16, v217
	v_and_b32_e32 v249, 0xffff0000, v217
	v_cvt_pk_bf16_f32 v216, v92, v93
	v_cvt_pk_bf16_f32 v217, v94, v95
	v_addc_co_u32_e32 v213, vcc, 0, v183, vcc
	v_lshlrev_b32_e32 v98, 16, v214
	v_and_b32_e32 v99, 0xffff0000, v214
	v_lshlrev_b32_e32 v96, 16, v215
	v_and_b32_e32 v97, 0xffff0000, v215
	global_store_dwordx4 v[212:213], v[214:217], off offset:2048
	v_lshlrev_b32_e32 v94, 16, v216
	v_and_b32_e32 v95, 0xffff0000, v216
	v_lshlrev_b32_e32 v92, 16, v217
	v_and_b32_e32 v93, 0xffff0000, v217
	v_pk_mul_f32 v[214:215], v[138:139], v[96:97]
	v_pk_mul_f32 v[216:217], v[136:137], v[98:99]
	s_mov_b32 s1, 0x40000
	v_lshlrev_b32_e32 v250, 16, v218
	v_and_b32_e32 v251, 0xffff0000, v218
	v_lshlrev_b32_e32 v252, 16, v219
	v_and_b32_e32 v253, 0xffff0000, v219
	v_pk_mul_f32 v[220:221], v[134:135], v[92:93]
	v_pk_mul_f32 v[218:219], v[132:133], v[94:95]
	v_cvt_pk_bf16_f32 v216, v216, v217
	v_cvt_pk_bf16_f32 v217, v214, v215
	v_add_co_u32_e32 v214, vcc, s1, v178
	v_cvt_pk_bf16_f32 v218, v218, v219
	v_cvt_pk_bf16_f32 v219, v220, v221
	v_addc_co_u32_e32 v215, vcc, 0, v179, vcc
	v_pk_fma_f32 v[90:91], v[90:91], v[176:177], v[248:249]
	global_store_dwordx4 v[214:215], v[216:219], off
	v_pk_fma_f32 v[88:89], v[88:89], v[174:175], v[246:247]
	v_pk_fma_f32 v[86:87], v[86:87], v[172:173], v[252:253]
	v_pk_fma_f32 v[84:85], v[84:85], v[164:165], v[250:251]
	v_cvt_pk_bf16_f32 v219, v90, v91
	v_add_co_u32_e32 v216, vcc, s26, v182
	v_cvt_pk_bf16_f32 v218, v88, v89
	v_cvt_pk_bf16_f32 v220, v84, v85
	v_cvt_pk_bf16_f32 v221, v86, v87
	v_addc_co_u32_e32 v217, vcc, 0, v183, vcc
	v_lshlrev_b32_e32 v88, 16, v219
	v_and_b32_e32 v89, 0xffff0000, v219
	global_store_dwordx4 v[216:217], v[218:221], off offset:2048
	v_lshlrev_b32_e32 v90, 16, v218
	v_and_b32_e32 v91, 0xffff0000, v218
	v_lshlrev_b32_e32 v86, 16, v220
	v_and_b32_e32 v87, 0xffff0000, v220
	v_lshlrev_b32_e32 v84, 16, v221
	v_and_b32_e32 v85, 0xffff0000, v221
	v_pk_mul_f32 v[218:219], v[138:139], v[88:89]
	s_mov_b32 s1, 0x48000
	v_pk_mul_f32 v[220:221], v[136:137], v[90:91]
	v_pk_mul_f32 v[234:235], v[134:135], v[84:85]
	v_pk_mul_f32 v[248:249], v[132:133], v[86:87]
	v_cvt_pk_bf16_f32 v247, v218, v219
	v_add_co_u32_e32 v218, vcc, s1, v178
	v_cvt_pk_bf16_f32 v246, v220, v221
	v_cvt_pk_bf16_f32 v248, v248, v249
	v_cvt_pk_bf16_f32 v249, v234, v235
	v_addc_co_u32_e32 v219, vcc, 0, v179, vcc
	global_store_dwordx4 v[218:219], v[246:249], off
	global_load_dwordx4 v[246:249], v[196:197], off offset:2304
	s_nop 0
	global_load_dwordx4 v[250:253], v[210:211], off offset:2304
	s_waitcnt vmcnt(0)
	v_lshlrev_b32_e32 v210, 16, v239
	v_and_b32_e32 v211, 0xffff0000, v239
	v_lshlrev_b32_e32 v196, 16, v238
	v_and_b32_e32 v197, 0xffff0000, v238
	v_pk_fma_f32 v[82:83], v[82:83], v[176:177], v[210:211]
	v_lshlrev_b32_e32 v220, 16, v240
	v_and_b32_e32 v221, 0xffff0000, v240
	v_lshlrev_b32_e32 v234, 16, v241
	v_and_b32_e32 v235, 0xffff0000, v241
	v_pk_fma_f32 v[80:81], v[80:81], v[174:175], v[196:197]
	v_cvt_pk_bf16_f32 v239, v82, v83
	v_pk_fma_f32 v[78:79], v[78:79], v[172:173], v[234:235]
	v_pk_fma_f32 v[76:77], v[76:77], v[164:165], v[220:221]
	v_cvt_pk_bf16_f32 v238, v80, v81
	v_add_co_u32_e32 v196, vcc, s76, v182
	v_lshlrev_b32_e32 v80, 16, v239
	v_and_b32_e32 v81, 0xffff0000, v239
	v_cvt_pk_bf16_f32 v240, v76, v77
	v_cvt_pk_bf16_f32 v241, v78, v79
	v_addc_co_u32_e32 v197, vcc, 0, v183, vcc
	v_pk_mul_f32 v[210:211], v[138:139], v[80:81]
	v_lshlrev_b32_e32 v166, 16, v242
	v_and_b32_e32 v167, 0xffff0000, v242
	v_lshlrev_b32_e32 v242, 16, v243
	v_and_b32_e32 v243, 0xffff0000, v243
	v_lshlrev_b32_e32 v168, 16, v244
	v_and_b32_e32 v169, 0xffff0000, v244
	v_lshlrev_b32_e32 v244, 16, v245
	v_and_b32_e32 v245, 0xffff0000, v245
	global_store_dwordx4 v[196:197], v[238:241], off offset:2048
	v_lshlrev_b32_e32 v82, 16, v238
	v_and_b32_e32 v83, 0xffff0000, v238
	v_cvt_pk_bf16_f32 v239, v210, v211
	v_add_co_u32_e32 v210, vcc, s77, v178
	v_lshlrev_b32_e32 v78, 16, v240
	v_and_b32_e32 v79, 0xffff0000, v240
	v_lshlrev_b32_e32 v76, 16, v241
	v_and_b32_e32 v77, 0xffff0000, v241
	v_pk_mul_f32 v[220:221], v[136:137], v[82:83]
	v_addc_co_u32_e32 v211, vcc, 0, v179, vcc
	v_pk_fma_f32 v[74:75], v[74:75], v[176:177], v[242:243]
	v_pk_fma_f32 v[72:73], v[72:73], v[174:175], v[166:167]
	v_pk_fma_f32 v[166:167], v[70:71], v[172:173], v[244:245]
	v_pk_fma_f32 v[70:71], v[68:69], v[164:165], v[168:169]
	v_pk_mul_f32 v[234:235], v[134:135], v[76:77]
	v_pk_mul_f32 v[240:241], v[132:133], v[78:79]
	v_cvt_pk_bf16_f32 v238, v220, v221
	v_cvt_pk_bf16_f32 v68, v72, v73
	v_cvt_pk_bf16_f32 v69, v74, v75
	v_cvt_pk_bf16_f32 v70, v70, v71
	v_cvt_pk_bf16_f32 v71, v166, v167
	v_add_co_u32_e32 v220, vcc, s0, v182
	v_cvt_pk_bf16_f32 v240, v240, v241
	v_cvt_pk_bf16_f32 v241, v234, v235
	v_addc_co_u32_e32 v221, vcc, 0, v183, vcc
	v_lshlrev_b32_e32 v176, 16, v68
	v_and_b32_e32 v177, 0xffff0000, v68
	v_lshlrev_b32_e32 v174, 16, v69
	v_and_b32_e32 v175, 0xffff0000, v69
	v_lshlrev_b32_e32 v172, 16, v70
	v_and_b32_e32 v173, 0xffff0000, v70
	v_lshlrev_b32_e32 v164, 16, v71
	v_and_b32_e32 v165, 0xffff0000, v71
	s_mov_b32 s0, 0x58000
	global_store_dwordx4 v[210:211], v[238:241], off
	global_store_dwordx4 v[220:221], v[68:71], off offset:2048
	v_pk_mul_f32 v[72:73], v[134:135], v[164:165]
	v_pk_mul_f32 v[74:75], v[132:133], v[172:173]
	v_pk_mul_f32 v[70:71], v[138:139], v[174:175]
	v_pk_mul_f32 v[68:69], v[136:137], v[176:177]
	v_add_co_u32_e32 v132, vcc, s0, v178
	v_cvt_pk_bf16_f32 v68, v68, v69
	v_cvt_pk_bf16_f32 v69, v70, v71
	v_cvt_pk_bf16_f32 v70, v74, v75
	v_cvt_pk_bf16_f32 v71, v72, v73
	v_addc_co_u32_e32 v133, vcc, 0, v179, vcc
	global_store_dwordx4 v[132:133], v[68:71], off
	global_load_dwordx4 v[134:137], v[184:185], off offset:2304
	global_load_dwordx4 v[238:241], v[188:189], off offset:2304
	s_nop 0
	global_load_dwordx4 v[68:71], v[180:181], off offset:528
	global_load_dwordx4 v[72:75], v[180:181], off offset:512
	v_lshlrev_b32_e32 v138, 16, v246
	v_and_b32_e32 v139, 0xffff0000, v246
	v_lshlrev_b32_e32 v166, 16, v247
	v_and_b32_e32 v167, 0xffff0000, v247
	v_lshlrev_b32_e32 v168, 16, v248
	v_and_b32_e32 v169, 0xffff0000, v248
	v_lshlrev_b32_e32 v180, 16, v249
	v_and_b32_e32 v181, 0xffff0000, v249
	v_pk_fma_f32 v[66:67], v[66:67], v[162:163], v[166:167]
	v_pk_fma_f32 v[64:65], v[64:65], v[160:161], v[138:139]
	v_pk_fma_f32 v[62:63], v[62:63], v[158:159], v[180:181]
	v_pk_fma_f32 v[60:61], v[60:61], v[156:157], v[168:169]
	v_cvt_pk_bf16_f32 v242, v64, v65
	v_cvt_pk_bf16_f32 v243, v66, v67
	v_cvt_pk_bf16_f32 v244, v60, v61
	v_cvt_pk_bf16_f32 v245, v62, v63
	v_lshlrev_b32_e32 v66, 16, v242
	v_and_b32_e32 v67, 0xffff0000, v242
	v_lshlrev_b32_e32 v64, 16, v243
	v_and_b32_e32 v65, 0xffff0000, v243
	v_lshlrev_b32_e32 v62, 16, v244
	v_and_b32_e32 v63, 0xffff0000, v244
	v_lshlrev_b32_e32 v60, 16, v245
	v_and_b32_e32 v61, 0xffff0000, v245
	v_lshlrev_b32_e32 v184, 16, v250
	v_and_b32_e32 v185, 0xffff0000, v250
	v_lshlrev_b32_e32 v188, 16, v251
	v_and_b32_e32 v189, 0xffff0000, v251
	v_lshlrev_b32_e32 v234, 16, v252
	v_and_b32_e32 v235, 0xffff0000, v252
	v_lshlrev_b32_e32 v246, 16, v253
	v_and_b32_e32 v247, 0xffff0000, v253
	global_store_dwordx4 v[182:183], v[242:245], off offset:2304
	v_pk_fma_f32 v[58:59], v[58:59], v[162:163], v[188:189]
	v_pk_fma_f32 v[56:57], v[56:57], v[160:161], v[184:185]
	v_pk_fma_f32 v[54:55], v[54:55], v[158:159], v[246:247]
	v_pk_fma_f32 v[52:53], v[52:53], v[156:157], v[234:235]
	s_waitcnt vmcnt(0)
	v_lshlrev_b32_e32 v188, 16, v240
	v_pk_mul_f32 v[168:169], v[70:71], v[60:61]
	v_pk_mul_f32 v[138:139], v[74:75], v[64:65]
	v_pk_mul_f32 v[166:167], v[72:73], v[66:67]
	v_pk_mul_f32 v[182:183], v[68:69], v[62:63]
	v_cvt_pk_bf16_f32 v180, v166, v167
	v_cvt_pk_bf16_f32 v181, v138, v139
	v_cvt_pk_bf16_f32 v182, v182, v183
	v_cvt_pk_bf16_f32 v183, v168, v169
	global_store_dwordx4 v[178:179], v[180:183], off offset:256
	v_cvt_pk_bf16_f32 v178, v56, v57
	v_cvt_pk_bf16_f32 v179, v58, v59
	v_cvt_pk_bf16_f32 v180, v52, v53
	v_cvt_pk_bf16_f32 v181, v54, v55
	v_lshlrev_b32_e32 v58, 16, v178
	v_and_b32_e32 v59, 0xffff0000, v178
	v_lshlrev_b32_e32 v56, 16, v179
	v_and_b32_e32 v57, 0xffff0000, v179
	v_lshlrev_b32_e32 v54, 16, v180
	v_and_b32_e32 v55, 0xffff0000, v180
	v_lshlrev_b32_e32 v52, 16, v181
	v_and_b32_e32 v53, 0xffff0000, v181
	global_store_dwordx4 v[186:187], v[178:181], off offset:2304
	v_pk_mul_f32 v[138:139], v[74:75], v[56:57]
	v_pk_mul_f32 v[166:167], v[72:73], v[58:59]
	v_pk_mul_f32 v[168:169], v[70:71], v[52:53]
	v_pk_mul_f32 v[180:181], v[68:69], v[54:55]
	v_cvt_pk_bf16_f32 v178, v166, v167
	v_cvt_pk_bf16_f32 v179, v138, v139
	v_cvt_pk_bf16_f32 v180, v180, v181
	v_cvt_pk_bf16_f32 v181, v168, v169
	v_lshlrev_b32_e32 v138, 16, v134
	v_and_b32_e32 v139, 0xffff0000, v134
	v_lshlrev_b32_e32 v134, 16, v135
	v_and_b32_e32 v135, 0xffff0000, v135
	v_lshlrev_b32_e32 v166, 16, v136
	v_and_b32_e32 v167, 0xffff0000, v136
	v_lshlrev_b32_e32 v136, 16, v137
	v_and_b32_e32 v137, 0xffff0000, v137
	global_store_dwordx4 v[190:191], v[178:181], off offset:256
	v_pk_fma_f32 v[50:51], v[50:51], v[162:163], v[134:135]
	v_pk_fma_f32 v[48:49], v[48:49], v[160:161], v[138:139]
	v_pk_fma_f32 v[46:47], v[46:47], v[158:159], v[136:137]
	v_pk_fma_f32 v[44:45], v[44:45], v[156:157], v[166:167]
	global_load_dwordx4 v[178:181], v[192:193], off offset:2304
	global_load_dwordx4 v[182:185], v[194:195], off offset:2304
	v_cvt_pk_bf16_f32 v134, v48, v49
	v_cvt_pk_bf16_f32 v135, v50, v51
	v_cvt_pk_bf16_f32 v136, v44, v45
	v_cvt_pk_bf16_f32 v137, v46, v47
	v_lshlrev_b32_e32 v50, 16, v134
	v_and_b32_e32 v51, 0xffff0000, v134
	v_lshlrev_b32_e32 v48, 16, v135
	v_and_b32_e32 v49, 0xffff0000, v135
	v_lshlrev_b32_e32 v46, 16, v136
	v_and_b32_e32 v47, 0xffff0000, v136
	v_lshlrev_b32_e32 v44, 16, v137
	v_and_b32_e32 v45, 0xffff0000, v137
	v_lshlrev_b32_e32 v168, 16, v238
	v_and_b32_e32 v169, 0xffff0000, v238
	v_lshlrev_b32_e32 v186, 16, v239
	v_and_b32_e32 v187, 0xffff0000, v239
	v_and_b32_e32 v189, 0xffff0000, v240
	v_lshlrev_b32_e32 v190, 16, v241
	v_and_b32_e32 v191, 0xffff0000, v241
	global_store_dwordx4 v[198:199], v[134:137], off offset:2304
	v_pk_mul_f32 v[138:139], v[70:71], v[44:45]
	v_pk_mul_f32 v[166:167], v[68:69], v[46:47]
	v_pk_mul_f32 v[136:137], v[74:75], v[48:49]
	v_pk_mul_f32 v[134:135], v[72:73], v[50:51]
	v_pk_fma_f32 v[42:43], v[42:43], v[162:163], v[186:187]
	v_cvt_pk_bf16_f32 v134, v134, v135
	v_cvt_pk_bf16_f32 v135, v136, v137
	v_cvt_pk_bf16_f32 v136, v166, v167
	v_cvt_pk_bf16_f32 v137, v138, v139
	v_pk_fma_f32 v[40:41], v[40:41], v[160:161], v[168:169]
	v_pk_fma_f32 v[38:39], v[38:39], v[158:159], v[190:191]
	v_pk_fma_f32 v[36:37], v[36:37], v[156:157], v[188:189]
	global_store_dwordx4 v[200:201], v[134:137], off offset:256
	v_mul_f32_e32 v67, v67, v67
	v_mul_f32_e32 v65, v65, v65
	v_cvt_pk_bf16_f32 v134, v40, v41
	v_cvt_pk_bf16_f32 v135, v42, v43
	v_cvt_pk_bf16_f32 v136, v36, v37
	v_cvt_pk_bf16_f32 v137, v38, v39
	v_lshlrev_b32_e32 v42, 16, v134
	v_and_b32_e32 v43, 0xffff0000, v134
	v_lshlrev_b32_e32 v40, 16, v135
	v_and_b32_e32 v41, 0xffff0000, v135
	v_lshlrev_b32_e32 v38, 16, v136
	v_and_b32_e32 v39, 0xffff0000, v136
	v_lshlrev_b32_e32 v36, 16, v137
	v_and_b32_e32 v37, 0xffff0000, v137
	global_store_dwordx4 v[202:203], v[134:137], off offset:2304
	v_pk_mul_f32 v[138:139], v[70:71], v[36:37]
	v_pk_mul_f32 v[166:167], v[68:69], v[38:39]
	v_pk_mul_f32 v[136:137], v[74:75], v[40:41]
	v_pk_mul_f32 v[134:135], v[72:73], v[42:43]
	v_fmac_f32_e32 v67, v66, v66
	v_cvt_pk_bf16_f32 v134, v134, v135
	v_cvt_pk_bf16_f32 v135, v136, v137
	v_cvt_pk_bf16_f32 v136, v166, v167
	v_cvt_pk_bf16_f32 v137, v138, v139
	global_store_dwordx4 v[204:205], v[134:137], off offset:256
	global_load_dwordx4 v[134:137], v[206:207], off offset:2304
	s_nop 0
	global_load_dwordx4 v[186:189], v[208:209], off offset:2304
	v_fmac_f32_e32 v65, v64, v64
	v_mul_f32_e32 v63, v63, v63
	v_mul_f32_e32 v61, v61, v61
	v_add_f32_e32 v64, v67, v65
	v_fmac_f32_e32 v63, v62, v62
	v_fmac_f32_e32 v61, v60, v60
	v_add_f32_e32 v60, v63, v61
	s_waitcnt vmcnt(0)
	v_lshlrev_b32_e32 v138, 16, v178
	v_and_b32_e32 v139, 0xffff0000, v178
	v_lshlrev_b32_e32 v166, 16, v179
	v_and_b32_e32 v167, 0xffff0000, v179
	v_lshlrev_b32_e32 v168, 16, v180
	v_and_b32_e32 v169, 0xffff0000, v180
	v_lshlrev_b32_e32 v178, 16, v181
	v_and_b32_e32 v179, 0xffff0000, v181
	v_pk_fma_f32 v[34:35], v[34:35], v[162:163], v[166:167]
	v_pk_fma_f32 v[32:33], v[32:33], v[160:161], v[138:139]
	v_pk_fma_f32 v[30:31], v[30:31], v[158:159], v[178:179]
	v_pk_fma_f32 v[28:29], v[28:29], v[156:157], v[168:169]
	v_cvt_pk_bf16_f32 v178, v32, v33
	v_cvt_pk_bf16_f32 v179, v34, v35
	v_cvt_pk_bf16_f32 v180, v28, v29
	v_cvt_pk_bf16_f32 v181, v30, v31
	v_lshlrev_b32_e32 v34, 16, v178
	v_and_b32_e32 v35, 0xffff0000, v178
	v_lshlrev_b32_e32 v32, 16, v179
	v_and_b32_e32 v33, 0xffff0000, v179
	v_lshlrev_b32_e32 v30, 16, v180
	v_and_b32_e32 v31, 0xffff0000, v180
	v_lshlrev_b32_e32 v28, 16, v181
	v_and_b32_e32 v29, 0xffff0000, v181
	v_lshlrev_b32_e32 v190, 16, v182
	v_and_b32_e32 v191, 0xffff0000, v182
	v_lshlrev_b32_e32 v182, 16, v183
	v_and_b32_e32 v183, 0xffff0000, v183
	global_store_dwordx4 v[212:213], v[178:181], off offset:2304
	v_pk_mul_f32 v[138:139], v[74:75], v[32:33]
	v_pk_mul_f32 v[166:167], v[72:73], v[34:35]
	v_pk_mul_f32 v[168:169], v[70:71], v[28:29]
	v_pk_mul_f32 v[180:181], v[68:69], v[30:31]
	v_cvt_pk_bf16_f32 v178, v166, v167
	v_cvt_pk_bf16_f32 v179, v138, v139
	v_cvt_pk_bf16_f32 v180, v180, v181
	v_cvt_pk_bf16_f32 v181, v168, v169
	v_pk_fma_f32 v[24:25], v[24:25], v[162:163], v[182:183]
	v_pk_fma_f32 v[22:23], v[22:23], v[160:161], v[190:191]
	v_lshlrev_b32_e32 v192, 16, v184
	v_and_b32_e32 v193, 0xffff0000, v184
	v_lshlrev_b32_e32 v184, 16, v185
	v_and_b32_e32 v185, 0xffff0000, v185
	global_store_dwordx4 v[214:215], v[178:181], off offset:256
	v_pk_fma_f32 v[20:21], v[20:21], v[158:159], v[184:185]
	v_pk_fma_f32 v[18:19], v[18:19], v[156:157], v[192:193]
	v_cvt_pk_bf16_f32 v178, v22, v23
	v_cvt_pk_bf16_f32 v179, v24, v25
	v_lshlrev_b32_e32 v24, 16, v178
	v_and_b32_e32 v25, 0xffff0000, v178
	v_lshlrev_b32_e32 v22, 16, v179
	v_and_b32_e32 v23, 0xffff0000, v179
	v_cvt_pk_bf16_f32 v180, v18, v19
	v_cvt_pk_bf16_f32 v181, v20, v21
	v_pk_mul_f32 v[138:139], v[74:75], v[22:23]
	v_pk_mul_f32 v[166:167], v[72:73], v[24:25]
	global_store_dwordx4 v[216:217], v[178:181], off offset:2304
	v_lshlrev_b32_e32 v20, 16, v180
	v_and_b32_e32 v21, 0xffff0000, v180
	v_cvt_pk_bf16_f32 v178, v166, v167
	v_cvt_pk_bf16_f32 v179, v138, v139
	v_lshlrev_b32_e32 v138, 16, v134
	v_and_b32_e32 v139, 0xffff0000, v134
	v_lshlrev_b32_e32 v134, 16, v135
	v_and_b32_e32 v135, 0xffff0000, v135
	v_lshlrev_b32_e32 v166, 16, v136
	v_and_b32_e32 v167, 0xffff0000, v136
	v_lshlrev_b32_e32 v136, 16, v137
	v_and_b32_e32 v137, 0xffff0000, v137
	v_lshlrev_b32_e32 v18, 16, v181
	v_and_b32_e32 v19, 0xffff0000, v181
	v_pk_fma_f32 v[16:17], v[16:17], v[162:163], v[134:135]
	v_pk_fma_f32 v[14:15], v[14:15], v[160:161], v[138:139]
	v_pk_fma_f32 v[12:13], v[12:13], v[158:159], v[136:137]
	v_pk_fma_f32 v[10:11], v[10:11], v[156:157], v[166:167]
	v_pk_mul_f32 v[168:169], v[70:71], v[18:19]
	v_pk_mul_f32 v[180:181], v[68:69], v[20:21]
	v_cvt_pk_bf16_f32 v134, v14, v15
	v_cvt_pk_bf16_f32 v135, v16, v17
	v_cvt_pk_bf16_f32 v136, v10, v11
	v_cvt_pk_bf16_f32 v137, v12, v13
	v_cvt_pk_bf16_f32 v180, v180, v181
	v_cvt_pk_bf16_f32 v181, v168, v169
	v_lshlrev_b32_e32 v16, 16, v134
	v_and_b32_e32 v17, 0xffff0000, v134
	v_lshlrev_b32_e32 v14, 16, v135
	v_and_b32_e32 v15, 0xffff0000, v135
	v_lshlrev_b32_e32 v12, 16, v136
	v_and_b32_e32 v13, 0xffff0000, v136
	v_lshlrev_b32_e32 v10, 16, v137
	v_and_b32_e32 v11, 0xffff0000, v137
	global_store_dwordx4 v[218:219], v[178:181], off offset:256
	v_lshlrev_b32_e32 v168, 16, v186
	v_and_b32_e32 v169, 0xffff0000, v186
	v_lshlrev_b32_e32 v178, 16, v187
	v_and_b32_e32 v179, 0xffff0000, v187
	v_lshlrev_b32_e32 v180, 16, v188
	v_and_b32_e32 v181, 0xffff0000, v188
	v_lshlrev_b32_e32 v182, 16, v189
	v_and_b32_e32 v183, 0xffff0000, v189
	global_store_dwordx4 v[196:197], v[134:137], off offset:2304
	v_pk_mul_f32 v[138:139], v[70:71], v[10:11]
	v_pk_mul_f32 v[166:167], v[68:69], v[12:13]
	v_pk_mul_f32 v[136:137], v[74:75], v[14:15]
	v_pk_mul_f32 v[134:135], v[72:73], v[16:17]
	v_pk_fma_f32 v[8:9], v[8:9], v[162:163], v[178:179]
	v_cvt_pk_bf16_f32 v134, v134, v135
	v_cvt_pk_bf16_f32 v135, v136, v137
	v_cvt_pk_bf16_f32 v136, v166, v167
	v_cvt_pk_bf16_f32 v137, v138, v139
	v_pk_fma_f32 v[6:7], v[6:7], v[160:161], v[168:169]
	v_pk_fma_f32 v[4:5], v[4:5], v[158:159], v[182:183]
	v_pk_fma_f32 v[2:3], v[2:3], v[156:157], v[180:181]
	global_store_dwordx4 v[210:211], v[134:137], off offset:256
	s_nop 1
	v_cvt_pk_bf16_f32 v134, v6, v7
	v_cvt_pk_bf16_f32 v135, v8, v9
	v_cvt_pk_bf16_f32 v136, v2, v3
	v_cvt_pk_bf16_f32 v137, v4, v5
	v_lshlrev_b32_e32 v8, 16, v134
	v_and_b32_e32 v9, 0xffff0000, v134
	v_lshlrev_b32_e32 v6, 16, v135
	v_and_b32_e32 v7, 0xffff0000, v135
	v_lshlrev_b32_e32 v4, 16, v136
	v_and_b32_e32 v5, 0xffff0000, v136
	v_lshlrev_b32_e32 v2, 16, v137
	v_and_b32_e32 v3, 0xffff0000, v137
	global_store_dwordx4 v[220:221], v[134:137], off offset:2304
	v_pk_mul_f32 v[74:75], v[74:75], v[6:7]
	v_pk_mul_f32 v[72:73], v[72:73], v[8:9]
	v_pk_mul_f32 v[134:135], v[70:71], v[2:3]
	v_pk_mul_f32 v[70:71], v[68:69], v[4:5]
	v_cvt_pk_bf16_f32 v68, v72, v73
	v_cvt_pk_bf16_f32 v69, v74, v75
	v_cvt_pk_bf16_f32 v70, v70, v71
	v_cvt_pk_bf16_f32 v71, v134, v135
	global_store_dwordx4 v[132:133], v[68:71], off offset:256
	v_xor_b32_e32 v72, 32, v227
	v_mul_f32_e32 v73, v129, v129
	v_and_b32_e32 v71, 64, v227
	v_xor_b32_e32 v70, 16, v227
	v_add_u32_e32 v71, 64, v71
	v_cmp_lt_i32_e32 vcc, v70, v71
	v_fmac_f32_e32 v73, v128, v128
	v_mul_f32_e32 v74, v125, v125
	v_cndmask_b32_e32 v70, v227, v70, vcc
	v_cmp_lt_i32_e32 vcc, v72, v71
	v_fmac_f32_e32 v74, v124, v124
	v_lshlrev_b32_e32 v70, 2, v70
	v_cndmask_b32_e32 v71, v227, v72, vcc
	v_mul_f32_e32 v72, v131, v131
	v_fmac_f32_e32 v72, v130, v130
	v_add_f32_e32 v72, v72, v73
	v_mul_f32_e32 v73, v127, v127
	v_fmac_f32_e32 v73, v126, v126
	v_add_f32_e32 v73, v73, v74
	v_add_f32_e32 v72, v72, v73
	v_add_f32_e32 v64, v72, v64
	v_add_f32_e32 v60, v60, v64
	ds_bpermute_b32 v61, v70, v60
	v_lshlrev_b32_e32 v71, 2, v71
	v_lshl_add_u64 v[68:69], v[150:151], 0, s[24:25]
	s_waitcnt lgkmcnt(0)
	v_add_f32_e32 v60, v60, v61
	ds_bpermute_b32 v61, v71, v60
	s_and_saveexec_b64 s[18:19], s[40:41]
	s_cbranch_execz .LBB0_364
	s_waitcnt lgkmcnt(0)
	v_add_f32_e32 v60, v60, v61
	global_atomic_add_f32 v[68:69], v60, off

.LBB0_395:
	s_add_u32 s26, s24, 0x100
	s_addc_u32 s27, s25, 0
	s_add_i32 s0, 0, 0x10000
	v_add_u32_e32 v160, s0, v233
	ds_read_b128 v[100:103], v160
	ds_read_b128 v[104:107], v160 offset:1024
	ds_read_b128 v[156:159], v160 offset:2048
	ds_read_b128 v[160:163], v160 offset:3072
	s_cmp_eq_u32 s52, 40
	s_cselect_b32 s31, s43, s27
	s_cselect_b32 s30, s42, s26
	s_cselect_b32 s29, s45, s19
	s_cselect_b32 s28, s44, s18
	v_lshl_add_u64 v[164:165], s[24:25], 0, v[152:153]
	s_add_i32 m0, s69, 0xc000
	ds_read_b128 v[172:175], v235
	ds_read_b128 v[176:179], v235 offset:1024
	ds_read_b128 v[180:183], v235 offset:2048
	ds_read_b128 v[184:187], v235 offset:3072
	ds_read_b128 v[188:191], v235 offset:4096
	ds_read_b128 v[192:195], v235 offset:5120
	ds_read_b128 v[196:199], v235 offset:6144
	ds_read_b128 v[200:203], v235 offset:7168
	global_load_lds_dwordx4 v[164:165], off
	v_lshl_add_u64 v[164:165], s[24:25], 0, v[154:155]
	s_add_i32 m0, s69, 0xe000
	s_nop 0
	global_load_lds_dwordx4 v[164:165], off
	s_waitcnt lgkmcnt(8)
	s_setprio 1
	s_barrier
	s_waitcnt lgkmcnt(0)
	v_mfma_f32_16x16x32_bf16 v[136:139], v[100:103], v[172:175], v[136:139]
	v_mfma_f32_16x16x32_bf16 v[132:135], v[156:159], v[172:175], v[132:135]
	v_mfma_f32_16x16x32_bf16 v[128:131], v[100:103], v[180:183], v[128:131]
	v_mfma_f32_16x16x32_bf16 v[124:127], v[156:159], v[180:183], v[124:127]
	v_mfma_f32_16x16x32_bf16 v[120:123], v[100:103], v[188:191], v[120:123]
	v_mfma_f32_16x16x32_bf16 v[116:119], v[156:159], v[188:191], v[116:119]
	v_mfma_f32_16x16x32_bf16 v[112:115], v[100:103], v[196:199], v[112:115]
	v_mfma_f32_16x16x32_bf16 v[108:111], v[156:159], v[196:199], v[108:111]
	v_mfma_f32_16x16x32_bf16 v[136:139], v[104:107], v[176:179], v[136:139]
	v_mfma_f32_16x16x32_bf16 v[132:135], v[160:163], v[176:179], v[132:135]
	v_mfma_f32_16x16x32_bf16 v[128:131], v[104:107], v[184:187], v[128:131]
	v_mfma_f32_16x16x32_bf16 v[124:127], v[160:163], v[184:187], v[124:127]
	v_mfma_f32_16x16x32_bf16 v[120:123], v[104:107], v[192:195], v[120:123]
	v_mfma_f32_16x16x32_bf16 v[116:119], v[160:163], v[192:195], v[116:119]
	v_mfma_f32_16x16x32_bf16 v[112:115], v[104:107], v[200:203], v[112:115]
	v_mfma_f32_16x16x32_bf16 v[108:111], v[160:163], v[200:203], v[108:111]
	s_barrier
	s_setprio 0
	s_add_i32 s24, 0, 0x14000
	v_add_u32_e32 v164, s24, v233
	s_add_i32 s0, s0, s68
	ds_read_b128 v[204:207], v164
	ds_read_b128 v[208:211], v164 offset:1024
	ds_read_b128 v[212:215], v164 offset:2048
	ds_read_b128 v[216:219], v164 offset:3072
	v_lshl_add_u64 v[164:165], s[28:29], 0, v[26:27]
	s_mov_b32 m0, s0
	v_lshl_add_u64 v[220:221], s[28:29], 0, v[140:141]
	global_load_lds_dwordx4 v[164:165], off
	s_add_i32 m0, s0, 0x2000
	s_nop 0
	global_load_lds_dwordx4 v[220:221], off
	s_setprio 1
	s_barrier
	s_waitcnt lgkmcnt(0)
	v_mfma_f32_16x16x32_bf16 v[64:67], v[204:207], v[172:175], v[64:67]
	v_mfma_f32_16x16x32_bf16 v[60:63], v[212:215], v[172:175], v[60:63]
	v_mfma_f32_16x16x32_bf16 v[56:59], v[204:207], v[180:183], v[56:59]
	v_mfma_f32_16x16x32_bf16 v[52:55], v[212:215], v[180:183], v[52:55]
	v_mfma_f32_16x16x32_bf16 v[48:51], v[204:207], v[188:191], v[48:51]
	v_mfma_f32_16x16x32_bf16 v[44:47], v[212:215], v[188:191], v[44:47]
	v_mfma_f32_16x16x32_bf16 v[40:43], v[204:207], v[196:199], v[40:43]
	v_mfma_f32_16x16x32_bf16 v[36:39], v[212:215], v[196:199], v[36:39]
	v_mfma_f32_16x16x32_bf16 v[64:67], v[208:211], v[176:179], v[64:67]
	v_mfma_f32_16x16x32_bf16 v[60:63], v[216:219], v[176:179], v[60:63]
	v_mfma_f32_16x16x32_bf16 v[56:59], v[208:211], v[184:187], v[56:59]
	v_mfma_f32_16x16x32_bf16 v[52:55], v[216:219], v[184:187], v[52:55]
	v_mfma_f32_16x16x32_bf16 v[48:51], v[208:211], v[192:195], v[48:51]
	v_mfma_f32_16x16x32_bf16 v[44:47], v[216:219], v[192:195], v[44:47]
	v_mfma_f32_16x16x32_bf16 v[40:43], v[208:211], v[200:203], v[40:43]
	v_mfma_f32_16x16x32_bf16 v[36:39], v[216:219], v[200:203], v[36:39]
	s_barrier
	s_setprio 0
	s_mov_b32 m0, s69
	v_lshl_add_u64 v[222:223], s[30:31], 0, v[144:145]
	ds_read_b128 v[172:175], v235 offset:16384
	ds_read_b128 v[176:179], v235 offset:17408
	ds_read_b128 v[180:183], v235 offset:18432
	ds_read_b128 v[184:187], v235 offset:19456
	ds_read_b128 v[188:191], v235 offset:20480
	ds_read_b128 v[192:195], v235 offset:21504
	ds_read_b128 v[196:199], v235 offset:22528
	ds_read_b128 v[200:203], v235 offset:23552
	global_load_lds_dwordx4 v[222:223], off
	v_lshl_add_u64 v[224:225], s[30:31], 0, v[142:143]
	s_mov_b32 m0, s72
	s_nop 0
	global_load_lds_dwordx4 v[224:225], off
	s_setprio 1
	s_barrier
	s_waitcnt lgkmcnt(0)
	v_mfma_f32_16x16x32_bf16 v[96:99], v[100:103], v[172:175], v[96:99]
	v_mfma_f32_16x16x32_bf16 v[92:95], v[156:159], v[172:175], v[92:95]
	v_mfma_f32_16x16x32_bf16 v[88:91], v[100:103], v[180:183], v[88:91]
	v_mfma_f32_16x16x32_bf16 v[84:87], v[156:159], v[180:183], v[84:87]
	v_mfma_f32_16x16x32_bf16 v[80:83], v[100:103], v[188:191], v[80:83]
	v_mfma_f32_16x16x32_bf16 v[76:79], v[156:159], v[188:191], v[76:79]
	v_mfma_f32_16x16x32_bf16 v[72:75], v[100:103], v[196:199], v[72:75]
	v_mfma_f32_16x16x32_bf16 v[68:71], v[156:159], v[196:199], v[68:71]
	v_mfma_f32_16x16x32_bf16 v[96:99], v[104:107], v[176:179], v[96:99]
	v_mfma_f32_16x16x32_bf16 v[92:95], v[160:163], v[176:179], v[92:95]
	v_mfma_f32_16x16x32_bf16 v[88:91], v[104:107], v[184:187], v[88:91]
	v_mfma_f32_16x16x32_bf16 v[84:87], v[160:163], v[184:187], v[84:87]
	v_mfma_f32_16x16x32_bf16 v[80:83], v[104:107], v[192:195], v[80:83]
	v_mfma_f32_16x16x32_bf16 v[76:79], v[160:163], v[192:195], v[76:79]
	v_mfma_f32_16x16x32_bf16 v[72:75], v[104:107], v[200:203], v[72:75]
	v_mfma_f32_16x16x32_bf16 v[68:71], v[160:163], v[200:203], v[68:71]
	s_barrier
	s_setprio 0
	s_add_u32 s0, s28, 0xb0000
	s_addc_u32 s1, s29, 0
	s_add_i32 s24, s24, s68
	v_lshl_add_u64 v[100:101], s[0:1], 0, v[26:27]
	s_mov_b32 m0, s24
	s_nop 0
	global_load_lds_dwordx4 v[100:101], off
	v_lshl_add_u64 v[100:101], s[0:1], 0, v[140:141]
	s_add_i32 m0, s24, 0x2000
	s_nop 0
	global_load_lds_dwordx4 v[100:101], off
	s_waitcnt vmcnt(6)
	s_setprio 1
	s_barrier
	v_mfma_f32_16x16x32_bf16 v[32:35], v[204:207], v[172:175], v[32:35]
	v_mfma_f32_16x16x32_bf16 v[28:31], v[212:215], v[172:175], v[28:31]
	v_mfma_f32_16x16x32_bf16 v[22:25], v[204:207], v[180:183], v[22:25]
	v_mfma_f32_16x16x32_bf16 v[18:21], v[212:215], v[180:183], v[18:21]
	v_mfma_f32_16x16x32_bf16 v[14:17], v[204:207], v[188:191], v[14:17]
	v_mfma_f32_16x16x32_bf16 v[10:13], v[212:215], v[188:191], v[10:13]
	v_mfma_f32_16x16x32_bf16 v[6:9], v[204:207], v[196:199], v[6:9]
	v_mfma_f32_16x16x32_bf16 v[2:5], v[212:215], v[196:199], v[2:5]
	v_mfma_f32_16x16x32_bf16 v[32:35], v[208:211], v[176:179], v[32:35]
	v_mfma_f32_16x16x32_bf16 v[28:31], v[216:219], v[176:179], v[28:31]
	v_mfma_f32_16x16x32_bf16 v[22:25], v[208:211], v[184:187], v[22:25]
	v_mfma_f32_16x16x32_bf16 v[18:21], v[216:219], v[184:187], v[18:21]
	v_mfma_f32_16x16x32_bf16 v[14:17], v[208:211], v[192:195], v[14:17]
	v_mfma_f32_16x16x32_bf16 v[10:13], v[216:219], v[192:195], v[10:13]
	v_mfma_f32_16x16x32_bf16 v[6:9], v[208:211], v[200:203], v[6:9]
	v_mfma_f32_16x16x32_bf16 v[2:5], v[216:219], v[200:203], v[2:5]
	s_barrier
	s_setprio 0
	s_add_i32 s24, 0, 0x18000
	v_add_u32_e32 v160, s24, v233
	ds_read_b128 v[100:103], v160
	ds_read_b128 v[104:107], v160 offset:1024
	ds_read_b128 v[156:159], v160 offset:2048
	ds_read_b128 v[160:163], v160 offset:3072
	s_add_u32 s0, s30, 0xb0000
	s_addc_u32 s1, s31, 0
	s_mov_b32 m0, s73
	v_lshl_add_u64 v[204:205], s[0:1], 0, v[144:145]
	ds_read_b128 v[172:175], v235 offset:32768
	ds_read_b128 v[176:179], v235 offset:33792
	ds_read_b128 v[180:183], v235 offset:34816
	ds_read_b128 v[184:187], v235 offset:35840
	ds_read_b128 v[188:191], v235 offset:36864
	ds_read_b128 v[192:195], v235 offset:37888
	ds_read_b128 v[196:199], v235 offset:38912
	ds_read_b128 v[200:203], v235 offset:39936
	global_load_lds_dwordx4 v[204:205], off
	v_lshl_add_u64 v[204:205], s[0:1], 0, v[142:143]
	s_mov_b32 m0, s81
	s_nop 0
	global_load_lds_dwordx4 v[204:205], off
	s_waitcnt lgkmcnt(8)
	s_setprio 1
	s_barrier
	s_waitcnt lgkmcnt(0)
	v_mfma_f32_16x16x32_bf16 v[136:139], v[100:103], v[172:175], v[136:139]
	v_mfma_f32_16x16x32_bf16 v[132:135], v[156:159], v[172:175], v[132:135]
	v_mfma_f32_16x16x32_bf16 v[128:131], v[100:103], v[180:183], v[128:131]
	v_mfma_f32_16x16x32_bf16 v[124:127], v[156:159], v[180:183], v[124:127]
	v_mfma_f32_16x16x32_bf16 v[120:123], v[100:103], v[188:191], v[120:123]
	v_mfma_f32_16x16x32_bf16 v[116:119], v[156:159], v[188:191], v[116:119]
	v_mfma_f32_16x16x32_bf16 v[112:115], v[100:103], v[196:199], v[112:115]
	v_mfma_f32_16x16x32_bf16 v[108:111], v[156:159], v[196:199], v[108:111]
	v_mfma_f32_16x16x32_bf16 v[136:139], v[104:107], v[176:179], v[136:139]
	v_mfma_f32_16x16x32_bf16 v[132:135], v[160:163], v[176:179], v[132:135]
	v_mfma_f32_16x16x32_bf16 v[128:131], v[104:107], v[184:187], v[128:131]
	v_mfma_f32_16x16x32_bf16 v[124:127], v[160:163], v[184:187], v[124:127]
	v_mfma_f32_16x16x32_bf16 v[120:123], v[104:107], v[192:195], v[120:123]
	v_mfma_f32_16x16x32_bf16 v[116:119], v[160:163], v[192:195], v[116:119]
	v_mfma_f32_16x16x32_bf16 v[112:115], v[104:107], v[200:203], v[112:115]
	v_mfma_f32_16x16x32_bf16 v[108:111], v[160:163], v[200:203], v[108:111]
	s_barrier
	s_setprio 0
	s_add_i32 s25, 0, 0x1c000
	s_add_i32 s0, s24, s68
	v_add_u32_e32 v166, s25, v233
	v_lshl_add_u64 v[164:165], v[164:165], 0, s[12:13]
	s_mov_b32 m0, s0
	ds_read_b128 v[204:207], v166
	ds_read_b128 v[208:211], v166 offset:1024
	ds_read_b128 v[212:215], v166 offset:2048
	ds_read_b128 v[216:219], v166 offset:3072
	global_load_lds_dwordx4 v[164:165], off
	v_lshl_add_u64 v[164:165], v[220:221], 0, s[12:13]
	s_add_i32 m0, s0, 0x2000
	s_nop 0
	global_load_lds_dwordx4 v[164:165], off
	s_setprio 1
	s_barrier
	s_waitcnt lgkmcnt(0)
	v_mfma_f32_16x16x32_bf16 v[64:67], v[204:207], v[172:175], v[64:67]
	v_mfma_f32_16x16x32_bf16 v[60:63], v[212:215], v[172:175], v[60:63]
	v_mfma_f32_16x16x32_bf16 v[56:59], v[204:207], v[180:183], v[56:59]
	v_mfma_f32_16x16x32_bf16 v[52:55], v[212:215], v[180:183], v[52:55]
	v_mfma_f32_16x16x32_bf16 v[48:51], v[204:207], v[188:191], v[48:51]
	v_mfma_f32_16x16x32_bf16 v[44:47], v[212:215], v[188:191], v[44:47]
	v_mfma_f32_16x16x32_bf16 v[40:43], v[204:207], v[196:199], v[40:43]
	v_mfma_f32_16x16x32_bf16 v[36:39], v[212:215], v[196:199], v[36:39]
	v_mfma_f32_16x16x32_bf16 v[64:67], v[208:211], v[176:179], v[64:67]
	v_mfma_f32_16x16x32_bf16 v[60:63], v[216:219], v[176:179], v[60:63]
	v_mfma_f32_16x16x32_bf16 v[56:59], v[208:211], v[184:187], v[56:59]
	v_mfma_f32_16x16x32_bf16 v[52:55], v[216:219], v[184:187], v[52:55]
	v_mfma_f32_16x16x32_bf16 v[48:51], v[208:211], v[192:195], v[48:51]
	v_mfma_f32_16x16x32_bf16 v[44:47], v[216:219], v[192:195], v[44:47]
	v_mfma_f32_16x16x32_bf16 v[40:43], v[208:211], v[200:203], v[40:43]
	v_mfma_f32_16x16x32_bf16 v[36:39], v[216:219], v[200:203], v[36:39]
	s_barrier
	s_setprio 0
	s_mov_b32 m0, s21
	v_lshl_add_u64 v[164:165], v[222:223], 0, s[12:13]
	ds_read_b128 v[172:175], v235 offset:49152
	ds_read_b128 v[176:179], v235 offset:50176
	ds_read_b128 v[180:183], v235 offset:51200
	ds_read_b128 v[184:187], v235 offset:52224
	ds_read_b128 v[188:191], v235 offset:53248
	ds_read_b128 v[192:195], v235 offset:54272
	ds_read_b128 v[196:199], v235 offset:55296
	ds_read_b128 v[200:203], v235 offset:56320
	global_load_lds_dwordx4 v[164:165], off
	v_lshl_add_u64 v[164:165], v[224:225], 0, s[12:13]
	s_mov_b32 m0, s48
	s_nop 0
	global_load_lds_dwordx4 v[164:165], off
	s_setprio 1
	s_barrier
	s_waitcnt lgkmcnt(0)
	v_mfma_f32_16x16x32_bf16 v[96:99], v[100:103], v[172:175], v[96:99]
	v_mfma_f32_16x16x32_bf16 v[92:95], v[156:159], v[172:175], v[92:95]
	v_mfma_f32_16x16x32_bf16 v[88:91], v[100:103], v[180:183], v[88:91]
	v_mfma_f32_16x16x32_bf16 v[84:87], v[156:159], v[180:183], v[84:87]
	v_mfma_f32_16x16x32_bf16 v[80:83], v[100:103], v[188:191], v[80:83]
	v_mfma_f32_16x16x32_bf16 v[76:79], v[156:159], v[188:191], v[76:79]
	v_mfma_f32_16x16x32_bf16 v[72:75], v[100:103], v[196:199], v[72:75]
	v_mfma_f32_16x16x32_bf16 v[68:71], v[156:159], v[196:199], v[68:71]
	v_mfma_f32_16x16x32_bf16 v[96:99], v[104:107], v[176:179], v[96:99]
	v_mfma_f32_16x16x32_bf16 v[92:95], v[160:163], v[176:179], v[92:95]
	v_mfma_f32_16x16x32_bf16 v[88:91], v[104:107], v[184:187], v[88:91]
	v_mfma_f32_16x16x32_bf16 v[84:87], v[160:163], v[184:187], v[84:87]
	v_mfma_f32_16x16x32_bf16 v[80:83], v[104:107], v[192:195], v[80:83]
	v_mfma_f32_16x16x32_bf16 v[76:79], v[160:163], v[192:195], v[76:79]
	v_mfma_f32_16x16x32_bf16 v[72:75], v[104:107], v[200:203], v[72:75]
	v_mfma_f32_16x16x32_bf16 v[68:71], v[160:163], v[200:203], v[68:71]
	s_barrier
	s_setprio 0
	s_add_u32 s0, s28, 0xb0080
	s_addc_u32 s1, s29, 0
	s_add_i32 s24, s25, s68
	v_lshl_add_u64 v[100:101], s[0:1], 0, v[26:27]
	s_mov_b32 m0, s24
	s_nop 0
	global_load_lds_dwordx4 v[100:101], off
	v_lshl_add_u64 v[100:101], s[0:1], 0, v[140:141]
	s_add_i32 m0, s24, 0x2000
	s_nop 0
	global_load_lds_dwordx4 v[100:101], off
	s_waitcnt vmcnt(6)
	s_setprio 1
	s_barrier
	v_mfma_f32_16x16x32_bf16 v[32:35], v[204:207], v[172:175], v[32:35]
	v_mfma_f32_16x16x32_bf16 v[28:31], v[212:215], v[172:175], v[28:31]
	v_mfma_f32_16x16x32_bf16 v[22:25], v[204:207], v[180:183], v[22:25]
	v_mfma_f32_16x16x32_bf16 v[18:21], v[212:215], v[180:183], v[18:21]
	v_mfma_f32_16x16x32_bf16 v[14:17], v[204:207], v[188:191], v[14:17]
	v_mfma_f32_16x16x32_bf16 v[10:13], v[212:215], v[188:191], v[10:13]
	v_mfma_f32_16x16x32_bf16 v[6:9], v[204:207], v[196:199], v[6:9]
	v_mfma_f32_16x16x32_bf16 v[2:5], v[212:215], v[196:199], v[2:5]
	v_mfma_f32_16x16x32_bf16 v[32:35], v[208:211], v[176:179], v[32:35]
	v_mfma_f32_16x16x32_bf16 v[28:31], v[216:219], v[176:179], v[28:31]
	v_mfma_f32_16x16x32_bf16 v[22:25], v[208:211], v[184:187], v[22:25]
	v_mfma_f32_16x16x32_bf16 v[18:21], v[216:219], v[184:187], v[18:21]
	v_mfma_f32_16x16x32_bf16 v[14:17], v[208:211], v[192:195], v[14:17]
	v_mfma_f32_16x16x32_bf16 v[10:13], v[216:219], v[192:195], v[10:13]
	v_mfma_f32_16x16x32_bf16 v[6:9], v[208:211], v[200:203], v[6:9]
	v_mfma_f32_16x16x32_bf16 v[2:5], v[216:219], v[200:203], v[2:5]
	s_barrier
	s_setprio 0
	s_add_i32 s52, s52, 2
	s_add_u32 s18, s18, 0x100
	s_addc_u32 s19, s19, 0
	s_cmp_gt_u32 s52, 41
	s_mov_b64 s[24:25], s[26:27]
	s_cbranch_scc0 .LBB0_395
	s_min_i32 s0, s22, 0x100
	s_ashr_i32 s0, s0, 5
	s_ashr_i32 s1, s0, 31
	s_add_i32 s18, s22, 0xffffff00
	s_cmpk_lt_i32 s22, 0x100
	s_cselect_b32 s18, s22, s18
	s_cselect_b32 s25, 0, s35
	s_cselect_b32 s24, 0, s34
	s_cselect_b32 s26, 0, s57
	s_cselect_b32 s27, 0, s58
	s_ashr_i32 s19, s18, 31
	s_add_u32 s24, s46, s24
	s_addc_u32 s25, s47, s25
	s_lshl_b64 s[18:19], s[18:19], 20
	v_lshl_add_u64 v[100:101], s[18:19], 0, v[146:147]
	s_add_u32 s18, s50, s26
	v_lshl_or_b32 v172, s23, 8, v234
	s_addc_u32 s19, s51, s27
	s_ashr_i32 s23, s22, 31
	v_lshl_add_u64 v[180:181], s[18:19], 0, v[100:101]
	s_lshl_b64 s[18:19], s[22:23], 19
	v_lshl_add_u64 v[184:185], v[148:149], 0, s[18:19]
	s_lshl_b64 s[52:53], s[22:23], 10
	s_mul_i32 s18, s0, 0x9000
	v_ashrrev_i32_e32 v173, 31, v172
	s_mul_hi_i32 s19, s0, 0x9000
	s_add_u32 s18, s36, s18
	s_addc_u32 s19, s37, s19
	v_lshlrev_b64 v[186:187], 2, v[172:173]
	v_lshl_add_u64 v[156:157], s[18:19], 0, v[186:187]
	v_lshl_add_u64 v[164:165], s[24:25], 0, v[100:101]
	global_load_dwordx4 v[100:103], v[156:157], off offset:16
	global_load_dwordx4 v[104:107], v[156:157], off
	s_lshl_b64 s[0:1], s[0:1], 12
	s_add_u32 s0, s59, s0
	s_addc_u32 s1, s20, s1
	v_lshl_add_u64 v[164:165], v[164:165], 0, v[186:187]
	s_mov_b32 s18, 0x20000
	s_waitcnt vmcnt(0)
	v_pk_mul_f32 v[178:179], v[102:103], 0.5 op_sel_hi:[1,0]
	v_pk_mul_f32 v[174:175], v[106:107], 0.5 op_sel_hi:[1,0]
	v_pk_mul_f32 v[176:177], v[104:105], 0.5 op_sel_hi:[1,0]
	v_pk_mul_f32 v[210:211], v[100:101], 0.5 op_sel_hi:[1,0]
	global_load_dwordx4 v[100:103], v[156:157], off offset:528
	global_load_dwordx4 v[104:107], v[156:157], off offset:512
	s_waitcnt vmcnt(0)
	v_pk_mul_f32 v[162:163], v[100:101], 0.5 op_sel_hi:[1,0]
	v_lshlrev_b64 v[100:101], 1, v[172:173]
	v_lshl_add_u64 v[182:183], v[180:181], 0, v[100:101]
	v_lshl_add_u64 v[180:181], v[184:185], 0, v[100:101]
	v_lshl_add_u64 v[184:185], s[0:1], 0, v[186:187]
	v_pk_mul_f32 v[156:157], v[106:107], 0.5 op_sel_hi:[1,0]
	v_pk_mul_f32 v[158:159], v[104:105], 0.5 op_sel_hi:[1,0]
	v_pk_mul_f32 v[160:161], v[102:103], 0.5 op_sel_hi:[1,0]
	global_load_dwordx4 v[100:103], v[184:185], off offset:16
	global_load_dwordx4 v[104:107], v[184:185], off
	global_load_dwordx4 v[188:191], v[164:165], off offset:16
	global_load_dwordx4 v[192:195], v[164:165], off
	v_add_co_u32_e32 v186, vcc, s65, v164
	s_mov_b64 s[0:1], 0x10000
	s_nop 0
	v_addc_co_u32_e32 v187, vcc, 0, v165, vcc
	v_lshl_add_u64 v[172:173], v[164:165], 0, s[0:1]
	global_load_dwordx4 v[196:199], v[186:187], off
	global_load_dwordx4 v[200:203], v[172:173], off offset:16
	s_mov_b32 s0, 0x8000
	s_waitcnt vmcnt(0)
	v_pk_fma_f32 v[134:135], v[134:135], v[178:179], v[190:191]
	v_pk_fma_f32 v[138:139], v[138:139], v[174:175], v[194:195]
	v_pk_fma_f32 v[136:137], v[136:137], v[176:177], v[192:193]
	v_pk_fma_f32 v[132:133], v[132:133], v[210:211], v[188:189]
	v_cvt_pk_bf16_f32 v188, v136, v137
	v_cvt_pk_bf16_f32 v189, v138, v139
	v_cvt_pk_bf16_f32 v190, v132, v133
	v_cvt_pk_bf16_f32 v191, v134, v135
	v_lshlrev_b32_e32 v138, 16, v188
	v_and_b32_e32 v139, 0xffff0000, v188
	v_lshlrev_b32_e32 v136, 16, v189
	v_and_b32_e32 v137, 0xffff0000, v189
	global_store_dwordx4 v[182:183], v[188:191], off offset:2048
	v_lshlrev_b32_e32 v134, 16, v190
	v_and_b32_e32 v135, 0xffff0000, v190
	v_lshlrev_b32_e32 v132, 16, v191
	v_and_b32_e32 v133, 0xffff0000, v191
	v_pk_mul_f32 v[172:173], v[106:107], v[136:137]
	v_pk_mul_f32 v[188:189], v[104:105], v[138:139]
	v_pk_mul_f32 v[192:193], v[102:103], v[132:133]
	v_pk_mul_f32 v[190:191], v[100:101], v[134:135]
	v_cvt_pk_bf16_f32 v188, v188, v189
	v_cvt_pk_bf16_f32 v189, v172, v173
	v_pk_fma_f32 v[130:131], v[130:131], v[174:175], v[198:199]
	v_pk_fma_f32 v[128:129], v[128:129], v[176:177], v[196:197]
	v_pk_fma_f32 v[172:173], v[126:127], v[178:179], v[202:203]
	v_pk_fma_f32 v[126:127], v[124:125], v[210:211], v[200:201]
	v_add_co_u32_e32 v202, vcc, s65, v182
	v_cvt_pk_bf16_f32 v190, v190, v191
	v_cvt_pk_bf16_f32 v191, v192, v193
	v_cvt_pk_bf16_f32 v124, v128, v129
	v_cvt_pk_bf16_f32 v125, v130, v131
	v_cvt_pk_bf16_f32 v126, v126, v127
	v_cvt_pk_bf16_f32 v127, v172, v173
	v_addc_co_u32_e32 v203, vcc, 0, v183, vcc
	global_store_dwordx4 v[180:181], v[188:191], off
	global_store_dwordx4 v[202:203], v[124:127], off offset:2048
	v_lshlrev_b32_e32 v128, 16, v124
	v_and_b32_e32 v129, 0xffff0000, v124
	v_lshlrev_b32_e32 v124, 16, v125
	v_and_b32_e32 v125, 0xffff0000, v125
	v_lshlrev_b32_e32 v130, 16, v126
	v_and_b32_e32 v131, 0xffff0000, v126
	v_lshlrev_b32_e32 v126, 16, v127
	v_and_b32_e32 v127, 0xffff0000, v127
	v_pk_mul_f32 v[172:173], v[106:107], v[124:125]
	v_pk_mul_f32 v[188:189], v[104:105], v[128:129]
	v_pk_mul_f32 v[192:193], v[102:103], v[126:127]
	v_pk_mul_f32 v[190:191], v[100:101], v[130:131]
	v_add_co_u32_e32 v220, vcc, s0, v180
	v_cvt_pk_bf16_f32 v188, v188, v189
	v_cvt_pk_bf16_f32 v189, v172, v173
	v_cvt_pk_bf16_f32 v190, v190, v191
	v_cvt_pk_bf16_f32 v191, v192, v193
	v_addc_co_u32_e32 v221, vcc, 0, v181, vcc
	global_store_dwordx4 v[220:221], v[188:191], off
	s_mov_b64 s[0:1], 0x20000
	v_lshl_add_u64 v[172:173], v[164:165], 0, s[0:1]
	v_add_co_u32_e32 v188, vcc, s18, v164
	s_mov_b64 s[0:1], 0x30000
	s_nop 0
	v_addc_co_u32_e32 v189, vcc, 0, v165, vcc
	global_load_dwordx4 v[192:195], v[188:189], off
	global_load_dwordx4 v[196:199], v[172:173], off offset:16
	v_lshl_add_u64 v[172:173], v[164:165], 0, s[0:1]
	s_mov_b32 s0, 0x30000
	v_add_co_u32_e32 v190, vcc, s0, v164
	s_waitcnt vmcnt(0)
	v_pk_fma_f32 v[120:121], v[120:121], v[176:177], v[192:193]
	v_addc_co_u32_e32 v191, vcc, 0, v165, vcc
	global_load_dwordx4 v[204:207], v[190:191], off
	global_load_dwordx4 v[212:215], v[172:173], off offset:16
	v_pk_fma_f32 v[122:123], v[122:123], v[174:175], v[194:195]
	v_pk_fma_f32 v[118:119], v[118:119], v[178:179], v[198:199]
	v_pk_fma_f32 v[116:117], v[116:117], v[210:211], v[196:197]
	v_cvt_pk_bf16_f32 v194, v120, v121
	v_add_co_u32_e32 v192, vcc, s18, v182
	v_cvt_pk_bf16_f32 v195, v122, v123
	v_cvt_pk_bf16_f32 v196, v116, v117
	v_cvt_pk_bf16_f32 v197, v118, v119
	v_addc_co_u32_e32 v193, vcc, 0, v183, vcc
	v_lshlrev_b32_e32 v122, 16, v194
	v_and_b32_e32 v123, 0xffff0000, v194
	global_store_dwordx4 v[192:193], v[194:197], off offset:2048
	v_lshlrev_b32_e32 v120, 16, v195
	v_and_b32_e32 v121, 0xffff0000, v195
	v_pk_mul_f32 v[194:195], v[104:105], v[122:123]
	v_lshlrev_b32_e32 v118, 16, v196
	v_and_b32_e32 v119, 0xffff0000, v196
	v_cvt_pk_bf16_f32 v196, v194, v195
	v_add_co_u32_e32 v194, vcc, s65, v180
	v_lshlrev_b32_e32 v116, 16, v197
	v_and_b32_e32 v117, 0xffff0000, v197
	v_pk_mul_f32 v[172:173], v[106:107], v[120:121]
	v_addc_co_u32_e32 v195, vcc, 0, v181, vcc
	v_pk_mul_f32 v[200:201], v[102:103], v[116:117]
	v_pk_mul_f32 v[198:199], v[100:101], v[118:119]
	v_cvt_pk_bf16_f32 v197, v172, v173
	v_cvt_pk_bf16_f32 v198, v198, v199
	v_cvt_pk_bf16_f32 v199, v200, v201
	global_store_dwordx4 v[194:195], v[196:199], off
	s_mov_b32 s18, 0x80000
	s_waitcnt vmcnt(0)
	v_pk_fma_f32 v[114:115], v[114:115], v[174:175], v[206:207]
	v_pk_fma_f32 v[112:113], v[112:113], v[176:177], v[204:205]
	v_pk_fma_f32 v[172:173], v[110:111], v[178:179], v[214:215]
	v_pk_fma_f32 v[110:111], v[108:109], v[210:211], v[212:213]
	v_add_co_u32_e32 v212, vcc, s0, v182
	v_cvt_pk_bf16_f32 v108, v112, v113
	v_cvt_pk_bf16_f32 v109, v114, v115
	v_cvt_pk_bf16_f32 v110, v110, v111
	v_cvt_pk_bf16_f32 v111, v172, v173
	v_addc_co_u32_e32 v213, vcc, 0, v183, vcc
	global_store_dwordx4 v[212:213], v[108:111], off offset:2048
	v_lshlrev_b32_e32 v112, 16, v108
	v_and_b32_e32 v113, 0xffff0000, v108
	v_lshlrev_b32_e32 v172, 16, v109
	v_and_b32_e32 v173, 0xffff0000, v109
	v_lshlrev_b32_e32 v114, 16, v110
	v_and_b32_e32 v115, 0xffff0000, v110
	v_lshlrev_b32_e32 v108, 16, v111
	v_and_b32_e32 v109, 0xffff0000, v111
	s_mov_b32 s0, 0x18000
	v_pk_mul_f32 v[110:111], v[106:107], v[172:173]
	v_pk_mul_f32 v[196:197], v[104:105], v[112:113]
	v_pk_mul_f32 v[200:201], v[102:103], v[108:109]
	v_pk_mul_f32 v[198:199], v[100:101], v[114:115]
	v_add_co_u32_e32 v222, vcc, s0, v180
	v_cvt_pk_bf16_f32 v196, v196, v197
	v_cvt_pk_bf16_f32 v197, v110, v111
	v_cvt_pk_bf16_f32 v198, v198, v199
	v_cvt_pk_bf16_f32 v199, v200, v201
	v_addc_co_u32_e32 v223, vcc, 0, v181, vcc
	global_store_dwordx4 v[222:223], v[196:199], off
	s_mov_b64 s[0:1], 0x80000
	v_lshl_add_u64 v[110:111], v[164:165], 0, s[0:1]
	v_add_co_u32_e32 v196, vcc, s18, v164
	s_mov_b64 s[0:1], 0x90000
	s_nop 0
	v_addc_co_u32_e32 v197, vcc, 0, v165, vcc
	global_load_dwordx4 v[204:207], v[196:197], off
	global_load_dwordx4 v[214:217], v[110:111], off offset:16
	v_lshl_add_u64 v[110:111], v[164:165], 0, s[0:1]
	s_mov_b32 s0, 0x90000
	v_add_co_u32_e32 v198, vcc, s0, v164
	s_mov_b32 s1, 0x40000
	s_nop 0
	v_addc_co_u32_e32 v199, vcc, 0, v165, vcc
	global_load_dwordx4 v[238:241], v[198:199], off
	global_load_dwordx4 v[242:245], v[110:111], off offset:16
	v_add_co_u32_e32 v200, vcc, s18, v182
	s_waitcnt vmcnt(0)
	v_pk_fma_f32 v[96:97], v[96:97], v[176:177], v[204:205]
	v_pk_fma_f32 v[98:99], v[98:99], v[174:175], v[206:207]
	v_pk_fma_f32 v[94:95], v[94:95], v[178:179], v[216:217]
	v_pk_fma_f32 v[92:93], v[92:93], v[210:211], v[214:215]
	v_cvt_pk_bf16_f32 v204, v96, v97
	v_cvt_pk_bf16_f32 v205, v98, v99
	v_cvt_pk_bf16_f32 v206, v92, v93
	v_cvt_pk_bf16_f32 v207, v94, v95
	v_addc_co_u32_e32 v201, vcc, 0, v183, vcc
	v_lshlrev_b32_e32 v98, 16, v204
	v_and_b32_e32 v99, 0xffff0000, v204
	global_store_dwordx4 v[200:201], v[204:207], off offset:2048
	v_lshlrev_b32_e32 v96, 16, v205
	v_and_b32_e32 v97, 0xffff0000, v205
	v_pk_mul_f32 v[204:205], v[104:105], v[98:99]
	v_lshlrev_b32_e32 v94, 16, v206
	v_and_b32_e32 v95, 0xffff0000, v206
	v_cvt_pk_bf16_f32 v206, v204, v205
	v_add_co_u32_e32 v204, vcc, s1, v180
	v_lshlrev_b32_e32 v92, 16, v207
	v_and_b32_e32 v93, 0xffff0000, v207
	v_pk_mul_f32 v[110:111], v[106:107], v[96:97]
	v_addc_co_u32_e32 v205, vcc, 0, v181, vcc
	v_pk_mul_f32 v[214:215], v[102:103], v[92:93]
	v_pk_mul_f32 v[208:209], v[100:101], v[94:95]
	v_cvt_pk_bf16_f32 v207, v110, v111
	v_pk_fma_f32 v[90:91], v[90:91], v[174:175], v[240:241]
	v_pk_fma_f32 v[88:89], v[88:89], v[176:177], v[238:239]
	v_pk_fma_f32 v[110:111], v[86:87], v[178:179], v[244:245]
	v_pk_fma_f32 v[86:87], v[84:85], v[210:211], v[242:243]
	v_add_co_u32_e32 v218, vcc, s0, v182
	v_cvt_pk_bf16_f32 v208, v208, v209
	v_cvt_pk_bf16_f32 v209, v214, v215
	v_cvt_pk_bf16_f32 v84, v88, v89
	v_cvt_pk_bf16_f32 v85, v90, v91
	v_cvt_pk_bf16_f32 v86, v86, v87
	v_cvt_pk_bf16_f32 v87, v110, v111
	v_addc_co_u32_e32 v219, vcc, 0, v183, vcc
	global_store_dwordx4 v[204:205], v[206:209], off
	global_store_dwordx4 v[218:219], v[84:87], off offset:2048
	v_lshlrev_b32_e32 v88, 16, v84
	v_and_b32_e32 v89, 0xffff0000, v84
	v_lshlrev_b32_e32 v110, 16, v85
	v_and_b32_e32 v111, 0xffff0000, v85
	v_lshlrev_b32_e32 v90, 16, v86
	v_and_b32_e32 v91, 0xffff0000, v86
	v_lshlrev_b32_e32 v84, 16, v87
	v_and_b32_e32 v85, 0xffff0000, v87
	s_mov_b32 s0, 0x48000
	v_pk_mul_f32 v[86:87], v[106:107], v[110:111]
	v_pk_mul_f32 v[206:207], v[104:105], v[88:89]
	v_pk_mul_f32 v[214:215], v[102:103], v[84:85]
	v_pk_mul_f32 v[208:209], v[100:101], v[90:91]
	v_add_co_u32_e32 v224, vcc, s0, v180
	v_cvt_pk_bf16_f32 v206, v206, v207
	v_cvt_pk_bf16_f32 v207, v86, v87
	v_cvt_pk_bf16_f32 v208, v208, v209
	v_cvt_pk_bf16_f32 v209, v214, v215
	v_addc_co_u32_e32 v225, vcc, 0, v181, vcc
	global_store_dwordx4 v[224:225], v[206:209], off
	s_mov_b64 s[0:1], 0xa0000
	v_lshl_add_u64 v[86:87], v[164:165], 0, s[0:1]
	v_add_co_u32_e32 v206, vcc, s76, v164
	s_mov_b64 s[0:1], 0xb0000
	s_nop 0
	v_addc_co_u32_e32 v207, vcc, 0, v165, vcc
	global_load_dwordx4 v[214:217], v[206:207], off
	global_load_dwordx4 v[238:241], v[86:87], off offset:16
	v_lshl_add_u64 v[86:87], v[164:165], 0, s[0:1]
	s_mov_b32 s0, 0xb0000
	v_add_co_u32_e32 v208, vcc, s0, v164
	s_waitcnt vmcnt(0)
	v_pk_fma_f32 v[80:81], v[80:81], v[176:177], v[214:215]
	v_addc_co_u32_e32 v209, vcc, 0, v165, vcc
	global_load_dwordx4 v[242:245], v[208:209], off
	global_load_dwordx4 v[246:249], v[86:87], off offset:16
	v_pk_fma_f32 v[82:83], v[82:83], v[174:175], v[216:217]
	v_pk_fma_f32 v[76:77], v[76:77], v[210:211], v[238:239]
	v_cvt_pk_bf16_f32 v238, v80, v81
	v_pk_fma_f32 v[78:79], v[78:79], v[178:179], v[240:241]
	v_cvt_pk_bf16_f32 v239, v82, v83
	v_add_co_u32_e32 v214, vcc, s76, v182
	v_lshlrev_b32_e32 v82, 16, v238
	v_and_b32_e32 v83, 0xffff0000, v238
	v_cvt_pk_bf16_f32 v240, v76, v77
	v_cvt_pk_bf16_f32 v241, v78, v79
	v_addc_co_u32_e32 v215, vcc, 0, v183, vcc
	v_lshlrev_b32_e32 v80, 16, v239
	v_and_b32_e32 v81, 0xffff0000, v239
	v_pk_mul_f32 v[216:217], v[104:105], v[82:83]
	global_store_dwordx4 v[214:215], v[238:241], off offset:2048
	v_pk_mul_f32 v[86:87], v[106:107], v[80:81]
	v_lshlrev_b32_e32 v78, 16, v240
	v_cvt_pk_bf16_f32 v238, v216, v217
	v_add_co_u32_e32 v216, vcc, s77, v180
	v_and_b32_e32 v79, 0xffff0000, v240
	v_lshlrev_b32_e32 v76, 16, v241
	v_and_b32_e32 v77, 0xffff0000, v241
	v_cvt_pk_bf16_f32 v239, v86, v87
	v_addc_co_u32_e32 v217, vcc, 0, v181, vcc
	v_pk_mul_f32 v[250:251], v[102:103], v[76:77]
	v_pk_mul_f32 v[240:241], v[100:101], v[78:79]
	s_waitcnt vmcnt(0)
	v_pk_fma_f32 v[74:75], v[74:75], v[174:175], v[244:245]
	v_pk_fma_f32 v[72:73], v[72:73], v[176:177], v[242:243]
	v_pk_fma_f32 v[86:87], v[70:71], v[178:179], v[248:249]
	v_pk_fma_f32 v[70:71], v[68:69], v[210:211], v[246:247]
	v_cvt_pk_bf16_f32 v68, v72, v73
	v_cvt_pk_bf16_f32 v69, v74, v75
	v_cvt_pk_bf16_f32 v70, v70, v71
	v_cvt_pk_bf16_f32 v71, v86, v87
	v_add_co_u32_e32 v210, vcc, s0, v182
	v_cvt_pk_bf16_f32 v240, v240, v241
	v_cvt_pk_bf16_f32 v241, v250, v251
	v_addc_co_u32_e32 v211, vcc, 0, v183, vcc
	v_lshlrev_b32_e32 v86, 16, v68
	v_and_b32_e32 v87, 0xffff0000, v68
	v_lshlrev_b32_e32 v178, 16, v69
	v_and_b32_e32 v179, 0xffff0000, v69
	v_lshlrev_b32_e32 v176, 16, v70
	v_and_b32_e32 v177, 0xffff0000, v70
	v_lshlrev_b32_e32 v174, 16, v71
	v_and_b32_e32 v175, 0xffff0000, v71
	s_mov_b32 s0, 0x58000
	global_store_dwordx4 v[216:217], v[238:241], off
	global_store_dwordx4 v[210:211], v[68:71], off offset:2048
	v_pk_mul_f32 v[72:73], v[102:103], v[174:175]
	v_pk_mul_f32 v[74:75], v[100:101], v[176:177]
	v_pk_mul_f32 v[70:71], v[106:107], v[178:179]
	v_pk_mul_f32 v[68:69], v[104:105], v[86:87]
	v_add_co_u32_e32 v100, vcc, s0, v180
	v_cvt_pk_bf16_f32 v68, v68, v69
	v_cvt_pk_bf16_f32 v69, v70, v71
	v_cvt_pk_bf16_f32 v70, v74, v75
	v_cvt_pk_bf16_f32 v71, v72, v73
	v_addc_co_u32_e32 v101, vcc, 0, v181, vcc
	global_store_dwordx4 v[100:101], v[68:71], off
	global_load_dwordx4 v[68:71], v[184:185], off offset:528
	s_nop 0
	global_load_dwordx4 v[72:75], v[184:185], off offset:512
	global_load_dwordx4 v[102:105], v[164:165], off offset:528
	global_load_dwordx4 v[238:241], v[164:165], off offset:512
	s_mov_b64 s[0:1], 0x10200
	v_lshl_add_u64 v[106:107], v[164:165], 0, s[0:1]
	global_load_dwordx4 v[184:187], v[186:187], off offset:512
	s_nop 0
	global_load_dwordx4 v[242:245], v[106:107], off offset:16
	s_mov_b64 s[0:1], 0x20200
	s_waitcnt vmcnt(0)
	v_pk_fma_f32 v[62:63], v[62:63], v[160:161], v[104:105]
	v_pk_fma_f32 v[66:67], v[66:67], v[156:157], v[240:241]
	v_pk_fma_f32 v[64:65], v[64:65], v[158:159], v[238:239]
	v_pk_fma_f32 v[60:61], v[60:61], v[162:163], v[102:103]
	v_cvt_pk_bf16_f32 v102, v64, v65
	v_cvt_pk_bf16_f32 v103, v66, v67
	v_cvt_pk_bf16_f32 v104, v60, v61
	v_cvt_pk_bf16_f32 v105, v62, v63
	v_lshlrev_b32_e32 v66, 16, v102
	v_and_b32_e32 v67, 0xffff0000, v102
	v_lshlrev_b32_e32 v64, 16, v103
	v_and_b32_e32 v65, 0xffff0000, v103
	v_lshlrev_b32_e32 v62, 16, v104
	v_and_b32_e32 v63, 0xffff0000, v104
	v_lshlrev_b32_e32 v60, 16, v105
	v_and_b32_e32 v61, 0xffff0000, v105
	global_store_dwordx4 v[182:183], v[102:105], off offset:2304
	v_pk_mul_f32 v[106:107], v[70:71], v[60:61]
	v_pk_mul_f32 v[182:183], v[68:69], v[62:63]
	v_pk_mul_f32 v[104:105], v[74:75], v[64:65]
	v_pk_mul_f32 v[102:103], v[72:73], v[66:67]
	v_pk_fma_f32 v[58:59], v[58:59], v[156:157], v[186:187]
	v_cvt_pk_bf16_f32 v102, v102, v103
	v_cvt_pk_bf16_f32 v103, v104, v105
	v_cvt_pk_bf16_f32 v104, v182, v183
	v_cvt_pk_bf16_f32 v105, v106, v107
	v_pk_fma_f32 v[56:57], v[56:57], v[158:159], v[184:185]
	v_pk_fma_f32 v[54:55], v[54:55], v[160:161], v[244:245]
	v_pk_fma_f32 v[52:53], v[52:53], v[162:163], v[242:243]
	global_store_dwordx4 v[180:181], v[102:105], off offset:256
	v_mul_f32_e32 v67, v67, v67
	v_mul_f32_e32 v65, v65, v65
	v_cvt_pk_bf16_f32 v102, v56, v57
	v_cvt_pk_bf16_f32 v103, v58, v59
	v_cvt_pk_bf16_f32 v104, v52, v53
	v_cvt_pk_bf16_f32 v105, v54, v55
	v_lshlrev_b32_e32 v58, 16, v102
	v_and_b32_e32 v59, 0xffff0000, v102
	v_lshlrev_b32_e32 v56, 16, v103
	v_and_b32_e32 v57, 0xffff0000, v103
	v_lshlrev_b32_e32 v54, 16, v104
	v_and_b32_e32 v55, 0xffff0000, v104
	v_lshlrev_b32_e32 v52, 16, v105
	v_and_b32_e32 v53, 0xffff0000, v105
	global_store_dwordx4 v[202:203], v[102:105], off offset:2304
	v_pk_mul_f32 v[106:107], v[70:71], v[52:53]
	v_pk_mul_f32 v[180:181], v[68:69], v[54:55]
	v_pk_mul_f32 v[104:105], v[74:75], v[56:57]
	v_pk_mul_f32 v[102:103], v[72:73], v[58:59]
	v_fmac_f32_e32 v67, v66, v66
	v_cvt_pk_bf16_f32 v102, v102, v103
	v_cvt_pk_bf16_f32 v103, v104, v105
	v_cvt_pk_bf16_f32 v104, v180, v181
	v_cvt_pk_bf16_f32 v105, v106, v107
	global_store_dwordx4 v[220:221], v[102:105], off offset:256
	v_lshl_add_u64 v[106:107], v[164:165], 0, s[0:1]
	global_load_dwordx4 v[102:105], v[188:189], off offset:512
	global_load_dwordx4 v[180:183], v[106:107], off offset:16
	s_mov_b64 s[0:1], 0x30200
	v_lshl_add_u64 v[106:107], v[164:165], 0, s[0:1]
	global_load_dwordx4 v[184:187], v[190:191], off offset:512
	s_nop 0
	global_load_dwordx4 v[188:191], v[106:107], off offset:16
	s_mov_b64 s[0:1], 0x80200
	v_fmac_f32_e32 v65, v64, v64
	v_mul_f32_e32 v63, v63, v63
	v_mul_f32_e32 v61, v61, v61
	v_add_f32_e32 v64, v67, v65
	v_fmac_f32_e32 v63, v62, v62
	v_fmac_f32_e32 v61, v60, v60
	v_add_f32_e32 v60, v63, v61
	s_waitcnt vmcnt(0)
	v_pk_fma_f32 v[50:51], v[50:51], v[156:157], v[104:105]
	v_pk_fma_f32 v[48:49], v[48:49], v[158:159], v[102:103]
	v_pk_fma_f32 v[46:47], v[46:47], v[160:161], v[182:183]
	v_pk_fma_f32 v[44:45], v[44:45], v[162:163], v[180:181]
	v_cvt_pk_bf16_f32 v102, v48, v49
	v_cvt_pk_bf16_f32 v103, v50, v51
	v_cvt_pk_bf16_f32 v104, v44, v45
	v_cvt_pk_bf16_f32 v105, v46, v47
	v_lshlrev_b32_e32 v50, 16, v102
	v_and_b32_e32 v51, 0xffff0000, v102
	v_lshlrev_b32_e32 v48, 16, v103
	v_and_b32_e32 v49, 0xffff0000, v103
	v_lshlrev_b32_e32 v46, 16, v104
	v_and_b32_e32 v47, 0xffff0000, v104
	v_lshlrev_b32_e32 v44, 16, v105
	v_and_b32_e32 v45, 0xffff0000, v105
	global_store_dwordx4 v[192:193], v[102:105], off offset:2304
	v_pk_mul_f32 v[106:107], v[70:71], v[44:45]
	v_pk_mul_f32 v[180:181], v[68:69], v[46:47]
	v_pk_mul_f32 v[104:105], v[74:75], v[48:49]
	v_pk_mul_f32 v[102:103], v[72:73], v[50:51]
	v_pk_fma_f32 v[42:43], v[42:43], v[156:157], v[186:187]
	v_cvt_pk_bf16_f32 v102, v102, v103
	v_cvt_pk_bf16_f32 v103, v104, v105
	v_cvt_pk_bf16_f32 v104, v180, v181
	v_cvt_pk_bf16_f32 v105, v106, v107
	v_pk_fma_f32 v[40:41], v[40:41], v[158:159], v[184:185]
	v_pk_fma_f32 v[38:39], v[38:39], v[160:161], v[190:191]
	v_pk_fma_f32 v[36:37], v[36:37], v[162:163], v[188:189]
	global_store_dwordx4 v[194:195], v[102:105], off offset:256
	s_nop 1
	v_cvt_pk_bf16_f32 v102, v40, v41
	v_cvt_pk_bf16_f32 v103, v42, v43
	v_cvt_pk_bf16_f32 v104, v36, v37
	v_cvt_pk_bf16_f32 v105, v38, v39
	v_lshlrev_b32_e32 v42, 16, v102
	v_and_b32_e32 v43, 0xffff0000, v102
	v_lshlrev_b32_e32 v40, 16, v103
	v_and_b32_e32 v41, 0xffff0000, v103
	v_lshlrev_b32_e32 v38, 16, v104
	v_and_b32_e32 v39, 0xffff0000, v104
	v_lshlrev_b32_e32 v36, 16, v105
	v_and_b32_e32 v37, 0xffff0000, v105
	global_store_dwordx4 v[212:213], v[102:105], off offset:2304
	v_pk_mul_f32 v[106:107], v[70:71], v[36:37]
	v_pk_mul_f32 v[180:181], v[68:69], v[38:39]
	v_pk_mul_f32 v[104:105], v[74:75], v[40:41]
	v_pk_mul_f32 v[102:103], v[72:73], v[42:43]
	s_nop 0
	v_cvt_pk_bf16_f32 v102, v102, v103
	v_cvt_pk_bf16_f32 v103, v104, v105
	v_cvt_pk_bf16_f32 v104, v180, v181
	v_cvt_pk_bf16_f32 v105, v106, v107
	global_store_dwordx4 v[222:223], v[102:105], off offset:256
	v_lshl_add_u64 v[106:107], v[164:165], 0, s[0:1]
	global_load_dwordx4 v[102:105], v[196:197], off offset:512
	global_load_dwordx4 v[180:183], v[106:107], off offset:16
	s_mov_b64 s[0:1], 0x90200
	v_lshl_add_u64 v[106:107], v[164:165], 0, s[0:1]
	global_load_dwordx4 v[184:187], v[198:199], off offset:512
	global_load_dwordx4 v[188:191], v[106:107], off offset:16
	s_mov_b64 s[0:1], 0xa0200
	s_waitcnt vmcnt(0)
	v_pk_fma_f32 v[34:35], v[34:35], v[156:157], v[104:105]
	v_pk_fma_f32 v[32:33], v[32:33], v[158:159], v[102:103]
	v_pk_fma_f32 v[30:31], v[30:31], v[160:161], v[182:183]
	v_pk_fma_f32 v[28:29], v[28:29], v[162:163], v[180:181]
	v_cvt_pk_bf16_f32 v102, v32, v33
	v_cvt_pk_bf16_f32 v103, v34, v35
	v_cvt_pk_bf16_f32 v104, v28, v29
	v_cvt_pk_bf16_f32 v105, v30, v31
	v_lshlrev_b32_e32 v34, 16, v102
	v_and_b32_e32 v35, 0xffff0000, v102
	v_lshlrev_b32_e32 v32, 16, v103
	v_and_b32_e32 v33, 0xffff0000, v103
	v_lshlrev_b32_e32 v30, 16, v104
	v_and_b32_e32 v31, 0xffff0000, v104
	v_lshlrev_b32_e32 v28, 16, v105
	v_and_b32_e32 v29, 0xffff0000, v105
	global_store_dwordx4 v[200:201], v[102:105], off offset:2304
	v_pk_mul_f32 v[106:107], v[70:71], v[28:29]
	v_pk_mul_f32 v[180:181], v[68:69], v[30:31]
	v_pk_mul_f32 v[104:105], v[74:75], v[32:33]
	v_pk_mul_f32 v[102:103], v[72:73], v[34:35]
	v_pk_fma_f32 v[24:25], v[24:25], v[156:157], v[186:187]
	v_cvt_pk_bf16_f32 v102, v102, v103
	v_cvt_pk_bf16_f32 v103, v104, v105
	v_cvt_pk_bf16_f32 v104, v180, v181
	v_cvt_pk_bf16_f32 v105, v106, v107
	v_pk_fma_f32 v[22:23], v[22:23], v[158:159], v[184:185]
	v_pk_fma_f32 v[20:21], v[20:21], v[160:161], v[190:191]
	v_pk_fma_f32 v[18:19], v[18:19], v[162:163], v[188:189]
	global_store_dwordx4 v[204:205], v[102:105], off offset:256
	s_nop 1
	v_cvt_pk_bf16_f32 v102, v22, v23
	v_cvt_pk_bf16_f32 v103, v24, v25
	v_cvt_pk_bf16_f32 v104, v18, v19
	v_cvt_pk_bf16_f32 v105, v20, v21
	v_lshlrev_b32_e32 v24, 16, v102
	v_and_b32_e32 v25, 0xffff0000, v102
	v_lshlrev_b32_e32 v22, 16, v103
	v_and_b32_e32 v23, 0xffff0000, v103
	v_lshlrev_b32_e32 v20, 16, v104
	v_and_b32_e32 v21, 0xffff0000, v104
	v_lshlrev_b32_e32 v18, 16, v105
	v_and_b32_e32 v19, 0xffff0000, v105
	global_store_dwordx4 v[218:219], v[102:105], off offset:2304
	v_pk_mul_f32 v[106:107], v[70:71], v[18:19]
	v_pk_mul_f32 v[180:181], v[68:69], v[20:21]
	v_pk_mul_f32 v[104:105], v[74:75], v[22:23]
	v_pk_mul_f32 v[102:103], v[72:73], v[24:25]
	s_nop 0
	v_cvt_pk_bf16_f32 v102, v102, v103
	v_cvt_pk_bf16_f32 v103, v104, v105
	v_cvt_pk_bf16_f32 v104, v180, v181
	v_cvt_pk_bf16_f32 v105, v106, v107
	global_store_dwordx4 v[224:225], v[102:105], off offset:256
	v_lshl_add_u64 v[106:107], v[164:165], 0, s[0:1]
	global_load_dwordx4 v[102:105], v[206:207], off offset:512
	global_load_dwordx4 v[180:183], v[106:107], off offset:16
	s_mov_b64 s[0:1], 0xb0200
	v_lshl_add_u64 v[106:107], v[164:165], 0, s[0:1]
	global_load_dwordx4 v[184:187], v[208:209], off offset:512
	global_load_dwordx4 v[188:191], v[106:107], off offset:16
	s_waitcnt vmcnt(0)
	v_pk_fma_f32 v[16:17], v[16:17], v[156:157], v[104:105]
	v_pk_fma_f32 v[14:15], v[14:15], v[158:159], v[102:103]
	v_pk_fma_f32 v[102:103], v[12:13], v[160:161], v[182:183]
	v_pk_fma_f32 v[12:13], v[10:11], v[162:163], v[180:181]
	v_cvt_pk_bf16_f32 v10, v14, v15
	v_cvt_pk_bf16_f32 v11, v16, v17
	v_cvt_pk_bf16_f32 v12, v12, v13
	v_cvt_pk_bf16_f32 v13, v102, v103
	v_lshlrev_b32_e32 v102, 16, v10
	v_and_b32_e32 v103, 0xffff0000, v10
	v_lshlrev_b32_e32 v16, 16, v11
	v_and_b32_e32 v17, 0xffff0000, v11
	global_store_dwordx4 v[214:215], v[10:13], off offset:2304
	v_lshlrev_b32_e32 v14, 16, v12
	v_and_b32_e32 v15, 0xffff0000, v12
	v_lshlrev_b32_e32 v12, 16, v13
	v_and_b32_e32 v13, 0xffff0000, v13
	v_pk_mul_f32 v[10:11], v[74:75], v[16:17]
	v_pk_mul_f32 v[104:105], v[72:73], v[102:103]
	v_pk_mul_f32 v[164:165], v[70:71], v[12:13]
	v_pk_mul_f32 v[106:107], v[68:69], v[14:15]
	v_cvt_pk_bf16_f32 v104, v104, v105
	v_cvt_pk_bf16_f32 v105, v10, v11
	v_pk_fma_f32 v[8:9], v[8:9], v[156:157], v[186:187]
	v_pk_fma_f32 v[6:7], v[6:7], v[158:159], v[184:185]
	v_pk_fma_f32 v[10:11], v[4:5], v[160:161], v[190:191]
	v_pk_fma_f32 v[4:5], v[2:3], v[162:163], v[188:189]
	v_cvt_pk_bf16_f32 v106, v106, v107
	v_cvt_pk_bf16_f32 v107, v164, v165
	v_cvt_pk_bf16_f32 v2, v6, v7
	v_cvt_pk_bf16_f32 v3, v8, v9
	v_cvt_pk_bf16_f32 v4, v4, v5
	v_cvt_pk_bf16_f32 v5, v10, v11
	global_store_dwordx4 v[216:217], v[104:107], off offset:256
	global_store_dwordx4 v[210:211], v[2:5], off offset:2304
	v_lshlrev_b32_e32 v10, 16, v2
	v_and_b32_e32 v11, 0xffff0000, v2
	v_lshlrev_b32_e32 v8, 16, v3
	v_and_b32_e32 v9, 0xffff0000, v3
	v_lshlrev_b32_e32 v6, 16, v4
	v_and_b32_e32 v7, 0xffff0000, v4
	v_lshlrev_b32_e32 v4, 16, v5
	v_and_b32_e32 v5, 0xffff0000, v5
	v_pk_mul_f32 v[2:3], v[74:75], v[8:9]
	v_pk_mul_f32 v[72:73], v[72:73], v[10:11]
	v_pk_mul_f32 v[74:75], v[70:71], v[4:5]
	v_pk_mul_f32 v[70:71], v[68:69], v[6:7]
	v_cvt_pk_bf16_f32 v68, v72, v73
	v_cvt_pk_bf16_f32 v69, v2, v3
	v_cvt_pk_bf16_f32 v70, v70, v71
	v_cvt_pk_bf16_f32 v71, v74, v75
	global_store_dwordx4 v[100:101], v[68:71], off offset:256
	v_mul_f32_e32 v72, v133, v133
	v_fmac_f32_e32 v72, v132, v132
	v_and_b32_e32 v69, 64, v227
	v_xor_b32_e32 v68, 16, v227
	v_add_u32_e32 v69, 64, v69
	v_cmp_lt_i32_e32 vcc, v68, v69
	v_xor_b32_e32 v70, 32, v227
	v_mul_f32_e32 v71, v137, v137
	v_cndmask_b32_e32 v68, v227, v68, vcc
	v_cmp_lt_i32_e32 vcc, v70, v69
	v_fmac_f32_e32 v71, v136, v136
	v_lshlrev_b32_e32 v68, 2, v68
	v_cndmask_b32_e32 v69, v227, v70, vcc
	v_mul_f32_e32 v70, v139, v139
	v_fmac_f32_e32 v70, v138, v138
	v_add_f32_e32 v70, v70, v71
	v_mul_f32_e32 v71, v135, v135
	v_fmac_f32_e32 v71, v134, v134
	v_add_f32_e32 v71, v71, v72
	v_add_f32_e32 v70, v70, v71
	v_add_f32_e32 v64, v70, v64
	v_add_f32_e32 v60, v64, v60
	ds_bpermute_b32 v61, v68, v60
	v_lshlrev_b32_e32 v69, 2, v69
	v_lshl_add_u64 v[2:3], v[150:151], 0, s[52:53]
	s_waitcnt lgkmcnt(0)
	v_add_f32_e32 v60, v60, v61
	ds_bpermute_b32 v61, v69, v60
	s_and_saveexec_b64 s[18:19], s[38:39]
	s_cbranch_execz .LBB0_398
	s_waitcnt lgkmcnt(0)
	v_add_f32_e32 v60, v60, v61
	global_atomic_add_f32 v[2:3], v60, off

.LBB0_479:
	s_add_u32 s0, s22, 0xfffc0080
	s_addc_u32 s1, s23, -1
	s_add_i32 s69, 0, 0x10000
	v_add_u32_e32 v154, s69, v163
	ds_read_b128 v[100:103], v154
	ds_read_b128 v[104:107], v154 offset:1024
	ds_read_b128 v[150:153], v154 offset:2048
	ds_read_b128 v[154:157], v154 offset:3072
	s_cmp_eq_u32 s68, 12
	s_cselect_b32 s27, s35, s1
	s_cselect_b32 s26, s40, s0
	s_cselect_b32 s25, s41, s59
	s_cselect_b32 s24, s49, s51
	v_lshl_add_u64 v[166:167], s[22:23], 0, v[146:147]
	s_add_i32 m0, s37, 0xc000
	ds_read_b128 v[158:161], v165
	ds_read_b128 v[172:175], v165 offset:1024
	ds_read_b128 v[176:179], v165 offset:2048
	ds_read_b128 v[180:183], v165 offset:3072
	ds_read_b128 v[184:187], v165 offset:4096
	ds_read_b128 v[188:191], v165 offset:5120
	ds_read_b128 v[192:195], v165 offset:6144
	ds_read_b128 v[196:199], v165 offset:7168
	global_load_lds_dwordx4 v[166:167], off
	v_lshl_add_u64 v[166:167], s[22:23], 0, v[148:149]
	s_add_i32 m0, s37, 0xe000
	s_nop 0
	global_load_lds_dwordx4 v[166:167], off
	s_waitcnt lgkmcnt(8)
	s_setprio 1
	s_barrier
	s_waitcnt lgkmcnt(0)
	v_mfma_f32_16x16x32_bf16 v[136:139], v[100:103], v[158:161], v[136:139]
	v_mfma_f32_16x16x32_bf16 v[132:135], v[150:153], v[158:161], v[132:135]
	v_mfma_f32_16x16x32_bf16 v[128:131], v[100:103], v[176:179], v[128:131]
	v_mfma_f32_16x16x32_bf16 v[124:127], v[150:153], v[176:179], v[124:127]
	v_mfma_f32_16x16x32_bf16 v[120:123], v[100:103], v[184:187], v[120:123]
	v_mfma_f32_16x16x32_bf16 v[116:119], v[150:153], v[184:187], v[116:119]
	v_mfma_f32_16x16x32_bf16 v[112:115], v[100:103], v[192:195], v[112:115]
	v_mfma_f32_16x16x32_bf16 v[108:111], v[150:153], v[192:195], v[108:111]
	v_mfma_f32_16x16x32_bf16 v[136:139], v[104:107], v[172:175], v[136:139]
	v_mfma_f32_16x16x32_bf16 v[132:135], v[154:157], v[172:175], v[132:135]
	v_mfma_f32_16x16x32_bf16 v[128:131], v[104:107], v[180:183], v[128:131]
	v_mfma_f32_16x16x32_bf16 v[124:127], v[154:157], v[180:183], v[124:127]
	v_mfma_f32_16x16x32_bf16 v[120:123], v[104:107], v[188:191], v[120:123]
	v_mfma_f32_16x16x32_bf16 v[116:119], v[154:157], v[188:191], v[116:119]
	v_mfma_f32_16x16x32_bf16 v[112:115], v[104:107], v[196:199], v[112:115]
	v_mfma_f32_16x16x32_bf16 v[108:111], v[154:157], v[196:199], v[108:111]
	s_barrier
	s_setprio 0
	s_add_i32 s72, 0, 0x14000
	v_add_u32_e32 v166, s72, v163
	s_add_i32 s0, s69, s36
	ds_read_b128 v[200:203], v166
	ds_read_b128 v[204:207], v166 offset:1024
	ds_read_b128 v[208:211], v166 offset:2048
	ds_read_b128 v[212:215], v166 offset:3072
	v_lshl_add_u64 v[166:167], s[24:25], 0, v[26:27]
	s_mov_b32 m0, s0
	v_lshl_add_u64 v[168:169], s[24:25], 0, v[140:141]
	global_load_lds_dwordx4 v[166:167], off
	s_add_i32 m0, s0, 0x2000
	s_nop 0
	global_load_lds_dwordx4 v[168:169], off
	s_setprio 1
	s_barrier
	s_waitcnt lgkmcnt(0)
	v_mfma_f32_16x16x32_bf16 v[64:67], v[200:203], v[158:161], v[64:67]
	v_mfma_f32_16x16x32_bf16 v[60:63], v[208:211], v[158:161], v[60:63]
	v_mfma_f32_16x16x32_bf16 v[56:59], v[200:203], v[176:179], v[56:59]
	v_mfma_f32_16x16x32_bf16 v[52:55], v[208:211], v[176:179], v[52:55]
	v_mfma_f32_16x16x32_bf16 v[48:51], v[200:203], v[184:187], v[48:51]
	v_mfma_f32_16x16x32_bf16 v[44:47], v[208:211], v[184:187], v[44:47]
	v_mfma_f32_16x16x32_bf16 v[40:43], v[200:203], v[192:195], v[40:43]
	v_mfma_f32_16x16x32_bf16 v[36:39], v[208:211], v[192:195], v[36:39]
	v_mfma_f32_16x16x32_bf16 v[64:67], v[204:207], v[172:175], v[64:67]
	v_mfma_f32_16x16x32_bf16 v[60:63], v[212:215], v[172:175], v[60:63]
	v_mfma_f32_16x16x32_bf16 v[56:59], v[204:207], v[180:183], v[56:59]
	v_mfma_f32_16x16x32_bf16 v[52:55], v[212:215], v[180:183], v[52:55]
	v_mfma_f32_16x16x32_bf16 v[48:51], v[204:207], v[188:191], v[48:51]
	v_mfma_f32_16x16x32_bf16 v[44:47], v[212:215], v[188:191], v[44:47]
	v_mfma_f32_16x16x32_bf16 v[40:43], v[204:207], v[196:199], v[40:43]
	v_mfma_f32_16x16x32_bf16 v[36:39], v[212:215], v[196:199], v[36:39]
	s_barrier
	s_setprio 0
	s_mov_b32 m0, s37
	v_lshl_add_u64 v[216:217], s[26:27], 0, v[144:145]
	ds_read_b128 v[158:161], v165 offset:16384
	ds_read_b128 v[172:175], v165 offset:17408
	ds_read_b128 v[176:179], v165 offset:18432
	ds_read_b128 v[180:183], v165 offset:19456
	ds_read_b128 v[184:187], v165 offset:20480
	ds_read_b128 v[188:191], v165 offset:21504
	ds_read_b128 v[192:195], v165 offset:22528
	ds_read_b128 v[196:199], v165 offset:23552
	global_load_lds_dwordx4 v[216:217], off
	v_lshl_add_u64 v[218:219], s[26:27], 0, v[142:143]
	s_mov_b32 m0, s56
	s_nop 0
	global_load_lds_dwordx4 v[218:219], off
	s_setprio 1
	s_barrier
	s_waitcnt lgkmcnt(0)
	v_mfma_f32_16x16x32_bf16 v[96:99], v[100:103], v[158:161], v[96:99]
	v_mfma_f32_16x16x32_bf16 v[92:95], v[150:153], v[158:161], v[92:95]
	v_mfma_f32_16x16x32_bf16 v[88:91], v[100:103], v[176:179], v[88:91]
	v_mfma_f32_16x16x32_bf16 v[84:87], v[150:153], v[176:179], v[84:87]
	v_mfma_f32_16x16x32_bf16 v[80:83], v[100:103], v[184:187], v[80:83]
	v_mfma_f32_16x16x32_bf16 v[76:79], v[150:153], v[184:187], v[76:79]
	v_mfma_f32_16x16x32_bf16 v[72:75], v[100:103], v[192:195], v[72:75]
	v_mfma_f32_16x16x32_bf16 v[68:71], v[150:153], v[192:195], v[68:71]
	v_mfma_f32_16x16x32_bf16 v[96:99], v[104:107], v[172:175], v[96:99]
	v_mfma_f32_16x16x32_bf16 v[92:95], v[154:157], v[172:175], v[92:95]
	v_mfma_f32_16x16x32_bf16 v[88:91], v[104:107], v[180:183], v[88:91]
	v_mfma_f32_16x16x32_bf16 v[84:87], v[154:157], v[180:183], v[84:87]
	v_mfma_f32_16x16x32_bf16 v[80:83], v[104:107], v[188:191], v[80:83]
	v_mfma_f32_16x16x32_bf16 v[76:79], v[154:157], v[188:191], v[76:79]
	v_mfma_f32_16x16x32_bf16 v[72:75], v[104:107], v[196:199], v[72:75]
	v_mfma_f32_16x16x32_bf16 v[68:71], v[154:157], v[196:199], v[68:71]
	s_barrier
	s_setprio 0
	s_add_u32 s0, s24, 0x40000
	s_addc_u32 s1, s25, 0
	s_add_i32 s69, s72, s36
	v_lshl_add_u64 v[100:101], s[0:1], 0, v[26:27]
	s_mov_b32 m0, s69
	s_nop 0
	global_load_lds_dwordx4 v[100:101], off
	v_lshl_add_u64 v[100:101], s[0:1], 0, v[140:141]
	s_add_i32 m0, s69, 0x2000
	s_nop 0
	global_load_lds_dwordx4 v[100:101], off
	s_waitcnt vmcnt(6)
	s_setprio 1
	s_barrier
	v_mfma_f32_16x16x32_bf16 v[32:35], v[200:203], v[158:161], v[32:35]
	v_mfma_f32_16x16x32_bf16 v[28:31], v[208:211], v[158:161], v[28:31]
	v_mfma_f32_16x16x32_bf16 v[22:25], v[200:203], v[176:179], v[22:25]
	v_mfma_f32_16x16x32_bf16 v[18:21], v[208:211], v[176:179], v[18:21]
	v_mfma_f32_16x16x32_bf16 v[14:17], v[200:203], v[184:187], v[14:17]
	v_mfma_f32_16x16x32_bf16 v[10:13], v[208:211], v[184:187], v[10:13]
	v_mfma_f32_16x16x32_bf16 v[6:9], v[200:203], v[192:195], v[6:9]
	v_mfma_f32_16x16x32_bf16 v[2:5], v[208:211], v[192:195], v[2:5]
	v_mfma_f32_16x16x32_bf16 v[32:35], v[204:207], v[172:175], v[32:35]
	v_mfma_f32_16x16x32_bf16 v[28:31], v[212:215], v[172:175], v[28:31]
	v_mfma_f32_16x16x32_bf16 v[22:25], v[204:207], v[180:183], v[22:25]
	v_mfma_f32_16x16x32_bf16 v[18:21], v[212:215], v[180:183], v[18:21]
	v_mfma_f32_16x16x32_bf16 v[14:17], v[204:207], v[188:191], v[14:17]
	v_mfma_f32_16x16x32_bf16 v[10:13], v[212:215], v[188:191], v[10:13]
	v_mfma_f32_16x16x32_bf16 v[6:9], v[204:207], v[196:199], v[6:9]
	v_mfma_f32_16x16x32_bf16 v[2:5], v[212:215], v[196:199], v[2:5]
	s_barrier
	s_setprio 0
	s_add_i32 s69, 0, 0x18000
	v_add_u32_e32 v154, s69, v163
	ds_read_b128 v[100:103], v154
	ds_read_b128 v[104:107], v154 offset:1024
	ds_read_b128 v[150:153], v154 offset:2048
	ds_read_b128 v[154:157], v154 offset:3072
	s_add_u32 s0, s26, 0x40000
	s_addc_u32 s1, s27, 0
	s_mov_b32 m0, s57
	v_lshl_add_u64 v[200:201], s[0:1], 0, v[144:145]
	ds_read_b128 v[158:161], v165 offset:32768
	ds_read_b128 v[172:175], v165 offset:33792
	ds_read_b128 v[176:179], v165 offset:34816
	ds_read_b128 v[180:183], v165 offset:35840
	ds_read_b128 v[184:187], v165 offset:36864
	ds_read_b128 v[188:191], v165 offset:37888
	ds_read_b128 v[192:195], v165 offset:38912
	ds_read_b128 v[196:199], v165 offset:39936
	global_load_lds_dwordx4 v[200:201], off
	v_lshl_add_u64 v[200:201], s[0:1], 0, v[142:143]
	s_mov_b32 m0, s58
	s_nop 0
	global_load_lds_dwordx4 v[200:201], off
	s_waitcnt lgkmcnt(8)
	s_setprio 1
	s_barrier
	s_waitcnt lgkmcnt(0)
	v_mfma_f32_16x16x32_bf16 v[136:139], v[100:103], v[158:161], v[136:139]
	v_mfma_f32_16x16x32_bf16 v[132:135], v[150:153], v[158:161], v[132:135]
	v_mfma_f32_16x16x32_bf16 v[128:131], v[100:103], v[176:179], v[128:131]
	v_mfma_f32_16x16x32_bf16 v[124:127], v[150:153], v[176:179], v[124:127]
	v_mfma_f32_16x16x32_bf16 v[120:123], v[100:103], v[184:187], v[120:123]
	v_mfma_f32_16x16x32_bf16 v[116:119], v[150:153], v[184:187], v[116:119]
	v_mfma_f32_16x16x32_bf16 v[112:115], v[100:103], v[192:195], v[112:115]
	v_mfma_f32_16x16x32_bf16 v[108:111], v[150:153], v[192:195], v[108:111]
	v_mfma_f32_16x16x32_bf16 v[136:139], v[104:107], v[172:175], v[136:139]
	v_mfma_f32_16x16x32_bf16 v[132:135], v[154:157], v[172:175], v[132:135]
	v_mfma_f32_16x16x32_bf16 v[128:131], v[104:107], v[180:183], v[128:131]
	v_mfma_f32_16x16x32_bf16 v[124:127], v[154:157], v[180:183], v[124:127]
	v_mfma_f32_16x16x32_bf16 v[120:123], v[104:107], v[188:191], v[120:123]
	v_mfma_f32_16x16x32_bf16 v[116:119], v[154:157], v[188:191], v[116:119]
	v_mfma_f32_16x16x32_bf16 v[112:115], v[104:107], v[196:199], v[112:115]
	v_mfma_f32_16x16x32_bf16 v[108:111], v[154:157], v[196:199], v[108:111]
	s_barrier
	s_setprio 0
	s_add_i32 s26, 0, 0x1c000
	s_add_i32 s0, s69, s36
	v_add_u32_e32 v212, s26, v163
	v_lshl_add_u64 v[166:167], v[166:167], 0, s[12:13]
	s_mov_b32 m0, s0
	ds_read_b128 v[200:203], v212
	ds_read_b128 v[204:207], v212 offset:1024
	ds_read_b128 v[208:211], v212 offset:2048
	ds_read_b128 v[212:215], v212 offset:3072
	global_load_lds_dwordx4 v[166:167], off
	v_lshl_add_u64 v[166:167], v[168:169], 0, s[12:13]
	s_add_i32 m0, s0, 0x2000
	s_nop 0
	global_load_lds_dwordx4 v[166:167], off
	s_setprio 1
	s_barrier
	s_waitcnt lgkmcnt(0)
	v_mfma_f32_16x16x32_bf16 v[64:67], v[200:203], v[158:161], v[64:67]
	v_mfma_f32_16x16x32_bf16 v[60:63], v[208:211], v[158:161], v[60:63]
	v_mfma_f32_16x16x32_bf16 v[56:59], v[200:203], v[176:179], v[56:59]
	v_mfma_f32_16x16x32_bf16 v[52:55], v[208:211], v[176:179], v[52:55]
	v_mfma_f32_16x16x32_bf16 v[48:51], v[200:203], v[184:187], v[48:51]
	v_mfma_f32_16x16x32_bf16 v[44:47], v[208:211], v[184:187], v[44:47]
	v_mfma_f32_16x16x32_bf16 v[40:43], v[200:203], v[192:195], v[40:43]
	v_mfma_f32_16x16x32_bf16 v[36:39], v[208:211], v[192:195], v[36:39]
	v_mfma_f32_16x16x32_bf16 v[64:67], v[204:207], v[172:175], v[64:67]
	v_mfma_f32_16x16x32_bf16 v[60:63], v[212:215], v[172:175], v[60:63]
	v_mfma_f32_16x16x32_bf16 v[56:59], v[204:207], v[180:183], v[56:59]
	v_mfma_f32_16x16x32_bf16 v[52:55], v[212:215], v[180:183], v[52:55]
	v_mfma_f32_16x16x32_bf16 v[48:51], v[204:207], v[188:191], v[48:51]
	v_mfma_f32_16x16x32_bf16 v[44:47], v[212:215], v[188:191], v[44:47]
	v_mfma_f32_16x16x32_bf16 v[40:43], v[204:207], v[196:199], v[40:43]
	v_mfma_f32_16x16x32_bf16 v[36:39], v[212:215], v[196:199], v[36:39]
	s_barrier
	s_setprio 0
	s_mov_b32 m0, s28
	v_lshl_add_u64 v[166:167], v[216:217], 0, s[12:13]
	ds_read_b128 v[158:161], v165 offset:49152
	ds_read_b128 v[172:175], v165 offset:50176
	ds_read_b128 v[176:179], v165 offset:51200
	ds_read_b128 v[180:183], v165 offset:52224
	ds_read_b128 v[184:187], v165 offset:53248
	ds_read_b128 v[188:191], v165 offset:54272
	ds_read_b128 v[192:195], v165 offset:55296
	ds_read_b128 v[196:199], v165 offset:56320
	global_load_lds_dwordx4 v[166:167], off
	v_lshl_add_u64 v[166:167], v[218:219], 0, s[12:13]
	s_mov_b32 m0, s29
	s_nop 0
	global_load_lds_dwordx4 v[166:167], off
	s_setprio 1
	s_barrier
	s_waitcnt lgkmcnt(0)
	v_mfma_f32_16x16x32_bf16 v[96:99], v[100:103], v[158:161], v[96:99]
	v_mfma_f32_16x16x32_bf16 v[92:95], v[150:153], v[158:161], v[92:95]
	v_mfma_f32_16x16x32_bf16 v[88:91], v[100:103], v[176:179], v[88:91]
	v_mfma_f32_16x16x32_bf16 v[84:87], v[150:153], v[176:179], v[84:87]
	v_mfma_f32_16x16x32_bf16 v[80:83], v[100:103], v[184:187], v[80:83]
	v_mfma_f32_16x16x32_bf16 v[76:79], v[150:153], v[184:187], v[76:79]
	v_mfma_f32_16x16x32_bf16 v[72:75], v[100:103], v[192:195], v[72:75]
	v_mfma_f32_16x16x32_bf16 v[68:71], v[150:153], v[192:195], v[68:71]
	v_mfma_f32_16x16x32_bf16 v[96:99], v[104:107], v[172:175], v[96:99]
	v_mfma_f32_16x16x32_bf16 v[92:95], v[154:157], v[172:175], v[92:95]
	v_mfma_f32_16x16x32_bf16 v[88:91], v[104:107], v[180:183], v[88:91]
	v_mfma_f32_16x16x32_bf16 v[84:87], v[154:157], v[180:183], v[84:87]
	v_mfma_f32_16x16x32_bf16 v[80:83], v[104:107], v[188:191], v[80:83]
	v_mfma_f32_16x16x32_bf16 v[76:79], v[154:157], v[188:191], v[76:79]
	v_mfma_f32_16x16x32_bf16 v[72:75], v[104:107], v[196:199], v[72:75]
	v_mfma_f32_16x16x32_bf16 v[68:71], v[154:157], v[196:199], v[68:71]
	s_barrier
	s_setprio 0
	s_add_u32 s0, s24, 0x40080
	s_addc_u32 s1, s25, 0
	s_add_i32 s24, s26, s36
	v_lshl_add_u64 v[100:101], s[0:1], 0, v[26:27]
	s_mov_b32 m0, s24
	s_nop 0
	global_load_lds_dwordx4 v[100:101], off
	v_lshl_add_u64 v[100:101], s[0:1], 0, v[140:141]
	s_add_i32 m0, s24, 0x2000
	s_nop 0
	global_load_lds_dwordx4 v[100:101], off
	s_waitcnt vmcnt(6)
	s_setprio 1
	s_barrier
	v_mfma_f32_16x16x32_bf16 v[32:35], v[200:203], v[158:161], v[32:35]
	v_mfma_f32_16x16x32_bf16 v[28:31], v[208:211], v[158:161], v[28:31]
	v_mfma_f32_16x16x32_bf16 v[22:25], v[200:203], v[176:179], v[22:25]
	v_mfma_f32_16x16x32_bf16 v[18:21], v[208:211], v[176:179], v[18:21]
	v_mfma_f32_16x16x32_bf16 v[14:17], v[200:203], v[184:187], v[14:17]
	v_mfma_f32_16x16x32_bf16 v[10:13], v[208:211], v[184:187], v[10:13]
	v_mfma_f32_16x16x32_bf16 v[6:9], v[200:203], v[192:195], v[6:9]
	v_mfma_f32_16x16x32_bf16 v[2:5], v[208:211], v[192:195], v[2:5]
	v_mfma_f32_16x16x32_bf16 v[32:35], v[204:207], v[172:175], v[32:35]
	v_mfma_f32_16x16x32_bf16 v[28:31], v[212:215], v[172:175], v[28:31]
	v_mfma_f32_16x16x32_bf16 v[22:25], v[204:207], v[180:183], v[22:25]
	v_mfma_f32_16x16x32_bf16 v[18:21], v[212:215], v[180:183], v[18:21]
	v_mfma_f32_16x16x32_bf16 v[14:17], v[204:207], v[188:191], v[14:17]
	v_mfma_f32_16x16x32_bf16 v[10:13], v[212:215], v[188:191], v[10:13]
	v_mfma_f32_16x16x32_bf16 v[6:9], v[204:207], v[196:199], v[6:9]
	v_mfma_f32_16x16x32_bf16 v[2:5], v[212:215], v[196:199], v[2:5]
	s_barrier
	s_setprio 0
	s_add_i32 s68, s68, 2
	s_add_u32 s22, s22, 0x100
	s_addc_u32 s23, s23, 0
	s_add_u32 s51, s51, 0x100
	s_addc_u32 s59, s59, 0
	s_cmp_gt_u32 s68, 13
	s_cbranch_scc0 .LBB0_479
	s_cmpk_gt_i32 s34, 0xff
	s_mov_b64 s[22:23], 0xb000
	s_cbranch_scc1 .LBB0_482
	s_ashr_i32 s0, s34, 5
	s_mul_hi_i32 s23, s0, 0x1600
	s_mul_i32 s22, s0, 0x1600

.LBB0_887:
	s_add_u32 s24, s22, 0x100
	s_addc_u32 s25, s23, 0
	s_add_i32 s0, 0, 0x10000
	v_add_u32_e32 v26, s0, v191
	ds_read_b128 v[134:137], v26
	ds_read_b128 v[138:141], v26 offset:1024
	ds_read_b128 v[142:145], v26 offset:2048
	ds_read_b128 v[146:149], v26 offset:3072
	s_cmp_eq_u32 s51, 4
	s_cselect_b32 s29, s47, s25
	s_cselect_b32 s28, s46, s24
	s_cselect_b32 s27, s18, s50
	s_cselect_b32 s26, s19, s45
	v_lshl_add_u64 v[28:29], s[22:23], 0, v[180:181]
	s_add_i32 m0, s58, 0xc000
	ds_read_b128 v[150:153], v193
	ds_read_b128 v[154:157], v193 offset:1024
	ds_read_b128 v[158:161], v193 offset:2048
	ds_read_b128 v[162:165], v193 offset:3072
	ds_read_b128 v[184:187], v193 offset:4096
	ds_read_b128 v[194:197], v193 offset:5120
	ds_read_b128 v[198:201], v193 offset:6144
	ds_read_b128 v[202:205], v193 offset:7168
	global_load_lds_dwordx4 v[28:29], off
	v_lshl_add_u64 v[28:29], s[22:23], 0, v[182:183]
	s_add_i32 m0, s58, 0xe000
	s_nop 0
	global_load_lds_dwordx4 v[28:29], off
	s_waitcnt lgkmcnt(8)
	s_setprio 1
	s_barrier
	s_waitcnt lgkmcnt(0)
	v_mfma_f32_16x16x32_bf16 v[130:133], v[134:137], v[150:153], v[130:133]
	v_mfma_f32_16x16x32_bf16 v[126:129], v[142:145], v[150:153], v[126:129]
	v_mfma_f32_16x16x32_bf16 v[122:125], v[134:137], v[158:161], v[122:125]
	v_mfma_f32_16x16x32_bf16 v[118:121], v[142:145], v[158:161], v[118:121]
	v_mfma_f32_16x16x32_bf16 v[114:117], v[134:137], v[184:187], v[114:117]
	v_mfma_f32_16x16x32_bf16 v[110:113], v[142:145], v[184:187], v[110:113]
	v_mfma_f32_16x16x32_bf16 v[106:109], v[134:137], v[198:201], v[106:109]
	v_mfma_f32_16x16x32_bf16 v[102:105], v[142:145], v[198:201], v[102:105]
	v_mfma_f32_16x16x32_bf16 v[130:133], v[138:141], v[154:157], v[130:133]
	v_mfma_f32_16x16x32_bf16 v[126:129], v[146:149], v[154:157], v[126:129]
	v_mfma_f32_16x16x32_bf16 v[122:125], v[138:141], v[162:165], v[122:125]
	v_mfma_f32_16x16x32_bf16 v[118:121], v[146:149], v[162:165], v[118:121]
	v_mfma_f32_16x16x32_bf16 v[114:117], v[138:141], v[194:197], v[114:117]
	v_mfma_f32_16x16x32_bf16 v[110:113], v[146:149], v[194:197], v[110:113]
	v_mfma_f32_16x16x32_bf16 v[106:109], v[138:141], v[202:205], v[106:109]
	v_mfma_f32_16x16x32_bf16 v[102:105], v[146:149], v[202:205], v[102:105]
	s_barrier
	s_setprio 0
	s_add_i32 s22, 0, 0x14000
	s_add_i32 s0, s0, s55
	v_add_u32_e32 v26, s22, v191
	v_lshl_add_u64 v[166:167], s[26:27], 0, v[176:177]
	s_mov_b32 m0, s0
	ds_read_b128 v[206:209], v26
	ds_read_b128 v[210:213], v26 offset:1024
	ds_read_b128 v[214:217], v26 offset:2048
	ds_read_b128 v[218:221], v26 offset:3072
	global_load_lds_dwordx4 v[166:167], off
	v_lshl_add_u64 v[168:169], s[26:27], 0, v[172:173]
	s_add_i32 m0, s0, 0x2000
	s_nop 0
	global_load_lds_dwordx4 v[168:169], off
	s_setprio 1
	s_barrier
	s_waitcnt lgkmcnt(0)
	v_mfma_f32_16x16x32_bf16 v[98:101], v[206:209], v[150:153], v[98:101]
	v_mfma_f32_16x16x32_bf16 v[94:97], v[214:217], v[150:153], v[94:97]
	v_mfma_f32_16x16x32_bf16 v[90:93], v[206:209], v[158:161], v[90:93]
	v_mfma_f32_16x16x32_bf16 v[86:89], v[214:217], v[158:161], v[86:89]
	v_mfma_f32_16x16x32_bf16 v[82:85], v[206:209], v[184:187], v[82:85]
	v_mfma_f32_16x16x32_bf16 v[78:81], v[214:217], v[184:187], v[78:81]
	v_mfma_f32_16x16x32_bf16 v[74:77], v[206:209], v[198:201], v[74:77]
	v_mfma_f32_16x16x32_bf16 v[70:73], v[214:217], v[198:201], v[70:73]
	v_mfma_f32_16x16x32_bf16 v[98:101], v[210:213], v[154:157], v[98:101]
	v_mfma_f32_16x16x32_bf16 v[94:97], v[218:221], v[154:157], v[94:97]
	v_mfma_f32_16x16x32_bf16 v[90:93], v[210:213], v[162:165], v[90:93]
	v_mfma_f32_16x16x32_bf16 v[86:89], v[218:221], v[162:165], v[86:89]
	v_mfma_f32_16x16x32_bf16 v[82:85], v[210:213], v[194:197], v[82:85]
	v_mfma_f32_16x16x32_bf16 v[78:81], v[218:221], v[194:197], v[78:81]
	v_mfma_f32_16x16x32_bf16 v[74:77], v[210:213], v[202:205], v[74:77]
	v_mfma_f32_16x16x32_bf16 v[70:73], v[218:221], v[202:205], v[70:73]
	s_barrier
	s_setprio 0
	s_mov_b32 m0, s58
	v_lshl_add_u64 v[188:189], s[28:29], 0, v[178:179]
	ds_read_b128 v[150:153], v193 offset:16384
	ds_read_b128 v[154:157], v193 offset:17408
	ds_read_b128 v[158:161], v193 offset:18432
	ds_read_b128 v[162:165], v193 offset:19456
	ds_read_b128 v[184:187], v193 offset:20480
	ds_read_b128 v[194:197], v193 offset:21504
	ds_read_b128 v[198:201], v193 offset:22528
	ds_read_b128 v[202:205], v193 offset:23552
	global_load_lds_dwordx4 v[188:189], off
	v_lshl_add_u64 v[222:223], s[28:29], 0, v[174:175]
	s_mov_b32 m0, s59
	s_nop 0
	global_load_lds_dwordx4 v[222:223], off
	s_setprio 1
	s_barrier
	s_waitcnt lgkmcnt(0)
	v_mfma_f32_16x16x32_bf16 v[66:69], v[134:137], v[150:153], v[66:69]
	v_mfma_f32_16x16x32_bf16 v[62:65], v[142:145], v[150:153], v[62:65]
	v_mfma_f32_16x16x32_bf16 v[58:61], v[134:137], v[158:161], v[58:61]
	v_mfma_f32_16x16x32_bf16 v[54:57], v[142:145], v[158:161], v[54:57]
	v_mfma_f32_16x16x32_bf16 v[50:53], v[134:137], v[184:187], v[50:53]
	v_mfma_f32_16x16x32_bf16 v[46:49], v[142:145], v[184:187], v[46:49]
	v_mfma_f32_16x16x32_bf16 v[42:45], v[134:137], v[198:201], v[42:45]
	v_mfma_f32_16x16x32_bf16 v[38:41], v[142:145], v[198:201], v[38:41]
	v_mfma_f32_16x16x32_bf16 v[66:69], v[138:141], v[154:157], v[66:69]
	v_mfma_f32_16x16x32_bf16 v[62:65], v[146:149], v[154:157], v[62:65]
	v_mfma_f32_16x16x32_bf16 v[58:61], v[138:141], v[162:165], v[58:61]
	v_mfma_f32_16x16x32_bf16 v[54:57], v[146:149], v[162:165], v[54:57]
	v_mfma_f32_16x16x32_bf16 v[50:53], v[138:141], v[194:197], v[50:53]
	v_mfma_f32_16x16x32_bf16 v[46:49], v[146:149], v[194:197], v[46:49]
	v_mfma_f32_16x16x32_bf16 v[42:45], v[138:141], v[202:205], v[42:45]
	v_mfma_f32_16x16x32_bf16 v[38:41], v[146:149], v[202:205], v[38:41]
	s_barrier
	s_setprio 0
	s_add_u32 s0, s26, 0x20000
	s_addc_u32 s1, s27, 0
	s_add_i32 s22, s22, s55
	v_lshl_add_u64 v[28:29], s[0:1], 0, v[176:177]
	s_mov_b32 m0, s22
	s_nop 0
	global_load_lds_dwordx4 v[28:29], off
	v_lshl_add_u64 v[28:29], s[0:1], 0, v[172:173]
	s_add_i32 m0, s22, 0x2000
	s_nop 0
	global_load_lds_dwordx4 v[28:29], off
	s_waitcnt vmcnt(6)
	s_setprio 1
	s_barrier
	v_mfma_f32_16x16x32_bf16 v[34:37], v[206:209], v[150:153], v[34:37]
	v_mfma_f32_16x16x32_bf16 v[28:31], v[214:217], v[150:153], v[30:33]
	v_mfma_f32_16x16x32_bf16 v[22:25], v[206:209], v[158:161], v[22:25]
	v_mfma_f32_16x16x32_bf16 v[18:21], v[214:217], v[158:161], v[18:21]
	v_mfma_f32_16x16x32_bf16 v[14:17], v[206:209], v[184:187], v[14:17]
	v_mfma_f32_16x16x32_bf16 v[10:13], v[214:217], v[184:187], v[10:13]
	v_mfma_f32_16x16x32_bf16 v[6:9], v[206:209], v[198:201], v[6:9]
	v_mfma_f32_16x16x32_bf16 v[2:5], v[214:217], v[198:201], v[2:5]
	v_mfma_f32_16x16x32_bf16 v[34:37], v[210:213], v[154:157], v[34:37]
	v_mfma_f32_16x16x32_bf16 v[28:31], v[218:221], v[154:157], v[28:31]
	v_mfma_f32_16x16x32_bf16 v[22:25], v[210:213], v[162:165], v[22:25]
	v_mfma_f32_16x16x32_bf16 v[18:21], v[218:221], v[162:165], v[18:21]
	v_mfma_f32_16x16x32_bf16 v[14:17], v[210:213], v[194:197], v[14:17]
	v_mfma_f32_16x16x32_bf16 v[10:13], v[218:221], v[194:197], v[10:13]
	v_mfma_f32_16x16x32_bf16 v[6:9], v[210:213], v[202:205], v[6:9]
	v_mfma_f32_16x16x32_bf16 v[2:5], v[218:221], v[202:205], v[2:5]
	s_barrier
	s_setprio 0
	s_add_i32 s22, 0, 0x18000
	v_add_u32_e32 v26, s22, v191
	ds_read_b128 v[134:137], v26
	ds_read_b128 v[138:141], v26 offset:1024
	ds_read_b128 v[142:145], v26 offset:2048
	ds_read_b128 v[146:149], v26 offset:3072
	s_add_u32 s0, s28, 0x140000
	s_addc_u32 s1, s29, 0
	s_mov_b32 m0, s68
	v_lshl_add_u64 v[32:33], s[0:1], 0, v[178:179]
	ds_read_b128 v[150:153], v193 offset:32768
	ds_read_b128 v[154:157], v193 offset:33792
	ds_read_b128 v[158:161], v193 offset:34816
	ds_read_b128 v[162:165], v193 offset:35840
	ds_read_b128 v[184:187], v193 offset:36864
	ds_read_b128 v[194:197], v193 offset:37888
	ds_read_b128 v[198:201], v193 offset:38912
	ds_read_b128 v[202:205], v193 offset:39936
	global_load_lds_dwordx4 v[32:33], off
	v_lshl_add_u64 v[32:33], s[0:1], 0, v[174:175]
	s_mov_b32 m0, s69
	s_nop 0
	global_load_lds_dwordx4 v[32:33], off
	s_waitcnt lgkmcnt(8)
	s_setprio 1
	s_barrier
	s_waitcnt lgkmcnt(0)
	v_mfma_f32_16x16x32_bf16 v[130:133], v[134:137], v[150:153], v[130:133]
	v_mfma_f32_16x16x32_bf16 v[126:129], v[142:145], v[150:153], v[126:129]
	v_mfma_f32_16x16x32_bf16 v[122:125], v[134:137], v[158:161], v[122:125]
	v_mfma_f32_16x16x32_bf16 v[118:121], v[142:145], v[158:161], v[118:121]
	v_mfma_f32_16x16x32_bf16 v[114:117], v[134:137], v[184:187], v[114:117]
	v_mfma_f32_16x16x32_bf16 v[110:113], v[142:145], v[184:187], v[110:113]
	v_mfma_f32_16x16x32_bf16 v[106:109], v[134:137], v[198:201], v[106:109]
	v_mfma_f32_16x16x32_bf16 v[102:105], v[142:145], v[198:201], v[102:105]
	v_mfma_f32_16x16x32_bf16 v[130:133], v[138:141], v[154:157], v[130:133]
	v_mfma_f32_16x16x32_bf16 v[126:129], v[146:149], v[154:157], v[126:129]
	v_mfma_f32_16x16x32_bf16 v[122:125], v[138:141], v[162:165], v[122:125]
	v_mfma_f32_16x16x32_bf16 v[118:121], v[146:149], v[162:165], v[118:121]
	v_mfma_f32_16x16x32_bf16 v[114:117], v[138:141], v[194:197], v[114:117]
	v_mfma_f32_16x16x32_bf16 v[110:113], v[146:149], v[194:197], v[110:113]
	v_mfma_f32_16x16x32_bf16 v[106:109], v[138:141], v[202:205], v[106:109]
	v_mfma_f32_16x16x32_bf16 v[102:105], v[146:149], v[202:205], v[102:105]
	s_barrier
	s_setprio 0
	s_add_i32 s23, 0, 0x1c000
	s_add_i32 s0, s22, s55
	v_add_u32_e32 v26, s23, v191
	v_lshl_add_u64 v[32:33], v[166:167], 0, s[12:13]
	s_mov_b32 m0, s0
	ds_read_b128 v[206:209], v26
	ds_read_b128 v[210:213], v26 offset:1024
	ds_read_b128 v[214:217], v26 offset:2048
	ds_read_b128 v[218:221], v26 offset:3072
	global_load_lds_dwordx4 v[32:33], off
	v_lshl_add_u64 v[32:33], v[168:169], 0, s[12:13]
	s_add_i32 m0, s0, 0x2000
	s_nop 0
	global_load_lds_dwordx4 v[32:33], off
	s_setprio 1
	s_barrier
	s_waitcnt lgkmcnt(0)
	v_mfma_f32_16x16x32_bf16 v[98:101], v[206:209], v[150:153], v[98:101]
	v_mfma_f32_16x16x32_bf16 v[94:97], v[214:217], v[150:153], v[94:97]
	v_mfma_f32_16x16x32_bf16 v[90:93], v[206:209], v[158:161], v[90:93]
	v_mfma_f32_16x16x32_bf16 v[86:89], v[214:217], v[158:161], v[86:89]
	v_mfma_f32_16x16x32_bf16 v[82:85], v[206:209], v[184:187], v[82:85]
	v_mfma_f32_16x16x32_bf16 v[78:81], v[214:217], v[184:187], v[78:81]
	v_mfma_f32_16x16x32_bf16 v[74:77], v[206:209], v[198:201], v[74:77]
	v_mfma_f32_16x16x32_bf16 v[70:73], v[214:217], v[198:201], v[70:73]
	v_mfma_f32_16x16x32_bf16 v[98:101], v[210:213], v[154:157], v[98:101]
	v_mfma_f32_16x16x32_bf16 v[94:97], v[218:221], v[154:157], v[94:97]
	v_mfma_f32_16x16x32_bf16 v[90:93], v[210:213], v[162:165], v[90:93]
	v_mfma_f32_16x16x32_bf16 v[86:89], v[218:221], v[162:165], v[86:89]
	v_mfma_f32_16x16x32_bf16 v[82:85], v[210:213], v[194:197], v[82:85]
	v_mfma_f32_16x16x32_bf16 v[78:81], v[218:221], v[194:197], v[78:81]
	v_mfma_f32_16x16x32_bf16 v[74:77], v[210:213], v[202:205], v[74:77]
	v_mfma_f32_16x16x32_bf16 v[70:73], v[218:221], v[202:205], v[70:73]
	s_barrier
	s_setprio 0
	s_mov_b32 m0, s30
	v_lshl_add_u64 v[32:33], v[188:189], 0, s[12:13]
	ds_read_b128 v[150:153], v193 offset:49152
	ds_read_b128 v[154:157], v193 offset:50176
	ds_read_b128 v[158:161], v193 offset:51200
	ds_read_b128 v[162:165], v193 offset:52224
	ds_read_b128 v[184:187], v193 offset:53248
	ds_read_b128 v[194:197], v193 offset:54272
	ds_read_b128 v[198:201], v193 offset:55296
	ds_read_b128 v[202:205], v193 offset:56320
	global_load_lds_dwordx4 v[32:33], off
	v_lshl_add_u64 v[32:33], v[222:223], 0, s[12:13]
	s_mov_b32 m0, s34
	s_nop 0
	global_load_lds_dwordx4 v[32:33], off
	s_setprio 1
	s_barrier
	s_waitcnt lgkmcnt(0)
	v_mfma_f32_16x16x32_bf16 v[66:69], v[134:137], v[150:153], v[66:69]
	v_mfma_f32_16x16x32_bf16 v[62:65], v[142:145], v[150:153], v[62:65]
	v_mfma_f32_16x16x32_bf16 v[58:61], v[134:137], v[158:161], v[58:61]
	v_mfma_f32_16x16x32_bf16 v[54:57], v[142:145], v[158:161], v[54:57]
	v_mfma_f32_16x16x32_bf16 v[50:53], v[134:137], v[184:187], v[50:53]
	v_mfma_f32_16x16x32_bf16 v[46:49], v[142:145], v[184:187], v[46:49]
	v_mfma_f32_16x16x32_bf16 v[42:45], v[134:137], v[198:201], v[42:45]
	v_mfma_f32_16x16x32_bf16 v[38:41], v[142:145], v[198:201], v[38:41]
	v_mfma_f32_16x16x32_bf16 v[66:69], v[138:141], v[154:157], v[66:69]
	v_mfma_f32_16x16x32_bf16 v[62:65], v[146:149], v[154:157], v[62:65]
	v_mfma_f32_16x16x32_bf16 v[58:61], v[138:141], v[162:165], v[58:61]
	v_mfma_f32_16x16x32_bf16 v[54:57], v[146:149], v[162:165], v[54:57]
	v_mfma_f32_16x16x32_bf16 v[50:53], v[138:141], v[194:197], v[50:53]
	v_mfma_f32_16x16x32_bf16 v[46:49], v[146:149], v[194:197], v[46:49]
	v_mfma_f32_16x16x32_bf16 v[42:45], v[138:141], v[202:205], v[42:45]
	v_mfma_f32_16x16x32_bf16 v[38:41], v[146:149], v[202:205], v[38:41]
	s_barrier
	s_setprio 0
	s_add_u32 s0, s26, 0x20080
	s_addc_u32 s1, s27, 0
	s_add_i32 s22, s23, s55
	v_lshl_add_u64 v[32:33], s[0:1], 0, v[176:177]
	s_mov_b32 m0, s22
	s_nop 0
	global_load_lds_dwordx4 v[32:33], off
	v_lshl_add_u64 v[32:33], s[0:1], 0, v[172:173]
	s_add_i32 m0, s22, 0x2000
	s_nop 0
	global_load_lds_dwordx4 v[32:33], off
	s_waitcnt vmcnt(6)
	s_setprio 1
	s_barrier
	v_mfma_f32_16x16x32_bf16 v[32:35], v[206:209], v[150:153], v[34:37]
	v_mfma_f32_16x16x32_bf16 v[28:31], v[214:217], v[150:153], v[28:31]
	v_mfma_f32_16x16x32_bf16 v[22:25], v[206:209], v[158:161], v[22:25]
	v_mfma_f32_16x16x32_bf16 v[18:21], v[214:217], v[158:161], v[18:21]
	v_mfma_f32_16x16x32_bf16 v[14:17], v[206:209], v[184:187], v[14:17]
	v_mfma_f32_16x16x32_bf16 v[10:13], v[214:217], v[184:187], v[10:13]
	v_mfma_f32_16x16x32_bf16 v[6:9], v[206:209], v[198:201], v[6:9]
	v_mfma_f32_16x16x32_bf16 v[2:5], v[214:217], v[198:201], v[2:5]
	v_mfma_f32_16x16x32_bf16 v[34:37], v[210:213], v[154:157], v[32:35]
	v_mfma_f32_16x16x32_bf16 v[30:33], v[218:221], v[154:157], v[28:31]
	v_mfma_f32_16x16x32_bf16 v[22:25], v[210:213], v[162:165], v[22:25]
	v_mfma_f32_16x16x32_bf16 v[18:21], v[218:221], v[162:165], v[18:21]
	v_mfma_f32_16x16x32_bf16 v[14:17], v[210:213], v[194:197], v[14:17]
	v_mfma_f32_16x16x32_bf16 v[10:13], v[218:221], v[194:197], v[10:13]
	v_mfma_f32_16x16x32_bf16 v[6:9], v[210:213], v[202:205], v[6:9]
	v_mfma_f32_16x16x32_bf16 v[2:5], v[218:221], v[202:205], v[2:5]
	s_barrier
	s_setprio 0
	s_add_i32 s51, s51, 2
	s_add_u32 s45, s45, 0x100
	s_addc_u32 s50, s50, 0
	s_cmp_gt_u32 s51, 5
	s_mov_b64 s[22:23], s[24:25]
	s_cbranch_scc0 .LBB0_887
	v_lshl_or_b32 v186, s17, 8, v192
	v_ashrrev_i32_e32 v187, 31, v186
	v_lshl_add_u32 v26, s16, 8, v190
	s_cmp_lg_u32 s81, 0
	v_lshl_add_u64 v[28:29], v[186:187], 1, s[40:41]
	s_cselect_b64 s[50:51], -1, 0
	s_cmp_eq_u32 s81, 0
	v_mad_i64_i32 v[184:185], s[0:1], v26, s78, v[28:29]
	v_or_b32_e32 v198, 16, v26
	v_or_b32_e32 v197, 32, v26
	v_or_b32_e32 v196, 48, v26
	v_add_u32_e32 v195, 0x80, v26
	v_add_u32_e32 v194, 0x90, v26
	s_cbranch_scc1 .LBB0_894
	v_add_co_u32_e32 v134, vcc, 0x2000, v184
	v_mad_i64_i32 v[166:167], s[0:1], v26, s78, 0
	s_nop 0
	v_addc_co_u32_e32 v135, vcc, 0, v185, vcc
	global_load_dwordx4 v[162:165], v[134:135], off
	global_load_dwordx4 v[158:161], v[134:135], off offset:256
	v_mad_i64_i32 v[134:135], s[0:1], v198, s78, v[28:29]
	v_add_co_u32_e32 v134, vcc, 0x2000, v134
	v_lshlrev_b64 v[186:187], 1, v[186:187]
	s_nop 0
	v_addc_co_u32_e32 v135, vcc, 0, v135, vcc
	global_load_dwordx4 v[154:157], v[134:135], off
	global_load_dwordx4 v[150:153], v[134:135], off offset:256
	v_mad_i64_i32 v[134:135], s[0:1], v197, s78, v[28:29]
	v_add_co_u32_e32 v134, vcc, 0x2000, v134
	s_movk_i32 s16, 0x2000
	s_nop 0
	v_addc_co_u32_e32 v135, vcc, 0, v135, vcc
	global_load_dwordx4 v[146:149], v[134:135], off
	global_load_dwordx4 v[142:145], v[134:135], off offset:256
	v_mad_i64_i32 v[134:135], s[0:1], v196, s78, v[28:29]
	v_add_co_u32_e32 v134, vcc, 0x2000, v134
	s_nop 1
	v_addc_co_u32_e32 v135, vcc, 0, v135, vcc
	global_load_dwordx4 v[138:141], v[134:135], off
	s_nop 0
	global_load_dwordx4 v[134:137], v[134:135], off offset:256
	s_waitcnt vmcnt(0)
	v_lshlrev_b32_e32 v168, 16, v162
	v_and_b32_e32 v162, 0xffff0000, v162
	v_mul_f32_e32 v162, 0xbfb8aa3b, v162
	v_exp_f32_e32 v162, v162
	v_mul_f32_e32 v168, 0xbfb8aa3b, v168
	v_exp_f32_e32 v168, v168
	v_add_f32_e32 v162, 1.0, v162
	v_rcp_f32_e32 v169, v162
	v_lshlrev_b32_e32 v162, 16, v163
	v_and_b32_e32 v163, 0xffff0000, v163
	v_mul_f32_e32 v162, 0xbfb8aa3b, v162
	v_mul_f32_e32 v163, 0xbfb8aa3b, v163
	v_exp_f32_e32 v162, v162
	v_exp_f32_e32 v163, v163
	v_add_f32_e32 v168, 1.0, v168
	v_rcp_f32_e32 v168, v168
	v_add_f32_e32 v162, 1.0, v162
	v_add_f32_e32 v163, 1.0, v163
	v_rcp_f32_e32 v162, v162
	v_rcp_f32_e32 v163, v163
	v_pk_mul_f32 v[168:169], v[130:131], v[168:169]
	v_pk_mul_f32 v[188:189], v[132:133], v[162:163]
	v_lshlrev_b32_e32 v162, 16, v164
	v_and_b32_e32 v163, 0xffff0000, v164
	v_mul_f32_e32 v162, 0xbfb8aa3b, v162
	v_mul_f32_e32 v163, 0xbfb8aa3b, v163
	v_exp_f32_e32 v162, v162
	v_exp_f32_e32 v163, v163
	v_add_f32_e32 v162, 1.0, v162
	v_add_f32_e32 v163, 1.0, v163
	v_rcp_f32_e32 v162, v162
	v_rcp_f32_e32 v163, v163
	s_nop 0
	v_pk_mul_f32 v[200:201], v[126:127], v[162:163]
	v_lshlrev_b32_e32 v162, 16, v165
	v_and_b32_e32 v163, 0xffff0000, v165
	v_mul_f32_e32 v162, 0xbfb8aa3b, v162
	v_mul_f32_e32 v163, 0xbfb8aa3b, v163
	v_exp_f32_e32 v162, v162
	v_exp_f32_e32 v163, v163
	v_cvt_pk_bf16_f32 v164, v200, v201
	v_add_f32_e32 v162, 1.0, v162
	v_add_f32_e32 v163, 1.0, v163
	v_rcp_f32_e32 v162, v162
	v_rcp_f32_e32 v163, v163
	s_nop 0
	v_pk_mul_f32 v[202:203], v[128:129], v[162:163]
	v_cvt_pk_bf16_f32 v163, v188, v189
	v_lshl_add_u64 v[188:189], s[42:43], 0, v[166:167]
	v_cvt_pk_bf16_f32 v162, v168, v169
	v_cvt_pk_bf16_f32 v165, v202, v203
	v_lshl_add_u64 v[188:189], v[188:189], 0, v[186:187]
	global_store_dwordx4 v[188:189], v[162:165], off
	s_nop 1
	v_lshlrev_b32_e32 v162, 16, v158
	v_and_b32_e32 v158, 0xffff0000, v158
	v_mul_f32_e32 v158, 0xbfb8aa3b, v158
	v_exp_f32_e32 v158, v158
	v_mul_f32_e32 v162, 0xbfb8aa3b, v162
	v_exp_f32_e32 v162, v162
	v_add_f32_e32 v158, 1.0, v158
	v_rcp_f32_e32 v163, v158
	v_lshlrev_b32_e32 v158, 16, v159
	v_and_b32_e32 v159, 0xffff0000, v159
	v_mul_f32_e32 v158, 0xbfb8aa3b, v158
	v_mul_f32_e32 v159, 0xbfb8aa3b, v159
	v_exp_f32_e32 v158, v158
	v_exp_f32_e32 v159, v159
	v_add_f32_e32 v162, 1.0, v162
	v_rcp_f32_e32 v162, v162
	v_add_f32_e32 v158, 1.0, v158
	v_add_f32_e32 v159, 1.0, v159
	v_rcp_f32_e32 v158, v158
	v_rcp_f32_e32 v159, v159
	v_pk_mul_f32 v[162:163], v[98:99], v[162:163]
	v_pk_mul_f32 v[164:165], v[100:101], v[158:159]
	v_lshlrev_b32_e32 v158, 16, v160
	v_and_b32_e32 v159, 0xffff0000, v160
	v_mul_f32_e32 v158, 0xbfb8aa3b, v158
	v_mul_f32_e32 v159, 0xbfb8aa3b, v159
	v_exp_f32_e32 v158, v158
	v_exp_f32_e32 v159, v159
	v_add_f32_e32 v158, 1.0, v158
	v_add_f32_e32 v159, 1.0, v159
	v_rcp_f32_e32 v158, v158
	v_rcp_f32_e32 v159, v159
	s_nop 0
	v_pk_mul_f32 v[166:167], v[94:95], v[158:159]
	v_lshlrev_b32_e32 v158, 16, v161
	v_and_b32_e32 v159, 0xffff0000, v161
	v_mul_f32_e32 v158, 0xbfb8aa3b, v158
	v_mul_f32_e32 v159, 0xbfb8aa3b, v159
	v_exp_f32_e32 v158, v158
	v_exp_f32_e32 v159, v159
	v_cvt_pk_bf16_f32 v160, v166, v167
	v_add_f32_e32 v158, 1.0, v158
	v_add_f32_e32 v159, 1.0, v159
	v_rcp_f32_e32 v158, v158
	v_rcp_f32_e32 v159, v159
	s_nop 0
	v_pk_mul_f32 v[168:169], v[96:97], v[158:159]
	v_cvt_pk_bf16_f32 v158, v162, v163
	v_cvt_pk_bf16_f32 v159, v164, v165
	v_cvt_pk_bf16_f32 v161, v168, v169
	global_store_dwordx4 v[188:189], v[158:161], off offset:256
	s_nop 1
	v_lshlrev_b32_e32 v158, 16, v154
	v_and_b32_e32 v154, 0xffff0000, v154
	v_mul_f32_e32 v154, 0xbfb8aa3b, v154
	v_exp_f32_e32 v154, v154
	v_mul_f32_e32 v158, 0xbfb8aa3b, v158
	v_exp_f32_e32 v158, v158
	v_add_f32_e32 v154, 1.0, v154
	v_rcp_f32_e32 v159, v154
	v_lshlrev_b32_e32 v154, 16, v155
	v_and_b32_e32 v155, 0xffff0000, v155
	v_mul_f32_e32 v154, 0xbfb8aa3b, v154
	v_mul_f32_e32 v155, 0xbfb8aa3b, v155
	v_exp_f32_e32 v154, v154
	v_exp_f32_e32 v155, v155
	v_add_f32_e32 v158, 1.0, v158
	v_rcp_f32_e32 v158, v158
	v_add_f32_e32 v154, 1.0, v154
	v_add_f32_e32 v155, 1.0, v155
	v_rcp_f32_e32 v154, v154
	v_rcp_f32_e32 v155, v155
	v_pk_mul_f32 v[158:159], v[122:123], v[158:159]
	v_pk_mul_f32 v[160:161], v[124:125], v[154:155]
	v_lshlrev_b32_e32 v154, 16, v156
	v_and_b32_e32 v155, 0xffff0000, v156
	v_mul_f32_e32 v154, 0xbfb8aa3b, v154
	v_mul_f32_e32 v155, 0xbfb8aa3b, v155
	v_exp_f32_e32 v154, v154
	v_exp_f32_e32 v155, v155
	v_add_f32_e32 v154, 1.0, v154
	v_add_f32_e32 v155, 1.0, v155
	v_rcp_f32_e32 v154, v154
	v_rcp_f32_e32 v155, v155
	s_nop 0
	v_pk_mul_f32 v[162:163], v[118:119], v[154:155]
	v_lshlrev_b32_e32 v154, 16, v157
	v_and_b32_e32 v155, 0xffff0000, v157
	v_mul_f32_e32 v154, 0xbfb8aa3b, v154
	v_mul_f32_e32 v155, 0xbfb8aa3b, v155
	v_exp_f32_e32 v154, v154
	v_exp_f32_e32 v155, v155
	v_cvt_pk_bf16_f32 v156, v162, v163
	v_mov_b64_e32 v[162:163], s[42:43]
	v_add_f32_e32 v154, 1.0, v154
	v_add_f32_e32 v155, 1.0, v155
	v_rcp_f32_e32 v154, v154
	v_rcp_f32_e32 v155, v155
	s_nop 0
	v_pk_mul_f32 v[164:165], v[120:121], v[154:155]
	v_cvt_pk_bf16_f32 v154, v158, v159
	v_mad_i64_i32 v[158:159], s[0:1], v198, s78, v[162:163]
	v_cvt_pk_bf16_f32 v155, v160, v161
	v_cvt_pk_bf16_f32 v157, v164, v165
	v_lshl_add_u64 v[158:159], v[158:159], 0, v[186:187]
	global_store_dwordx4 v[158:159], v[154:157], off
	s_nop 1
	v_lshlrev_b32_e32 v154, 16, v150
	v_and_b32_e32 v150, 0xffff0000, v150
	v_mul_f32_e32 v150, 0xbfb8aa3b, v150
	v_exp_f32_e32 v150, v150
	v_mul_f32_e32 v154, 0xbfb8aa3b, v154
	v_exp_f32_e32 v154, v154
	v_add_f32_e32 v150, 1.0, v150
	v_rcp_f32_e32 v155, v150
	v_lshlrev_b32_e32 v150, 16, v151
	v_and_b32_e32 v151, 0xffff0000, v151
	v_mul_f32_e32 v150, 0xbfb8aa3b, v150
	v_mul_f32_e32 v151, 0xbfb8aa3b, v151
	v_exp_f32_e32 v150, v150
	v_exp_f32_e32 v151, v151
	v_add_f32_e32 v154, 1.0, v154
	v_rcp_f32_e32 v154, v154
	v_add_f32_e32 v150, 1.0, v150
	v_add_f32_e32 v151, 1.0, v151
	v_rcp_f32_e32 v150, v150
	v_rcp_f32_e32 v151, v151
	v_pk_mul_f32 v[154:155], v[90:91], v[154:155]
	v_pk_mul_f32 v[156:157], v[92:93], v[150:151]
	v_lshlrev_b32_e32 v150, 16, v152
	v_and_b32_e32 v151, 0xffff0000, v152
	v_mul_f32_e32 v150, 0xbfb8aa3b, v150
	v_mul_f32_e32 v151, 0xbfb8aa3b, v151
	v_exp_f32_e32 v150, v150
	v_exp_f32_e32 v151, v151
	v_add_f32_e32 v150, 1.0, v150
	v_add_f32_e32 v151, 1.0, v151
	v_rcp_f32_e32 v150, v150
	v_rcp_f32_e32 v151, v151
	s_nop 0
	v_pk_mul_f32 v[160:161], v[86:87], v[150:151]
	v_lshlrev_b32_e32 v150, 16, v153
	v_and_b32_e32 v151, 0xffff0000, v153
	v_mul_f32_e32 v150, 0xbfb8aa3b, v150
	v_mul_f32_e32 v151, 0xbfb8aa3b, v151
	v_exp_f32_e32 v150, v150
	v_exp_f32_e32 v151, v151
	v_cvt_pk_bf16_f32 v152, v160, v161
	v_add_f32_e32 v150, 1.0, v150
	v_add_f32_e32 v151, 1.0, v151
	v_rcp_f32_e32 v150, v150
	v_rcp_f32_e32 v151, v151
	s_nop 0
	v_pk_mul_f32 v[164:165], v[88:89], v[150:151]
	v_cvt_pk_bf16_f32 v150, v154, v155
	v_cvt_pk_bf16_f32 v151, v156, v157
	v_cvt_pk_bf16_f32 v153, v164, v165
	global_store_dwordx4 v[158:159], v[150:153], off offset:256
	v_add_u32_e32 v165, 0xa0, v26
	v_add_u32_e32 v164, 0xb0, v26
	v_lshlrev_b32_e32 v150, 16, v146
	v_and_b32_e32 v146, 0xffff0000, v146
	v_mul_f32_e32 v146, 0xbfb8aa3b, v146
	v_exp_f32_e32 v146, v146
	v_mul_f32_e32 v150, 0xbfb8aa3b, v150
	v_exp_f32_e32 v150, v150
	v_add_f32_e32 v146, 1.0, v146
	v_rcp_f32_e32 v151, v146
	v_lshlrev_b32_e32 v146, 16, v147
	v_and_b32_e32 v147, 0xffff0000, v147
	v_mul_f32_e32 v146, 0xbfb8aa3b, v146
	v_mul_f32_e32 v147, 0xbfb8aa3b, v147
	v_exp_f32_e32 v146, v146
	v_exp_f32_e32 v147, v147
	v_add_f32_e32 v150, 1.0, v150
	v_rcp_f32_e32 v150, v150
	v_add_f32_e32 v146, 1.0, v146
	v_add_f32_e32 v147, 1.0, v147
	v_rcp_f32_e32 v146, v146
	v_rcp_f32_e32 v147, v147
	v_pk_mul_f32 v[150:151], v[114:115], v[150:151]
	v_pk_mul_f32 v[152:153], v[116:117], v[146:147]
	v_lshlrev_b32_e32 v146, 16, v148
	v_and_b32_e32 v147, 0xffff0000, v148
	v_mul_f32_e32 v146, 0xbfb8aa3b, v146
	v_mul_f32_e32 v147, 0xbfb8aa3b, v147
	v_exp_f32_e32 v146, v146
	v_exp_f32_e32 v147, v147
	v_add_f32_e32 v146, 1.0, v146
	v_add_f32_e32 v147, 1.0, v147
	v_rcp_f32_e32 v146, v146
	v_rcp_f32_e32 v147, v147
	s_nop 0
	v_pk_mul_f32 v[154:155], v[110:111], v[146:147]
	v_lshlrev_b32_e32 v146, 16, v149
	v_and_b32_e32 v147, 0xffff0000, v149
	v_mul_f32_e32 v146, 0xbfb8aa3b, v146
	v_mul_f32_e32 v147, 0xbfb8aa3b, v147
	v_exp_f32_e32 v146, v146
	v_exp_f32_e32 v147, v147
	v_cvt_pk_bf16_f32 v148, v154, v155
	v_add_f32_e32 v146, 1.0, v146
	v_add_f32_e32 v147, 1.0, v147
	v_rcp_f32_e32 v146, v146
	v_rcp_f32_e32 v147, v147
	s_nop 0
	v_pk_mul_f32 v[156:157], v[112:113], v[146:147]
	v_cvt_pk_bf16_f32 v146, v150, v151
	v_mad_i64_i32 v[150:151], s[0:1], v197, s78, v[162:163]
	v_cvt_pk_bf16_f32 v147, v152, v153
	v_cvt_pk_bf16_f32 v149, v156, v157
	v_lshl_add_u64 v[150:151], v[150:151], 0, v[186:187]
	global_store_dwordx4 v[150:151], v[146:149], off
	s_nop 1
	v_lshlrev_b32_e32 v146, 16, v142
	v_and_b32_e32 v142, 0xffff0000, v142
	v_mul_f32_e32 v142, 0xbfb8aa3b, v142
	v_exp_f32_e32 v142, v142
	v_mul_f32_e32 v146, 0xbfb8aa3b, v146
	v_exp_f32_e32 v146, v146
	v_add_f32_e32 v142, 1.0, v142
	v_rcp_f32_e32 v147, v142
	v_lshlrev_b32_e32 v142, 16, v143
	v_and_b32_e32 v143, 0xffff0000, v143
	v_mul_f32_e32 v142, 0xbfb8aa3b, v142
	v_mul_f32_e32 v143, 0xbfb8aa3b, v143
	v_exp_f32_e32 v142, v142
	v_exp_f32_e32 v143, v143
	v_add_f32_e32 v146, 1.0, v146
	v_rcp_f32_e32 v146, v146
	v_add_f32_e32 v142, 1.0, v142
	v_add_f32_e32 v143, 1.0, v143
	v_rcp_f32_e32 v142, v142
	v_rcp_f32_e32 v143, v143
	v_pk_mul_f32 v[146:147], v[82:83], v[146:147]
	v_pk_mul_f32 v[148:149], v[84:85], v[142:143]
	v_lshlrev_b32_e32 v142, 16, v144
	v_and_b32_e32 v143, 0xffff0000, v144
	v_mul_f32_e32 v142, 0xbfb8aa3b, v142
	v_mul_f32_e32 v143, 0xbfb8aa3b, v143
	v_exp_f32_e32 v142, v142
	v_exp_f32_e32 v143, v143
	v_add_f32_e32 v142, 1.0, v142
	v_add_f32_e32 v143, 1.0, v143
	v_rcp_f32_e32 v142, v142
	v_rcp_f32_e32 v143, v143
	s_nop 0
	v_pk_mul_f32 v[152:153], v[78:79], v[142:143]
	v_lshlrev_b32_e32 v142, 16, v145
	v_and_b32_e32 v143, 0xffff0000, v145
	v_mul_f32_e32 v142, 0xbfb8aa3b, v142
	v_mul_f32_e32 v143, 0xbfb8aa3b, v143
	v_exp_f32_e32 v142, v142
	v_exp_f32_e32 v143, v143
	v_cvt_pk_bf16_f32 v144, v152, v153
	v_add_f32_e32 v142, 1.0, v142
	v_add_f32_e32 v143, 1.0, v143
	v_rcp_f32_e32 v142, v142
	v_rcp_f32_e32 v143, v143
	s_nop 0
	v_pk_mul_f32 v[154:155], v[80:81], v[142:143]
	v_cvt_pk_bf16_f32 v142, v146, v147
	v_cvt_pk_bf16_f32 v143, v148, v149
	v_cvt_pk_bf16_f32 v145, v154, v155
	global_store_dwordx4 v[150:151], v[142:145], off offset:256
	s_nop 1
	v_lshlrev_b32_e32 v142, 16, v138
	v_and_b32_e32 v138, 0xffff0000, v138
	v_mul_f32_e32 v138, 0xbfb8aa3b, v138
	v_exp_f32_e32 v138, v138
	v_mul_f32_e32 v142, 0xbfb8aa3b, v142
	v_exp_f32_e32 v142, v142
	v_add_f32_e32 v138, 1.0, v138
	v_rcp_f32_e32 v143, v138
	v_lshlrev_b32_e32 v138, 16, v139
	v_and_b32_e32 v139, 0xffff0000, v139
	v_mul_f32_e32 v138, 0xbfb8aa3b, v138
	v_mul_f32_e32 v139, 0xbfb8aa3b, v139
	v_exp_f32_e32 v138, v138
	v_exp_f32_e32 v139, v139
	v_add_f32_e32 v142, 1.0, v142
	v_rcp_f32_e32 v142, v142
	v_add_f32_e32 v138, 1.0, v138
	v_add_f32_e32 v139, 1.0, v139
	v_rcp_f32_e32 v138, v138
	v_rcp_f32_e32 v139, v139
	v_pk_mul_f32 v[142:143], v[106:107], v[142:143]
	v_pk_mul_f32 v[144:145], v[108:109], v[138:139]
	v_lshlrev_b32_e32 v138, 16, v140
	v_and_b32_e32 v139, 0xffff0000, v140
	v_mul_f32_e32 v138, 0xbfb8aa3b, v138
	v_mul_f32_e32 v139, 0xbfb8aa3b, v139
	v_exp_f32_e32 v138, v138
	v_exp_f32_e32 v139, v139
	v_add_f32_e32 v138, 1.0, v138
	v_add_f32_e32 v139, 1.0, v139
	v_rcp_f32_e32 v138, v138
	v_rcp_f32_e32 v139, v139
	s_nop 0
	v_pk_mul_f32 v[146:147], v[102:103], v[138:139]
	v_lshlrev_b32_e32 v138, 16, v141
	v_and_b32_e32 v139, 0xffff0000, v141
	v_mul_f32_e32 v138, 0xbfb8aa3b, v138
	v_mul_f32_e32 v139, 0xbfb8aa3b, v139
	v_exp_f32_e32 v138, v138
	v_exp_f32_e32 v139, v139
	v_cvt_pk_bf16_f32 v140, v146, v147
	v_add_f32_e32 v138, 1.0, v138
	v_add_f32_e32 v139, 1.0, v139
	v_rcp_f32_e32 v138, v138
	v_rcp_f32_e32 v139, v139
	s_nop 0
	v_pk_mul_f32 v[148:149], v[104:105], v[138:139]
	v_cvt_pk_bf16_f32 v138, v142, v143
	v_mad_i64_i32 v[142:143], s[0:1], v196, s78, v[162:163]
	v_cvt_pk_bf16_f32 v139, v144, v145
	v_cvt_pk_bf16_f32 v141, v148, v149
	v_lshl_add_u64 v[142:143], v[142:143], 0, v[186:187]
	global_store_dwordx4 v[142:143], v[138:141], off
	s_nop 1
	v_lshlrev_b32_e32 v138, 16, v134
	v_and_b32_e32 v134, 0xffff0000, v134
	v_mul_f32_e32 v134, 0xbfb8aa3b, v134
	v_exp_f32_e32 v134, v134
	v_mul_f32_e32 v138, 0xbfb8aa3b, v138
	v_exp_f32_e32 v138, v138
	v_add_f32_e32 v134, 1.0, v134
	v_rcp_f32_e32 v139, v134
	v_lshlrev_b32_e32 v134, 16, v135
	v_and_b32_e32 v135, 0xffff0000, v135
	v_mul_f32_e32 v134, 0xbfb8aa3b, v134
	v_mul_f32_e32 v135, 0xbfb8aa3b, v135
	v_exp_f32_e32 v134, v134
	v_exp_f32_e32 v135, v135
	v_add_f32_e32 v138, 1.0, v138
	v_rcp_f32_e32 v138, v138
	v_add_f32_e32 v134, 1.0, v134
	v_add_f32_e32 v135, 1.0, v135
	v_rcp_f32_e32 v134, v134
	v_rcp_f32_e32 v135, v135
	v_pk_mul_f32 v[138:139], v[74:75], v[138:139]
	v_pk_mul_f32 v[140:141], v[76:77], v[134:135]
	v_lshlrev_b32_e32 v134, 16, v136
	v_and_b32_e32 v135, 0xffff0000, v136
	v_mul_f32_e32 v134, 0xbfb8aa3b, v134
	v_mul_f32_e32 v135, 0xbfb8aa3b, v135
	v_exp_f32_e32 v134, v134
	v_exp_f32_e32 v135, v135
	v_add_f32_e32 v134, 1.0, v134
	v_add_f32_e32 v135, 1.0, v135
	v_rcp_f32_e32 v134, v134
	v_rcp_f32_e32 v135, v135
	s_nop 0
	v_pk_mul_f32 v[144:145], v[70:71], v[134:135]
	v_lshlrev_b32_e32 v134, 16, v137
	v_and_b32_e32 v135, 0xffff0000, v137
	v_mul_f32_e32 v134, 0xbfb8aa3b, v134
	v_mul_f32_e32 v135, 0xbfb8aa3b, v135
	v_exp_f32_e32 v134, v134
	v_exp_f32_e32 v135, v135
	v_cvt_pk_bf16_f32 v136, v144, v145
	v_add_f32_e32 v134, 1.0, v134
	v_add_f32_e32 v135, 1.0, v135
	v_rcp_f32_e32 v134, v134
	v_rcp_f32_e32 v135, v135
	s_nop 0
	v_pk_mul_f32 v[146:147], v[72:73], v[134:135]
	v_cvt_pk_bf16_f32 v134, v138, v139
	v_cvt_pk_bf16_f32 v135, v140, v141
	v_cvt_pk_bf16_f32 v137, v146, v147
	global_store_dwordx4 v[142:143], v[134:137], off offset:256
	s_nop 1
	v_mad_i64_i32 v[134:135], s[0:1], v195, s78, v[28:29]
	v_add_co_u32_e32 v134, vcc, s16, v134
	s_nop 1
	v_addc_co_u32_e32 v135, vcc, 0, v135, vcc
	global_load_dwordx4 v[200:203], v[134:135], off
	global_load_dwordx4 v[158:161], v[134:135], off offset:256
	v_mad_i64_i32 v[134:135], s[0:1], v194, s78, v[28:29]
	v_add_co_u32_e32 v134, vcc, s16, v134
	s_waitcnt vmcnt(0)
	v_lshlrev_b32_e32 v199, 16, v203
	v_addc_co_u32_e32 v135, vcc, 0, v135, vcc
	global_load_dwordx4 v[154:157], v[134:135], off
	global_load_dwordx4 v[150:153], v[134:135], off offset:256
	v_mul_f32_e32 v199, 0xbfb8aa3b, v199
	v_exp_f32_e32 v199, v199
	v_lshlrev_b32_e32 v168, 16, v201
	v_and_b32_e32 v169, 0xffff0000, v201
	v_lshlrev_b32_e32 v166, 16, v200
	v_add_f32_e32 v199, 1.0, v199
	v_and_b32_e32 v167, 0xffff0000, v200
	v_mul_f32_e32 v168, 0xbfb8aa3b, v168
	v_mul_f32_e32 v169, 0xbfb8aa3b, v169
	v_rcp_f32_e32 v200, v199
	v_and_b32_e32 v199, 0xffff0000, v203
	v_exp_f32_e32 v168, v168
	v_exp_f32_e32 v169, v169
	v_mul_f32_e32 v199, 0xbfb8aa3b, v199
	v_exp_f32_e32 v199, v199
	v_add_f32_e32 v168, 1.0, v168
	v_add_f32_e32 v169, 1.0, v169
	v_rcp_f32_e32 v168, v168
	v_rcp_f32_e32 v169, v169
	v_add_f32_e32 v199, 1.0, v199
	v_rcp_f32_e32 v201, v199
	v_lshlrev_b32_e32 v188, 16, v202
	v_pk_mul_f32 v[168:169], v[68:69], v[168:169]
	v_and_b32_e32 v189, 0xffff0000, v202
	v_pk_mul_f32 v[204:205], v[64:65], v[200:201]
	v_cvt_pk_bf16_f32 v201, v168, v169
	v_lshlrev_b32_e32 v168, 16, v158
	v_and_b32_e32 v158, 0xffff0000, v158
	v_mul_f32_e32 v158, 0xbfb8aa3b, v158
	v_exp_f32_e32 v158, v158
	v_mul_f32_e32 v188, 0xbfb8aa3b, v188
	v_mul_f32_e32 v189, 0xbfb8aa3b, v189
	v_exp_f32_e32 v188, v188
	v_add_f32_e32 v158, 1.0, v158
	v_rcp_f32_e32 v169, v158
	v_lshlrev_b32_e32 v158, 16, v159
	v_and_b32_e32 v159, 0xffff0000, v159
	v_exp_f32_e32 v189, v189
	v_mul_f32_e32 v158, 0xbfb8aa3b, v158
	v_mul_f32_e32 v159, 0xbfb8aa3b, v159
	v_exp_f32_e32 v158, v158
	v_exp_f32_e32 v159, v159
	v_add_f32_e32 v188, 1.0, v188
	v_add_f32_e32 v189, 1.0, v189
	v_rcp_f32_e32 v188, v188
	v_rcp_f32_e32 v189, v189
	v_add_f32_e32 v158, 1.0, v158
	v_add_f32_e32 v159, 1.0, v159
	v_rcp_f32_e32 v158, v158
	v_rcp_f32_e32 v159, v159
	v_mul_f32_e32 v166, 0xbfb8aa3b, v166
	v_mul_f32_e32 v167, 0xbfb8aa3b, v167
	v_exp_f32_e32 v166, v166
	v_exp_f32_e32 v167, v167
	v_pk_mul_f32 v[188:189], v[62:63], v[188:189]
	v_mad_i64_i32 v[134:135], s[0:1], v165, s78, v[28:29]
	v_cvt_pk_bf16_f32 v202, v188, v189
	v_pk_mul_f32 v[188:189], v[36:37], v[158:159]
	v_lshlrev_b32_e32 v158, 16, v160
	v_and_b32_e32 v159, 0xffff0000, v160
	v_mul_f32_e32 v158, 0xbfb8aa3b, v158
	v_mul_f32_e32 v159, 0xbfb8aa3b, v159
	v_exp_f32_e32 v158, v158
	v_exp_f32_e32 v159, v159
	v_add_f32_e32 v166, 1.0, v166
	v_add_f32_e32 v167, 1.0, v167
	v_rcp_f32_e32 v166, v166
	v_rcp_f32_e32 v167, v167
	v_add_co_u32_e32 v134, vcc, s16, v134
	v_add_f32_e32 v158, 1.0, v158
	v_add_f32_e32 v159, 1.0, v159
	v_addc_co_u32_e32 v135, vcc, 0, v135, vcc
	v_rcp_f32_e32 v158, v158
	v_rcp_f32_e32 v159, v159
	global_load_dwordx4 v[146:149], v[134:135], off
	global_load_dwordx4 v[142:145], v[134:135], off offset:256
	v_mad_i64_i32 v[134:135], s[0:1], v164, s78, v[28:29]
	v_pk_mul_f32 v[166:167], v[66:67], v[166:167]
	v_add_co_u32_e32 v134, vcc, s16, v134
	v_cvt_pk_bf16_f32 v200, v166, v167
	v_mad_i64_i32 v[166:167], s[0:1], v195, s78, v[162:163]
	v_addc_co_u32_e32 v135, vcc, 0, v135, vcc
	v_cvt_pk_bf16_f32 v203, v204, v205
	v_lshl_add_u64 v[166:167], v[166:167], 0, v[186:187]
	global_load_dwordx4 v[138:141], v[134:135], off
	s_nop 0
	global_load_dwordx4 v[134:137], v[134:135], off offset:256
	v_mul_f32_e32 v168, 0xbfb8aa3b, v168
	global_store_dwordx4 v[166:167], v[200:203], off
	v_exp_f32_e32 v168, v168
	s_nop 0
	v_pk_mul_f32 v[200:201], v[30:31], v[158:159]
	v_lshlrev_b32_e32 v158, 16, v161
	v_and_b32_e32 v159, 0xffff0000, v161
	v_mul_f32_e32 v158, 0xbfb8aa3b, v158
	v_mul_f32_e32 v159, 0xbfb8aa3b, v159
	v_exp_f32_e32 v158, v158
	v_exp_f32_e32 v159, v159
	v_add_f32_e32 v168, 1.0, v168
	v_rcp_f32_e32 v168, v168
	v_add_f32_e32 v158, 1.0, v158
	v_add_f32_e32 v159, 1.0, v159
	v_rcp_f32_e32 v158, v158
	v_rcp_f32_e32 v159, v159
	v_pk_mul_f32 v[168:169], v[34:35], v[168:169]
	v_cvt_pk_bf16_f32 v160, v200, v201
	v_pk_mul_f32 v[202:203], v[32:33], v[158:159]
	v_cvt_pk_bf16_f32 v158, v168, v169
	v_cvt_pk_bf16_f32 v159, v188, v189
	v_cvt_pk_bf16_f32 v161, v202, v203
	global_store_dwordx4 v[166:167], v[158:161], off offset:256
	s_waitcnt vmcnt(0)
	s_nop 0
	v_lshlrev_b32_e32 v158, 16, v154
	v_and_b32_e32 v154, 0xffff0000, v154
	v_mul_f32_e32 v154, 0xbfb8aa3b, v154
	v_exp_f32_e32 v154, v154
	v_mul_f32_e32 v158, 0xbfb8aa3b, v158
	v_exp_f32_e32 v158, v158
	v_add_f32_e32 v154, 1.0, v154
	v_rcp_f32_e32 v159, v154
	v_lshlrev_b32_e32 v154, 16, v155
	v_and_b32_e32 v155, 0xffff0000, v155
	v_mul_f32_e32 v154, 0xbfb8aa3b, v154
	v_mul_f32_e32 v155, 0xbfb8aa3b, v155
	v_exp_f32_e32 v154, v154
	v_exp_f32_e32 v155, v155
	v_add_f32_e32 v158, 1.0, v158
	v_rcp_f32_e32 v158, v158
	v_add_f32_e32 v154, 1.0, v154
	v_add_f32_e32 v155, 1.0, v155
	v_rcp_f32_e32 v154, v154
	v_rcp_f32_e32 v155, v155
	v_pk_mul_f32 v[158:159], v[58:59], v[158:159]
	v_pk_mul_f32 v[160:161], v[60:61], v[154:155]
	v_lshlrev_b32_e32 v154, 16, v156
	v_and_b32_e32 v155, 0xffff0000, v156
	v_mul_f32_e32 v154, 0xbfb8aa3b, v154
	v_mul_f32_e32 v155, 0xbfb8aa3b, v155
	v_exp_f32_e32 v154, v154
	v_exp_f32_e32 v155, v155
	v_add_f32_e32 v154, 1.0, v154
	v_add_f32_e32 v155, 1.0, v155
	v_rcp_f32_e32 v154, v154
	v_rcp_f32_e32 v155, v155
	s_nop 0
	v_pk_mul_f32 v[166:167], v[54:55], v[154:155]
	v_lshlrev_b32_e32 v154, 16, v157
	v_and_b32_e32 v155, 0xffff0000, v157
	v_mul_f32_e32 v154, 0xbfb8aa3b, v154
	v_mul_f32_e32 v155, 0xbfb8aa3b, v155
	v_exp_f32_e32 v154, v154
	v_exp_f32_e32 v155, v155
	v_cvt_pk_bf16_f32 v156, v166, v167
	v_add_f32_e32 v154, 1.0, v154
	v_add_f32_e32 v155, 1.0, v155
	v_rcp_f32_e32 v154, v154
	v_rcp_f32_e32 v155, v155
	s_nop 0
	v_pk_mul_f32 v[168:169], v[56:57], v[154:155]
	v_cvt_pk_bf16_f32 v154, v158, v159
	v_mad_i64_i32 v[158:159], s[0:1], v194, s78, v[162:163]
	v_cvt_pk_bf16_f32 v155, v160, v161
	v_cvt_pk_bf16_f32 v157, v168, v169
	v_lshl_add_u64 v[158:159], v[158:159], 0, v[186:187]
	global_store_dwordx4 v[158:159], v[154:157], off
	s_nop 1
	v_lshlrev_b32_e32 v154, 16, v150
	v_and_b32_e32 v150, 0xffff0000, v150
	v_mul_f32_e32 v150, 0xbfb8aa3b, v150
	v_exp_f32_e32 v150, v150
	v_mul_f32_e32 v154, 0xbfb8aa3b, v154
	v_exp_f32_e32 v154, v154
	v_add_f32_e32 v150, 1.0, v150
	v_rcp_f32_e32 v155, v150
	v_lshlrev_b32_e32 v150, 16, v151
	v_and_b32_e32 v151, 0xffff0000, v151
	v_mul_f32_e32 v150, 0xbfb8aa3b, v150
	v_mul_f32_e32 v151, 0xbfb8aa3b, v151
	v_exp_f32_e32 v150, v150
	v_exp_f32_e32 v151, v151
	v_add_f32_e32 v154, 1.0, v154
	v_rcp_f32_e32 v154, v154
	v_add_f32_e32 v150, 1.0, v150
	v_add_f32_e32 v151, 1.0, v151
	v_rcp_f32_e32 v150, v150
	v_rcp_f32_e32 v151, v151
	v_pk_mul_f32 v[154:155], v[22:23], v[154:155]
	v_pk_mul_f32 v[156:157], v[24:25], v[150:151]
	v_lshlrev_b32_e32 v150, 16, v152
	v_and_b32_e32 v151, 0xffff0000, v152
	v_mul_f32_e32 v150, 0xbfb8aa3b, v150
	v_mul_f32_e32 v151, 0xbfb8aa3b, v151
	v_exp_f32_e32 v150, v150
	v_exp_f32_e32 v151, v151
	v_add_f32_e32 v150, 1.0, v150
	v_add_f32_e32 v151, 1.0, v151
	v_rcp_f32_e32 v150, v150
	v_rcp_f32_e32 v151, v151
	s_nop 0
	v_pk_mul_f32 v[160:161], v[18:19], v[150:151]
	v_lshlrev_b32_e32 v150, 16, v153
	v_and_b32_e32 v151, 0xffff0000, v153
	v_mul_f32_e32 v150, 0xbfb8aa3b, v150
	v_mul_f32_e32 v151, 0xbfb8aa3b, v151
	v_exp_f32_e32 v150, v150
	v_exp_f32_e32 v151, v151
	v_cvt_pk_bf16_f32 v152, v160, v161
	v_add_f32_e32 v150, 1.0, v150
	v_add_f32_e32 v151, 1.0, v151
	v_rcp_f32_e32 v150, v150
	v_rcp_f32_e32 v151, v151
	s_nop 0
	v_pk_mul_f32 v[166:167], v[20:21], v[150:151]
	v_cvt_pk_bf16_f32 v150, v154, v155
	v_cvt_pk_bf16_f32 v151, v156, v157
	v_cvt_pk_bf16_f32 v153, v166, v167
	global_store_dwordx4 v[158:159], v[150:153], off offset:256
	s_nop 1
	v_lshlrev_b32_e32 v150, 16, v146
	v_and_b32_e32 v146, 0xffff0000, v146
	v_mul_f32_e32 v146, 0xbfb8aa3b, v146
	v_exp_f32_e32 v146, v146
	v_mul_f32_e32 v150, 0xbfb8aa3b, v150
	v_exp_f32_e32 v150, v150
	v_add_f32_e32 v146, 1.0, v146
	v_rcp_f32_e32 v151, v146
	v_lshlrev_b32_e32 v146, 16, v147
	v_and_b32_e32 v147, 0xffff0000, v147
	v_mul_f32_e32 v146, 0xbfb8aa3b, v146
	v_mul_f32_e32 v147, 0xbfb8aa3b, v147
	v_exp_f32_e32 v146, v146
	v_exp_f32_e32 v147, v147
	v_add_f32_e32 v150, 1.0, v150
	v_rcp_f32_e32 v150, v150
	v_add_f32_e32 v146, 1.0, v146
	v_add_f32_e32 v147, 1.0, v147
	v_rcp_f32_e32 v146, v146
	v_rcp_f32_e32 v147, v147
	v_pk_mul_f32 v[150:151], v[50:51], v[150:151]
	v_pk_mul_f32 v[152:153], v[52:53], v[146:147]
	v_lshlrev_b32_e32 v146, 16, v148
	v_and_b32_e32 v147, 0xffff0000, v148
	v_mul_f32_e32 v146, 0xbfb8aa3b, v146
	v_mul_f32_e32 v147, 0xbfb8aa3b, v147
	v_exp_f32_e32 v146, v146
	v_exp_f32_e32 v147, v147
	v_add_f32_e32 v146, 1.0, v146
	v_add_f32_e32 v147, 1.0, v147
	v_rcp_f32_e32 v146, v146
	v_rcp_f32_e32 v147, v147
	s_nop 0
	v_pk_mul_f32 v[154:155], v[46:47], v[146:147]
	v_lshlrev_b32_e32 v146, 16, v149
	v_and_b32_e32 v147, 0xffff0000, v149
	v_mul_f32_e32 v146, 0xbfb8aa3b, v146
	v_mul_f32_e32 v147, 0xbfb8aa3b, v147
	v_exp_f32_e32 v146, v146
	v_exp_f32_e32 v147, v147
	v_cvt_pk_bf16_f32 v148, v154, v155
	v_add_f32_e32 v146, 1.0, v146
	v_add_f32_e32 v147, 1.0, v147
	v_rcp_f32_e32 v146, v146
	v_rcp_f32_e32 v147, v147
	s_nop 0
	v_pk_mul_f32 v[156:157], v[48:49], v[146:147]
	v_cvt_pk_bf16_f32 v146, v150, v151
	v_mad_i64_i32 v[150:151], s[0:1], v165, s78, v[162:163]
	v_cvt_pk_bf16_f32 v147, v152, v153
	v_cvt_pk_bf16_f32 v149, v156, v157
	v_lshl_add_u64 v[150:151], v[150:151], 0, v[186:187]
	global_store_dwordx4 v[150:151], v[146:149], off
	s_nop 1
	v_lshlrev_b32_e32 v146, 16, v142
	v_and_b32_e32 v142, 0xffff0000, v142
	v_mul_f32_e32 v142, 0xbfb8aa3b, v142
	v_exp_f32_e32 v142, v142
	v_mul_f32_e32 v146, 0xbfb8aa3b, v146
	v_exp_f32_e32 v146, v146
	v_add_f32_e32 v142, 1.0, v142
	v_rcp_f32_e32 v147, v142
	v_lshlrev_b32_e32 v142, 16, v143
	v_and_b32_e32 v143, 0xffff0000, v143
	v_mul_f32_e32 v142, 0xbfb8aa3b, v142
	v_mul_f32_e32 v143, 0xbfb8aa3b, v143
	v_exp_f32_e32 v142, v142
	v_exp_f32_e32 v143, v143
	v_add_f32_e32 v146, 1.0, v146
	v_rcp_f32_e32 v146, v146
	v_add_f32_e32 v142, 1.0, v142
	v_add_f32_e32 v143, 1.0, v143
	v_rcp_f32_e32 v142, v142
	v_rcp_f32_e32 v143, v143
	v_pk_mul_f32 v[146:147], v[14:15], v[146:147]
	v_pk_mul_f32 v[148:149], v[16:17], v[142:143]
	v_lshlrev_b32_e32 v142, 16, v144
	v_and_b32_e32 v143, 0xffff0000, v144
	v_mul_f32_e32 v142, 0xbfb8aa3b, v142
	v_mul_f32_e32 v143, 0xbfb8aa3b, v143
	v_exp_f32_e32 v142, v142
	v_exp_f32_e32 v143, v143
	v_add_f32_e32 v142, 1.0, v142
	v_add_f32_e32 v143, 1.0, v143
	v_rcp_f32_e32 v142, v142
	v_rcp_f32_e32 v143, v143
	s_nop 0
	v_pk_mul_f32 v[152:153], v[10:11], v[142:143]
	v_lshlrev_b32_e32 v142, 16, v145
	v_and_b32_e32 v143, 0xffff0000, v145
	v_mul_f32_e32 v142, 0xbfb8aa3b, v142
	v_mul_f32_e32 v143, 0xbfb8aa3b, v143
	v_exp_f32_e32 v142, v142
	v_exp_f32_e32 v143, v143
	v_cvt_pk_bf16_f32 v144, v152, v153
	v_add_f32_e32 v142, 1.0, v142
	v_add_f32_e32 v143, 1.0, v143
	v_rcp_f32_e32 v142, v142
	v_rcp_f32_e32 v143, v143
	s_nop 0
	v_pk_mul_f32 v[154:155], v[12:13], v[142:143]
	v_cvt_pk_bf16_f32 v142, v146, v147
	v_cvt_pk_bf16_f32 v143, v148, v149
	v_cvt_pk_bf16_f32 v145, v154, v155
	global_store_dwordx4 v[150:151], v[142:145], off offset:256
	s_nop 1
	v_lshlrev_b32_e32 v142, 16, v138
	v_and_b32_e32 v138, 0xffff0000, v138
	v_mul_f32_e32 v138, 0xbfb8aa3b, v138
	v_exp_f32_e32 v138, v138
	v_mul_f32_e32 v142, 0xbfb8aa3b, v142
	v_exp_f32_e32 v142, v142
	v_add_f32_e32 v138, 1.0, v138
	v_rcp_f32_e32 v143, v138
	v_lshlrev_b32_e32 v138, 16, v139
	v_and_b32_e32 v139, 0xffff0000, v139
	v_mul_f32_e32 v138, 0xbfb8aa3b, v138
	v_mul_f32_e32 v139, 0xbfb8aa3b, v139
	v_exp_f32_e32 v138, v138
	v_exp_f32_e32 v139, v139
	v_add_f32_e32 v142, 1.0, v142
	v_rcp_f32_e32 v142, v142
	v_add_f32_e32 v138, 1.0, v138
	v_add_f32_e32 v139, 1.0, v139
	v_rcp_f32_e32 v138, v138
	v_rcp_f32_e32 v139, v139
	v_pk_mul_f32 v[142:143], v[42:43], v[142:143]
	v_pk_mul_f32 v[144:145], v[44:45], v[138:139]
	v_lshlrev_b32_e32 v138, 16, v140
	v_and_b32_e32 v139, 0xffff0000, v140
	v_mul_f32_e32 v138, 0xbfb8aa3b, v138
	v_mul_f32_e32 v139, 0xbfb8aa3b, v139
	v_exp_f32_e32 v138, v138
	v_exp_f32_e32 v139, v139
	v_add_f32_e32 v138, 1.0, v138
	v_add_f32_e32 v139, 1.0, v139
	v_rcp_f32_e32 v138, v138
	v_rcp_f32_e32 v139, v139
	s_nop 0
	v_pk_mul_f32 v[146:147], v[38:39], v[138:139]
	v_lshlrev_b32_e32 v138, 16, v141
	v_and_b32_e32 v139, 0xffff0000, v141
	v_mul_f32_e32 v138, 0xbfb8aa3b, v138
	v_mul_f32_e32 v139, 0xbfb8aa3b, v139
	v_exp_f32_e32 v138, v138
	v_exp_f32_e32 v139, v139
	v_cvt_pk_bf16_f32 v140, v146, v147
	v_add_f32_e32 v138, 1.0, v138
	v_add_f32_e32 v139, 1.0, v139
	v_rcp_f32_e32 v138, v138
	v_rcp_f32_e32 v139, v139
	s_nop 0
	v_pk_mul_f32 v[148:149], v[40:41], v[138:139]
	v_cvt_pk_bf16_f32 v138, v142, v143
	v_mad_i64_i32 v[142:143], s[0:1], v164, s78, v[162:163]
	v_cvt_pk_bf16_f32 v139, v144, v145
	v_cvt_pk_bf16_f32 v141, v148, v149
	v_lshl_add_u64 v[142:143], v[142:143], 0, v[186:187]
	global_store_dwordx4 v[142:143], v[138:141], off
	s_nop 1
	v_lshlrev_b32_e32 v138, 16, v134
	v_and_b32_e32 v134, 0xffff0000, v134
	v_mul_f32_e32 v134, 0xbfb8aa3b, v134
	v_exp_f32_e32 v134, v134
	v_mul_f32_e32 v138, 0xbfb8aa3b, v138
	v_exp_f32_e32 v138, v138
	v_add_f32_e32 v134, 1.0, v134
	v_rcp_f32_e32 v139, v134
	v_lshlrev_b32_e32 v134, 16, v135
	v_and_b32_e32 v135, 0xffff0000, v135
	v_mul_f32_e32 v134, 0xbfb8aa3b, v134
	v_mul_f32_e32 v135, 0xbfb8aa3b, v135
	v_exp_f32_e32 v134, v134
	v_exp_f32_e32 v135, v135
	v_add_f32_e32 v138, 1.0, v138
	v_rcp_f32_e32 v138, v138
	v_add_f32_e32 v134, 1.0, v134
	v_add_f32_e32 v135, 1.0, v135
	v_rcp_f32_e32 v134, v134
	v_rcp_f32_e32 v135, v135
	v_pk_mul_f32 v[138:139], v[6:7], v[138:139]
	v_pk_mul_f32 v[140:141], v[8:9], v[134:135]
	v_lshlrev_b32_e32 v134, 16, v136
	v_and_b32_e32 v135, 0xffff0000, v136
	v_mul_f32_e32 v134, 0xbfb8aa3b, v134
	v_mul_f32_e32 v135, 0xbfb8aa3b, v135
	v_exp_f32_e32 v134, v134
	v_exp_f32_e32 v135, v135
	v_add_f32_e32 v134, 1.0, v134
	v_add_f32_e32 v135, 1.0, v135
	v_rcp_f32_e32 v134, v134
	v_rcp_f32_e32 v135, v135
	s_nop 0
	v_pk_mul_f32 v[144:145], v[2:3], v[134:135]
	v_lshlrev_b32_e32 v134, 16, v137
	v_and_b32_e32 v135, 0xffff0000, v137
	v_mul_f32_e32 v134, 0xbfb8aa3b, v134
	v_mul_f32_e32 v135, 0xbfb8aa3b, v135
	v_exp_f32_e32 v134, v134
	v_exp_f32_e32 v135, v135
	v_cvt_pk_bf16_f32 v136, v144, v145
	v_add_f32_e32 v134, 1.0, v134
	v_add_f32_e32 v135, 1.0, v135
	v_rcp_f32_e32 v134, v134
	v_rcp_f32_e32 v135, v135
	s_nop 0
	v_pk_mul_f32 v[146:147], v[4:5], v[134:135]
	v_cvt_pk_bf16_f32 v134, v138, v139
	v_cvt_pk_bf16_f32 v135, v140, v141
	v_cvt_pk_bf16_f32 v137, v146, v147
	global_store_dwordx4 v[142:143], v[134:137], off offset:256
	s_cbranch_execnz .LBB0_891

.LBB0_965:
	s_add_u32 s36, s34, 0x100
	s_addc_u32 s37, s35, 0
	s_add_i32 s0, 0, 0x10000
	v_add_u32_e32 v144, s0, v222
	ds_read_b128 v[100:103], v144
	ds_read_b128 v[104:107], v144 offset:1024
	ds_read_b128 v[140:143], v144 offset:2048
	ds_read_b128 v[144:147], v144 offset:3072
	s_cmp_eq_u32 s31, 12
	s_cselect_b32 s47, s25, s37
	s_cselect_b32 s46, s24, s36
	s_cselect_b32 s43, s18, s29
	s_cselect_b32 s42, s19, s23
	v_lshl_add_u64 v[166:167], s[34:35], 0, v[174:175]
	s_add_i32 m0, s54, 0xc000
	ds_read_b128 v[148:151], v224
	ds_read_b128 v[152:155], v224 offset:1024
	ds_read_b128 v[178:181], v224 offset:2048
	ds_read_b128 v[182:185], v224 offset:3072
	ds_read_b128 v[186:189], v224 offset:4096
	ds_read_b128 v[190:193], v224 offset:5120
	ds_read_b128 v[194:197], v224 offset:6144
	ds_read_b128 v[198:201], v224 offset:7168
	global_load_lds_dwordx4 v[166:167], off
	v_lshl_add_u64 v[166:167], s[34:35], 0, v[176:177]
	s_add_i32 m0, s54, 0xe000
	s_nop 0
	global_load_lds_dwordx4 v[166:167], off
	s_waitcnt lgkmcnt(8)
	s_setprio 1
	s_barrier
	s_waitcnt lgkmcnt(0)
	v_mfma_f32_16x16x32_bf16 v[136:139], v[100:103], v[148:151], v[136:139]
	v_mfma_f32_16x16x32_bf16 v[132:135], v[140:143], v[148:151], v[132:135]
	v_mfma_f32_16x16x32_bf16 v[128:131], v[100:103], v[178:181], v[128:131]
	v_mfma_f32_16x16x32_bf16 v[124:127], v[140:143], v[178:181], v[124:127]
	v_mfma_f32_16x16x32_bf16 v[120:123], v[100:103], v[186:189], v[120:123]
	v_mfma_f32_16x16x32_bf16 v[116:119], v[140:143], v[186:189], v[116:119]
	v_mfma_f32_16x16x32_bf16 v[112:115], v[100:103], v[194:197], v[112:115]
	v_mfma_f32_16x16x32_bf16 v[108:111], v[140:143], v[194:197], v[108:111]
	v_mfma_f32_16x16x32_bf16 v[136:139], v[104:107], v[152:155], v[136:139]
	v_mfma_f32_16x16x32_bf16 v[132:135], v[144:147], v[152:155], v[132:135]
	v_mfma_f32_16x16x32_bf16 v[128:131], v[104:107], v[182:185], v[128:131]
	v_mfma_f32_16x16x32_bf16 v[124:127], v[144:147], v[182:185], v[124:127]
	v_mfma_f32_16x16x32_bf16 v[120:123], v[104:107], v[190:193], v[120:123]
	v_mfma_f32_16x16x32_bf16 v[116:119], v[144:147], v[190:193], v[116:119]
	v_mfma_f32_16x16x32_bf16 v[112:115], v[104:107], v[198:201], v[112:115]
	v_mfma_f32_16x16x32_bf16 v[108:111], v[144:147], v[198:201], v[108:111]
	s_barrier
	s_setprio 0
	s_add_i32 s34, 0, 0x14000
	v_add_u32_e32 v166, s34, v222
	s_add_i32 s0, s0, s53
	ds_read_b128 v[202:205], v166
	ds_read_b128 v[206:209], v166 offset:1024
	ds_read_b128 v[210:213], v166 offset:2048
	ds_read_b128 v[214:217], v166 offset:3072
	v_lshl_add_u64 v[166:167], s[42:43], 0, v[26:27]
	s_mov_b32 m0, s0
	v_lshl_add_u64 v[168:169], s[42:43], 0, v[160:161]
	global_load_lds_dwordx4 v[166:167], off
	s_add_i32 m0, s0, 0x2000
	s_nop 0
	global_load_lds_dwordx4 v[168:169], off
	s_setprio 1
	s_barrier
	s_waitcnt lgkmcnt(0)
	v_mfma_f32_16x16x32_bf16 v[64:67], v[202:205], v[148:151], v[64:67]
	v_mfma_f32_16x16x32_bf16 v[60:63], v[210:213], v[148:151], v[60:63]
	v_mfma_f32_16x16x32_bf16 v[56:59], v[202:205], v[178:181], v[56:59]
	v_mfma_f32_16x16x32_bf16 v[52:55], v[210:213], v[178:181], v[52:55]
	v_mfma_f32_16x16x32_bf16 v[48:51], v[202:205], v[186:189], v[48:51]
	v_mfma_f32_16x16x32_bf16 v[44:47], v[210:213], v[186:189], v[44:47]
	v_mfma_f32_16x16x32_bf16 v[40:43], v[202:205], v[194:197], v[40:43]
	v_mfma_f32_16x16x32_bf16 v[36:39], v[210:213], v[194:197], v[36:39]
	v_mfma_f32_16x16x32_bf16 v[64:67], v[206:209], v[152:155], v[64:67]
	v_mfma_f32_16x16x32_bf16 v[60:63], v[214:217], v[152:155], v[60:63]
	v_mfma_f32_16x16x32_bf16 v[56:59], v[206:209], v[182:185], v[56:59]
	v_mfma_f32_16x16x32_bf16 v[52:55], v[214:217], v[182:185], v[52:55]
	v_mfma_f32_16x16x32_bf16 v[48:51], v[206:209], v[190:193], v[48:51]
	v_mfma_f32_16x16x32_bf16 v[44:47], v[214:217], v[190:193], v[44:47]
	v_mfma_f32_16x16x32_bf16 v[40:43], v[206:209], v[198:201], v[40:43]
	v_mfma_f32_16x16x32_bf16 v[36:39], v[214:217], v[198:201], v[36:39]
	s_barrier
	s_setprio 0
	s_mov_b32 m0, s54
	v_lshl_add_u64 v[218:219], s[46:47], 0, v[156:157]
	ds_read_b128 v[148:151], v224 offset:16384
	ds_read_b128 v[152:155], v224 offset:17408
	ds_read_b128 v[178:181], v224 offset:18432
	ds_read_b128 v[182:185], v224 offset:19456
	ds_read_b128 v[186:189], v224 offset:20480
	ds_read_b128 v[190:193], v224 offset:21504
	ds_read_b128 v[194:197], v224 offset:22528
	ds_read_b128 v[198:201], v224 offset:23552
	global_load_lds_dwordx4 v[218:219], off
	v_lshl_add_u64 v[220:221], s[46:47], 0, v[158:159]
	s_mov_b32 m0, s55
	s_nop 0
	global_load_lds_dwordx4 v[220:221], off
	s_setprio 1
	s_barrier
	s_waitcnt lgkmcnt(0)
	v_mfma_f32_16x16x32_bf16 v[96:99], v[100:103], v[148:151], v[96:99]
	v_mfma_f32_16x16x32_bf16 v[92:95], v[140:143], v[148:151], v[92:95]
	v_mfma_f32_16x16x32_bf16 v[88:91], v[100:103], v[178:181], v[88:91]
	v_mfma_f32_16x16x32_bf16 v[84:87], v[140:143], v[178:181], v[84:87]
	v_mfma_f32_16x16x32_bf16 v[80:83], v[100:103], v[186:189], v[80:83]
	v_mfma_f32_16x16x32_bf16 v[76:79], v[140:143], v[186:189], v[76:79]
	v_mfma_f32_16x16x32_bf16 v[72:75], v[100:103], v[194:197], v[72:75]
	v_mfma_f32_16x16x32_bf16 v[68:71], v[140:143], v[194:197], v[68:71]
	v_mfma_f32_16x16x32_bf16 v[96:99], v[104:107], v[152:155], v[96:99]
	v_mfma_f32_16x16x32_bf16 v[92:95], v[144:147], v[152:155], v[92:95]
	v_mfma_f32_16x16x32_bf16 v[88:91], v[104:107], v[182:185], v[88:91]
	v_mfma_f32_16x16x32_bf16 v[84:87], v[144:147], v[182:185], v[84:87]
	v_mfma_f32_16x16x32_bf16 v[80:83], v[104:107], v[190:193], v[80:83]
	v_mfma_f32_16x16x32_bf16 v[76:79], v[144:147], v[190:193], v[76:79]
	v_mfma_f32_16x16x32_bf16 v[72:75], v[104:107], v[198:201], v[72:75]
	v_mfma_f32_16x16x32_bf16 v[68:71], v[144:147], v[198:201], v[68:71]
	s_barrier
	s_setprio 0
	s_add_u32 s0, s42, 0x40000
	s_addc_u32 s1, s43, 0
	s_add_i32 s34, s34, s53
	v_lshl_add_u64 v[100:101], s[0:1], 0, v[26:27]
	s_mov_b32 m0, s34
	s_nop 0
	global_load_lds_dwordx4 v[100:101], off
	v_lshl_add_u64 v[100:101], s[0:1], 0, v[160:161]
	s_add_i32 m0, s34, 0x2000
	s_nop 0
	global_load_lds_dwordx4 v[100:101], off
	s_waitcnt vmcnt(6)
	s_setprio 1
	s_barrier
	v_mfma_f32_16x16x32_bf16 v[32:35], v[202:205], v[148:151], v[32:35]
	v_mfma_f32_16x16x32_bf16 v[28:31], v[210:213], v[148:151], v[28:31]
	v_mfma_f32_16x16x32_bf16 v[22:25], v[202:205], v[178:181], v[22:25]
	v_mfma_f32_16x16x32_bf16 v[18:21], v[210:213], v[178:181], v[18:21]
	v_mfma_f32_16x16x32_bf16 v[14:17], v[202:205], v[186:189], v[14:17]
	v_mfma_f32_16x16x32_bf16 v[10:13], v[210:213], v[186:189], v[10:13]
	v_mfma_f32_16x16x32_bf16 v[6:9], v[202:205], v[194:197], v[6:9]
	v_mfma_f32_16x16x32_bf16 v[2:5], v[210:213], v[194:197], v[2:5]
	v_mfma_f32_16x16x32_bf16 v[32:35], v[206:209], v[152:155], v[32:35]
	v_mfma_f32_16x16x32_bf16 v[28:31], v[214:217], v[152:155], v[28:31]
	v_mfma_f32_16x16x32_bf16 v[22:25], v[206:209], v[182:185], v[22:25]
	v_mfma_f32_16x16x32_bf16 v[18:21], v[214:217], v[182:185], v[18:21]
	v_mfma_f32_16x16x32_bf16 v[14:17], v[206:209], v[190:193], v[14:17]
	v_mfma_f32_16x16x32_bf16 v[10:13], v[214:217], v[190:193], v[10:13]
	v_mfma_f32_16x16x32_bf16 v[6:9], v[206:209], v[198:201], v[6:9]
	v_mfma_f32_16x16x32_bf16 v[2:5], v[214:217], v[198:201], v[2:5]
	s_barrier
	s_setprio 0
	s_add_i32 s34, 0, 0x18000
	v_add_u32_e32 v144, s34, v222
	ds_read_b128 v[100:103], v144
	ds_read_b128 v[104:107], v144 offset:1024
	ds_read_b128 v[140:143], v144 offset:2048
	ds_read_b128 v[144:147], v144 offset:3072
	s_add_u32 s0, s46, 0x140000
	s_addc_u32 s1, s47, 0
	s_mov_b32 m0, s56
	v_lshl_add_u64 v[202:203], s[0:1], 0, v[156:157]
	ds_read_b128 v[148:151], v224 offset:32768
	ds_read_b128 v[152:155], v224 offset:33792
	ds_read_b128 v[178:181], v224 offset:34816
	ds_read_b128 v[182:185], v224 offset:35840
	ds_read_b128 v[186:189], v224 offset:36864
	ds_read_b128 v[190:193], v224 offset:37888
	ds_read_b128 v[194:197], v224 offset:38912
	ds_read_b128 v[198:201], v224 offset:39936
	global_load_lds_dwordx4 v[202:203], off
	v_lshl_add_u64 v[202:203], s[0:1], 0, v[158:159]
	s_mov_b32 m0, s57
	s_nop 0
	global_load_lds_dwordx4 v[202:203], off
	s_waitcnt lgkmcnt(8)
	s_setprio 1
	s_barrier
	s_waitcnt lgkmcnt(0)
	v_mfma_f32_16x16x32_bf16 v[136:139], v[100:103], v[148:151], v[136:139]
	v_mfma_f32_16x16x32_bf16 v[132:135], v[140:143], v[148:151], v[132:135]
	v_mfma_f32_16x16x32_bf16 v[128:131], v[100:103], v[178:181], v[128:131]
	v_mfma_f32_16x16x32_bf16 v[124:127], v[140:143], v[178:181], v[124:127]
	v_mfma_f32_16x16x32_bf16 v[120:123], v[100:103], v[186:189], v[120:123]
	v_mfma_f32_16x16x32_bf16 v[116:119], v[140:143], v[186:189], v[116:119]
	v_mfma_f32_16x16x32_bf16 v[112:115], v[100:103], v[194:197], v[112:115]
	v_mfma_f32_16x16x32_bf16 v[108:111], v[140:143], v[194:197], v[108:111]
	v_mfma_f32_16x16x32_bf16 v[136:139], v[104:107], v[152:155], v[136:139]
	v_mfma_f32_16x16x32_bf16 v[132:135], v[144:147], v[152:155], v[132:135]
	v_mfma_f32_16x16x32_bf16 v[128:131], v[104:107], v[182:185], v[128:131]
	v_mfma_f32_16x16x32_bf16 v[124:127], v[144:147], v[182:185], v[124:127]
	v_mfma_f32_16x16x32_bf16 v[120:123], v[104:107], v[190:193], v[120:123]
	v_mfma_f32_16x16x32_bf16 v[116:119], v[144:147], v[190:193], v[116:119]
	v_mfma_f32_16x16x32_bf16 v[112:115], v[104:107], v[198:201], v[112:115]
	v_mfma_f32_16x16x32_bf16 v[108:111], v[144:147], v[198:201], v[108:111]
	s_barrier
	s_setprio 0
	s_add_i32 s35, 0, 0x1c000
	s_add_i32 s0, s34, s53
	v_add_u32_e32 v214, s35, v222
	v_lshl_add_u64 v[166:167], v[166:167], 0, s[12:13]
	s_mov_b32 m0, s0
	ds_read_b128 v[202:205], v214
	ds_read_b128 v[206:209], v214 offset:1024
	ds_read_b128 v[210:213], v214 offset:2048
	ds_read_b128 v[214:217], v214 offset:3072
	global_load_lds_dwordx4 v[166:167], off
	v_lshl_add_u64 v[166:167], v[168:169], 0, s[12:13]
	s_add_i32 m0, s0, 0x2000
	s_nop 0
	global_load_lds_dwordx4 v[166:167], off
	s_setprio 1
	s_barrier
	s_waitcnt lgkmcnt(0)
	v_mfma_f32_16x16x32_bf16 v[64:67], v[202:205], v[148:151], v[64:67]
	v_mfma_f32_16x16x32_bf16 v[60:63], v[210:213], v[148:151], v[60:63]
	v_mfma_f32_16x16x32_bf16 v[56:59], v[202:205], v[178:181], v[56:59]
	v_mfma_f32_16x16x32_bf16 v[52:55], v[210:213], v[178:181], v[52:55]
	v_mfma_f32_16x16x32_bf16 v[48:51], v[202:205], v[186:189], v[48:51]
	v_mfma_f32_16x16x32_bf16 v[44:47], v[210:213], v[186:189], v[44:47]
	v_mfma_f32_16x16x32_bf16 v[40:43], v[202:205], v[194:197], v[40:43]
	v_mfma_f32_16x16x32_bf16 v[36:39], v[210:213], v[194:197], v[36:39]
	v_mfma_f32_16x16x32_bf16 v[64:67], v[206:209], v[152:155], v[64:67]
	v_mfma_f32_16x16x32_bf16 v[60:63], v[214:217], v[152:155], v[60:63]
	v_mfma_f32_16x16x32_bf16 v[56:59], v[206:209], v[182:185], v[56:59]
	v_mfma_f32_16x16x32_bf16 v[52:55], v[214:217], v[182:185], v[52:55]
	v_mfma_f32_16x16x32_bf16 v[48:51], v[206:209], v[190:193], v[48:51]
	v_mfma_f32_16x16x32_bf16 v[44:47], v[214:217], v[190:193], v[44:47]
	v_mfma_f32_16x16x32_bf16 v[40:43], v[206:209], v[198:201], v[40:43]
	v_mfma_f32_16x16x32_bf16 v[36:39], v[214:217], v[198:201], v[36:39]
	s_barrier
	s_setprio 0
	s_mov_b32 m0, s81
	v_lshl_add_u64 v[166:167], v[218:219], 0, s[12:13]
	ds_read_b128 v[148:151], v224 offset:49152
	ds_read_b128 v[152:155], v224 offset:50176
	ds_read_b128 v[178:181], v224 offset:51200
	ds_read_b128 v[182:185], v224 offset:52224
	ds_read_b128 v[186:189], v224 offset:53248
	ds_read_b128 v[190:193], v224 offset:54272
	ds_read_b128 v[194:197], v224 offset:55296
	ds_read_b128 v[198:201], v224 offset:56320
	global_load_lds_dwordx4 v[166:167], off
	v_lshl_add_u64 v[166:167], v[220:221], 0, s[12:13]
	s_mov_b32 m0, s17
	s_nop 0
	global_load_lds_dwordx4 v[166:167], off
	s_setprio 1
	s_barrier
	s_waitcnt lgkmcnt(0)
	v_mfma_f32_16x16x32_bf16 v[96:99], v[100:103], v[148:151], v[96:99]
	v_mfma_f32_16x16x32_bf16 v[92:95], v[140:143], v[148:151], v[92:95]
	v_mfma_f32_16x16x32_bf16 v[88:91], v[100:103], v[178:181], v[88:91]
	v_mfma_f32_16x16x32_bf16 v[84:87], v[140:143], v[178:181], v[84:87]
	v_mfma_f32_16x16x32_bf16 v[80:83], v[100:103], v[186:189], v[80:83]
	v_mfma_f32_16x16x32_bf16 v[76:79], v[140:143], v[186:189], v[76:79]
	v_mfma_f32_16x16x32_bf16 v[72:75], v[100:103], v[194:197], v[72:75]
	v_mfma_f32_16x16x32_bf16 v[68:71], v[140:143], v[194:197], v[68:71]
	v_mfma_f32_16x16x32_bf16 v[96:99], v[104:107], v[152:155], v[96:99]
	v_mfma_f32_16x16x32_bf16 v[92:95], v[144:147], v[152:155], v[92:95]
	v_mfma_f32_16x16x32_bf16 v[88:91], v[104:107], v[182:185], v[88:91]
	v_mfma_f32_16x16x32_bf16 v[84:87], v[144:147], v[182:185], v[84:87]
	v_mfma_f32_16x16x32_bf16 v[80:83], v[104:107], v[190:193], v[80:83]
	v_mfma_f32_16x16x32_bf16 v[76:79], v[144:147], v[190:193], v[76:79]
	v_mfma_f32_16x16x32_bf16 v[72:75], v[104:107], v[198:201], v[72:75]
	v_mfma_f32_16x16x32_bf16 v[68:71], v[144:147], v[198:201], v[68:71]
	s_barrier
	s_setprio 0
	s_add_u32 s0, s42, 0x40080
	s_addc_u32 s1, s43, 0
	s_add_i32 s34, s35, s53
	v_lshl_add_u64 v[100:101], s[0:1], 0, v[26:27]
	s_mov_b32 m0, s34
	s_nop 0
	global_load_lds_dwordx4 v[100:101], off
	v_lshl_add_u64 v[100:101], s[0:1], 0, v[160:161]
	s_add_i32 m0, s34, 0x2000
	s_nop 0
	global_load_lds_dwordx4 v[100:101], off
	s_waitcnt vmcnt(6)
	s_setprio 1
	s_barrier
	v_mfma_f32_16x16x32_bf16 v[32:35], v[202:205], v[148:151], v[32:35]
	v_mfma_f32_16x16x32_bf16 v[28:31], v[210:213], v[148:151], v[28:31]
	v_mfma_f32_16x16x32_bf16 v[22:25], v[202:205], v[178:181], v[22:25]
	v_mfma_f32_16x16x32_bf16 v[18:21], v[210:213], v[178:181], v[18:21]
	v_mfma_f32_16x16x32_bf16 v[14:17], v[202:205], v[186:189], v[14:17]
	v_mfma_f32_16x16x32_bf16 v[10:13], v[210:213], v[186:189], v[10:13]
	v_mfma_f32_16x16x32_bf16 v[6:9], v[202:205], v[194:197], v[6:9]
	v_mfma_f32_16x16x32_bf16 v[2:5], v[210:213], v[194:197], v[2:5]
	v_mfma_f32_16x16x32_bf16 v[32:35], v[206:209], v[152:155], v[32:35]
	v_mfma_f32_16x16x32_bf16 v[28:31], v[214:217], v[152:155], v[28:31]
	v_mfma_f32_16x16x32_bf16 v[22:25], v[206:209], v[182:185], v[22:25]
	v_mfma_f32_16x16x32_bf16 v[18:21], v[214:217], v[182:185], v[18:21]
	v_mfma_f32_16x16x32_bf16 v[14:17], v[206:209], v[190:193], v[14:17]
	v_mfma_f32_16x16x32_bf16 v[10:13], v[214:217], v[190:193], v[10:13]
	v_mfma_f32_16x16x32_bf16 v[6:9], v[206:209], v[198:201], v[6:9]
	v_mfma_f32_16x16x32_bf16 v[2:5], v[214:217], v[198:201], v[2:5]
	s_barrier
	s_setprio 0
	s_add_i32 s31, s31, 2
	s_add_u32 s23, s23, 0x100
	s_addc_u32 s29, s29, 0
	s_cmp_gt_u32 s31, 13
	s_mov_b64 s[34:35], s[36:37]
	s_cbranch_scc0 .LBB0_965
	s_min_i32 s0, s28, 0x100
	s_ashr_i32 s0, s0, 5
	s_ashr_i32 s1, s0, 31
	s_add_i32 s18, s28, 0xffffff00
	s_cmpk_lt_i32 s28, 0x100
	s_cselect_b32 s18, s28, s18
	s_cselect_b32 s23, 0, s59
	s_cselect_b32 s29, 0, s58
	s_ashr_i32 s19, s18, 31
	s_lshl_b64 s[18:19], s[18:19], 19
	v_lshl_or_b32 v148, s30, 8, v223
	s_add_u32 s30, s44, s29
	s_addc_u32 s31, s45, s23
	s_ashr_i32 s29, s28, 31
	v_lshl_add_u64 v[100:101], s[18:19], 0, v[162:163]
	s_lshl_b64 s[18:19], s[28:29], 19
	v_lshl_add_u64 v[152:153], v[164:165], 0, s[18:19]
	s_lshl_b64 s[28:29], s[28:29], 10
	s_mul_i32 s18, s0, 0x9000
	s_mul_hi_i32 s19, s0, 0x9000
	s_add_u32 s18, s68, s18
	s_addc_u32 s19, s69, s19
	s_lshl_b64 s[0:1], s[0:1], 12
	v_ashrrev_i32_e32 v149, 31, v148
	s_add_u32 s0, s72, s0
	v_lshlrev_b64 v[154:155], 2, v[148:149]
	s_addc_u32 s1, s73, s1
	v_lshl_add_u64 v[150:151], v[100:101], 0, v[148:149]
	v_lshl_add_u64 v[104:105], s[18:19], 0, v[154:155]
	v_lshlrev_b64 v[168:169], 1, v[148:149]
	v_lshl_add_u64 v[180:181], s[0:1], 0, v[154:155]
	v_lshl_add_u64 v[166:167], v[100:101], 1, s[30:31]
	global_load_dwordx4 v[140:143], v[104:105], off offset:16
	global_load_dwordx4 v[144:147], v[104:105], off
	global_load_dwordx4 v[100:103], v[104:105], off offset:528
	s_nop 0
	global_load_dwordx4 v[104:107], v[104:105], off offset:512
	v_lshl_add_u64 v[196:197], v[150:151], 1, s[30:31]
	v_lshl_add_u64 v[178:179], v[152:153], 0, v[168:169]
	global_load_dwordx4 v[148:151], v[180:181], off offset:16
	global_load_dwordx4 v[152:155], v[180:181], off
	global_load_dwordx4 v[190:193], v[196:197], off offset:2048
	v_add_co_u32_e32 v210, vcc, s65, v196
	s_mov_b32 s1, 0x20000
	s_nop 0
	v_addc_co_u32_e32 v211, vcc, 0, v197, vcc
	global_load_dwordx4 v[198:201], v[210:211], off offset:2048
	v_add_co_u32_e32 v184, vcc, s1, v196
	s_mov_b32 s18, 0x30000
	s_nop 0
	v_addc_co_u32_e32 v185, vcc, 0, v197, vcc
	global_load_dwordx4 v[202:205], v[184:185], off offset:2048
	v_add_co_u32_e32 v188, vcc, s18, v196
	v_lshl_add_u64 v[182:183], v[166:167], 0, v[168:169]
	s_nop 0
	v_addc_co_u32_e32 v189, vcc, 0, v197, vcc
	global_load_dwordx4 v[206:209], v[188:189], off offset:2048
	s_mov_b32 s0, 0x8000
	s_mov_b32 s19, 0x80000
	s_mov_b32 s23, 0x90000
	s_waitcnt vmcnt(0)
	v_lshlrev_b32_e32 v166, 16, v190
	v_and_b32_e32 v167, 0xffff0000, v190
	v_lshlrev_b32_e32 v168, 16, v191
	v_and_b32_e32 v169, 0xffff0000, v191
	v_lshlrev_b32_e32 v186, 16, v192
	v_and_b32_e32 v187, 0xffff0000, v192
	v_lshlrev_b32_e32 v190, 16, v193
	v_and_b32_e32 v191, 0xffff0000, v193
	v_pk_fma_f32 v[138:139], v[138:139], v[146:147], v[168:169]
	v_pk_fma_f32 v[136:137], v[136:137], v[144:145], v[166:167]
	v_pk_fma_f32 v[134:135], v[134:135], v[142:143], v[190:191]
	v_pk_fma_f32 v[132:133], v[132:133], v[140:141], v[186:187]
	v_cvt_pk_bf16_f32 v190, v136, v137
	v_cvt_pk_bf16_f32 v191, v138, v139
	v_cvt_pk_bf16_f32 v192, v132, v133
	v_cvt_pk_bf16_f32 v193, v134, v135
	v_lshlrev_b32_e32 v138, 16, v190
	v_and_b32_e32 v139, 0xffff0000, v190
	v_lshlrev_b32_e32 v136, 16, v191
	v_and_b32_e32 v137, 0xffff0000, v191
	v_lshlrev_b32_e32 v134, 16, v192
	v_and_b32_e32 v135, 0xffff0000, v192
	v_lshlrev_b32_e32 v132, 16, v193
	v_and_b32_e32 v133, 0xffff0000, v193
	v_lshlrev_b32_e32 v212, 16, v200
	v_and_b32_e32 v213, 0xffff0000, v200
	v_lshlrev_b32_e32 v200, 16, v201
	v_and_b32_e32 v201, 0xffff0000, v201
	global_store_dwordx4 v[182:183], v[190:193], off offset:2048
	v_pk_mul_f32 v[166:167], v[154:155], v[136:137]
	v_pk_mul_f32 v[168:169], v[152:153], v[138:139]
	v_pk_mul_f32 v[186:187], v[150:151], v[132:133]
	v_pk_mul_f32 v[192:193], v[148:149], v[134:135]
	v_lshlrev_b32_e32 v194, 16, v198
	v_and_b32_e32 v195, 0xffff0000, v198
	v_lshlrev_b32_e32 v198, 16, v199
	v_and_b32_e32 v199, 0xffff0000, v199
	v_cvt_pk_bf16_f32 v190, v168, v169
	v_cvt_pk_bf16_f32 v191, v166, v167
	v_cvt_pk_bf16_f32 v192, v192, v193
	v_cvt_pk_bf16_f32 v193, v186, v187
	v_pk_fma_f32 v[126:127], v[126:127], v[142:143], v[200:201]
	v_pk_fma_f32 v[124:125], v[124:125], v[140:141], v[212:213]
	global_store_dwordx4 v[178:179], v[190:193], off
	v_pk_fma_f32 v[130:131], v[130:131], v[146:147], v[198:199]
	v_pk_fma_f32 v[128:129], v[128:129], v[144:145], v[194:195]
	v_cvt_pk_bf16_f32 v192, v124, v125
	v_cvt_pk_bf16_f32 v193, v126, v127
	v_add_co_u32_e32 v186, vcc, s65, v182
	v_cvt_pk_bf16_f32 v190, v128, v129
	v_cvt_pk_bf16_f32 v191, v130, v131
	v_addc_co_u32_e32 v187, vcc, 0, v183, vcc
	v_lshlrev_b32_e32 v126, 16, v192
	v_and_b32_e32 v127, 0xffff0000, v192
	v_lshlrev_b32_e32 v124, 16, v193
	v_and_b32_e32 v125, 0xffff0000, v193
	global_store_dwordx4 v[186:187], v[190:193], off offset:2048
	v_lshlrev_b32_e32 v130, 16, v190
	v_and_b32_e32 v131, 0xffff0000, v190
	v_lshlrev_b32_e32 v128, 16, v191
	v_and_b32_e32 v129, 0xffff0000, v191
	v_pk_mul_f32 v[190:191], v[150:151], v[124:125]
	v_pk_mul_f32 v[194:195], v[148:149], v[126:127]
	v_pk_mul_f32 v[166:167], v[154:155], v[128:129]
	v_pk_mul_f32 v[168:169], v[152:153], v[130:131]
	v_cvt_pk_bf16_f32 v194, v194, v195
	v_cvt_pk_bf16_f32 v195, v190, v191
	v_add_co_u32_e32 v190, vcc, s0, v178
	v_cvt_pk_bf16_f32 v192, v168, v169
	v_cvt_pk_bf16_f32 v193, v166, v167
	v_addc_co_u32_e32 v191, vcc, 0, v179, vcc
	global_store_dwordx4 v[190:191], v[192:195], off
	v_lshlrev_b32_e32 v198, 16, v204
	v_and_b32_e32 v199, 0xffff0000, v204
	v_add_co_u32_e32 v192, vcc, s19, v196
	v_lshlrev_b32_e32 v200, 16, v205
	s_nop 0
	v_addc_co_u32_e32 v193, vcc, 0, v197, vcc
	v_add_co_u32_e32 v194, vcc, s23, v196
	v_and_b32_e32 v201, 0xffff0000, v205
	global_load_dwordx4 v[212:215], v[192:193], off offset:2048
	v_addc_co_u32_e32 v195, vcc, 0, v197, vcc
	v_lshlrev_b32_e32 v166, 16, v202
	v_and_b32_e32 v167, 0xffff0000, v202
	v_lshlrev_b32_e32 v168, 16, v203
	v_and_b32_e32 v169, 0xffff0000, v203
	v_pk_fma_f32 v[118:119], v[118:119], v[142:143], v[200:201]
	v_pk_fma_f32 v[116:117], v[116:117], v[140:141], v[198:199]
	v_pk_fma_f32 v[122:123], v[122:123], v[146:147], v[168:169]
	v_pk_fma_f32 v[120:121], v[120:121], v[144:145], v[166:167]
	v_cvt_pk_bf16_f32 v202, v116, v117
	v_cvt_pk_bf16_f32 v203, v118, v119
	v_add_co_u32_e32 v198, vcc, s1, v182
	global_load_dwordx4 v[216:219], v[194:195], off offset:2048
	v_cvt_pk_bf16_f32 v200, v120, v121
	v_cvt_pk_bf16_f32 v201, v122, v123
	v_addc_co_u32_e32 v199, vcc, 0, v183, vcc
	v_lshlrev_b32_e32 v118, 16, v202
	v_and_b32_e32 v119, 0xffff0000, v202
	v_lshlrev_b32_e32 v116, 16, v203
	v_and_b32_e32 v117, 0xffff0000, v203
	global_store_dwordx4 v[198:199], v[200:203], off offset:2048
	v_lshlrev_b32_e32 v122, 16, v200
	v_and_b32_e32 v123, 0xffff0000, v200
	v_lshlrev_b32_e32 v120, 16, v201
	v_and_b32_e32 v121, 0xffff0000, v201
	v_pk_mul_f32 v[200:201], v[150:151], v[116:117]
	v_pk_mul_f32 v[204:205], v[148:149], v[118:119]
	v_lshlrev_b32_e32 v234, 16, v208
	v_and_b32_e32 v235, 0xffff0000, v208
	v_lshlrev_b32_e32 v208, 16, v209
	v_and_b32_e32 v209, 0xffff0000, v209
	v_pk_mul_f32 v[166:167], v[154:155], v[120:121]
	v_pk_mul_f32 v[168:169], v[152:153], v[122:123]
	v_cvt_pk_bf16_f32 v204, v204, v205
	v_cvt_pk_bf16_f32 v205, v200, v201
	v_add_co_u32_e32 v200, vcc, s65, v178
	v_lshlrev_b32_e32 v220, 16, v206
	v_and_b32_e32 v221, 0xffff0000, v206
	v_lshlrev_b32_e32 v206, 16, v207
	v_and_b32_e32 v207, 0xffff0000, v207
	v_cvt_pk_bf16_f32 v202, v168, v169
	v_cvt_pk_bf16_f32 v203, v166, v167
	v_addc_co_u32_e32 v201, vcc, 0, v179, vcc
	v_pk_fma_f32 v[110:111], v[110:111], v[142:143], v[208:209]
	v_pk_fma_f32 v[108:109], v[108:109], v[140:141], v[234:235]
	global_store_dwordx4 v[200:201], v[202:205], off
	v_pk_fma_f32 v[114:115], v[114:115], v[146:147], v[206:207]
	v_pk_fma_f32 v[112:113], v[112:113], v[144:145], v[220:221]
	v_cvt_pk_bf16_f32 v206, v108, v109
	v_cvt_pk_bf16_f32 v207, v110, v111
	v_add_co_u32_e32 v202, vcc, s18, v182
	v_cvt_pk_bf16_f32 v204, v112, v113
	v_cvt_pk_bf16_f32 v205, v114, v115
	v_addc_co_u32_e32 v203, vcc, 0, v183, vcc
	v_lshlrev_b32_e32 v110, 16, v206
	v_and_b32_e32 v111, 0xffff0000, v206
	v_lshlrev_b32_e32 v108, 16, v207
	v_and_b32_e32 v109, 0xffff0000, v207
	global_store_dwordx4 v[202:203], v[204:207], off offset:2048
	v_lshlrev_b32_e32 v114, 16, v204
	v_and_b32_e32 v115, 0xffff0000, v204
	v_lshlrev_b32_e32 v112, 16, v205
	v_and_b32_e32 v113, 0xffff0000, v205
	v_pk_mul_f32 v[204:205], v[150:151], v[108:109]
	v_pk_mul_f32 v[208:209], v[148:149], v[110:111]
	s_mov_b32 s0, 0x18000
	v_pk_mul_f32 v[166:167], v[154:155], v[112:113]
	v_pk_mul_f32 v[168:169], v[152:153], v[114:115]
	v_cvt_pk_bf16_f32 v208, v208, v209
	v_cvt_pk_bf16_f32 v209, v204, v205
	v_add_co_u32_e32 v204, vcc, s0, v178
	v_cvt_pk_bf16_f32 v206, v168, v169
	v_cvt_pk_bf16_f32 v207, v166, v167
	v_addc_co_u32_e32 v205, vcc, 0, v179, vcc
	global_store_dwordx4 v[204:205], v[206:209], off
	s_mov_b32 s0, 0xb0000
	s_waitcnt vmcnt(0)
	v_lshlrev_b32_e32 v166, 16, v212
	v_add_co_u32_e32 v206, vcc, s76, v196
	v_and_b32_e32 v167, 0xffff0000, v212
	s_nop 0
	v_addc_co_u32_e32 v207, vcc, 0, v197, vcc
	global_load_dwordx4 v[238:241], v[206:207], off offset:2048
	v_add_co_u32_e32 v208, vcc, s0, v196
	v_lshlrev_b32_e32 v168, 16, v213
	s_nop 0
	v_addc_co_u32_e32 v209, vcc, 0, v197, vcc
	global_load_dwordx4 v[242:245], v[208:209], off offset:2048
	v_and_b32_e32 v169, 0xffff0000, v213
	v_lshlrev_b32_e32 v212, 16, v214
	v_and_b32_e32 v213, 0xffff0000, v214
	v_lshlrev_b32_e32 v214, 16, v215
	v_and_b32_e32 v215, 0xffff0000, v215
	v_pk_fma_f32 v[94:95], v[94:95], v[142:143], v[214:215]
	v_pk_fma_f32 v[92:93], v[92:93], v[140:141], v[212:213]
	v_lshlrev_b32_e32 v220, 16, v216
	v_and_b32_e32 v221, 0xffff0000, v216
	v_lshlrev_b32_e32 v234, 16, v217
	v_and_b32_e32 v235, 0xffff0000, v217
	v_pk_fma_f32 v[98:99], v[98:99], v[146:147], v[168:169]
	v_pk_fma_f32 v[96:97], v[96:97], v[144:145], v[166:167]
	v_cvt_pk_bf16_f32 v216, v92, v93
	v_cvt_pk_bf16_f32 v217, v94, v95
	v_add_co_u32_e32 v212, vcc, s19, v182
	v_cvt_pk_bf16_f32 v214, v96, v97
	v_cvt_pk_bf16_f32 v215, v98, v99
	v_addc_co_u32_e32 v213, vcc, 0, v183, vcc
	v_lshlrev_b32_e32 v94, 16, v216
	v_and_b32_e32 v95, 0xffff0000, v216
	v_lshlrev_b32_e32 v92, 16, v217
	v_and_b32_e32 v93, 0xffff0000, v217
	v_lshlrev_b32_e32 v246, 16, v218
	v_and_b32_e32 v247, 0xffff0000, v218
	v_lshlrev_b32_e32 v248, 16, v219
	v_and_b32_e32 v249, 0xffff0000, v219
	global_store_dwordx4 v[212:213], v[214:217], off offset:2048
	v_lshlrev_b32_e32 v98, 16, v214
	v_and_b32_e32 v99, 0xffff0000, v214
	v_lshlrev_b32_e32 v96, 16, v215
	v_and_b32_e32 v97, 0xffff0000, v215
	v_pk_mul_f32 v[214:215], v[150:151], v[92:93]
	v_pk_mul_f32 v[218:219], v[148:149], v[94:95]
	s_mov_b32 s1, 0x40000
	v_pk_mul_f32 v[166:167], v[154:155], v[96:97]
	v_pk_mul_f32 v[168:169], v[152:153], v[98:99]
	v_cvt_pk_bf16_f32 v218, v218, v219
	v_cvt_pk_bf16_f32 v219, v214, v215
	v_add_co_u32_e32 v214, vcc, s1, v178
	v_cvt_pk_bf16_f32 v216, v168, v169
	v_cvt_pk_bf16_f32 v217, v166, v167
	v_addc_co_u32_e32 v215, vcc, 0, v179, vcc
	v_pk_fma_f32 v[86:87], v[86:87], v[142:143], v[248:249]
	global_store_dwordx4 v[214:215], v[216:219], off
	v_pk_fma_f32 v[90:91], v[90:91], v[146:147], v[234:235]
	v_pk_fma_f32 v[88:89], v[88:89], v[144:145], v[220:221]
	v_pk_fma_f32 v[84:85], v[84:85], v[140:141], v[246:247]
	v_cvt_pk_bf16_f32 v221, v86, v87
	v_add_co_u32_e32 v216, vcc, s23, v182
	v_cvt_pk_bf16_f32 v218, v88, v89
	v_cvt_pk_bf16_f32 v219, v90, v91
	v_cvt_pk_bf16_f32 v220, v84, v85
	v_addc_co_u32_e32 v217, vcc, 0, v183, vcc
	v_lshlrev_b32_e32 v84, 16, v221
	v_and_b32_e32 v85, 0xffff0000, v221
	global_store_dwordx4 v[216:217], v[218:221], off offset:2048
	v_lshlrev_b32_e32 v90, 16, v218
	v_and_b32_e32 v91, 0xffff0000, v218
	v_lshlrev_b32_e32 v88, 16, v219
	v_and_b32_e32 v89, 0xffff0000, v219
	v_lshlrev_b32_e32 v86, 16, v220
	v_and_b32_e32 v87, 0xffff0000, v220
	v_pk_mul_f32 v[218:219], v[150:151], v[84:85]
	s_mov_b32 s1, 0x48000
	v_pk_mul_f32 v[166:167], v[154:155], v[88:89]
	v_pk_mul_f32 v[168:169], v[152:153], v[90:91]
	v_pk_mul_f32 v[220:221], v[148:149], v[86:87]
	v_cvt_pk_bf16_f32 v249, v218, v219
	v_add_co_u32_e32 v218, vcc, s1, v178
	v_cvt_pk_bf16_f32 v246, v168, v169
	v_cvt_pk_bf16_f32 v247, v166, v167
	v_cvt_pk_bf16_f32 v248, v220, v221
	v_addc_co_u32_e32 v219, vcc, 0, v179, vcc
	global_store_dwordx4 v[218:219], v[246:249], off
	global_load_dwordx4 v[246:249], v[196:197], off offset:2304
	s_nop 0
	global_load_dwordx4 v[250:253], v[210:211], off offset:2304
	s_waitcnt vmcnt(0)
	v_lshlrev_b32_e32 v196, 16, v240
	v_and_b32_e32 v197, 0xffff0000, v240
	v_lshlrev_b32_e32 v210, 16, v241
	v_and_b32_e32 v211, 0xffff0000, v241
	v_lshlrev_b32_e32 v166, 16, v238
	v_and_b32_e32 v167, 0xffff0000, v238
	v_lshlrev_b32_e32 v168, 16, v239
	v_and_b32_e32 v169, 0xffff0000, v239
	v_pk_fma_f32 v[78:79], v[78:79], v[142:143], v[210:211]
	v_pk_fma_f32 v[76:77], v[76:77], v[140:141], v[196:197]
	v_pk_fma_f32 v[82:83], v[82:83], v[146:147], v[168:169]
	v_pk_fma_f32 v[80:81], v[80:81], v[144:145], v[166:167]
	v_cvt_pk_bf16_f32 v240, v76, v77
	v_cvt_pk_bf16_f32 v241, v78, v79
	v_add_co_u32_e32 v196, vcc, s76, v182
	v_cvt_pk_bf16_f32 v238, v80, v81
	v_cvt_pk_bf16_f32 v239, v82, v83
	v_addc_co_u32_e32 v197, vcc, 0, v183, vcc
	v_lshlrev_b32_e32 v78, 16, v240
	v_and_b32_e32 v79, 0xffff0000, v240
	v_lshlrev_b32_e32 v76, 16, v241
	v_and_b32_e32 v77, 0xffff0000, v241
	global_store_dwordx4 v[196:197], v[238:241], off offset:2048
	v_pk_mul_f32 v[210:211], v[150:151], v[76:77]
	v_lshlrev_b32_e32 v220, 16, v242
	v_pk_mul_f32 v[240:241], v[148:149], v[78:79]
	v_and_b32_e32 v221, 0xffff0000, v242
	v_lshlrev_b32_e32 v234, 16, v243
	v_and_b32_e32 v235, 0xffff0000, v243
	v_lshlrev_b32_e32 v242, 16, v244
	v_and_b32_e32 v243, 0xffff0000, v244
	v_lshlrev_b32_e32 v244, 16, v245
	v_and_b32_e32 v245, 0xffff0000, v245
	v_cvt_pk_bf16_f32 v240, v240, v241
	v_cvt_pk_bf16_f32 v241, v210, v211
	v_add_co_u32_e32 v210, vcc, s77, v178
	v_lshlrev_b32_e32 v82, 16, v238
	v_and_b32_e32 v83, 0xffff0000, v238
	v_lshlrev_b32_e32 v80, 16, v239
	v_and_b32_e32 v81, 0xffff0000, v239
	v_addc_co_u32_e32 v211, vcc, 0, v179, vcc
	v_pk_fma_f32 v[74:75], v[74:75], v[146:147], v[234:235]
	v_pk_fma_f32 v[72:73], v[72:73], v[144:145], v[220:221]
	v_pk_fma_f32 v[142:143], v[70:71], v[142:143], v[244:245]
	v_pk_fma_f32 v[70:71], v[68:69], v[140:141], v[242:243]
	v_pk_mul_f32 v[166:167], v[154:155], v[80:81]
	v_pk_mul_f32 v[168:169], v[152:153], v[82:83]
	v_cvt_pk_bf16_f32 v68, v72, v73
	v_cvt_pk_bf16_f32 v69, v74, v75
	v_cvt_pk_bf16_f32 v70, v70, v71
	v_cvt_pk_bf16_f32 v71, v142, v143
	v_add_co_u32_e32 v220, vcc, s0, v182
	v_cvt_pk_bf16_f32 v238, v168, v169
	v_cvt_pk_bf16_f32 v239, v166, v167
	v_addc_co_u32_e32 v221, vcc, 0, v183, vcc
	v_lshlrev_b32_e32 v146, 16, v68
	v_and_b32_e32 v147, 0xffff0000, v68
	v_lshlrev_b32_e32 v144, 16, v69
	v_and_b32_e32 v145, 0xffff0000, v69
	v_lshlrev_b32_e32 v142, 16, v70
	v_and_b32_e32 v143, 0xffff0000, v70
	v_lshlrev_b32_e32 v140, 16, v71
	v_and_b32_e32 v141, 0xffff0000, v71
	s_mov_b32 s0, 0x58000
	global_store_dwordx4 v[210:211], v[238:241], off
	global_store_dwordx4 v[220:221], v[68:71], off offset:2048
	v_pk_mul_f32 v[72:73], v[150:151], v[140:141]
	v_pk_mul_f32 v[74:75], v[148:149], v[142:143]
	v_pk_mul_f32 v[70:71], v[154:155], v[144:145]
	v_pk_mul_f32 v[68:69], v[152:153], v[146:147]
	v_add_co_u32_e32 v148, vcc, s0, v178
	v_cvt_pk_bf16_f32 v68, v68, v69
	v_cvt_pk_bf16_f32 v69, v70, v71
	v_cvt_pk_bf16_f32 v70, v74, v75
	v_cvt_pk_bf16_f32 v71, v72, v73
	v_addc_co_u32_e32 v149, vcc, 0, v179, vcc
	global_store_dwordx4 v[148:149], v[68:71], off
	global_load_dwordx4 v[150:153], v[184:185], off offset:2304
	global_load_dwordx4 v[238:241], v[188:189], off offset:2304
	s_nop 0
	global_load_dwordx4 v[68:71], v[180:181], off offset:528
	global_load_dwordx4 v[72:75], v[180:181], off offset:512
	v_lshlrev_b32_e32 v154, 16, v246
	v_and_b32_e32 v155, 0xffff0000, v246
	v_lshlrev_b32_e32 v166, 16, v247
	v_and_b32_e32 v167, 0xffff0000, v247
	v_lshlrev_b32_e32 v168, 16, v248
	v_and_b32_e32 v169, 0xffff0000, v248
	v_lshlrev_b32_e32 v180, 16, v249
	v_and_b32_e32 v181, 0xffff0000, v249
	v_pk_fma_f32 v[66:67], v[66:67], v[106:107], v[166:167]
	v_pk_fma_f32 v[64:65], v[64:65], v[104:105], v[154:155]
	v_pk_fma_f32 v[62:63], v[62:63], v[102:103], v[180:181]
	v_pk_fma_f32 v[60:61], v[60:61], v[100:101], v[168:169]
	v_cvt_pk_bf16_f32 v242, v64, v65
	v_cvt_pk_bf16_f32 v243, v66, v67
	v_cvt_pk_bf16_f32 v244, v60, v61
	v_cvt_pk_bf16_f32 v245, v62, v63
	v_lshlrev_b32_e32 v66, 16, v242
	v_and_b32_e32 v67, 0xffff0000, v242
	v_lshlrev_b32_e32 v64, 16, v243
	v_and_b32_e32 v65, 0xffff0000, v243
	v_lshlrev_b32_e32 v62, 16, v244
	v_and_b32_e32 v63, 0xffff0000, v244
	v_lshlrev_b32_e32 v60, 16, v245
	v_and_b32_e32 v61, 0xffff0000, v245
	v_lshlrev_b32_e32 v184, 16, v250
	v_and_b32_e32 v185, 0xffff0000, v250
	v_lshlrev_b32_e32 v188, 16, v251
	v_and_b32_e32 v189, 0xffff0000, v251
	v_lshlrev_b32_e32 v234, 16, v252
	v_and_b32_e32 v235, 0xffff0000, v252
	v_lshlrev_b32_e32 v246, 16, v253
	v_and_b32_e32 v247, 0xffff0000, v253
	global_store_dwordx4 v[182:183], v[242:245], off offset:2304
	v_pk_fma_f32 v[58:59], v[58:59], v[106:107], v[188:189]
	v_pk_fma_f32 v[56:57], v[56:57], v[104:105], v[184:185]
	v_pk_fma_f32 v[54:55], v[54:55], v[102:103], v[246:247]
	v_pk_fma_f32 v[52:53], v[52:53], v[100:101], v[234:235]
	s_waitcnt vmcnt(0)
	v_lshlrev_b32_e32 v188, 16, v240
	v_pk_mul_f32 v[168:169], v[70:71], v[60:61]
	v_pk_mul_f32 v[154:155], v[74:75], v[64:65]
	v_pk_mul_f32 v[166:167], v[72:73], v[66:67]
	v_pk_mul_f32 v[182:183], v[68:69], v[62:63]
	v_cvt_pk_bf16_f32 v180, v166, v167
	v_cvt_pk_bf16_f32 v181, v154, v155
	v_cvt_pk_bf16_f32 v182, v182, v183
	v_cvt_pk_bf16_f32 v183, v168, v169
	global_store_dwordx4 v[178:179], v[180:183], off offset:256
	v_cvt_pk_bf16_f32 v178, v56, v57
	v_cvt_pk_bf16_f32 v179, v58, v59
	v_cvt_pk_bf16_f32 v180, v52, v53
	v_cvt_pk_bf16_f32 v181, v54, v55
	v_lshlrev_b32_e32 v58, 16, v178
	v_and_b32_e32 v59, 0xffff0000, v178
	v_lshlrev_b32_e32 v56, 16, v179
	v_and_b32_e32 v57, 0xffff0000, v179
	v_lshlrev_b32_e32 v54, 16, v180
	v_and_b32_e32 v55, 0xffff0000, v180
	v_lshlrev_b32_e32 v52, 16, v181
	v_and_b32_e32 v53, 0xffff0000, v181
	global_store_dwordx4 v[186:187], v[178:181], off offset:2304
	v_pk_mul_f32 v[154:155], v[74:75], v[56:57]
	v_pk_mul_f32 v[166:167], v[72:73], v[58:59]
	v_pk_mul_f32 v[168:169], v[70:71], v[52:53]
	v_pk_mul_f32 v[180:181], v[68:69], v[54:55]
	v_cvt_pk_bf16_f32 v178, v166, v167
	v_cvt_pk_bf16_f32 v179, v154, v155
	v_cvt_pk_bf16_f32 v180, v180, v181
	v_cvt_pk_bf16_f32 v181, v168, v169
	v_lshlrev_b32_e32 v154, 16, v150
	v_and_b32_e32 v155, 0xffff0000, v150
	v_lshlrev_b32_e32 v150, 16, v151
	v_and_b32_e32 v151, 0xffff0000, v151
	v_lshlrev_b32_e32 v166, 16, v152
	v_and_b32_e32 v167, 0xffff0000, v152
	v_lshlrev_b32_e32 v152, 16, v153
	v_and_b32_e32 v153, 0xffff0000, v153
	global_store_dwordx4 v[190:191], v[178:181], off offset:256
	v_pk_fma_f32 v[50:51], v[50:51], v[106:107], v[150:151]
	v_pk_fma_f32 v[48:49], v[48:49], v[104:105], v[154:155]
	v_pk_fma_f32 v[46:47], v[46:47], v[102:103], v[152:153]
	v_pk_fma_f32 v[44:45], v[44:45], v[100:101], v[166:167]
	global_load_dwordx4 v[178:181], v[192:193], off offset:2304
	global_load_dwordx4 v[182:185], v[194:195], off offset:2304
	v_cvt_pk_bf16_f32 v150, v48, v49
	v_cvt_pk_bf16_f32 v151, v50, v51
	v_cvt_pk_bf16_f32 v152, v44, v45
	v_cvt_pk_bf16_f32 v153, v46, v47
	v_lshlrev_b32_e32 v50, 16, v150
	v_and_b32_e32 v51, 0xffff0000, v150
	v_lshlrev_b32_e32 v48, 16, v151
	v_and_b32_e32 v49, 0xffff0000, v151
	v_lshlrev_b32_e32 v46, 16, v152
	v_and_b32_e32 v47, 0xffff0000, v152
	v_lshlrev_b32_e32 v44, 16, v153
	v_and_b32_e32 v45, 0xffff0000, v153
	v_lshlrev_b32_e32 v168, 16, v238
	v_and_b32_e32 v169, 0xffff0000, v238
	v_lshlrev_b32_e32 v186, 16, v239
	v_and_b32_e32 v187, 0xffff0000, v239
	v_and_b32_e32 v189, 0xffff0000, v240
	v_lshlrev_b32_e32 v190, 16, v241
	v_and_b32_e32 v191, 0xffff0000, v241
	global_store_dwordx4 v[198:199], v[150:153], off offset:2304
	v_pk_mul_f32 v[154:155], v[70:71], v[44:45]
	v_pk_mul_f32 v[166:167], v[68:69], v[46:47]
	v_pk_mul_f32 v[152:153], v[74:75], v[48:49]
	v_pk_mul_f32 v[150:151], v[72:73], v[50:51]
	v_pk_fma_f32 v[42:43], v[42:43], v[106:107], v[186:187]
	v_cvt_pk_bf16_f32 v150, v150, v151
	v_cvt_pk_bf16_f32 v151, v152, v153
	v_cvt_pk_bf16_f32 v152, v166, v167
	v_cvt_pk_bf16_f32 v153, v154, v155
	v_pk_fma_f32 v[40:41], v[40:41], v[104:105], v[168:169]
	v_pk_fma_f32 v[38:39], v[38:39], v[102:103], v[190:191]
	v_pk_fma_f32 v[36:37], v[36:37], v[100:101], v[188:189]
	global_store_dwordx4 v[200:201], v[150:153], off offset:256
	v_mul_f32_e32 v67, v67, v67
	v_mul_f32_e32 v65, v65, v65
	v_cvt_pk_bf16_f32 v150, v40, v41
	v_cvt_pk_bf16_f32 v151, v42, v43
	v_cvt_pk_bf16_f32 v152, v36, v37
	v_cvt_pk_bf16_f32 v153, v38, v39
	v_lshlrev_b32_e32 v42, 16, v150
	v_and_b32_e32 v43, 0xffff0000, v150
	v_lshlrev_b32_e32 v40, 16, v151
	v_and_b32_e32 v41, 0xffff0000, v151
	v_lshlrev_b32_e32 v38, 16, v152
	v_and_b32_e32 v39, 0xffff0000, v152
	v_lshlrev_b32_e32 v36, 16, v153
	v_and_b32_e32 v37, 0xffff0000, v153
	global_store_dwordx4 v[202:203], v[150:153], off offset:2304
	v_pk_mul_f32 v[154:155], v[70:71], v[36:37]
	v_pk_mul_f32 v[166:167], v[68:69], v[38:39]
	v_pk_mul_f32 v[152:153], v[74:75], v[40:41]
	v_pk_mul_f32 v[150:151], v[72:73], v[42:43]
	v_fmac_f32_e32 v67, v66, v66
	v_cvt_pk_bf16_f32 v150, v150, v151
	v_cvt_pk_bf16_f32 v151, v152, v153
	v_cvt_pk_bf16_f32 v152, v166, v167
	v_cvt_pk_bf16_f32 v153, v154, v155
	global_store_dwordx4 v[204:205], v[150:153], off offset:256
	global_load_dwordx4 v[150:153], v[206:207], off offset:2304
	s_nop 0
	global_load_dwordx4 v[186:189], v[208:209], off offset:2304
	v_fmac_f32_e32 v65, v64, v64
	v_mul_f32_e32 v63, v63, v63
	v_mul_f32_e32 v61, v61, v61
	v_add_f32_e32 v64, v67, v65
	v_fmac_f32_e32 v63, v62, v62
	v_fmac_f32_e32 v61, v60, v60
	v_add_f32_e32 v60, v63, v61
	s_waitcnt vmcnt(0)
	v_lshlrev_b32_e32 v154, 16, v178
	v_and_b32_e32 v155, 0xffff0000, v178
	v_lshlrev_b32_e32 v166, 16, v179
	v_and_b32_e32 v167, 0xffff0000, v179
	v_lshlrev_b32_e32 v168, 16, v180
	v_and_b32_e32 v169, 0xffff0000, v180
	v_lshlrev_b32_e32 v178, 16, v181
	v_and_b32_e32 v179, 0xffff0000, v181
	v_pk_fma_f32 v[34:35], v[34:35], v[106:107], v[166:167]
	v_pk_fma_f32 v[32:33], v[32:33], v[104:105], v[154:155]
	v_pk_fma_f32 v[30:31], v[30:31], v[102:103], v[178:179]
	v_pk_fma_f32 v[28:29], v[28:29], v[100:101], v[168:169]
	v_cvt_pk_bf16_f32 v178, v32, v33
	v_cvt_pk_bf16_f32 v179, v34, v35
	v_cvt_pk_bf16_f32 v180, v28, v29
	v_cvt_pk_bf16_f32 v181, v30, v31
	v_lshlrev_b32_e32 v34, 16, v178
	v_and_b32_e32 v35, 0xffff0000, v178
	v_lshlrev_b32_e32 v32, 16, v179
	v_and_b32_e32 v33, 0xffff0000, v179
	v_lshlrev_b32_e32 v30, 16, v180
	v_and_b32_e32 v31, 0xffff0000, v180
	v_lshlrev_b32_e32 v28, 16, v181
	v_and_b32_e32 v29, 0xffff0000, v181
	v_lshlrev_b32_e32 v190, 16, v182
	v_and_b32_e32 v191, 0xffff0000, v182
	v_lshlrev_b32_e32 v182, 16, v183
	v_and_b32_e32 v183, 0xffff0000, v183
	global_store_dwordx4 v[212:213], v[178:181], off offset:2304
	v_pk_mul_f32 v[154:155], v[74:75], v[32:33]
	v_pk_mul_f32 v[166:167], v[72:73], v[34:35]
	v_pk_mul_f32 v[168:169], v[70:71], v[28:29]
	v_pk_mul_f32 v[180:181], v[68:69], v[30:31]
	v_lshlrev_b32_e32 v192, 16, v184
	v_and_b32_e32 v193, 0xffff0000, v184
	v_lshlrev_b32_e32 v184, 16, v185
	v_and_b32_e32 v185, 0xffff0000, v185
	v_cvt_pk_bf16_f32 v178, v166, v167
	v_cvt_pk_bf16_f32 v179, v154, v155
	v_cvt_pk_bf16_f32 v180, v180, v181
	v_cvt_pk_bf16_f32 v181, v168, v169
	v_pk_fma_f32 v[24:25], v[24:25], v[106:107], v[182:183]
	v_pk_fma_f32 v[22:23], v[22:23], v[104:105], v[190:191]
	global_store_dwordx4 v[214:215], v[178:181], off offset:256
	v_pk_fma_f32 v[20:21], v[20:21], v[102:103], v[184:185]
	v_pk_fma_f32 v[18:19], v[18:19], v[100:101], v[192:193]
	v_cvt_pk_bf16_f32 v178, v22, v23
	v_cvt_pk_bf16_f32 v179, v24, v25
	v_cvt_pk_bf16_f32 v180, v18, v19
	v_cvt_pk_bf16_f32 v181, v20, v21
	v_lshlrev_b32_e32 v24, 16, v178
	v_and_b32_e32 v25, 0xffff0000, v178
	v_lshlrev_b32_e32 v22, 16, v179
	v_and_b32_e32 v23, 0xffff0000, v179
	v_lshlrev_b32_e32 v20, 16, v180
	v_and_b32_e32 v21, 0xffff0000, v180
	v_lshlrev_b32_e32 v18, 16, v181
	v_and_b32_e32 v19, 0xffff0000, v181
	v_pk_mul_f32 v[154:155], v[74:75], v[22:23]
	v_pk_mul_f32 v[166:167], v[72:73], v[24:25]
	global_store_dwordx4 v[216:217], v[178:181], off offset:2304
	v_pk_mul_f32 v[168:169], v[70:71], v[18:19]
	v_lshlrev_b32_e32 v182, 16, v189
	v_pk_mul_f32 v[180:181], v[68:69], v[20:21]
	v_cvt_pk_bf16_f32 v178, v166, v167
	v_cvt_pk_bf16_f32 v179, v154, v155
	v_lshlrev_b32_e32 v154, 16, v150
	v_and_b32_e32 v155, 0xffff0000, v150
	v_lshlrev_b32_e32 v150, 16, v151
	v_and_b32_e32 v151, 0xffff0000, v151
	v_lshlrev_b32_e32 v166, 16, v152
	v_and_b32_e32 v167, 0xffff0000, v152
	v_lshlrev_b32_e32 v152, 16, v153
	v_and_b32_e32 v153, 0xffff0000, v153
	v_cvt_pk_bf16_f32 v180, v180, v181
	v_cvt_pk_bf16_f32 v181, v168, v169
	v_pk_fma_f32 v[16:17], v[16:17], v[106:107], v[150:151]
	v_pk_fma_f32 v[14:15], v[14:15], v[104:105], v[154:155]
	v_pk_fma_f32 v[12:13], v[12:13], v[102:103], v[152:153]
	v_pk_fma_f32 v[10:11], v[10:11], v[100:101], v[166:167]
	global_store_dwordx4 v[218:219], v[178:181], off offset:256
	v_lshlrev_b32_e32 v168, 16, v186
	v_and_b32_e32 v169, 0xffff0000, v186
	v_lshlrev_b32_e32 v178, 16, v187
	v_and_b32_e32 v179, 0xffff0000, v187
	v_lshlrev_b32_e32 v180, 16, v188
	v_and_b32_e32 v181, 0xffff0000, v188
	v_and_b32_e32 v183, 0xffff0000, v189
	v_cvt_pk_bf16_f32 v150, v14, v15
	v_cvt_pk_bf16_f32 v151, v16, v17
	v_cvt_pk_bf16_f32 v152, v10, v11
	v_cvt_pk_bf16_f32 v153, v12, v13
	v_lshlrev_b32_e32 v16, 16, v150
	v_and_b32_e32 v17, 0xffff0000, v150
	v_lshlrev_b32_e32 v14, 16, v151
	v_and_b32_e32 v15, 0xffff0000, v151
	v_lshlrev_b32_e32 v12, 16, v152
	v_and_b32_e32 v13, 0xffff0000, v152
	v_lshlrev_b32_e32 v10, 16, v153
	v_and_b32_e32 v11, 0xffff0000, v153
	v_pk_fma_f32 v[8:9], v[8:9], v[106:107], v[178:179]
	v_pk_fma_f32 v[6:7], v[6:7], v[104:105], v[168:169]
	v_pk_fma_f32 v[4:5], v[4:5], v[102:103], v[182:183]
	v_pk_fma_f32 v[2:3], v[2:3], v[100:101], v[180:181]
	global_store_dwordx4 v[196:197], v[150:153], off offset:2304
	v_pk_mul_f32 v[154:155], v[70:71], v[10:11]
	v_pk_mul_f32 v[166:167], v[68:69], v[12:13]
	v_pk_mul_f32 v[152:153], v[74:75], v[14:15]
	v_pk_mul_f32 v[150:151], v[72:73], v[16:17]
	v_cvt_pk_bf16_f32 v100, v6, v7
	v_cvt_pk_bf16_f32 v101, v8, v9
	v_cvt_pk_bf16_f32 v102, v2, v3
	v_cvt_pk_bf16_f32 v103, v4, v5
	v_cvt_pk_bf16_f32 v150, v150, v151
	v_cvt_pk_bf16_f32 v151, v152, v153
	v_cvt_pk_bf16_f32 v152, v166, v167
	v_cvt_pk_bf16_f32 v153, v154, v155
	v_lshlrev_b32_e32 v8, 16, v100
	v_and_b32_e32 v9, 0xffff0000, v100
	v_lshlrev_b32_e32 v6, 16, v101
	v_and_b32_e32 v7, 0xffff0000, v101
	v_lshlrev_b32_e32 v4, 16, v102
	v_and_b32_e32 v5, 0xffff0000, v102
	v_lshlrev_b32_e32 v2, 16, v103
	v_and_b32_e32 v3, 0xffff0000, v103
	global_store_dwordx4 v[210:211], v[150:153], off offset:256
	global_store_dwordx4 v[220:221], v[100:103], off offset:2304
	v_pk_mul_f32 v[74:75], v[74:75], v[6:7]
	v_pk_mul_f32 v[72:73], v[72:73], v[8:9]
	v_pk_mul_f32 v[100:101], v[70:71], v[2:3]
	v_pk_mul_f32 v[70:71], v[68:69], v[4:5]
	v_cvt_pk_bf16_f32 v68, v72, v73
	v_cvt_pk_bf16_f32 v69, v74, v75
	v_cvt_pk_bf16_f32 v70, v70, v71
	v_cvt_pk_bf16_f32 v71, v100, v101
	global_store_dwordx4 v[148:149], v[68:71], off offset:256
	v_xor_b32_e32 v72, 32, v227
	v_mul_f32_e32 v73, v137, v137
	v_and_b32_e32 v71, 64, v227
	v_xor_b32_e32 v70, 16, v227
	v_add_u32_e32 v71, 64, v71
	v_cmp_lt_i32_e32 vcc, v70, v71
	v_fmac_f32_e32 v73, v136, v136
	v_mul_f32_e32 v74, v133, v133
	v_cndmask_b32_e32 v70, v227, v70, vcc
	v_cmp_lt_i32_e32 vcc, v72, v71
	v_fmac_f32_e32 v74, v132, v132
	v_lshlrev_b32_e32 v70, 2, v70
	v_cndmask_b32_e32 v71, v227, v72, vcc
	v_mul_f32_e32 v72, v139, v139
	v_fmac_f32_e32 v72, v138, v138
	v_add_f32_e32 v72, v72, v73
	v_mul_f32_e32 v73, v135, v135
	v_fmac_f32_e32 v73, v134, v134
	v_add_f32_e32 v73, v73, v74
	v_add_f32_e32 v72, v72, v73
	v_add_f32_e32 v64, v72, v64
	v_add_f32_e32 v60, v60, v64
	ds_bpermute_b32 v61, v70, v60
	v_lshlrev_b32_e32 v71, 2, v71
	v_lshl_add_u64 v[68:69], v[172:173], 0, s[28:29]
	s_waitcnt lgkmcnt(0)
	v_add_f32_e32 v60, v60, v61
	ds_bpermute_b32 v61, v71, v60
	s_and_saveexec_b64 s[18:19], s[38:39]
	s_cbranch_execz .LBB0_968
	s_waitcnt lgkmcnt(0)
	v_add_f32_e32 v60, v60, v61
	global_atomic_add_f32 v[68:69], v60, off

.LBB0_1048:
	s_add_u32 s0, s24, 0xfffc0080
	s_addc_u32 s1, s25, -1
	s_add_i32 s83, 0, 0x10000
	v_add_u32_e32 v80, s83, v163
	ds_read_b128 v[68:71], v80
	ds_read_b128 v[72:75], v80 offset:1024
	ds_read_b128 v[76:79], v80 offset:2048
	ds_read_b128 v[80:83], v80 offset:3072
	s_cmp_eq_u32 s82, 12
	s_cselect_b32 s29, s43, s1
	s_cselect_b32 s28, s69, s0
	s_cselect_b32 s27, s45, s81
	s_cselect_b32 s26, s72, s73
	v_lshl_add_u64 v[166:167], s[24:25], 0, v[154:155]
	s_add_i32 m0, s23, 0xc000
	ds_read_b128 v[158:161], v165
	ds_read_b128 v[174:177], v165 offset:1024
	ds_read_b128 v[178:181], v165 offset:2048
	ds_read_b128 v[182:185], v165 offset:3072
	ds_read_b128 v[186:189], v165 offset:4096
	ds_read_b128 v[190:193], v165 offset:5120
	ds_read_b128 v[194:197], v165 offset:6144
	ds_read_b128 v[198:201], v165 offset:7168
	global_load_lds_dwordx4 v[166:167], off
	v_lshl_add_u64 v[166:167], s[24:25], 0, v[156:157]
	s_add_i32 m0, s23, 0xe000
	s_nop 0
	global_load_lds_dwordx4 v[166:167], off
	s_waitcnt lgkmcnt(8)
	s_setprio 1
	s_barrier
	s_waitcnt lgkmcnt(0)
	v_mfma_f32_16x16x32_bf16 v[144:147], v[68:71], v[158:161], v[144:147]
	v_mfma_f32_16x16x32_bf16 v[140:143], v[76:79], v[158:161], v[140:143]
	v_mfma_f32_16x16x32_bf16 v[128:131], v[68:71], v[178:181], v[128:131]
	v_mfma_f32_16x16x32_bf16 v[124:127], v[76:79], v[178:181], v[124:127]
	v_mfma_f32_16x16x32_bf16 v[112:115], v[68:71], v[186:189], v[112:115]
	v_mfma_f32_16x16x32_bf16 v[108:111], v[76:79], v[186:189], v[108:111]
	v_mfma_f32_16x16x32_bf16 v[96:99], v[68:71], v[194:197], v[96:99]
	v_mfma_f32_16x16x32_bf16 v[92:95], v[76:79], v[194:197], v[92:95]
	v_mfma_f32_16x16x32_bf16 v[144:147], v[72:75], v[174:177], v[144:147]
	v_mfma_f32_16x16x32_bf16 v[140:143], v[80:83], v[174:177], v[140:143]
	v_mfma_f32_16x16x32_bf16 v[128:131], v[72:75], v[182:185], v[128:131]
	v_mfma_f32_16x16x32_bf16 v[124:127], v[80:83], v[182:185], v[124:127]
	v_mfma_f32_16x16x32_bf16 v[112:115], v[72:75], v[190:193], v[112:115]
	v_mfma_f32_16x16x32_bf16 v[108:111], v[80:83], v[190:193], v[108:111]
	v_mfma_f32_16x16x32_bf16 v[96:99], v[72:75], v[198:201], v[96:99]
	v_mfma_f32_16x16x32_bf16 v[92:95], v[80:83], v[198:201], v[92:95]
	s_barrier
	s_setprio 0
	s_add_i32 s84, 0, 0x14000
	v_add_u32_e32 v166, s84, v163
	s_add_i32 s0, s83, s54
	ds_read_b128 v[202:205], v166
	ds_read_b128 v[206:209], v166 offset:1024
	ds_read_b128 v[210:213], v166 offset:2048
	ds_read_b128 v[214:217], v166 offset:3072
	v_lshl_add_u64 v[166:167], s[26:27], 0, v[26:27]
	s_mov_b32 m0, s0
	v_lshl_add_u64 v[168:169], s[26:27], 0, v[148:149]
	global_load_lds_dwordx4 v[166:167], off
	s_add_i32 m0, s0, 0x2000
	s_nop 0
	global_load_lds_dwordx4 v[168:169], off
	s_setprio 1
	s_barrier
	s_waitcnt lgkmcnt(0)
	v_mfma_f32_16x16x32_bf16 v[136:139], v[202:205], v[158:161], v[136:139]
	v_mfma_f32_16x16x32_bf16 v[132:135], v[210:213], v[158:161], v[132:135]
	v_mfma_f32_16x16x32_bf16 v[120:123], v[202:205], v[178:181], v[120:123]
	v_mfma_f32_16x16x32_bf16 v[116:119], v[210:213], v[178:181], v[116:119]
	v_mfma_f32_16x16x32_bf16 v[104:107], v[202:205], v[186:189], v[104:107]
	v_mfma_f32_16x16x32_bf16 v[100:103], v[210:213], v[186:189], v[100:103]
	v_mfma_f32_16x16x32_bf16 v[88:91], v[202:205], v[194:197], v[88:91]
	v_mfma_f32_16x16x32_bf16 v[84:87], v[210:213], v[194:197], v[84:87]
	v_mfma_f32_16x16x32_bf16 v[136:139], v[206:209], v[174:177], v[136:139]
	v_mfma_f32_16x16x32_bf16 v[132:135], v[214:217], v[174:177], v[132:135]
	v_mfma_f32_16x16x32_bf16 v[120:123], v[206:209], v[182:185], v[120:123]
	v_mfma_f32_16x16x32_bf16 v[116:119], v[214:217], v[182:185], v[116:119]
	v_mfma_f32_16x16x32_bf16 v[104:107], v[206:209], v[190:193], v[104:107]
	v_mfma_f32_16x16x32_bf16 v[100:103], v[214:217], v[190:193], v[100:103]
	v_mfma_f32_16x16x32_bf16 v[88:91], v[206:209], v[198:201], v[88:91]
	v_mfma_f32_16x16x32_bf16 v[84:87], v[214:217], v[198:201], v[84:87]
	s_barrier
	s_setprio 0
	s_mov_b32 m0, s23
	v_lshl_add_u64 v[218:219], s[28:29], 0, v[152:153]
	ds_read_b128 v[158:161], v165 offset:16384
	ds_read_b128 v[174:177], v165 offset:17408
	ds_read_b128 v[178:181], v165 offset:18432
	ds_read_b128 v[182:185], v165 offset:19456
	ds_read_b128 v[186:189], v165 offset:20480
	ds_read_b128 v[190:193], v165 offset:21504
	ds_read_b128 v[194:197], v165 offset:22528
	ds_read_b128 v[198:201], v165 offset:23552
	global_load_lds_dwordx4 v[218:219], off
	v_lshl_add_u64 v[220:221], s[28:29], 0, v[150:151]
	s_mov_b32 m0, s57
	s_nop 0
	global_load_lds_dwordx4 v[220:221], off
	s_setprio 1
	s_barrier
	s_waitcnt lgkmcnt(0)
	v_mfma_f32_16x16x32_bf16 v[64:67], v[68:71], v[158:161], v[64:67]
	v_mfma_f32_16x16x32_bf16 v[60:63], v[76:79], v[158:161], v[60:63]
	v_mfma_f32_16x16x32_bf16 v[48:51], v[68:71], v[178:181], v[48:51]
	v_mfma_f32_16x16x32_bf16 v[44:47], v[76:79], v[178:181], v[44:47]
	v_mfma_f32_16x16x32_bf16 v[32:35], v[68:71], v[186:189], v[32:35]
	v_mfma_f32_16x16x32_bf16 v[28:31], v[76:79], v[186:189], v[28:31]
	v_mfma_f32_16x16x32_bf16 v[14:17], v[68:71], v[194:197], v[14:17]
	v_mfma_f32_16x16x32_bf16 v[10:13], v[76:79], v[194:197], v[10:13]
	v_mfma_f32_16x16x32_bf16 v[64:67], v[72:75], v[174:177], v[64:67]
	v_mfma_f32_16x16x32_bf16 v[60:63], v[80:83], v[174:177], v[60:63]
	v_mfma_f32_16x16x32_bf16 v[48:51], v[72:75], v[182:185], v[48:51]
	v_mfma_f32_16x16x32_bf16 v[44:47], v[80:83], v[182:185], v[44:47]
	v_mfma_f32_16x16x32_bf16 v[32:35], v[72:75], v[190:193], v[32:35]
	v_mfma_f32_16x16x32_bf16 v[28:31], v[80:83], v[190:193], v[28:31]
	v_mfma_f32_16x16x32_bf16 v[14:17], v[72:75], v[198:201], v[14:17]
	v_mfma_f32_16x16x32_bf16 v[10:13], v[80:83], v[198:201], v[10:13]
	s_barrier
	s_setprio 0
	s_add_u32 s0, s26, 0x40000
	s_addc_u32 s1, s27, 0
	s_add_i32 s83, s84, s54
	v_lshl_add_u64 v[68:69], s[0:1], 0, v[26:27]
	s_mov_b32 m0, s83
	s_nop 0
	global_load_lds_dwordx4 v[68:69], off
	v_lshl_add_u64 v[68:69], s[0:1], 0, v[148:149]
	s_add_i32 m0, s83, 0x2000
	s_nop 0
	global_load_lds_dwordx4 v[68:69], off
	s_waitcnt vmcnt(6)
	s_setprio 1
	s_barrier
	v_mfma_f32_16x16x32_bf16 v[56:59], v[202:205], v[158:161], v[56:59]
	v_mfma_f32_16x16x32_bf16 v[52:55], v[210:213], v[158:161], v[52:55]
	v_mfma_f32_16x16x32_bf16 v[40:43], v[202:205], v[178:181], v[40:43]
	v_mfma_f32_16x16x32_bf16 v[36:39], v[210:213], v[178:181], v[36:39]
	v_mfma_f32_16x16x32_bf16 v[22:25], v[202:205], v[186:189], v[22:25]
	v_mfma_f32_16x16x32_bf16 v[18:21], v[210:213], v[186:189], v[18:21]
	v_mfma_f32_16x16x32_bf16 v[6:9], v[202:205], v[194:197], v[6:9]
	v_mfma_f32_16x16x32_bf16 v[2:5], v[210:213], v[194:197], v[2:5]
	v_mfma_f32_16x16x32_bf16 v[56:59], v[206:209], v[174:177], v[56:59]
	v_mfma_f32_16x16x32_bf16 v[52:55], v[214:217], v[174:177], v[52:55]
	v_mfma_f32_16x16x32_bf16 v[40:43], v[206:209], v[182:185], v[40:43]
	v_mfma_f32_16x16x32_bf16 v[36:39], v[214:217], v[182:185], v[36:39]
	v_mfma_f32_16x16x32_bf16 v[22:25], v[206:209], v[190:193], v[22:25]
	v_mfma_f32_16x16x32_bf16 v[18:21], v[214:217], v[190:193], v[18:21]
	v_mfma_f32_16x16x32_bf16 v[6:9], v[206:209], v[198:201], v[6:9]
	v_mfma_f32_16x16x32_bf16 v[2:5], v[214:217], v[198:201], v[2:5]
	s_barrier
	s_setprio 0
	s_add_i32 s83, 0, 0x18000
	v_add_u32_e32 v80, s83, v163
	ds_read_b128 v[68:71], v80
	ds_read_b128 v[72:75], v80 offset:1024
	ds_read_b128 v[76:79], v80 offset:2048
	ds_read_b128 v[80:83], v80 offset:3072
	s_add_u32 s0, s28, 0x40000
	s_addc_u32 s1, s29, 0
	s_mov_b32 m0, s58
	v_lshl_add_u64 v[202:203], s[0:1], 0, v[152:153]
	ds_read_b128 v[158:161], v165 offset:32768
	ds_read_b128 v[174:177], v165 offset:33792
	ds_read_b128 v[178:181], v165 offset:34816
	ds_read_b128 v[182:185], v165 offset:35840
	ds_read_b128 v[186:189], v165 offset:36864
	ds_read_b128 v[190:193], v165 offset:37888
	ds_read_b128 v[194:197], v165 offset:38912
	ds_read_b128 v[198:201], v165 offset:39936
	global_load_lds_dwordx4 v[202:203], off
	v_lshl_add_u64 v[202:203], s[0:1], 0, v[150:151]
	s_mov_b32 m0, s59
	s_nop 0
	global_load_lds_dwordx4 v[202:203], off
	s_waitcnt lgkmcnt(8)
	s_setprio 1
	s_barrier
	s_waitcnt lgkmcnt(0)
	v_mfma_f32_16x16x32_bf16 v[144:147], v[68:71], v[158:161], v[144:147]
	v_mfma_f32_16x16x32_bf16 v[140:143], v[76:79], v[158:161], v[140:143]
	v_mfma_f32_16x16x32_bf16 v[128:131], v[68:71], v[178:181], v[128:131]
	v_mfma_f32_16x16x32_bf16 v[124:127], v[76:79], v[178:181], v[124:127]
	v_mfma_f32_16x16x32_bf16 v[112:115], v[68:71], v[186:189], v[112:115]
	v_mfma_f32_16x16x32_bf16 v[108:111], v[76:79], v[186:189], v[108:111]
	v_mfma_f32_16x16x32_bf16 v[96:99], v[68:71], v[194:197], v[96:99]
	v_mfma_f32_16x16x32_bf16 v[92:95], v[76:79], v[194:197], v[92:95]
	v_mfma_f32_16x16x32_bf16 v[144:147], v[72:75], v[174:177], v[144:147]
	v_mfma_f32_16x16x32_bf16 v[140:143], v[80:83], v[174:177], v[140:143]
	v_mfma_f32_16x16x32_bf16 v[128:131], v[72:75], v[182:185], v[128:131]
	v_mfma_f32_16x16x32_bf16 v[124:127], v[80:83], v[182:185], v[124:127]
	v_mfma_f32_16x16x32_bf16 v[112:115], v[72:75], v[190:193], v[112:115]
	v_mfma_f32_16x16x32_bf16 v[108:111], v[80:83], v[190:193], v[108:111]
	v_mfma_f32_16x16x32_bf16 v[96:99], v[72:75], v[198:201], v[96:99]
	v_mfma_f32_16x16x32_bf16 v[92:95], v[80:83], v[198:201], v[92:95]
	s_barrier
	s_setprio 0
	s_add_i32 s28, 0, 0x1c000
	s_add_i32 s0, s83, s54
	v_add_u32_e32 v173, s28, v163
	v_lshl_add_u64 v[166:167], v[166:167], 0, s[12:13]
	s_mov_b32 m0, s0
	ds_read_b128 v[202:205], v173
	ds_read_b128 v[206:209], v173 offset:1024
	ds_read_b128 v[210:213], v173 offset:2048
	ds_read_b128 v[214:217], v173 offset:3072
	global_load_lds_dwordx4 v[166:167], off
	v_lshl_add_u64 v[166:167], v[168:169], 0, s[12:13]
	s_add_i32 m0, s0, 0x2000
	s_nop 0
	global_load_lds_dwordx4 v[166:167], off
	s_setprio 1
	s_barrier
	s_waitcnt lgkmcnt(0)
	v_mfma_f32_16x16x32_bf16 v[136:139], v[202:205], v[158:161], v[136:139]
	v_mfma_f32_16x16x32_bf16 v[132:135], v[210:213], v[158:161], v[132:135]
	v_mfma_f32_16x16x32_bf16 v[120:123], v[202:205], v[178:181], v[120:123]
	v_mfma_f32_16x16x32_bf16 v[116:119], v[210:213], v[178:181], v[116:119]
	v_mfma_f32_16x16x32_bf16 v[104:107], v[202:205], v[186:189], v[104:107]
	v_mfma_f32_16x16x32_bf16 v[100:103], v[210:213], v[186:189], v[100:103]
	v_mfma_f32_16x16x32_bf16 v[88:91], v[202:205], v[194:197], v[88:91]
	v_mfma_f32_16x16x32_bf16 v[84:87], v[210:213], v[194:197], v[84:87]
	v_mfma_f32_16x16x32_bf16 v[136:139], v[206:209], v[174:177], v[136:139]
	v_mfma_f32_16x16x32_bf16 v[132:135], v[214:217], v[174:177], v[132:135]
	v_mfma_f32_16x16x32_bf16 v[120:123], v[206:209], v[182:185], v[120:123]
	v_mfma_f32_16x16x32_bf16 v[116:119], v[214:217], v[182:185], v[116:119]
	v_mfma_f32_16x16x32_bf16 v[104:107], v[206:209], v[190:193], v[104:107]
	v_mfma_f32_16x16x32_bf16 v[100:103], v[214:217], v[190:193], v[100:103]
	v_mfma_f32_16x16x32_bf16 v[88:91], v[206:209], v[198:201], v[88:91]
	v_mfma_f32_16x16x32_bf16 v[84:87], v[214:217], v[198:201], v[84:87]
	s_barrier
	s_setprio 0
	s_mov_b32 m0, s34
	v_lshl_add_u64 v[166:167], v[218:219], 0, s[12:13]
	ds_read_b128 v[158:161], v165 offset:49152
	ds_read_b128 v[174:177], v165 offset:50176
	ds_read_b128 v[178:181], v165 offset:51200
	ds_read_b128 v[182:185], v165 offset:52224
	ds_read_b128 v[186:189], v165 offset:53248
	ds_read_b128 v[190:193], v165 offset:54272
	ds_read_b128 v[194:197], v165 offset:55296
	ds_read_b128 v[198:201], v165 offset:56320
	global_load_lds_dwordx4 v[166:167], off
	v_lshl_add_u64 v[166:167], v[220:221], 0, s[12:13]
	s_mov_b32 m0, s35
	s_nop 0
	global_load_lds_dwordx4 v[166:167], off
	s_setprio 1
	s_barrier
	s_waitcnt lgkmcnt(0)
	v_mfma_f32_16x16x32_bf16 v[64:67], v[68:71], v[158:161], v[64:67]
	v_mfma_f32_16x16x32_bf16 v[60:63], v[76:79], v[158:161], v[60:63]
	v_mfma_f32_16x16x32_bf16 v[48:51], v[68:71], v[178:181], v[48:51]
	v_mfma_f32_16x16x32_bf16 v[44:47], v[76:79], v[178:181], v[44:47]
	v_mfma_f32_16x16x32_bf16 v[32:35], v[68:71], v[186:189], v[32:35]
	v_mfma_f32_16x16x32_bf16 v[28:31], v[76:79], v[186:189], v[28:31]
	v_mfma_f32_16x16x32_bf16 v[14:17], v[68:71], v[194:197], v[14:17]
	v_mfma_f32_16x16x32_bf16 v[10:13], v[76:79], v[194:197], v[10:13]
	v_mfma_f32_16x16x32_bf16 v[64:67], v[72:75], v[174:177], v[64:67]
	v_mfma_f32_16x16x32_bf16 v[60:63], v[80:83], v[174:177], v[60:63]
	v_mfma_f32_16x16x32_bf16 v[48:51], v[72:75], v[182:185], v[48:51]
	v_mfma_f32_16x16x32_bf16 v[44:47], v[80:83], v[182:185], v[44:47]
	v_mfma_f32_16x16x32_bf16 v[32:35], v[72:75], v[190:193], v[32:35]
	v_mfma_f32_16x16x32_bf16 v[28:31], v[80:83], v[190:193], v[28:31]
	v_mfma_f32_16x16x32_bf16 v[14:17], v[72:75], v[198:201], v[14:17]
	v_mfma_f32_16x16x32_bf16 v[10:13], v[80:83], v[198:201], v[10:13]
	s_barrier
	s_setprio 0
	s_add_u32 s0, s26, 0x40080
	s_addc_u32 s1, s27, 0
	s_add_i32 s26, s28, s54
	v_lshl_add_u64 v[68:69], s[0:1], 0, v[26:27]
	s_mov_b32 m0, s26
	s_nop 0
	global_load_lds_dwordx4 v[68:69], off
	v_lshl_add_u64 v[68:69], s[0:1], 0, v[148:149]
	s_add_i32 m0, s26, 0x2000
	s_nop 0
	global_load_lds_dwordx4 v[68:69], off
	s_waitcnt vmcnt(6)
	s_setprio 1
	s_barrier
	v_mfma_f32_16x16x32_bf16 v[56:59], v[202:205], v[158:161], v[56:59]
	v_mfma_f32_16x16x32_bf16 v[52:55], v[210:213], v[158:161], v[52:55]
	v_mfma_f32_16x16x32_bf16 v[40:43], v[202:205], v[178:181], v[40:43]
	v_mfma_f32_16x16x32_bf16 v[36:39], v[210:213], v[178:181], v[36:39]
	v_mfma_f32_16x16x32_bf16 v[22:25], v[202:205], v[186:189], v[22:25]
	v_mfma_f32_16x16x32_bf16 v[18:21], v[210:213], v[186:189], v[18:21]
	v_mfma_f32_16x16x32_bf16 v[6:9], v[202:205], v[194:197], v[6:9]
	v_mfma_f32_16x16x32_bf16 v[2:5], v[210:213], v[194:197], v[2:5]
	v_mfma_f32_16x16x32_bf16 v[56:59], v[206:209], v[174:177], v[56:59]
	v_mfma_f32_16x16x32_bf16 v[52:55], v[214:217], v[174:177], v[52:55]
	v_mfma_f32_16x16x32_bf16 v[40:43], v[206:209], v[182:185], v[40:43]
	v_mfma_f32_16x16x32_bf16 v[36:39], v[214:217], v[182:185], v[36:39]
	v_mfma_f32_16x16x32_bf16 v[22:25], v[206:209], v[190:193], v[22:25]
	v_mfma_f32_16x16x32_bf16 v[18:21], v[214:217], v[190:193], v[18:21]
	v_mfma_f32_16x16x32_bf16 v[6:9], v[206:209], v[198:201], v[6:9]
	v_mfma_f32_16x16x32_bf16 v[2:5], v[214:217], v[198:201], v[2:5]
	s_barrier
	s_setprio 0
	s_add_i32 s82, s82, 2
	s_add_u32 s24, s24, 0x100
	s_addc_u32 s25, s25, 0
	s_add_u32 s73, s73, 0x100
	s_addc_u32 s81, s81, 0
	s_cmp_gt_u32 s82, 13
	s_cbranch_scc0 .LBB0_1048
	v_readlane_b32 s82, v255, 51
	s_cmpk_gt_i32 s22, 0xff
	s_mov_b64 s[24:25], 0xb000
	v_readlane_b32 s83, v255, 52
	s_cbranch_scc1 .LBB0_1044
	s_ashr_i32 s0, s22, 5
	s_mul_hi_i32 s25, s0, 0x1600
	s_mul_i32 s24, s0, 0x1600
	s_branch .LBB0_1044

.LBB0_1122:
	s_add_u32 s26, s24, 0x100
	s_addc_u32 s27, s25, 0
	s_add_i32 s0, 0, 0x10000
	v_add_u32_e32 v158, s0, v186
	ds_read_b128 v[132:135], v158
	ds_read_b128 v[136:139], v158 offset:1024
	ds_read_b128 v[154:157], v158 offset:2048
	ds_read_b128 v[158:161], v158 offset:3072
	s_cmp_eq_u32 s72, 40
	s_cselect_b32 s31, s43, s27
	s_cselect_b32 s30, s42, s26
	s_cselect_b32 s29, s45, s69
	s_cselect_b32 s28, s44, s68
	v_lshl_add_u64 v[166:167], s[24:25], 0, v[150:151]
	s_add_i32 m0, s36, 0xc000
	ds_read_b128 v[162:165], v188
	ds_read_b128 v[172:175], v188 offset:1024
	ds_read_b128 v[176:179], v188 offset:2048
	ds_read_b128 v[180:183], v188 offset:3072
	ds_read_b128 v[190:193], v188 offset:4096
	ds_read_b128 v[194:197], v188 offset:5120
	ds_read_b128 v[198:201], v188 offset:6144
	ds_read_b128 v[202:205], v188 offset:7168
	global_load_lds_dwordx4 v[166:167], off
	v_lshl_add_u64 v[166:167], s[24:25], 0, v[152:153]
	s_add_i32 m0, s36, 0xe000
	s_nop 0
	global_load_lds_dwordx4 v[166:167], off
	s_waitcnt lgkmcnt(8)
	s_setprio 1
	s_barrier
	s_waitcnt lgkmcnt(0)
	v_mfma_f32_16x16x32_bf16 v[128:131], v[132:135], v[162:165], v[128:131]
	v_mfma_f32_16x16x32_bf16 v[124:127], v[154:157], v[162:165], v[124:127]
	v_mfma_f32_16x16x32_bf16 v[120:123], v[132:135], v[176:179], v[120:123]
	v_mfma_f32_16x16x32_bf16 v[116:119], v[154:157], v[176:179], v[116:119]
	v_mfma_f32_16x16x32_bf16 v[112:115], v[132:135], v[190:193], v[112:115]
	v_mfma_f32_16x16x32_bf16 v[108:111], v[154:157], v[190:193], v[108:111]
	v_mfma_f32_16x16x32_bf16 v[104:107], v[132:135], v[198:201], v[104:107]
	v_mfma_f32_16x16x32_bf16 v[100:103], v[154:157], v[198:201], v[100:103]
	v_mfma_f32_16x16x32_bf16 v[128:131], v[136:139], v[172:175], v[128:131]
	v_mfma_f32_16x16x32_bf16 v[124:127], v[158:161], v[172:175], v[124:127]
	v_mfma_f32_16x16x32_bf16 v[120:123], v[136:139], v[180:183], v[120:123]
	v_mfma_f32_16x16x32_bf16 v[116:119], v[158:161], v[180:183], v[116:119]
	v_mfma_f32_16x16x32_bf16 v[112:115], v[136:139], v[194:197], v[112:115]
	v_mfma_f32_16x16x32_bf16 v[108:111], v[158:161], v[194:197], v[108:111]
	v_mfma_f32_16x16x32_bf16 v[104:107], v[136:139], v[202:205], v[104:107]
	v_mfma_f32_16x16x32_bf16 v[100:103], v[158:161], v[202:205], v[100:103]
	s_barrier
	s_setprio 0
	s_add_i32 s24, 0, 0x14000
	v_add_u32_e32 v166, s24, v186
	s_add_i32 s0, s0, s17
	ds_read_b128 v[206:209], v166
	ds_read_b128 v[210:213], v166 offset:1024
	ds_read_b128 v[214:217], v166 offset:2048
	ds_read_b128 v[218:221], v166 offset:3072
	v_lshl_add_u64 v[166:167], s[28:29], 0, v[26:27]
	s_mov_b32 m0, s0
	v_lshl_add_u64 v[168:169], s[28:29], 0, v[144:145]
	global_load_lds_dwordx4 v[166:167], off
	s_add_i32 m0, s0, 0x2000
	s_nop 0
	global_load_lds_dwordx4 v[168:169], off
	s_setprio 1
	s_barrier
	s_waitcnt lgkmcnt(0)
	v_mfma_f32_16x16x32_bf16 v[68:71], v[206:209], v[162:165], v[68:71]
	v_mfma_f32_16x16x32_bf16 v[60:63], v[214:217], v[162:165], v[60:63]
	v_mfma_f32_16x16x32_bf16 v[56:59], v[206:209], v[176:179], v[56:59]
	v_mfma_f32_16x16x32_bf16 v[52:55], v[214:217], v[176:179], v[52:55]
	v_mfma_f32_16x16x32_bf16 v[48:51], v[206:209], v[190:193], v[48:51]
	v_mfma_f32_16x16x32_bf16 v[44:47], v[214:217], v[190:193], v[44:47]
	v_mfma_f32_16x16x32_bf16 v[40:43], v[206:209], v[198:201], v[40:43]
	v_mfma_f32_16x16x32_bf16 v[36:39], v[214:217], v[198:201], v[36:39]
	v_mfma_f32_16x16x32_bf16 v[68:71], v[210:213], v[172:175], v[68:71]
	v_mfma_f32_16x16x32_bf16 v[60:63], v[218:221], v[172:175], v[60:63]
	v_mfma_f32_16x16x32_bf16 v[56:59], v[210:213], v[180:183], v[56:59]
	v_mfma_f32_16x16x32_bf16 v[52:55], v[218:221], v[180:183], v[52:55]
	v_mfma_f32_16x16x32_bf16 v[48:51], v[210:213], v[194:197], v[48:51]
	v_mfma_f32_16x16x32_bf16 v[44:47], v[218:221], v[194:197], v[44:47]
	v_mfma_f32_16x16x32_bf16 v[40:43], v[210:213], v[202:205], v[40:43]
	v_mfma_f32_16x16x32_bf16 v[36:39], v[218:221], v[202:205], v[36:39]
	s_barrier
	s_setprio 0
	s_mov_b32 m0, s36
	v_lshl_add_u64 v[184:185], s[30:31], 0, v[140:141]
	ds_read_b128 v[162:165], v188 offset:16384
	ds_read_b128 v[172:175], v188 offset:17408
	ds_read_b128 v[176:179], v188 offset:18432
	ds_read_b128 v[180:183], v188 offset:19456
	ds_read_b128 v[190:193], v188 offset:20480
	ds_read_b128 v[194:197], v188 offset:21504
	ds_read_b128 v[198:201], v188 offset:22528
	ds_read_b128 v[202:205], v188 offset:23552
	global_load_lds_dwordx4 v[184:185], off
	v_lshl_add_u64 v[222:223], s[30:31], 0, v[142:143]
	s_mov_b32 m0, s37
	s_nop 0
	global_load_lds_dwordx4 v[222:223], off
	s_setprio 1
	s_barrier
	s_waitcnt lgkmcnt(0)
	v_mfma_f32_16x16x32_bf16 v[96:99], v[132:135], v[162:165], v[96:99]
	v_mfma_f32_16x16x32_bf16 v[92:95], v[154:157], v[162:165], v[92:95]
	v_mfma_f32_16x16x32_bf16 v[88:91], v[132:135], v[176:179], v[88:91]
	v_mfma_f32_16x16x32_bf16 v[84:87], v[154:157], v[176:179], v[84:87]
	v_mfma_f32_16x16x32_bf16 v[80:83], v[132:135], v[190:193], v[80:83]
	v_mfma_f32_16x16x32_bf16 v[76:79], v[154:157], v[190:193], v[76:79]
	v_mfma_f32_16x16x32_bf16 v[72:75], v[132:135], v[198:201], v[72:75]
	v_mfma_f32_16x16x32_bf16 v[64:67], v[154:157], v[198:201], v[64:67]
	v_mfma_f32_16x16x32_bf16 v[96:99], v[136:139], v[172:175], v[96:99]
	v_mfma_f32_16x16x32_bf16 v[92:95], v[158:161], v[172:175], v[92:95]
	v_mfma_f32_16x16x32_bf16 v[88:91], v[136:139], v[180:183], v[88:91]
	v_mfma_f32_16x16x32_bf16 v[84:87], v[158:161], v[180:183], v[84:87]
	v_mfma_f32_16x16x32_bf16 v[80:83], v[136:139], v[194:197], v[80:83]
	v_mfma_f32_16x16x32_bf16 v[76:79], v[158:161], v[194:197], v[76:79]
	v_mfma_f32_16x16x32_bf16 v[72:75], v[136:139], v[202:205], v[72:75]
	v_mfma_f32_16x16x32_bf16 v[64:67], v[158:161], v[202:205], v[64:67]
	s_barrier
	s_setprio 0
	s_add_u32 s0, s28, 0xb0000
	s_addc_u32 s1, s29, 0
	s_add_i32 s24, s24, s17
	v_lshl_add_u64 v[132:133], s[0:1], 0, v[26:27]
	s_mov_b32 m0, s24
	s_nop 0
	global_load_lds_dwordx4 v[132:133], off
	v_lshl_add_u64 v[132:133], s[0:1], 0, v[144:145]
	s_add_i32 m0, s24, 0x2000
	s_nop 0
	global_load_lds_dwordx4 v[132:133], off
	s_waitcnt vmcnt(6)
	s_setprio 1
	s_barrier
	v_mfma_f32_16x16x32_bf16 v[32:35], v[206:209], v[162:165], v[32:35]
	v_mfma_f32_16x16x32_bf16 v[28:31], v[214:217], v[162:165], v[28:31]
	v_mfma_f32_16x16x32_bf16 v[22:25], v[206:209], v[176:179], v[22:25]
	v_mfma_f32_16x16x32_bf16 v[18:21], v[214:217], v[176:179], v[18:21]
	v_mfma_f32_16x16x32_bf16 v[14:17], v[206:209], v[190:193], v[14:17]
	v_mfma_f32_16x16x32_bf16 v[10:13], v[214:217], v[190:193], v[10:13]
	v_mfma_f32_16x16x32_bf16 v[6:9], v[206:209], v[198:201], v[6:9]
	v_mfma_f32_16x16x32_bf16 v[2:5], v[214:217], v[198:201], v[2:5]
	v_mfma_f32_16x16x32_bf16 v[32:35], v[210:213], v[172:175], v[32:35]
	v_mfma_f32_16x16x32_bf16 v[28:31], v[218:221], v[172:175], v[28:31]
	v_mfma_f32_16x16x32_bf16 v[22:25], v[210:213], v[180:183], v[22:25]
	v_mfma_f32_16x16x32_bf16 v[18:21], v[218:221], v[180:183], v[18:21]
	v_mfma_f32_16x16x32_bf16 v[14:17], v[210:213], v[194:197], v[14:17]
	v_mfma_f32_16x16x32_bf16 v[10:13], v[218:221], v[194:197], v[10:13]
	v_mfma_f32_16x16x32_bf16 v[6:9], v[210:213], v[202:205], v[6:9]
	v_mfma_f32_16x16x32_bf16 v[2:5], v[218:221], v[202:205], v[2:5]
	s_barrier
	s_setprio 0
	s_add_i32 s24, 0, 0x18000
	v_add_u32_e32 v158, s24, v186
	ds_read_b128 v[132:135], v158
	ds_read_b128 v[136:139], v158 offset:1024
	ds_read_b128 v[154:157], v158 offset:2048
	ds_read_b128 v[158:161], v158 offset:3072
	s_add_u32 s0, s30, 0xb0000
	s_addc_u32 s1, s31, 0
	s_mov_b32 m0, s52
	v_lshl_add_u64 v[206:207], s[0:1], 0, v[140:141]
	ds_read_b128 v[162:165], v188 offset:32768
	ds_read_b128 v[172:175], v188 offset:33792
	ds_read_b128 v[176:179], v188 offset:34816
	ds_read_b128 v[180:183], v188 offset:35840
	ds_read_b128 v[190:193], v188 offset:36864
	ds_read_b128 v[194:197], v188 offset:37888
	ds_read_b128 v[198:201], v188 offset:38912
	ds_read_b128 v[202:205], v188 offset:39936
	global_load_lds_dwordx4 v[206:207], off
	v_lshl_add_u64 v[206:207], s[0:1], 0, v[142:143]
	s_mov_b32 m0, s54
	s_nop 0
	global_load_lds_dwordx4 v[206:207], off
	s_waitcnt lgkmcnt(8)
	s_setprio 1
	s_barrier
	s_waitcnt lgkmcnt(0)
	v_mfma_f32_16x16x32_bf16 v[128:131], v[132:135], v[162:165], v[128:131]
	v_mfma_f32_16x16x32_bf16 v[124:127], v[154:157], v[162:165], v[124:127]
	v_mfma_f32_16x16x32_bf16 v[120:123], v[132:135], v[176:179], v[120:123]
	v_mfma_f32_16x16x32_bf16 v[116:119], v[154:157], v[176:179], v[116:119]
	v_mfma_f32_16x16x32_bf16 v[112:115], v[132:135], v[190:193], v[112:115]
	v_mfma_f32_16x16x32_bf16 v[108:111], v[154:157], v[190:193], v[108:111]
	v_mfma_f32_16x16x32_bf16 v[104:107], v[132:135], v[198:201], v[104:107]
	v_mfma_f32_16x16x32_bf16 v[100:103], v[154:157], v[198:201], v[100:103]
	v_mfma_f32_16x16x32_bf16 v[128:131], v[136:139], v[172:175], v[128:131]
	v_mfma_f32_16x16x32_bf16 v[124:127], v[158:161], v[172:175], v[124:127]
	v_mfma_f32_16x16x32_bf16 v[120:123], v[136:139], v[180:183], v[120:123]
	v_mfma_f32_16x16x32_bf16 v[116:119], v[158:161], v[180:183], v[116:119]
	v_mfma_f32_16x16x32_bf16 v[112:115], v[136:139], v[194:197], v[112:115]
	v_mfma_f32_16x16x32_bf16 v[108:111], v[158:161], v[194:197], v[108:111]
	v_mfma_f32_16x16x32_bf16 v[104:107], v[136:139], v[202:205], v[104:107]
	v_mfma_f32_16x16x32_bf16 v[100:103], v[158:161], v[202:205], v[100:103]
	s_barrier
	s_setprio 0
	s_add_i32 s25, 0, 0x1c000
	s_add_i32 s0, s24, s17
	v_add_u32_e32 v189, s25, v186
	v_lshl_add_u64 v[166:167], v[166:167], 0, s[12:13]
	s_mov_b32 m0, s0
	ds_read_b128 v[206:209], v189
	ds_read_b128 v[210:213], v189 offset:1024
	ds_read_b128 v[214:217], v189 offset:2048
	ds_read_b128 v[218:221], v189 offset:3072
	global_load_lds_dwordx4 v[166:167], off
	v_lshl_add_u64 v[166:167], v[168:169], 0, s[12:13]
	s_add_i32 m0, s0, 0x2000
	s_nop 0
	global_load_lds_dwordx4 v[166:167], off
	s_setprio 1
	s_barrier
	s_waitcnt lgkmcnt(0)
	v_mfma_f32_16x16x32_bf16 v[68:71], v[206:209], v[162:165], v[68:71]
	v_mfma_f32_16x16x32_bf16 v[60:63], v[214:217], v[162:165], v[60:63]
	v_mfma_f32_16x16x32_bf16 v[56:59], v[206:209], v[176:179], v[56:59]
	v_mfma_f32_16x16x32_bf16 v[52:55], v[214:217], v[176:179], v[52:55]
	v_mfma_f32_16x16x32_bf16 v[48:51], v[206:209], v[190:193], v[48:51]
	v_mfma_f32_16x16x32_bf16 v[44:47], v[214:217], v[190:193], v[44:47]
	v_mfma_f32_16x16x32_bf16 v[40:43], v[206:209], v[198:201], v[40:43]
	v_mfma_f32_16x16x32_bf16 v[36:39], v[214:217], v[198:201], v[36:39]
	v_mfma_f32_16x16x32_bf16 v[68:71], v[210:213], v[172:175], v[68:71]
	v_mfma_f32_16x16x32_bf16 v[60:63], v[218:221], v[172:175], v[60:63]
	v_mfma_f32_16x16x32_bf16 v[56:59], v[210:213], v[180:183], v[56:59]
	v_mfma_f32_16x16x32_bf16 v[52:55], v[218:221], v[180:183], v[52:55]
	v_mfma_f32_16x16x32_bf16 v[48:51], v[210:213], v[194:197], v[48:51]
	v_mfma_f32_16x16x32_bf16 v[44:47], v[218:221], v[194:197], v[44:47]
	v_mfma_f32_16x16x32_bf16 v[40:43], v[210:213], v[202:205], v[40:43]
	v_mfma_f32_16x16x32_bf16 v[36:39], v[218:221], v[202:205], v[36:39]
	s_barrier
	s_setprio 0
	s_mov_b32 m0, s55
	v_lshl_add_u64 v[166:167], v[184:185], 0, s[12:13]
	ds_read_b128 v[162:165], v188 offset:49152
	ds_read_b128 v[172:175], v188 offset:50176
	ds_read_b128 v[176:179], v188 offset:51200
	ds_read_b128 v[180:183], v188 offset:52224
	ds_read_b128 v[190:193], v188 offset:53248
	ds_read_b128 v[194:197], v188 offset:54272
	ds_read_b128 v[198:201], v188 offset:55296
	ds_read_b128 v[202:205], v188 offset:56320
	global_load_lds_dwordx4 v[166:167], off
	v_lshl_add_u64 v[166:167], v[222:223], 0, s[12:13]
	s_mov_b32 m0, s56
	s_nop 0
	global_load_lds_dwordx4 v[166:167], off
	s_setprio 1
	s_barrier
	s_waitcnt lgkmcnt(0)
	v_mfma_f32_16x16x32_bf16 v[96:99], v[132:135], v[162:165], v[96:99]
	v_mfma_f32_16x16x32_bf16 v[92:95], v[154:157], v[162:165], v[92:95]
	v_mfma_f32_16x16x32_bf16 v[88:91], v[132:135], v[176:179], v[88:91]
	v_mfma_f32_16x16x32_bf16 v[84:87], v[154:157], v[176:179], v[84:87]
	v_mfma_f32_16x16x32_bf16 v[80:83], v[132:135], v[190:193], v[80:83]
	v_mfma_f32_16x16x32_bf16 v[76:79], v[154:157], v[190:193], v[76:79]
	v_mfma_f32_16x16x32_bf16 v[72:75], v[132:135], v[198:201], v[72:75]
	v_mfma_f32_16x16x32_bf16 v[64:67], v[154:157], v[198:201], v[64:67]
	v_mfma_f32_16x16x32_bf16 v[96:99], v[136:139], v[172:175], v[96:99]
	v_mfma_f32_16x16x32_bf16 v[92:95], v[158:161], v[172:175], v[92:95]
	v_mfma_f32_16x16x32_bf16 v[88:91], v[136:139], v[180:183], v[88:91]
	v_mfma_f32_16x16x32_bf16 v[84:87], v[158:161], v[180:183], v[84:87]
	v_mfma_f32_16x16x32_bf16 v[80:83], v[136:139], v[194:197], v[80:83]
	v_mfma_f32_16x16x32_bf16 v[76:79], v[158:161], v[194:197], v[76:79]
	v_mfma_f32_16x16x32_bf16 v[72:75], v[136:139], v[202:205], v[72:75]
	v_mfma_f32_16x16x32_bf16 v[64:67], v[158:161], v[202:205], v[64:67]
	s_barrier
	s_setprio 0
	s_add_u32 s0, s28, 0xb0080
	s_addc_u32 s1, s29, 0
	s_add_i32 s24, s25, s17
	v_lshl_add_u64 v[132:133], s[0:1], 0, v[26:27]
	s_mov_b32 m0, s24
	s_nop 0
	global_load_lds_dwordx4 v[132:133], off
	v_lshl_add_u64 v[132:133], s[0:1], 0, v[144:145]
	s_add_i32 m0, s24, 0x2000
	s_nop 0
	global_load_lds_dwordx4 v[132:133], off
	s_waitcnt vmcnt(6)
	s_setprio 1
	s_barrier
	v_mfma_f32_16x16x32_bf16 v[32:35], v[206:209], v[162:165], v[32:35]
	v_mfma_f32_16x16x32_bf16 v[28:31], v[214:217], v[162:165], v[28:31]
	v_mfma_f32_16x16x32_bf16 v[22:25], v[206:209], v[176:179], v[22:25]
	v_mfma_f32_16x16x32_bf16 v[18:21], v[214:217], v[176:179], v[18:21]
	v_mfma_f32_16x16x32_bf16 v[14:17], v[206:209], v[190:193], v[14:17]
	v_mfma_f32_16x16x32_bf16 v[10:13], v[214:217], v[190:193], v[10:13]
	v_mfma_f32_16x16x32_bf16 v[6:9], v[206:209], v[198:201], v[6:9]
	v_mfma_f32_16x16x32_bf16 v[2:5], v[214:217], v[198:201], v[2:5]
	v_mfma_f32_16x16x32_bf16 v[32:35], v[210:213], v[172:175], v[32:35]
	v_mfma_f32_16x16x32_bf16 v[28:31], v[218:221], v[172:175], v[28:31]
	v_mfma_f32_16x16x32_bf16 v[22:25], v[210:213], v[180:183], v[22:25]
	v_mfma_f32_16x16x32_bf16 v[18:21], v[218:221], v[180:183], v[18:21]
	v_mfma_f32_16x16x32_bf16 v[14:17], v[210:213], v[194:197], v[14:17]
	v_mfma_f32_16x16x32_bf16 v[10:13], v[218:221], v[194:197], v[10:13]
	v_mfma_f32_16x16x32_bf16 v[6:9], v[210:213], v[202:205], v[6:9]
	v_mfma_f32_16x16x32_bf16 v[2:5], v[218:221], v[202:205], v[2:5]
	s_barrier
	s_setprio 0
	s_add_i32 s72, s72, 2
	s_add_u32 s68, s68, 0x100
	s_addc_u32 s69, s69, 0
	s_cmp_gt_u32 s72, 41
	s_mov_b64 s[24:25], s[26:27]
	s_cbranch_scc0 .LBB0_1122
	s_min_i32 s0, s22, 0x100
	s_ashr_i32 s26, s0, 5
	s_add_i32 s0, s22, 0xffffff00
	s_cmpk_lt_i32 s22, 0x100
	s_cselect_b32 s0, s22, s0
	s_cselect_b32 s25, 0, s51
	s_cselect_b32 s24, 0, s50
	s_ashr_i32 s1, s0, 31
	s_lshl_b64 s[0:1], s[0:1], 19
	s_add_u32 s24, s20, s24
	v_lshl_or_b32 v166, s23, 8, v187
	s_addc_u32 s25, s21, s25
	s_ashr_i32 s23, s22, 31
	v_lshl_add_u64 v[132:133], s[0:1], 0, v[146:147]
	s_lshl_b64 s[22:23], s[22:23], 10
	s_mul_hi_i32 s1, s26, 0x9000
	s_mul_i32 s26, s26, 0x9000
	s_add_u32 s0, s34, s26
	v_ashrrev_i32_e32 v167, 31, v166
	s_addc_u32 s1, s35, s1
	v_lshl_add_u64 v[154:155], v[166:167], 2, s[0:1]
	v_lshl_add_u64 v[168:169], v[132:133], 0, v[166:167]
	v_lshl_add_u64 v[176:177], v[132:133], 1, s[24:25]
	global_load_dwordx4 v[132:135], v[154:155], off offset:16
	global_load_dwordx4 v[136:139], v[154:155], off
	v_lshl_add_u64 v[182:183], v[168:169], 1, s[24:25]
	v_add_co_u32_e32 v184, vcc, s65, v182
	s_mov_b32 s0, 0x20000
	s_nop 0
	v_addc_co_u32_e32 v185, vcc, 0, v183, vcc
	v_add_co_u32_e32 v178, vcc, s0, v182
	s_mov_b32 s1, 0x30000
	s_nop 0
	v_addc_co_u32_e32 v179, vcc, 0, v183, vcc
	v_add_co_u32_e32 v180, vcc, s1, v182
	v_lshl_add_u64 v[176:177], v[166:167], 1, v[176:177]
	s_nop 0
	v_addc_co_u32_e32 v181, vcc, 0, v183, vcc
	s_mov_b32 s24, 0x80000
	s_mov_b32 s25, 0x90000
	s_waitcnt vmcnt(0)
	v_pk_mul_f32 v[164:165], v[134:135], 0.5 op_sel_hi:[1,0]
	v_pk_mul_f32 v[174:175], v[138:139], 0.5 op_sel_hi:[1,0]
	v_pk_mul_f32 v[172:173], v[136:137], 0.5 op_sel_hi:[1,0]
	v_pk_mul_f32 v[162:163], v[132:133], 0.5 op_sel_hi:[1,0]
	global_load_dwordx4 v[132:135], v[154:155], off offset:528
	global_load_dwordx4 v[136:139], v[154:155], off offset:512
	global_load_dwordx4 v[190:193], v[182:183], off offset:2048
	global_load_dwordx4 v[194:197], v[184:185], off offset:2048
	s_waitcnt vmcnt(0)
	v_pk_mul_f32 v[156:157], v[134:135], 0.5 op_sel_hi:[1,0]
	v_pk_mul_f32 v[160:161], v[138:139], 0.5 op_sel_hi:[1,0]
	v_pk_mul_f32 v[158:159], v[136:137], 0.5 op_sel_hi:[1,0]
	global_load_dwordx4 v[136:139], v[178:179], off offset:2048
	v_pk_mul_f32 v[154:155], v[132:133], 0.5 op_sel_hi:[1,0]
	global_load_dwordx4 v[132:135], v[180:181], off offset:2048
	v_lshlrev_b32_e32 v166, 16, v190
	v_and_b32_e32 v167, 0xffff0000, v190
	v_lshlrev_b32_e32 v168, 16, v191
	v_and_b32_e32 v169, 0xffff0000, v191
	v_lshlrev_b32_e32 v190, 16, v192
	v_and_b32_e32 v191, 0xffff0000, v192
	v_lshlrev_b32_e32 v192, 16, v193
	v_and_b32_e32 v193, 0xffff0000, v193
	v_pk_fma_f32 v[130:131], v[130:131], v[174:175], v[168:169]
	v_pk_fma_f32 v[128:129], v[128:129], v[172:173], v[166:167]
	v_pk_fma_f32 v[166:167], v[126:127], v[164:165], v[192:193]
	v_pk_fma_f32 v[126:127], v[124:125], v[162:163], v[190:191]
	v_lshlrev_b32_e32 v202, 16, v196
	v_and_b32_e32 v203, 0xffff0000, v196
	v_lshlrev_b32_e32 v204, 16, v197
	v_and_b32_e32 v205, 0xffff0000, v197
	v_cvt_pk_bf16_f32 v124, v128, v129
	v_cvt_pk_bf16_f32 v125, v130, v131
	v_cvt_pk_bf16_f32 v126, v126, v127
	v_cvt_pk_bf16_f32 v127, v166, v167
	v_lshlrev_b32_e32 v200, 16, v195
	v_and_b32_e32 v201, 0xffff0000, v195
	global_store_dwordx4 v[176:177], v[124:127], off offset:2048
	v_lshlrev_b32_e32 v193, 16, v124
	v_and_b32_e32 v196, 0xffff0000, v124
	v_lshlrev_b32_e32 v191, 16, v125
	v_and_b32_e32 v195, 0xffff0000, v125
	v_pk_fma_f32 v[124:125], v[118:119], v[164:165], v[204:205]
	v_pk_fma_f32 v[118:119], v[116:117], v[162:163], v[202:203]
	v_lshlrev_b32_e32 v198, 16, v194
	v_cvt_pk_bf16_f32 v118, v118, v119
	v_cvt_pk_bf16_f32 v119, v124, v125
	v_add_co_u32_e32 v124, vcc, s65, v176
	v_and_b32_e32 v199, 0xffff0000, v194
	s_nop 0
	v_addc_co_u32_e32 v125, vcc, 0, v177, vcc
	v_lshlrev_b32_e32 v190, 16, v126
	v_and_b32_e32 v194, 0xffff0000, v126
	v_add_co_u32_e32 v126, vcc, s24, v182
	v_lshlrev_b32_e32 v189, 16, v127
	v_and_b32_e32 v192, 0xffff0000, v127
	v_addc_co_u32_e32 v127, vcc, 0, v183, vcc
	v_add_co_u32_e32 v128, vcc, s25, v182
	v_pk_fma_f32 v[122:123], v[122:123], v[174:175], v[200:201]
	v_pk_fma_f32 v[120:121], v[120:121], v[172:173], v[198:199]
	v_addc_co_u32_e32 v129, vcc, 0, v183, vcc
	v_cvt_pk_bf16_f32 v116, v120, v121
	v_cvt_pk_bf16_f32 v117, v122, v123
	global_store_dwordx4 v[124:125], v[116:119], off offset:2048
	global_load_dwordx4 v[120:123], v[126:127], off offset:2048
	global_load_dwordx4 v[198:201], v[128:129], off offset:2048
	s_waitcnt vmcnt(0)
	v_lshlrev_b32_e32 v130, 16, v136
	v_and_b32_e32 v131, 0xffff0000, v136
	v_lshlrev_b32_e32 v166, 16, v138
	v_and_b32_e32 v167, 0xffff0000, v138
	v_lshlrev_b32_e32 v138, 16, v139
	v_and_b32_e32 v139, 0xffff0000, v139
	v_pk_fma_f32 v[112:113], v[112:113], v[172:173], v[130:131]
	v_pk_fma_f32 v[130:131], v[110:111], v[164:165], v[138:139]
	v_pk_fma_f32 v[110:111], v[108:109], v[162:163], v[166:167]
	v_lshlrev_b32_e32 v168, 16, v132
	v_cvt_pk_bf16_f32 v110, v110, v111
	v_cvt_pk_bf16_f32 v111, v130, v131
	v_add_co_u32_e32 v130, vcc, s0, v176
	v_and_b32_e32 v169, 0xffff0000, v132
	v_lshlrev_b32_e32 v132, 16, v133
	v_and_b32_e32 v133, 0xffff0000, v133
	v_addc_co_u32_e32 v131, vcc, 0, v177, vcc
	v_lshlrev_b32_e32 v136, 16, v137
	v_and_b32_e32 v137, 0xffff0000, v137
	v_lshlrev_b32_e32 v202, 16, v134
	v_and_b32_e32 v203, 0xffff0000, v134
	v_lshlrev_b32_e32 v134, 16, v135
	v_and_b32_e32 v135, 0xffff0000, v135
	v_pk_fma_f32 v[106:107], v[106:107], v[174:175], v[132:133]
	v_add_co_u32_e32 v132, vcc, s1, v176
	v_pk_fma_f32 v[114:115], v[114:115], v[174:175], v[136:137]
	v_cvt_pk_bf16_f32 v108, v112, v113
	v_pk_fma_f32 v[104:105], v[104:105], v[172:173], v[168:169]
	v_pk_fma_f32 v[112:113], v[102:103], v[164:165], v[134:135]
	v_pk_fma_f32 v[102:103], v[100:101], v[162:163], v[202:203]
	v_addc_co_u32_e32 v133, vcc, 0, v177, vcc
	v_cvt_pk_bf16_f32 v109, v114, v115
	v_cvt_pk_bf16_f32 v100, v104, v105
	v_cvt_pk_bf16_f32 v101, v106, v107
	v_cvt_pk_bf16_f32 v102, v102, v103
	v_cvt_pk_bf16_f32 v103, v112, v113
	v_add_co_u32_e32 v134, vcc, s76, v182
	global_store_dwordx4 v[130:131], v[108:111], off offset:2048
	global_store_dwordx4 v[132:133], v[100:103], off offset:2048
	v_addc_co_u32_e32 v135, vcc, 0, v183, vcc
	s_mov_b32 s0, 0xb0000
	global_load_dwordx4 v[112:115], v[134:135], off offset:2048
	v_add_co_u32_e32 v136, vcc, s0, v182
	v_lshlrev_b32_e32 v138, 16, v120
	s_nop 0
	v_addc_co_u32_e32 v137, vcc, 0, v183, vcc
	global_load_dwordx4 v[104:107], v[136:137], off offset:2048
	v_and_b32_e32 v139, 0xffff0000, v120
	v_lshlrev_b32_e32 v120, 16, v121
	v_and_b32_e32 v121, 0xffff0000, v121
	v_lshlrev_b32_e32 v166, 16, v122
	v_and_b32_e32 v167, 0xffff0000, v122
	v_lshlrev_b32_e32 v122, 16, v123
	v_and_b32_e32 v123, 0xffff0000, v123
	v_pk_fma_f32 v[96:97], v[96:97], v[172:173], v[138:139]
	v_lshlrev_b32_e32 v168, 16, v198
	v_and_b32_e32 v169, 0xffff0000, v198
	v_lshlrev_b32_e32 v198, 16, v199
	v_and_b32_e32 v199, 0xffff0000, v199
	v_pk_fma_f32 v[98:99], v[98:99], v[174:175], v[120:121]
	v_pk_fma_f32 v[120:121], v[94:95], v[164:165], v[122:123]
	v_pk_fma_f32 v[94:95], v[92:93], v[162:163], v[166:167]
	v_cvt_pk_bf16_f32 v92, v96, v97
	v_add_co_u32_e32 v96, vcc, s24, v176
	v_lshlrev_b32_e32 v202, 16, v200
	v_and_b32_e32 v203, 0xffff0000, v200
	v_lshlrev_b32_e32 v200, 16, v201
	v_and_b32_e32 v201, 0xffff0000, v201
	v_addc_co_u32_e32 v97, vcc, 0, v177, vcc
	v_pk_fma_f32 v[90:91], v[90:91], v[174:175], v[198:199]
	v_pk_fma_f32 v[88:89], v[88:89], v[172:173], v[168:169]
	v_cvt_pk_bf16_f32 v93, v98, v99
	v_pk_fma_f32 v[98:99], v[86:87], v[164:165], v[200:201]
	v_pk_fma_f32 v[86:87], v[84:85], v[162:163], v[202:203]
	v_cvt_pk_bf16_f32 v84, v88, v89
	v_cvt_pk_bf16_f32 v85, v90, v91
	v_add_co_u32_e32 v88, vcc, s25, v176
	v_cvt_pk_bf16_f32 v86, v86, v87
	v_cvt_pk_bf16_f32 v87, v98, v99
	v_addc_co_u32_e32 v89, vcc, 0, v177, vcc
	v_cvt_pk_bf16_f32 v94, v94, v95
	v_cvt_pk_bf16_f32 v95, v120, v121
	global_store_dwordx4 v[96:97], v[92:95], off offset:2048
	global_store_dwordx4 v[88:89], v[84:87], off offset:2048
	global_load_dwordx4 v[120:123], v[182:183], off offset:2304
	s_nop 0
	global_load_dwordx4 v[182:185], v[184:185], off offset:2304
	s_waitcnt vmcnt(0)
	v_lshlrev_b32_e32 v90, 16, v112
	v_and_b32_e32 v91, 0xffff0000, v112
	v_lshlrev_b32_e32 v98, 16, v113
	v_and_b32_e32 v99, 0xffff0000, v113
	v_lshlrev_b32_e32 v112, 16, v114
	v_and_b32_e32 v113, 0xffff0000, v114
	v_lshlrev_b32_e32 v114, 16, v115
	v_and_b32_e32 v115, 0xffff0000, v115
	v_pk_fma_f32 v[80:81], v[80:81], v[172:173], v[90:91]
	v_pk_fma_f32 v[90:91], v[78:79], v[164:165], v[114:115]
	v_pk_fma_f32 v[78:79], v[76:77], v[162:163], v[112:113]
	v_cvt_pk_bf16_f32 v76, v80, v81
	v_add_co_u32_e32 v80, vcc, s76, v176
	v_lshlrev_b32_e32 v138, 16, v104
	v_and_b32_e32 v139, 0xffff0000, v104
	v_lshlrev_b32_e32 v104, 16, v105
	v_and_b32_e32 v105, 0xffff0000, v105
	v_lshlrev_b32_e32 v166, 16, v106
	v_and_b32_e32 v167, 0xffff0000, v106
	v_lshlrev_b32_e32 v106, 16, v107
	v_and_b32_e32 v107, 0xffff0000, v107
	v_pk_fma_f32 v[82:83], v[82:83], v[174:175], v[98:99]
	v_addc_co_u32_e32 v81, vcc, 0, v177, vcc
	v_pk_fma_f32 v[72:73], v[72:73], v[172:173], v[138:139]
	v_cvt_pk_bf16_f32 v77, v82, v83
	v_pk_fma_f32 v[74:75], v[74:75], v[174:175], v[104:105]
	v_pk_fma_f32 v[82:83], v[66:67], v[164:165], v[106:107]
	v_pk_fma_f32 v[66:67], v[64:65], v[162:163], v[166:167]
	v_cvt_pk_bf16_f32 v64, v72, v73
	v_add_co_u32_e32 v72, vcc, s0, v176
	v_cvt_pk_bf16_f32 v78, v78, v79
	v_cvt_pk_bf16_f32 v79, v90, v91
	v_cvt_pk_bf16_f32 v65, v74, v75
	v_cvt_pk_bf16_f32 v66, v66, v67
	v_cvt_pk_bf16_f32 v67, v82, v83
	v_addc_co_u32_e32 v73, vcc, 0, v177, vcc
	global_store_dwordx4 v[80:81], v[76:79], off offset:2048
	global_store_dwordx4 v[72:73], v[64:67], off offset:2048
	global_load_dwordx4 v[104:107], v[178:179], off offset:2304
	global_load_dwordx4 v[112:115], v[180:181], off offset:2304
	v_lshlrev_b32_e32 v74, 16, v120
	v_and_b32_e32 v75, 0xffff0000, v120
	v_lshlrev_b32_e32 v82, 16, v121
	v_and_b32_e32 v83, 0xffff0000, v121
	v_lshlrev_b32_e32 v90, 16, v122
	v_and_b32_e32 v91, 0xffff0000, v122
	v_lshlrev_b32_e32 v98, 16, v123
	v_and_b32_e32 v99, 0xffff0000, v123
	v_pk_fma_f32 v[70:71], v[70:71], v[160:161], v[82:83]
	v_pk_fma_f32 v[68:69], v[68:69], v[158:159], v[74:75]
	v_pk_fma_f32 v[74:75], v[62:63], v[156:157], v[98:99]
	v_pk_fma_f32 v[62:63], v[60:61], v[154:155], v[90:91]
	v_lshlrev_b32_e32 v120, 16, v182
	v_and_b32_e32 v121, 0xffff0000, v182
	v_lshlrev_b32_e32 v122, 16, v183
	v_and_b32_e32 v123, 0xffff0000, v183
	v_lshlrev_b32_e32 v138, 16, v184
	v_and_b32_e32 v139, 0xffff0000, v184
	v_lshlrev_b32_e32 v162, 16, v185
	v_and_b32_e32 v163, 0xffff0000, v185
	v_cvt_pk_bf16_f32 v60, v68, v69
	v_cvt_pk_bf16_f32 v61, v70, v71
	v_cvt_pk_bf16_f32 v62, v62, v63
	v_cvt_pk_bf16_f32 v63, v74, v75
	global_store_dwordx4 v[176:177], v[60:63], off offset:2304
	v_lshlrev_b32_e32 v164, 16, v60
	v_and_b32_e32 v165, 0xffff0000, v60
	v_lshlrev_b32_e32 v166, 16, v61
	v_and_b32_e32 v167, 0xffff0000, v61
	v_pk_fma_f32 v[58:59], v[58:59], v[160:161], v[122:123]
	v_pk_fma_f32 v[56:57], v[56:57], v[158:159], v[120:121]
	v_pk_fma_f32 v[60:61], v[54:55], v[156:157], v[162:163]
	v_pk_fma_f32 v[54:55], v[52:53], v[154:155], v[138:139]
	v_cvt_pk_bf16_f32 v52, v56, v57
	v_cvt_pk_bf16_f32 v53, v58, v59
	v_cvt_pk_bf16_f32 v54, v54, v55
	v_cvt_pk_bf16_f32 v55, v60, v61
	global_store_dwordx4 v[124:125], v[52:55], off offset:2304
	v_lshlrev_b32_e32 v168, 16, v62
	v_and_b32_e32 v169, 0xffff0000, v62
	v_lshlrev_b32_e32 v172, 16, v63
	v_and_b32_e32 v173, 0xffff0000, v63
	global_load_dwordx4 v[56:59], v[126:127], off offset:2304
	global_load_dwordx4 v[60:63], v[128:129], off offset:2304
	s_waitcnt vmcnt(0)
	v_lshlrev_b32_e32 v68, 16, v104
	v_and_b32_e32 v69, 0xffff0000, v104
	v_lshlrev_b32_e32 v70, 16, v105
	v_and_b32_e32 v71, 0xffff0000, v105
	v_lshlrev_b32_e32 v74, 16, v106
	v_and_b32_e32 v75, 0xffff0000, v106
	v_lshlrev_b32_e32 v82, 16, v107
	v_and_b32_e32 v83, 0xffff0000, v107
	v_lshlrev_b32_e32 v90, 16, v112
	v_and_b32_e32 v91, 0xffff0000, v112
	v_lshlrev_b32_e32 v98, 16, v113
	v_and_b32_e32 v99, 0xffff0000, v113
	v_lshlrev_b32_e32 v104, 16, v114
	v_and_b32_e32 v105, 0xffff0000, v114
	v_lshlrev_b32_e32 v106, 16, v115
	v_and_b32_e32 v107, 0xffff0000, v115
	v_pk_fma_f32 v[48:49], v[48:49], v[158:159], v[68:69]
	v_pk_fma_f32 v[50:51], v[50:51], v[160:161], v[70:71]
	v_pk_fma_f32 v[68:69], v[46:47], v[156:157], v[82:83]
	v_pk_fma_f32 v[46:47], v[44:45], v[154:155], v[74:75]
	v_cvt_pk_bf16_f32 v44, v48, v49
	v_pk_fma_f32 v[42:43], v[42:43], v[160:161], v[98:99]
	v_pk_fma_f32 v[40:41], v[40:41], v[158:159], v[90:91]
	v_pk_fma_f32 v[48:49], v[38:39], v[156:157], v[106:107]
	v_pk_fma_f32 v[38:39], v[36:37], v[154:155], v[104:105]
	v_cvt_pk_bf16_f32 v45, v50, v51
	v_cvt_pk_bf16_f32 v46, v46, v47
	v_cvt_pk_bf16_f32 v47, v68, v69
	v_cvt_pk_bf16_f32 v36, v40, v41
	v_cvt_pk_bf16_f32 v37, v42, v43
	v_cvt_pk_bf16_f32 v38, v38, v39
	v_cvt_pk_bf16_f32 v39, v48, v49
	global_store_dwordx4 v[130:131], v[44:47], off offset:2304
	global_store_dwordx4 v[132:133], v[36:39], off offset:2304
	global_load_dwordx4 v[40:43], v[134:135], off offset:2304
	global_load_dwordx4 v[48:51], v[136:137], off offset:2304
	v_lshlrev_b32_e32 v68, 16, v56
	v_and_b32_e32 v69, 0xffff0000, v56
	v_lshlrev_b32_e32 v56, 16, v57
	v_and_b32_e32 v57, 0xffff0000, v57
	v_lshlrev_b32_e32 v70, 16, v58
	v_and_b32_e32 v71, 0xffff0000, v58
	v_lshlrev_b32_e32 v58, 16, v59
	v_and_b32_e32 v59, 0xffff0000, v59
	v_lshlrev_b32_e32 v74, 16, v60
	v_and_b32_e32 v75, 0xffff0000, v60
	v_lshlrev_b32_e32 v82, 16, v62
	v_and_b32_e32 v83, 0xffff0000, v62
	v_lshlrev_b32_e32 v62, 16, v63
	v_and_b32_e32 v63, 0xffff0000, v63
	v_pk_fma_f32 v[32:33], v[32:33], v[158:159], v[68:69]
	v_lshlrev_b32_e32 v60, 16, v61
	v_and_b32_e32 v61, 0xffff0000, v61
	v_pk_fma_f32 v[34:35], v[34:35], v[160:161], v[56:57]
	v_pk_fma_f32 v[56:57], v[30:31], v[156:157], v[58:59]
	v_pk_fma_f32 v[30:31], v[28:29], v[154:155], v[70:71]
	v_cvt_pk_bf16_f32 v28, v32, v33
	v_pk_fma_f32 v[22:23], v[22:23], v[158:159], v[74:75]
	v_pk_fma_f32 v[32:33], v[20:21], v[156:157], v[62:63]
	v_pk_fma_f32 v[20:21], v[18:19], v[154:155], v[82:83]
	v_cvt_pk_bf16_f32 v29, v34, v35
	v_pk_fma_f32 v[24:25], v[24:25], v[160:161], v[60:61]
	v_cvt_pk_bf16_f32 v18, v22, v23
	v_cvt_pk_bf16_f32 v20, v20, v21
	v_cvt_pk_bf16_f32 v21, v32, v33
	v_cvt_pk_bf16_f32 v19, v24, v25
	v_cvt_pk_bf16_f32 v30, v30, v31
	v_cvt_pk_bf16_f32 v31, v56, v57
	global_store_dwordx4 v[96:97], v[28:31], off offset:2304
	global_store_dwordx4 v[88:89], v[18:21], off offset:2304
	s_waitcnt vmcnt(0)
	v_lshlrev_b32_e32 v22, 16, v40
	v_and_b32_e32 v23, 0xffff0000, v40
	v_lshlrev_b32_e32 v32, 16, v42
	v_and_b32_e32 v33, 0xffff0000, v42
	v_lshlrev_b32_e32 v34, 16, v43
	v_and_b32_e32 v35, 0xffff0000, v43
	v_lshlrev_b32_e32 v42, 16, v49
	v_and_b32_e32 v43, 0xffff0000, v49
	v_lshlrev_b32_e32 v24, 16, v41
	v_and_b32_e32 v25, 0xffff0000, v41
	v_lshlrev_b32_e32 v40, 16, v48
	v_and_b32_e32 v41, 0xffff0000, v48
	v_lshlrev_b32_e32 v48, 16, v50
	v_and_b32_e32 v49, 0xffff0000, v50
	v_lshlrev_b32_e32 v50, 16, v51
	v_and_b32_e32 v51, 0xffff0000, v51
	v_pk_fma_f32 v[14:15], v[14:15], v[158:159], v[22:23]
	v_pk_fma_f32 v[8:9], v[8:9], v[160:161], v[42:43]
	v_pk_fma_f32 v[22:23], v[12:13], v[156:157], v[34:35]
	v_pk_fma_f32 v[12:13], v[10:11], v[154:155], v[32:33]
	v_cvt_pk_bf16_f32 v10, v14, v15
	v_pk_fma_f32 v[14:15], v[4:5], v[156:157], v[50:51]
	v_pk_fma_f32 v[4:5], v[2:3], v[154:155], v[48:49]
	v_cvt_pk_bf16_f32 v3, v8, v9
	v_and_b32_e32 v9, 64, v227
	v_xor_b32_e32 v8, 16, v227
	v_add_u32_e32 v9, 64, v9
	v_cvt_pk_bf16_f32 v4, v4, v5
	v_cvt_pk_bf16_f32 v5, v14, v15
	v_cmp_lt_i32_e32 vcc, v8, v9
	v_xor_b32_e32 v14, 32, v227
	v_mul_f32_e32 v15, v195, v195
	v_cndmask_b32_e32 v8, v227, v8, vcc
	v_cmp_lt_i32_e32 vcc, v14, v9
	v_pk_fma_f32 v[16:17], v[16:17], v[160:161], v[24:25]
	v_fmac_f32_e32 v15, v191, v191
	v_cndmask_b32_e32 v9, v227, v14, vcc
	v_mul_f32_e32 v14, v196, v196
	v_fmac_f32_e32 v14, v193, v193
	v_cvt_pk_bf16_f32 v11, v16, v17
	v_add_f32_e32 v14, v14, v15
	v_mul_f32_e32 v15, v194, v194
	v_mul_f32_e32 v16, v192, v192
	v_fmac_f32_e32 v15, v190, v190
	v_fmac_f32_e32 v16, v189, v189
	v_add_f32_e32 v15, v15, v16
	v_add_f32_e32 v14, v14, v15
	v_mul_f32_e32 v15, v165, v165
	v_mul_f32_e32 v16, v167, v167
	v_fmac_f32_e32 v15, v164, v164
	v_fmac_f32_e32 v16, v166, v166
	v_add_f32_e32 v15, v15, v16
	v_add_f32_e32 v14, v14, v15
	v_mul_f32_e32 v15, v169, v169
	v_mul_f32_e32 v16, v173, v173
	v_fmac_f32_e32 v15, v168, v168
	v_fmac_f32_e32 v16, v172, v172
	v_add_f32_e32 v15, v15, v16
	v_lshlrev_b32_e32 v8, 2, v8
	v_add_f32_e32 v14, v15, v14
	ds_bpermute_b32 v15, v8, v14
	v_lshlrev_b32_e32 v9, 2, v9
	v_pk_fma_f32 v[6:7], v[6:7], v[158:159], v[40:41]
	v_cvt_pk_bf16_f32 v12, v12, v13
	v_cvt_pk_bf16_f32 v13, v22, v23
	s_waitcnt lgkmcnt(0)
	v_add_f32_e32 v14, v14, v15
	ds_bpermute_b32 v15, v9, v14
	v_cvt_pk_bf16_f32 v2, v6, v7
	v_lshl_add_u64 v[6:7], v[148:149], 0, s[22:23]
	global_store_dwordx4 v[80:81], v[10:13], off offset:2304
	global_store_dwordx4 v[72:73], v[2:5], off offset:2304
	s_and_saveexec_b64 s[22:23], s[38:39]
	s_cbranch_execz .LBB0_1125
	s_waitcnt lgkmcnt(0)
	v_add_f32_e32 v14, v14, v15
	global_atomic_add_f32 v[6:7], v14, off

.LBB0_1156:
	s_add_u32 s28, s26, 0x100
	s_addc_u32 s29, s27, 0
	s_add_i32 s0, 0, 0x10000
	v_add_u32_e32 v160, s0, v222
	ds_read_b128 v[132:135], v160
	ds_read_b128 v[136:139], v160 offset:1024
	ds_read_b128 v[156:159], v160 offset:2048
	ds_read_b128 v[160:163], v160 offset:3072
	s_cmp_eq_u32 s81, 40
	s_cselect_b32 s35, s43, s29
	s_cselect_b32 s34, s42, s28
	s_cselect_b32 s31, s23, s45
	s_cselect_b32 s30, s22, s44
	v_lshl_add_u64 v[164:165], s[26:27], 0, v[152:153]
	s_add_i32 m0, s52, 0xc000
	ds_read_b128 v[172:175], v224
	ds_read_b128 v[176:179], v224 offset:1024
	ds_read_b128 v[180:183], v224 offset:2048
	ds_read_b128 v[184:187], v224 offset:3072
	ds_read_b128 v[188:191], v224 offset:4096
	ds_read_b128 v[192:195], v224 offset:5120
	ds_read_b128 v[196:199], v224 offset:6144
	ds_read_b128 v[200:203], v224 offset:7168
	global_load_lds_dwordx4 v[164:165], off
	v_lshl_add_u64 v[164:165], s[26:27], 0, v[154:155]
	s_add_i32 m0, s52, 0xe000
	s_nop 0
	global_load_lds_dwordx4 v[164:165], off
	s_waitcnt lgkmcnt(8)
	s_setprio 1
	s_barrier
	s_waitcnt lgkmcnt(0)
	v_mfma_f32_16x16x32_bf16 v[128:131], v[132:135], v[172:175], v[128:131]
	v_mfma_f32_16x16x32_bf16 v[124:127], v[156:159], v[172:175], v[124:127]
	v_mfma_f32_16x16x32_bf16 v[120:123], v[132:135], v[180:183], v[120:123]
	v_mfma_f32_16x16x32_bf16 v[116:119], v[156:159], v[180:183], v[116:119]
	v_mfma_f32_16x16x32_bf16 v[112:115], v[132:135], v[188:191], v[112:115]
	v_mfma_f32_16x16x32_bf16 v[108:111], v[156:159], v[188:191], v[108:111]
	v_mfma_f32_16x16x32_bf16 v[104:107], v[132:135], v[196:199], v[104:107]
	v_mfma_f32_16x16x32_bf16 v[100:103], v[156:159], v[196:199], v[100:103]
	v_mfma_f32_16x16x32_bf16 v[128:131], v[136:139], v[176:179], v[128:131]
	v_mfma_f32_16x16x32_bf16 v[124:127], v[160:163], v[176:179], v[124:127]
	v_mfma_f32_16x16x32_bf16 v[120:123], v[136:139], v[184:187], v[120:123]
	v_mfma_f32_16x16x32_bf16 v[116:119], v[160:163], v[184:187], v[116:119]
	v_mfma_f32_16x16x32_bf16 v[112:115], v[136:139], v[192:195], v[112:115]
	v_mfma_f32_16x16x32_bf16 v[108:111], v[160:163], v[192:195], v[108:111]
	v_mfma_f32_16x16x32_bf16 v[104:107], v[136:139], v[200:203], v[104:107]
	v_mfma_f32_16x16x32_bf16 v[100:103], v[160:163], v[200:203], v[100:103]
	s_barrier
	s_setprio 0
	s_add_i32 s26, 0, 0x14000
	v_add_u32_e32 v164, s26, v222
	s_add_i32 s0, s0, s17
	ds_read_b128 v[204:207], v164
	ds_read_b128 v[208:211], v164 offset:1024
	ds_read_b128 v[212:215], v164 offset:2048
	ds_read_b128 v[216:219], v164 offset:3072
	v_lshl_add_u64 v[164:165], s[30:31], 0, v[26:27]
	s_mov_b32 m0, s0
	v_lshl_add_u64 v[166:167], s[30:31], 0, v[144:145]
	global_load_lds_dwordx4 v[164:165], off
	s_add_i32 m0, s0, 0x2000
	s_nop 0
	global_load_lds_dwordx4 v[166:167], off
	s_setprio 1
	s_barrier
	s_waitcnt lgkmcnt(0)
	v_mfma_f32_16x16x32_bf16 v[64:67], v[204:207], v[172:175], v[64:67]
	v_mfma_f32_16x16x32_bf16 v[60:63], v[212:215], v[172:175], v[60:63]
	v_mfma_f32_16x16x32_bf16 v[56:59], v[204:207], v[180:183], v[56:59]
	v_mfma_f32_16x16x32_bf16 v[52:55], v[212:215], v[180:183], v[52:55]
	v_mfma_f32_16x16x32_bf16 v[48:51], v[204:207], v[188:191], v[48:51]
	v_mfma_f32_16x16x32_bf16 v[44:47], v[212:215], v[188:191], v[44:47]
	v_mfma_f32_16x16x32_bf16 v[40:43], v[204:207], v[196:199], v[40:43]
	v_mfma_f32_16x16x32_bf16 v[36:39], v[212:215], v[196:199], v[36:39]
	v_mfma_f32_16x16x32_bf16 v[64:67], v[208:211], v[176:179], v[64:67]
	v_mfma_f32_16x16x32_bf16 v[60:63], v[216:219], v[176:179], v[60:63]
	v_mfma_f32_16x16x32_bf16 v[56:59], v[208:211], v[184:187], v[56:59]
	v_mfma_f32_16x16x32_bf16 v[52:55], v[216:219], v[184:187], v[52:55]
	v_mfma_f32_16x16x32_bf16 v[48:51], v[208:211], v[192:195], v[48:51]
	v_mfma_f32_16x16x32_bf16 v[44:47], v[216:219], v[192:195], v[44:47]
	v_mfma_f32_16x16x32_bf16 v[40:43], v[208:211], v[200:203], v[40:43]
	v_mfma_f32_16x16x32_bf16 v[36:39], v[216:219], v[200:203], v[36:39]
	s_barrier
	s_setprio 0
	s_mov_b32 m0, s52
	v_lshl_add_u64 v[168:169], s[34:35], 0, v[140:141]
	ds_read_b128 v[172:175], v224 offset:16384
	ds_read_b128 v[176:179], v224 offset:17408
	ds_read_b128 v[180:183], v224 offset:18432
	ds_read_b128 v[184:187], v224 offset:19456
	ds_read_b128 v[188:191], v224 offset:20480
	ds_read_b128 v[192:195], v224 offset:21504
	ds_read_b128 v[196:199], v224 offset:22528
	ds_read_b128 v[200:203], v224 offset:23552
	global_load_lds_dwordx4 v[168:169], off
	v_lshl_add_u64 v[220:221], s[34:35], 0, v[142:143]
	s_mov_b32 m0, s54
	s_nop 0
	global_load_lds_dwordx4 v[220:221], off
	s_setprio 1
	s_barrier
	s_waitcnt lgkmcnt(0)
	v_mfma_f32_16x16x32_bf16 v[96:99], v[132:135], v[172:175], v[96:99]
	v_mfma_f32_16x16x32_bf16 v[92:95], v[156:159], v[172:175], v[92:95]
	v_mfma_f32_16x16x32_bf16 v[88:91], v[132:135], v[180:183], v[88:91]
	v_mfma_f32_16x16x32_bf16 v[84:87], v[156:159], v[180:183], v[84:87]
	v_mfma_f32_16x16x32_bf16 v[80:83], v[132:135], v[188:191], v[80:83]
	v_mfma_f32_16x16x32_bf16 v[76:79], v[156:159], v[188:191], v[76:79]
	v_mfma_f32_16x16x32_bf16 v[72:75], v[132:135], v[196:199], v[72:75]
	v_mfma_f32_16x16x32_bf16 v[68:71], v[156:159], v[196:199], v[68:71]
	v_mfma_f32_16x16x32_bf16 v[96:99], v[136:139], v[176:179], v[96:99]
	v_mfma_f32_16x16x32_bf16 v[92:95], v[160:163], v[176:179], v[92:95]
	v_mfma_f32_16x16x32_bf16 v[88:91], v[136:139], v[184:187], v[88:91]
	v_mfma_f32_16x16x32_bf16 v[84:87], v[160:163], v[184:187], v[84:87]
	v_mfma_f32_16x16x32_bf16 v[80:83], v[136:139], v[192:195], v[80:83]
	v_mfma_f32_16x16x32_bf16 v[76:79], v[160:163], v[192:195], v[76:79]
	v_mfma_f32_16x16x32_bf16 v[72:75], v[136:139], v[200:203], v[72:75]
	v_mfma_f32_16x16x32_bf16 v[68:71], v[160:163], v[200:203], v[68:71]
	s_barrier
	s_setprio 0
	s_add_u32 s0, s30, 0xb0000
	s_addc_u32 s1, s31, 0
	s_add_i32 s26, s26, s17
	v_lshl_add_u64 v[132:133], s[0:1], 0, v[26:27]
	s_mov_b32 m0, s26
	s_nop 0
	global_load_lds_dwordx4 v[132:133], off
	v_lshl_add_u64 v[132:133], s[0:1], 0, v[144:145]
	s_add_i32 m0, s26, 0x2000
	s_nop 0
	global_load_lds_dwordx4 v[132:133], off
	s_waitcnt vmcnt(6)
	s_setprio 1
	s_barrier
	v_mfma_f32_16x16x32_bf16 v[32:35], v[204:207], v[172:175], v[32:35]
	v_mfma_f32_16x16x32_bf16 v[28:31], v[212:215], v[172:175], v[28:31]
	v_mfma_f32_16x16x32_bf16 v[22:25], v[204:207], v[180:183], v[22:25]
	v_mfma_f32_16x16x32_bf16 v[18:21], v[212:215], v[180:183], v[18:21]
	v_mfma_f32_16x16x32_bf16 v[14:17], v[204:207], v[188:191], v[14:17]
	v_mfma_f32_16x16x32_bf16 v[10:13], v[212:215], v[188:191], v[10:13]
	v_mfma_f32_16x16x32_bf16 v[6:9], v[204:207], v[196:199], v[6:9]
	v_mfma_f32_16x16x32_bf16 v[2:5], v[212:215], v[196:199], v[2:5]
	v_mfma_f32_16x16x32_bf16 v[32:35], v[208:211], v[176:179], v[32:35]
	v_mfma_f32_16x16x32_bf16 v[28:31], v[216:219], v[176:179], v[28:31]
	v_mfma_f32_16x16x32_bf16 v[22:25], v[208:211], v[184:187], v[22:25]
	v_mfma_f32_16x16x32_bf16 v[18:21], v[216:219], v[184:187], v[18:21]
	v_mfma_f32_16x16x32_bf16 v[14:17], v[208:211], v[192:195], v[14:17]
	v_mfma_f32_16x16x32_bf16 v[10:13], v[216:219], v[192:195], v[10:13]
	v_mfma_f32_16x16x32_bf16 v[6:9], v[208:211], v[200:203], v[6:9]
	v_mfma_f32_16x16x32_bf16 v[2:5], v[216:219], v[200:203], v[2:5]
	s_barrier
	s_setprio 0
	s_add_i32 s26, 0, 0x18000
	v_add_u32_e32 v160, s26, v222
	ds_read_b128 v[132:135], v160
	ds_read_b128 v[136:139], v160 offset:1024
	ds_read_b128 v[156:159], v160 offset:2048
	ds_read_b128 v[160:163], v160 offset:3072
	s_add_u32 s0, s34, 0xb0000
	s_addc_u32 s1, s35, 0
	s_mov_b32 m0, s55
	v_lshl_add_u64 v[204:205], s[0:1], 0, v[140:141]
	ds_read_b128 v[172:175], v224 offset:32768
	ds_read_b128 v[176:179], v224 offset:33792
	ds_read_b128 v[180:183], v224 offset:34816
	ds_read_b128 v[184:187], v224 offset:35840
	ds_read_b128 v[188:191], v224 offset:36864
	ds_read_b128 v[192:195], v224 offset:37888
	ds_read_b128 v[196:199], v224 offset:38912
	ds_read_b128 v[200:203], v224 offset:39936
	global_load_lds_dwordx4 v[204:205], off
	v_lshl_add_u64 v[204:205], s[0:1], 0, v[142:143]
	s_mov_b32 m0, s56
	s_nop 0
	global_load_lds_dwordx4 v[204:205], off
	s_waitcnt lgkmcnt(8)
	s_setprio 1
	s_barrier
	s_waitcnt lgkmcnt(0)
	v_mfma_f32_16x16x32_bf16 v[128:131], v[132:135], v[172:175], v[128:131]
	v_mfma_f32_16x16x32_bf16 v[124:127], v[156:159], v[172:175], v[124:127]
	v_mfma_f32_16x16x32_bf16 v[120:123], v[132:135], v[180:183], v[120:123]
	v_mfma_f32_16x16x32_bf16 v[116:119], v[156:159], v[180:183], v[116:119]
	v_mfma_f32_16x16x32_bf16 v[112:115], v[132:135], v[188:191], v[112:115]
	v_mfma_f32_16x16x32_bf16 v[108:111], v[156:159], v[188:191], v[108:111]
	v_mfma_f32_16x16x32_bf16 v[104:107], v[132:135], v[196:199], v[104:107]
	v_mfma_f32_16x16x32_bf16 v[100:103], v[156:159], v[196:199], v[100:103]
	v_mfma_f32_16x16x32_bf16 v[128:131], v[136:139], v[176:179], v[128:131]
	v_mfma_f32_16x16x32_bf16 v[124:127], v[160:163], v[176:179], v[124:127]
	v_mfma_f32_16x16x32_bf16 v[120:123], v[136:139], v[184:187], v[120:123]
	v_mfma_f32_16x16x32_bf16 v[116:119], v[160:163], v[184:187], v[116:119]
	v_mfma_f32_16x16x32_bf16 v[112:115], v[136:139], v[192:195], v[112:115]
	v_mfma_f32_16x16x32_bf16 v[108:111], v[160:163], v[192:195], v[108:111]
	v_mfma_f32_16x16x32_bf16 v[104:107], v[136:139], v[200:203], v[104:107]
	v_mfma_f32_16x16x32_bf16 v[100:103], v[160:163], v[200:203], v[100:103]
	s_barrier
	s_setprio 0
	s_add_i32 s27, 0, 0x1c000
	s_add_i32 s0, s26, s17
	v_add_u32_e32 v216, s27, v222
	v_lshl_add_u64 v[164:165], v[164:165], 0, s[12:13]
	s_mov_b32 m0, s0
	ds_read_b128 v[204:207], v216
	ds_read_b128 v[208:211], v216 offset:1024
	ds_read_b128 v[212:215], v216 offset:2048
	ds_read_b128 v[216:219], v216 offset:3072
	global_load_lds_dwordx4 v[164:165], off
	v_lshl_add_u64 v[164:165], v[166:167], 0, s[12:13]
	s_add_i32 m0, s0, 0x2000
	s_nop 0
	global_load_lds_dwordx4 v[164:165], off
	s_setprio 1
	s_barrier
	s_waitcnt lgkmcnt(0)
	v_mfma_f32_16x16x32_bf16 v[64:67], v[204:207], v[172:175], v[64:67]
	v_mfma_f32_16x16x32_bf16 v[60:63], v[212:215], v[172:175], v[60:63]
	v_mfma_f32_16x16x32_bf16 v[56:59], v[204:207], v[180:183], v[56:59]
	v_mfma_f32_16x16x32_bf16 v[52:55], v[212:215], v[180:183], v[52:55]
	v_mfma_f32_16x16x32_bf16 v[48:51], v[204:207], v[188:191], v[48:51]
	v_mfma_f32_16x16x32_bf16 v[44:47], v[212:215], v[188:191], v[44:47]
	v_mfma_f32_16x16x32_bf16 v[40:43], v[204:207], v[196:199], v[40:43]
	v_mfma_f32_16x16x32_bf16 v[36:39], v[212:215], v[196:199], v[36:39]
	v_mfma_f32_16x16x32_bf16 v[64:67], v[208:211], v[176:179], v[64:67]
	v_mfma_f32_16x16x32_bf16 v[60:63], v[216:219], v[176:179], v[60:63]
	v_mfma_f32_16x16x32_bf16 v[56:59], v[208:211], v[184:187], v[56:59]
	v_mfma_f32_16x16x32_bf16 v[52:55], v[216:219], v[184:187], v[52:55]
	v_mfma_f32_16x16x32_bf16 v[48:51], v[208:211], v[192:195], v[48:51]
	v_mfma_f32_16x16x32_bf16 v[44:47], v[216:219], v[192:195], v[44:47]
	v_mfma_f32_16x16x32_bf16 v[40:43], v[208:211], v[200:203], v[40:43]
	v_mfma_f32_16x16x32_bf16 v[36:39], v[216:219], v[200:203], v[36:39]
	s_barrier
	s_setprio 0
	s_mov_b32 m0, s59
	v_lshl_add_u64 v[164:165], v[168:169], 0, s[12:13]
	ds_read_b128 v[172:175], v224 offset:49152
	ds_read_b128 v[176:179], v224 offset:50176
	ds_read_b128 v[180:183], v224 offset:51200
	ds_read_b128 v[184:187], v224 offset:52224
	ds_read_b128 v[188:191], v224 offset:53248
	ds_read_b128 v[192:195], v224 offset:54272
	ds_read_b128 v[196:199], v224 offset:55296
	ds_read_b128 v[200:203], v224 offset:56320
	global_load_lds_dwordx4 v[164:165], off
	v_lshl_add_u64 v[164:165], v[220:221], 0, s[12:13]
	s_mov_b32 m0, s68
	s_nop 0
	global_load_lds_dwordx4 v[164:165], off
	s_setprio 1
	s_barrier
	s_waitcnt lgkmcnt(0)
	v_mfma_f32_16x16x32_bf16 v[96:99], v[132:135], v[172:175], v[96:99]
	v_mfma_f32_16x16x32_bf16 v[92:95], v[156:159], v[172:175], v[92:95]
	v_mfma_f32_16x16x32_bf16 v[88:91], v[132:135], v[180:183], v[88:91]
	v_mfma_f32_16x16x32_bf16 v[84:87], v[156:159], v[180:183], v[84:87]
	v_mfma_f32_16x16x32_bf16 v[80:83], v[132:135], v[188:191], v[80:83]
	v_mfma_f32_16x16x32_bf16 v[76:79], v[156:159], v[188:191], v[76:79]
	v_mfma_f32_16x16x32_bf16 v[72:75], v[132:135], v[196:199], v[72:75]
	v_mfma_f32_16x16x32_bf16 v[68:71], v[156:159], v[196:199], v[68:71]
	v_mfma_f32_16x16x32_bf16 v[96:99], v[136:139], v[176:179], v[96:99]
	v_mfma_f32_16x16x32_bf16 v[92:95], v[160:163], v[176:179], v[92:95]
	v_mfma_f32_16x16x32_bf16 v[88:91], v[136:139], v[184:187], v[88:91]
	v_mfma_f32_16x16x32_bf16 v[84:87], v[160:163], v[184:187], v[84:87]
	v_mfma_f32_16x16x32_bf16 v[80:83], v[136:139], v[192:195], v[80:83]
	v_mfma_f32_16x16x32_bf16 v[76:79], v[160:163], v[192:195], v[76:79]
	v_mfma_f32_16x16x32_bf16 v[72:75], v[136:139], v[200:203], v[72:75]
	v_mfma_f32_16x16x32_bf16 v[68:71], v[160:163], v[200:203], v[68:71]
	s_barrier
	s_setprio 0
	s_add_u32 s0, s30, 0xb0080
	s_addc_u32 s1, s31, 0
	s_add_i32 s26, s27, s17
	v_lshl_add_u64 v[132:133], s[0:1], 0, v[26:27]
	s_mov_b32 m0, s26
	s_nop 0
	global_load_lds_dwordx4 v[132:133], off
	v_lshl_add_u64 v[132:133], s[0:1], 0, v[144:145]
	s_add_i32 m0, s26, 0x2000
	s_nop 0
	global_load_lds_dwordx4 v[132:133], off
	s_waitcnt vmcnt(6)
	s_setprio 1
	s_barrier
	v_mfma_f32_16x16x32_bf16 v[32:35], v[204:207], v[172:175], v[32:35]
	v_mfma_f32_16x16x32_bf16 v[28:31], v[212:215], v[172:175], v[28:31]
	v_mfma_f32_16x16x32_bf16 v[22:25], v[204:207], v[180:183], v[22:25]
	v_mfma_f32_16x16x32_bf16 v[18:21], v[212:215], v[180:183], v[18:21]
	v_mfma_f32_16x16x32_bf16 v[14:17], v[204:207], v[188:191], v[14:17]
	v_mfma_f32_16x16x32_bf16 v[10:13], v[212:215], v[188:191], v[10:13]
	v_mfma_f32_16x16x32_bf16 v[6:9], v[204:207], v[196:199], v[6:9]
	v_mfma_f32_16x16x32_bf16 v[2:5], v[212:215], v[196:199], v[2:5]
	v_mfma_f32_16x16x32_bf16 v[32:35], v[208:211], v[176:179], v[32:35]
	v_mfma_f32_16x16x32_bf16 v[28:31], v[216:219], v[176:179], v[28:31]
	v_mfma_f32_16x16x32_bf16 v[22:25], v[208:211], v[184:187], v[22:25]
	v_mfma_f32_16x16x32_bf16 v[18:21], v[216:219], v[184:187], v[18:21]
	v_mfma_f32_16x16x32_bf16 v[14:17], v[208:211], v[192:195], v[14:17]
	v_mfma_f32_16x16x32_bf16 v[10:13], v[216:219], v[192:195], v[10:13]
	v_mfma_f32_16x16x32_bf16 v[6:9], v[208:211], v[200:203], v[6:9]
	v_mfma_f32_16x16x32_bf16 v[2:5], v[216:219], v[200:203], v[2:5]
	s_barrier
	s_setprio 0
	s_add_i32 s81, s81, 2
	s_add_u32 s44, s44, 0x100
	s_addc_u32 s45, s45, 0
	s_cmp_gt_u32 s81, 41
	s_mov_b64 s[26:27], s[28:29]
	s_cbranch_scc0 .LBB0_1156
	s_min_i32 s0, s24, 0x100
	s_ashr_i32 s0, s0, 5
	s_ashr_i32 s1, s0, 31
	s_add_i32 s26, s24, 0xffffff00
	s_cmpk_lt_i32 s24, 0x100
	s_cselect_b32 s26, s24, s26
	s_cselect_b32 s28, 0, s51
	s_cselect_b32 s29, 0, s50
	s_ashr_i32 s27, s26, 31
	s_lshl_b64 s[26:27], s[26:27], 19
	v_lshl_add_u64 v[132:133], s[26:27], 0, v[146:147]
	s_add_u32 s26, s20, s29
	v_lshl_or_b32 v166, s25, 8, v223
	s_addc_u32 s27, s21, s28
	s_ashr_i32 s25, s24, 31
	s_lshl_b64 s[28:29], s[24:25], 19
	v_lshl_add_u64 v[178:179], v[148:149], 0, s[28:29]
	s_lshl_b64 s[24:25], s[24:25], 10
	s_mul_i32 s28, s0, 0x9000
	v_ashrrev_i32_e32 v167, 31, v166
	s_mul_hi_i32 s29, s0, 0x9000
	s_add_u32 s28, s36, s28
	s_addc_u32 s29, s37, s29
	v_lshlrev_b64 v[180:181], 2, v[166:167]
	v_lshl_add_u64 v[156:157], s[28:29], 0, v[180:181]
	v_lshl_add_u64 v[168:169], v[132:133], 0, v[166:167]
	v_lshl_add_u64 v[182:183], v[132:133], 1, s[26:27]
	global_load_dwordx4 v[132:135], v[156:157], off offset:16
	global_load_dwordx4 v[136:139], v[156:157], off
	s_lshl_b64 s[0:1], s[0:1], 12
	s_add_u32 s28, s57, s0
	s_addc_u32 s29, s58, s1
	v_lshl_add_u64 v[180:181], s[28:29], 0, v[180:181]
	v_lshl_add_u64 v[196:197], v[168:169], 1, s[26:27]
	v_add_co_u32_e32 v210, vcc, s65, v196
	s_mov_b32 s1, 0x20000
	s_nop 0
	v_addc_co_u32_e32 v211, vcc, 0, v197, vcc
	v_add_co_u32_e32 v184, vcc, s1, v196
	s_mov_b32 s26, 0x30000
	s_nop 0
	v_addc_co_u32_e32 v185, vcc, 0, v197, vcc
	v_add_co_u32_e32 v188, vcc, s26, v196
	v_lshlrev_b64 v[166:167], 1, v[166:167]
	s_nop 0
	v_addc_co_u32_e32 v189, vcc, 0, v197, vcc
	v_lshl_add_u64 v[178:179], v[178:179], 0, v[166:167]
	v_lshl_add_u64 v[182:183], v[182:183], 0, v[166:167]
	s_mov_b32 s0, 0x8000
	s_mov_b32 s27, 0x80000
	s_mov_b32 s28, 0x90000
	s_waitcnt vmcnt(0)
	v_pk_mul_f32 v[172:173], v[134:135], 0.5 op_sel_hi:[1,0]
	v_pk_mul_f32 v[176:177], v[138:139], 0.5 op_sel_hi:[1,0]
	v_pk_mul_f32 v[174:175], v[136:137], 0.5 op_sel_hi:[1,0]
	v_pk_mul_f32 v[164:165], v[132:133], 0.5 op_sel_hi:[1,0]
	global_load_dwordx4 v[132:135], v[156:157], off offset:528
	global_load_dwordx4 v[136:139], v[156:157], off offset:512
	s_waitcnt vmcnt(0)
	v_pk_mul_f32 v[158:159], v[134:135], 0.5 op_sel_hi:[1,0]
	v_pk_mul_f32 v[162:163], v[138:139], 0.5 op_sel_hi:[1,0]
	v_pk_mul_f32 v[160:161], v[136:137], 0.5 op_sel_hi:[1,0]
	v_pk_mul_f32 v[156:157], v[132:133], 0.5 op_sel_hi:[1,0]
	global_load_dwordx4 v[132:135], v[180:181], off offset:16
	global_load_dwordx4 v[136:139], v[180:181], off
	global_load_dwordx4 v[190:193], v[196:197], off offset:2048
	global_load_dwordx4 v[198:201], v[210:211], off offset:2048
	global_load_dwordx4 v[202:205], v[184:185], off offset:2048
	global_load_dwordx4 v[206:209], v[188:189], off offset:2048
	s_waitcnt vmcnt(0)
	v_lshlrev_b32_e32 v166, 16, v190
	v_and_b32_e32 v167, 0xffff0000, v190
	v_lshlrev_b32_e32 v168, 16, v191
	v_and_b32_e32 v169, 0xffff0000, v191
	v_lshlrev_b32_e32 v186, 16, v192
	v_and_b32_e32 v187, 0xffff0000, v192
	v_lshlrev_b32_e32 v190, 16, v193
	v_and_b32_e32 v191, 0xffff0000, v193
	v_pk_fma_f32 v[130:131], v[130:131], v[176:177], v[168:169]
	v_pk_fma_f32 v[128:129], v[128:129], v[174:175], v[166:167]
	v_pk_fma_f32 v[126:127], v[126:127], v[172:173], v[190:191]
	v_pk_fma_f32 v[124:125], v[124:125], v[164:165], v[186:187]
	v_cvt_pk_bf16_f32 v190, v128, v129
	v_cvt_pk_bf16_f32 v191, v130, v131
	v_cvt_pk_bf16_f32 v192, v124, v125
	v_cvt_pk_bf16_f32 v193, v126, v127
	v_lshlrev_b32_e32 v130, 16, v190
	v_and_b32_e32 v131, 0xffff0000, v190
	v_lshlrev_b32_e32 v128, 16, v191
	v_and_b32_e32 v129, 0xffff0000, v191
	v_lshlrev_b32_e32 v126, 16, v192
	v_and_b32_e32 v127, 0xffff0000, v192
	v_lshlrev_b32_e32 v124, 16, v193
	v_and_b32_e32 v125, 0xffff0000, v193
	v_lshlrev_b32_e32 v212, 16, v200
	v_and_b32_e32 v213, 0xffff0000, v200
	v_lshlrev_b32_e32 v200, 16, v201
	v_and_b32_e32 v201, 0xffff0000, v201
	global_store_dwordx4 v[182:183], v[190:193], off offset:2048
	v_pk_mul_f32 v[166:167], v[138:139], v[128:129]
	v_pk_mul_f32 v[168:169], v[136:137], v[130:131]
	v_pk_mul_f32 v[186:187], v[134:135], v[124:125]
	v_pk_mul_f32 v[192:193], v[132:133], v[126:127]
	v_lshlrev_b32_e32 v194, 16, v198
	v_and_b32_e32 v195, 0xffff0000, v198
	v_lshlrev_b32_e32 v198, 16, v199
	v_and_b32_e32 v199, 0xffff0000, v199
	v_cvt_pk_bf16_f32 v190, v168, v169
	v_cvt_pk_bf16_f32 v191, v166, v167
	v_cvt_pk_bf16_f32 v192, v192, v193
	v_cvt_pk_bf16_f32 v193, v186, v187
	v_pk_fma_f32 v[118:119], v[118:119], v[172:173], v[200:201]
	v_pk_fma_f32 v[116:117], v[116:117], v[164:165], v[212:213]
	global_store_dwordx4 v[178:179], v[190:193], off
	v_pk_fma_f32 v[122:123], v[122:123], v[176:177], v[198:199]
	v_pk_fma_f32 v[120:121], v[120:121], v[174:175], v[194:195]
	v_cvt_pk_bf16_f32 v192, v116, v117
	v_cvt_pk_bf16_f32 v193, v118, v119
	v_add_co_u32_e32 v186, vcc, s65, v182
	v_cvt_pk_bf16_f32 v190, v120, v121
	v_cvt_pk_bf16_f32 v191, v122, v123
	v_addc_co_u32_e32 v187, vcc, 0, v183, vcc
	v_lshlrev_b32_e32 v118, 16, v192
	v_and_b32_e32 v119, 0xffff0000, v192
	v_lshlrev_b32_e32 v116, 16, v193
	v_and_b32_e32 v117, 0xffff0000, v193
	global_store_dwordx4 v[186:187], v[190:193], off offset:2048
	v_lshlrev_b32_e32 v122, 16, v190
	v_and_b32_e32 v123, 0xffff0000, v190
	v_lshlrev_b32_e32 v120, 16, v191
	v_and_b32_e32 v121, 0xffff0000, v191
	v_pk_mul_f32 v[190:191], v[134:135], v[116:117]
	v_pk_mul_f32 v[194:195], v[132:133], v[118:119]
	v_pk_mul_f32 v[166:167], v[138:139], v[120:121]
	v_pk_mul_f32 v[168:169], v[136:137], v[122:123]
	v_cvt_pk_bf16_f32 v194, v194, v195
	v_cvt_pk_bf16_f32 v195, v190, v191
	v_add_co_u32_e32 v190, vcc, s0, v178
	v_cvt_pk_bf16_f32 v192, v168, v169
	v_cvt_pk_bf16_f32 v193, v166, v167
	v_addc_co_u32_e32 v191, vcc, 0, v179, vcc
	global_store_dwordx4 v[190:191], v[192:195], off
	v_lshlrev_b32_e32 v198, 16, v204
	v_and_b32_e32 v199, 0xffff0000, v204
	v_add_co_u32_e32 v192, vcc, s27, v196
	v_lshlrev_b32_e32 v200, 16, v205
	s_nop 0
	v_addc_co_u32_e32 v193, vcc, 0, v197, vcc
	v_add_co_u32_e32 v194, vcc, s28, v196
	v_and_b32_e32 v201, 0xffff0000, v205
	global_load_dwordx4 v[212:215], v[192:193], off offset:2048
	v_addc_co_u32_e32 v195, vcc, 0, v197, vcc
	v_lshlrev_b32_e32 v166, 16, v202
	v_and_b32_e32 v167, 0xffff0000, v202
	v_lshlrev_b32_e32 v168, 16, v203
	v_and_b32_e32 v169, 0xffff0000, v203
	v_pk_fma_f32 v[110:111], v[110:111], v[172:173], v[200:201]
	v_pk_fma_f32 v[108:109], v[108:109], v[164:165], v[198:199]
	v_pk_fma_f32 v[114:115], v[114:115], v[176:177], v[168:169]
	v_pk_fma_f32 v[112:113], v[112:113], v[174:175], v[166:167]
	v_cvt_pk_bf16_f32 v202, v108, v109
	v_cvt_pk_bf16_f32 v203, v110, v111
	v_add_co_u32_e32 v198, vcc, s1, v182
	global_load_dwordx4 v[216:219], v[194:195], off offset:2048
	v_cvt_pk_bf16_f32 v200, v112, v113
	v_cvt_pk_bf16_f32 v201, v114, v115
	v_addc_co_u32_e32 v199, vcc, 0, v183, vcc
	v_lshlrev_b32_e32 v110, 16, v202
	v_and_b32_e32 v111, 0xffff0000, v202
	v_lshlrev_b32_e32 v108, 16, v203
	v_and_b32_e32 v109, 0xffff0000, v203
	global_store_dwordx4 v[198:199], v[200:203], off offset:2048
	v_lshlrev_b32_e32 v114, 16, v200
	v_and_b32_e32 v115, 0xffff0000, v200
	v_lshlrev_b32_e32 v112, 16, v201
	v_and_b32_e32 v113, 0xffff0000, v201
	v_pk_mul_f32 v[200:201], v[134:135], v[108:109]
	v_pk_mul_f32 v[204:205], v[132:133], v[110:111]
	v_lshlrev_b32_e32 v234, 16, v208
	v_and_b32_e32 v235, 0xffff0000, v208
	v_lshlrev_b32_e32 v208, 16, v209
	v_and_b32_e32 v209, 0xffff0000, v209
	v_pk_mul_f32 v[166:167], v[138:139], v[112:113]
	v_pk_mul_f32 v[168:169], v[136:137], v[114:115]
	v_cvt_pk_bf16_f32 v204, v204, v205
	v_cvt_pk_bf16_f32 v205, v200, v201
	v_add_co_u32_e32 v200, vcc, s65, v178
	v_lshlrev_b32_e32 v220, 16, v206
	v_and_b32_e32 v221, 0xffff0000, v206
	v_lshlrev_b32_e32 v206, 16, v207
	v_and_b32_e32 v207, 0xffff0000, v207
	v_cvt_pk_bf16_f32 v202, v168, v169
	v_cvt_pk_bf16_f32 v203, v166, v167
	v_addc_co_u32_e32 v201, vcc, 0, v179, vcc
	v_pk_fma_f32 v[102:103], v[102:103], v[172:173], v[208:209]
	v_pk_fma_f32 v[100:101], v[100:101], v[164:165], v[234:235]
	global_store_dwordx4 v[200:201], v[202:205], off
	v_pk_fma_f32 v[106:107], v[106:107], v[176:177], v[206:207]
	v_pk_fma_f32 v[104:105], v[104:105], v[174:175], v[220:221]
	v_cvt_pk_bf16_f32 v206, v100, v101
	v_cvt_pk_bf16_f32 v207, v102, v103
	v_add_co_u32_e32 v202, vcc, s26, v182
	v_cvt_pk_bf16_f32 v204, v104, v105
	v_cvt_pk_bf16_f32 v205, v106, v107
	v_addc_co_u32_e32 v203, vcc, 0, v183, vcc
	v_lshlrev_b32_e32 v102, 16, v206
	v_and_b32_e32 v103, 0xffff0000, v206
	v_lshlrev_b32_e32 v100, 16, v207
	v_and_b32_e32 v101, 0xffff0000, v207
	global_store_dwordx4 v[202:203], v[204:207], off offset:2048
	v_lshlrev_b32_e32 v106, 16, v204
	v_and_b32_e32 v107, 0xffff0000, v204
	v_lshlrev_b32_e32 v104, 16, v205
	v_and_b32_e32 v105, 0xffff0000, v205
	v_pk_mul_f32 v[204:205], v[134:135], v[100:101]
	v_pk_mul_f32 v[208:209], v[132:133], v[102:103]
	s_mov_b32 s0, 0x18000
	v_pk_mul_f32 v[166:167], v[138:139], v[104:105]
	v_pk_mul_f32 v[168:169], v[136:137], v[106:107]
	v_cvt_pk_bf16_f32 v208, v208, v209
	v_cvt_pk_bf16_f32 v209, v204, v205
	v_add_co_u32_e32 v204, vcc, s0, v178
	v_cvt_pk_bf16_f32 v206, v168, v169
	v_cvt_pk_bf16_f32 v207, v166, v167
	v_addc_co_u32_e32 v205, vcc, 0, v179, vcc
	global_store_dwordx4 v[204:205], v[206:209], off
	s_mov_b32 s0, 0xb0000
	s_waitcnt vmcnt(0)
	v_lshlrev_b32_e32 v166, 16, v212
	v_add_co_u32_e32 v206, vcc, s76, v196
	v_and_b32_e32 v167, 0xffff0000, v212
	s_nop 0
	v_addc_co_u32_e32 v207, vcc, 0, v197, vcc
	global_load_dwordx4 v[238:241], v[206:207], off offset:2048
	v_add_co_u32_e32 v208, vcc, s0, v196
	v_lshlrev_b32_e32 v168, 16, v213
	s_nop 0
	v_addc_co_u32_e32 v209, vcc, 0, v197, vcc
	global_load_dwordx4 v[242:245], v[208:209], off offset:2048
	v_and_b32_e32 v169, 0xffff0000, v213
	v_lshlrev_b32_e32 v212, 16, v214
	v_and_b32_e32 v213, 0xffff0000, v214
	v_lshlrev_b32_e32 v214, 16, v215
	v_and_b32_e32 v215, 0xffff0000, v215
	v_pk_fma_f32 v[94:95], v[94:95], v[172:173], v[214:215]
	v_pk_fma_f32 v[92:93], v[92:93], v[164:165], v[212:213]
	v_lshlrev_b32_e32 v220, 16, v216
	v_and_b32_e32 v221, 0xffff0000, v216
	v_lshlrev_b32_e32 v234, 16, v217
	v_and_b32_e32 v235, 0xffff0000, v217
	v_pk_fma_f32 v[98:99], v[98:99], v[176:177], v[168:169]
	v_pk_fma_f32 v[96:97], v[96:97], v[174:175], v[166:167]
	v_cvt_pk_bf16_f32 v216, v92, v93
	v_cvt_pk_bf16_f32 v217, v94, v95
	v_add_co_u32_e32 v212, vcc, s27, v182
	v_cvt_pk_bf16_f32 v214, v96, v97
	v_cvt_pk_bf16_f32 v215, v98, v99
	v_addc_co_u32_e32 v213, vcc, 0, v183, vcc
	v_lshlrev_b32_e32 v94, 16, v216
	v_and_b32_e32 v95, 0xffff0000, v216
	v_lshlrev_b32_e32 v92, 16, v217
	v_and_b32_e32 v93, 0xffff0000, v217
	v_lshlrev_b32_e32 v246, 16, v218
	v_and_b32_e32 v247, 0xffff0000, v218
	v_lshlrev_b32_e32 v248, 16, v219
	v_and_b32_e32 v249, 0xffff0000, v219
	global_store_dwordx4 v[212:213], v[214:217], off offset:2048
	v_lshlrev_b32_e32 v98, 16, v214
	v_and_b32_e32 v99, 0xffff0000, v214
	v_lshlrev_b32_e32 v96, 16, v215
	v_and_b32_e32 v97, 0xffff0000, v215
	v_pk_mul_f32 v[214:215], v[134:135], v[92:93]
	v_pk_mul_f32 v[218:219], v[132:133], v[94:95]
	s_mov_b32 s1, 0x40000
	v_pk_mul_f32 v[166:167], v[138:139], v[96:97]
	v_pk_mul_f32 v[168:169], v[136:137], v[98:99]
	v_cvt_pk_bf16_f32 v218, v218, v219
	v_cvt_pk_bf16_f32 v219, v214, v215
	v_add_co_u32_e32 v214, vcc, s1, v178
	v_cvt_pk_bf16_f32 v216, v168, v169
	v_cvt_pk_bf16_f32 v217, v166, v167
	v_addc_co_u32_e32 v215, vcc, 0, v179, vcc
	v_pk_fma_f32 v[86:87], v[86:87], v[172:173], v[248:249]
	global_store_dwordx4 v[214:215], v[216:219], off
	v_pk_fma_f32 v[90:91], v[90:91], v[176:177], v[234:235]
	v_pk_fma_f32 v[88:89], v[88:89], v[174:175], v[220:221]
	v_pk_fma_f32 v[84:85], v[84:85], v[164:165], v[246:247]
	v_cvt_pk_bf16_f32 v221, v86, v87
	v_add_co_u32_e32 v216, vcc, s28, v182
	v_cvt_pk_bf16_f32 v218, v88, v89
	v_cvt_pk_bf16_f32 v219, v90, v91
	v_cvt_pk_bf16_f32 v220, v84, v85
	v_addc_co_u32_e32 v217, vcc, 0, v183, vcc
	v_lshlrev_b32_e32 v84, 16, v221
	v_and_b32_e32 v85, 0xffff0000, v221
	global_store_dwordx4 v[216:217], v[218:221], off offset:2048
	v_lshlrev_b32_e32 v90, 16, v218
	v_and_b32_e32 v91, 0xffff0000, v218
	v_lshlrev_b32_e32 v88, 16, v219
	v_and_b32_e32 v89, 0xffff0000, v219
	v_lshlrev_b32_e32 v86, 16, v220
	v_and_b32_e32 v87, 0xffff0000, v220
	v_pk_mul_f32 v[218:219], v[134:135], v[84:85]
	s_mov_b32 s1, 0x48000
	v_pk_mul_f32 v[166:167], v[138:139], v[88:89]
	v_pk_mul_f32 v[168:169], v[136:137], v[90:91]
	v_pk_mul_f32 v[220:221], v[132:133], v[86:87]
	v_cvt_pk_bf16_f32 v249, v218, v219
	v_add_co_u32_e32 v218, vcc, s1, v178
	v_cvt_pk_bf16_f32 v246, v168, v169
	v_cvt_pk_bf16_f32 v247, v166, v167
	v_cvt_pk_bf16_f32 v248, v220, v221
	v_addc_co_u32_e32 v219, vcc, 0, v179, vcc
	global_store_dwordx4 v[218:219], v[246:249], off
	global_load_dwordx4 v[246:249], v[196:197], off offset:2304
	s_nop 0
	global_load_dwordx4 v[250:253], v[210:211], off offset:2304
	s_waitcnt vmcnt(0)
	v_lshlrev_b32_e32 v196, 16, v240
	v_and_b32_e32 v197, 0xffff0000, v240
	v_lshlrev_b32_e32 v210, 16, v241
	v_and_b32_e32 v211, 0xffff0000, v241
	v_lshlrev_b32_e32 v166, 16, v238
	v_and_b32_e32 v167, 0xffff0000, v238
	v_lshlrev_b32_e32 v168, 16, v239
	v_and_b32_e32 v169, 0xffff0000, v239
	v_pk_fma_f32 v[78:79], v[78:79], v[172:173], v[210:211]
	v_pk_fma_f32 v[76:77], v[76:77], v[164:165], v[196:197]
	v_pk_fma_f32 v[82:83], v[82:83], v[176:177], v[168:169]
	v_pk_fma_f32 v[80:81], v[80:81], v[174:175], v[166:167]
	v_cvt_pk_bf16_f32 v240, v76, v77
	v_cvt_pk_bf16_f32 v241, v78, v79
	v_add_co_u32_e32 v196, vcc, s76, v182
	v_cvt_pk_bf16_f32 v238, v80, v81
	v_cvt_pk_bf16_f32 v239, v82, v83
	v_addc_co_u32_e32 v197, vcc, 0, v183, vcc
	v_lshlrev_b32_e32 v78, 16, v240
	v_and_b32_e32 v79, 0xffff0000, v240
	v_lshlrev_b32_e32 v76, 16, v241
	v_and_b32_e32 v77, 0xffff0000, v241
	global_store_dwordx4 v[196:197], v[238:241], off offset:2048
	v_lshlrev_b32_e32 v80, 16, v239
	v_and_b32_e32 v81, 0xffff0000, v239
	v_pk_mul_f32 v[210:211], v[134:135], v[76:77]
	v_pk_mul_f32 v[240:241], v[132:133], v[78:79]
	v_lshlrev_b32_e32 v220, 16, v242
	v_and_b32_e32 v221, 0xffff0000, v242
	v_lshlrev_b32_e32 v234, 16, v243
	v_and_b32_e32 v235, 0xffff0000, v243
	v_lshlrev_b32_e32 v242, 16, v244
	v_and_b32_e32 v243, 0xffff0000, v244
	v_lshlrev_b32_e32 v244, 16, v245
	v_and_b32_e32 v245, 0xffff0000, v245
	v_pk_mul_f32 v[166:167], v[138:139], v[80:81]
	v_cvt_pk_bf16_f32 v240, v240, v241
	v_cvt_pk_bf16_f32 v241, v210, v211
	v_add_co_u32_e32 v210, vcc, s77, v178
	v_lshlrev_b32_e32 v82, 16, v238
	v_and_b32_e32 v83, 0xffff0000, v238
	v_cvt_pk_bf16_f32 v239, v166, v167
	v_addc_co_u32_e32 v211, vcc, 0, v179, vcc
	v_pk_fma_f32 v[74:75], v[74:75], v[176:177], v[234:235]
	v_pk_fma_f32 v[72:73], v[72:73], v[174:175], v[220:221]
	v_pk_fma_f32 v[166:167], v[70:71], v[172:173], v[244:245]
	v_pk_fma_f32 v[70:71], v[68:69], v[164:165], v[242:243]
	v_pk_mul_f32 v[168:169], v[136:137], v[82:83]
	v_cvt_pk_bf16_f32 v68, v72, v73
	v_cvt_pk_bf16_f32 v69, v74, v75
	v_cvt_pk_bf16_f32 v70, v70, v71
	v_cvt_pk_bf16_f32 v71, v166, v167
	v_add_co_u32_e32 v220, vcc, s0, v182
	v_cvt_pk_bf16_f32 v238, v168, v169
	s_nop 0
	v_addc_co_u32_e32 v221, vcc, 0, v183, vcc
	v_lshlrev_b32_e32 v176, 16, v68
	v_and_b32_e32 v177, 0xffff0000, v68
	v_lshlrev_b32_e32 v174, 16, v69
	v_and_b32_e32 v175, 0xffff0000, v69
	v_lshlrev_b32_e32 v172, 16, v70
	v_and_b32_e32 v173, 0xffff0000, v70
	v_lshlrev_b32_e32 v164, 16, v71
	v_and_b32_e32 v165, 0xffff0000, v71
	s_mov_b32 s0, 0x58000
	global_store_dwordx4 v[210:211], v[238:241], off
	global_store_dwordx4 v[220:221], v[68:71], off offset:2048
	v_pk_mul_f32 v[72:73], v[134:135], v[164:165]
	v_pk_mul_f32 v[74:75], v[132:133], v[172:173]
	v_pk_mul_f32 v[70:71], v[138:139], v[174:175]
	v_pk_mul_f32 v[68:69], v[136:137], v[176:177]
	v_add_co_u32_e32 v132, vcc, s0, v178
	v_cvt_pk_bf16_f32 v68, v68, v69
	v_cvt_pk_bf16_f32 v69, v70, v71
	v_cvt_pk_bf16_f32 v70, v74, v75
	v_cvt_pk_bf16_f32 v71, v72, v73
	v_addc_co_u32_e32 v133, vcc, 0, v179, vcc
	global_store_dwordx4 v[132:133], v[68:71], off
	global_load_dwordx4 v[134:137], v[184:185], off offset:2304
	global_load_dwordx4 v[238:241], v[188:189], off offset:2304
	s_nop 0
	global_load_dwordx4 v[68:71], v[180:181], off offset:528
	global_load_dwordx4 v[72:75], v[180:181], off offset:512
	v_lshlrev_b32_e32 v138, 16, v246
	v_and_b32_e32 v139, 0xffff0000, v246
	v_lshlrev_b32_e32 v166, 16, v247
	v_and_b32_e32 v167, 0xffff0000, v247
	v_lshlrev_b32_e32 v168, 16, v248
	v_and_b32_e32 v169, 0xffff0000, v248
	v_lshlrev_b32_e32 v180, 16, v249
	v_and_b32_e32 v181, 0xffff0000, v249
	v_pk_fma_f32 v[66:67], v[66:67], v[162:163], v[166:167]
	v_pk_fma_f32 v[64:65], v[64:65], v[160:161], v[138:139]
	v_pk_fma_f32 v[62:63], v[62:63], v[158:159], v[180:181]
	v_pk_fma_f32 v[60:61], v[60:61], v[156:157], v[168:169]
	v_cvt_pk_bf16_f32 v242, v64, v65
	v_cvt_pk_bf16_f32 v243, v66, v67
	v_cvt_pk_bf16_f32 v244, v60, v61
	v_cvt_pk_bf16_f32 v245, v62, v63
	v_lshlrev_b32_e32 v66, 16, v242
	v_and_b32_e32 v67, 0xffff0000, v242
	v_lshlrev_b32_e32 v64, 16, v243
	v_and_b32_e32 v65, 0xffff0000, v243
	v_lshlrev_b32_e32 v62, 16, v244
	v_and_b32_e32 v63, 0xffff0000, v244
	v_lshlrev_b32_e32 v60, 16, v245
	v_and_b32_e32 v61, 0xffff0000, v245
	v_lshlrev_b32_e32 v184, 16, v250
	v_and_b32_e32 v185, 0xffff0000, v250
	v_lshlrev_b32_e32 v188, 16, v251
	v_and_b32_e32 v189, 0xffff0000, v251
	v_lshlrev_b32_e32 v234, 16, v252
	v_and_b32_e32 v235, 0xffff0000, v252
	v_lshlrev_b32_e32 v246, 16, v253
	v_and_b32_e32 v247, 0xffff0000, v253
	global_store_dwordx4 v[182:183], v[242:245], off offset:2304
	v_pk_fma_f32 v[58:59], v[58:59], v[162:163], v[188:189]
	v_pk_fma_f32 v[56:57], v[56:57], v[160:161], v[184:185]
	v_pk_fma_f32 v[54:55], v[54:55], v[158:159], v[246:247]
	v_pk_fma_f32 v[52:53], v[52:53], v[156:157], v[234:235]
	s_waitcnt vmcnt(0)
	v_lshlrev_b32_e32 v188, 16, v240
	v_pk_mul_f32 v[168:169], v[70:71], v[60:61]
	v_pk_mul_f32 v[138:139], v[74:75], v[64:65]
	v_pk_mul_f32 v[166:167], v[72:73], v[66:67]
	v_pk_mul_f32 v[182:183], v[68:69], v[62:63]
	v_cvt_pk_bf16_f32 v180, v166, v167
	v_cvt_pk_bf16_f32 v181, v138, v139
	v_cvt_pk_bf16_f32 v182, v182, v183
	v_cvt_pk_bf16_f32 v183, v168, v169
	global_store_dwordx4 v[178:179], v[180:183], off offset:256
	v_cvt_pk_bf16_f32 v178, v56, v57
	v_cvt_pk_bf16_f32 v179, v58, v59
	v_cvt_pk_bf16_f32 v180, v52, v53
	v_cvt_pk_bf16_f32 v181, v54, v55
	v_lshlrev_b32_e32 v58, 16, v178
	v_and_b32_e32 v59, 0xffff0000, v178
	v_lshlrev_b32_e32 v56, 16, v179
	v_and_b32_e32 v57, 0xffff0000, v179
	v_lshlrev_b32_e32 v54, 16, v180
	v_and_b32_e32 v55, 0xffff0000, v180
	v_lshlrev_b32_e32 v52, 16, v181
	v_and_b32_e32 v53, 0xffff0000, v181
	global_store_dwordx4 v[186:187], v[178:181], off offset:2304
	v_pk_mul_f32 v[138:139], v[74:75], v[56:57]
	v_pk_mul_f32 v[166:167], v[72:73], v[58:59]
	v_pk_mul_f32 v[168:169], v[70:71], v[52:53]
	v_pk_mul_f32 v[180:181], v[68:69], v[54:55]
	v_cvt_pk_bf16_f32 v178, v166, v167
	v_cvt_pk_bf16_f32 v179, v138, v139
	v_cvt_pk_bf16_f32 v180, v180, v181
	v_cvt_pk_bf16_f32 v181, v168, v169
	v_lshlrev_b32_e32 v138, 16, v134
	v_and_b32_e32 v139, 0xffff0000, v134
	v_lshlrev_b32_e32 v134, 16, v135
	v_and_b32_e32 v135, 0xffff0000, v135
	v_lshlrev_b32_e32 v166, 16, v136
	v_and_b32_e32 v167, 0xffff0000, v136
	v_lshlrev_b32_e32 v136, 16, v137
	v_and_b32_e32 v137, 0xffff0000, v137
	global_store_dwordx4 v[190:191], v[178:181], off offset:256
	v_pk_fma_f32 v[50:51], v[50:51], v[162:163], v[134:135]
	v_pk_fma_f32 v[48:49], v[48:49], v[160:161], v[138:139]
	v_pk_fma_f32 v[46:47], v[46:47], v[158:159], v[136:137]
	v_pk_fma_f32 v[44:45], v[44:45], v[156:157], v[166:167]
	global_load_dwordx4 v[178:181], v[192:193], off offset:2304
	global_load_dwordx4 v[182:185], v[194:195], off offset:2304
	v_cvt_pk_bf16_f32 v134, v48, v49
	v_cvt_pk_bf16_f32 v135, v50, v51
	v_cvt_pk_bf16_f32 v136, v44, v45
	v_cvt_pk_bf16_f32 v137, v46, v47
	v_lshlrev_b32_e32 v50, 16, v134
	v_and_b32_e32 v51, 0xffff0000, v134
	v_lshlrev_b32_e32 v48, 16, v135
	v_and_b32_e32 v49, 0xffff0000, v135
	v_lshlrev_b32_e32 v46, 16, v136
	v_and_b32_e32 v47, 0xffff0000, v136
	v_lshlrev_b32_e32 v44, 16, v137
	v_and_b32_e32 v45, 0xffff0000, v137
	v_lshlrev_b32_e32 v168, 16, v238
	v_and_b32_e32 v169, 0xffff0000, v238
	v_lshlrev_b32_e32 v186, 16, v239
	v_and_b32_e32 v187, 0xffff0000, v239
	v_and_b32_e32 v189, 0xffff0000, v240
	v_lshlrev_b32_e32 v190, 16, v241
	v_and_b32_e32 v191, 0xffff0000, v241
	global_store_dwordx4 v[198:199], v[134:137], off offset:2304
	v_pk_mul_f32 v[138:139], v[70:71], v[44:45]
	v_pk_mul_f32 v[166:167], v[68:69], v[46:47]
	v_pk_mul_f32 v[136:137], v[74:75], v[48:49]
	v_pk_mul_f32 v[134:135], v[72:73], v[50:51]
	v_pk_fma_f32 v[42:43], v[42:43], v[162:163], v[186:187]
	v_cvt_pk_bf16_f32 v134, v134, v135
	v_cvt_pk_bf16_f32 v135, v136, v137
	v_cvt_pk_bf16_f32 v136, v166, v167
	v_cvt_pk_bf16_f32 v137, v138, v139
	v_pk_fma_f32 v[40:41], v[40:41], v[160:161], v[168:169]
	v_pk_fma_f32 v[38:39], v[38:39], v[158:159], v[190:191]
	v_pk_fma_f32 v[36:37], v[36:37], v[156:157], v[188:189]
	global_store_dwordx4 v[200:201], v[134:137], off offset:256
	v_mul_f32_e32 v67, v67, v67
	v_mul_f32_e32 v65, v65, v65
	v_cvt_pk_bf16_f32 v134, v40, v41
	v_cvt_pk_bf16_f32 v135, v42, v43
	v_cvt_pk_bf16_f32 v136, v36, v37
	v_cvt_pk_bf16_f32 v137, v38, v39
	v_lshlrev_b32_e32 v42, 16, v134
	v_and_b32_e32 v43, 0xffff0000, v134
	v_lshlrev_b32_e32 v40, 16, v135
	v_and_b32_e32 v41, 0xffff0000, v135
	v_lshlrev_b32_e32 v38, 16, v136
	v_and_b32_e32 v39, 0xffff0000, v136
	v_lshlrev_b32_e32 v36, 16, v137
	v_and_b32_e32 v37, 0xffff0000, v137
	global_store_dwordx4 v[202:203], v[134:137], off offset:2304
	v_pk_mul_f32 v[138:139], v[70:71], v[36:37]
	v_pk_mul_f32 v[166:167], v[68:69], v[38:39]
	v_pk_mul_f32 v[136:137], v[74:75], v[40:41]
	v_pk_mul_f32 v[134:135], v[72:73], v[42:43]
	v_fmac_f32_e32 v67, v66, v66
	v_cvt_pk_bf16_f32 v134, v134, v135
	v_cvt_pk_bf16_f32 v135, v136, v137
	v_cvt_pk_bf16_f32 v136, v166, v167
	v_cvt_pk_bf16_f32 v137, v138, v139
	global_store_dwordx4 v[204:205], v[134:137], off offset:256
	global_load_dwordx4 v[134:137], v[206:207], off offset:2304
	s_nop 0
	global_load_dwordx4 v[186:189], v[208:209], off offset:2304
	v_fmac_f32_e32 v65, v64, v64
	v_mul_f32_e32 v63, v63, v63
	v_mul_f32_e32 v61, v61, v61
	v_add_f32_e32 v64, v67, v65
	v_fmac_f32_e32 v63, v62, v62
	v_fmac_f32_e32 v61, v60, v60
	v_add_f32_e32 v60, v63, v61
	s_waitcnt vmcnt(0)
	v_lshlrev_b32_e32 v138, 16, v178
	v_and_b32_e32 v139, 0xffff0000, v178
	v_lshlrev_b32_e32 v166, 16, v179
	v_and_b32_e32 v167, 0xffff0000, v179
	v_lshlrev_b32_e32 v168, 16, v180
	v_and_b32_e32 v169, 0xffff0000, v180
	v_lshlrev_b32_e32 v178, 16, v181
	v_and_b32_e32 v179, 0xffff0000, v181
	v_pk_fma_f32 v[34:35], v[34:35], v[162:163], v[166:167]
	v_pk_fma_f32 v[32:33], v[32:33], v[160:161], v[138:139]
	v_pk_fma_f32 v[30:31], v[30:31], v[158:159], v[178:179]
	v_pk_fma_f32 v[28:29], v[28:29], v[156:157], v[168:169]
	v_cvt_pk_bf16_f32 v178, v32, v33
	v_cvt_pk_bf16_f32 v179, v34, v35
	v_cvt_pk_bf16_f32 v180, v28, v29
	v_cvt_pk_bf16_f32 v181, v30, v31
	v_lshlrev_b32_e32 v34, 16, v178
	v_and_b32_e32 v35, 0xffff0000, v178
	v_lshlrev_b32_e32 v32, 16, v179
	v_and_b32_e32 v33, 0xffff0000, v179
	v_lshlrev_b32_e32 v30, 16, v180
	v_and_b32_e32 v31, 0xffff0000, v180
	v_lshlrev_b32_e32 v28, 16, v181
	v_and_b32_e32 v29, 0xffff0000, v181
	v_lshlrev_b32_e32 v190, 16, v182
	v_and_b32_e32 v191, 0xffff0000, v182
	v_lshlrev_b32_e32 v182, 16, v183
	v_and_b32_e32 v183, 0xffff0000, v183
	global_store_dwordx4 v[212:213], v[178:181], off offset:2304
	v_pk_mul_f32 v[138:139], v[74:75], v[32:33]
	v_pk_mul_f32 v[166:167], v[72:73], v[34:35]
	v_pk_mul_f32 v[168:169], v[70:71], v[28:29]
	v_pk_mul_f32 v[180:181], v[68:69], v[30:31]
	v_cvt_pk_bf16_f32 v178, v166, v167
	v_cvt_pk_bf16_f32 v179, v138, v139
	v_cvt_pk_bf16_f32 v180, v180, v181
	v_cvt_pk_bf16_f32 v181, v168, v169
	v_pk_fma_f32 v[24:25], v[24:25], v[162:163], v[182:183]
	v_pk_fma_f32 v[22:23], v[22:23], v[160:161], v[190:191]
	v_lshlrev_b32_e32 v192, 16, v184
	v_and_b32_e32 v193, 0xffff0000, v184
	v_lshlrev_b32_e32 v184, 16, v185
	v_and_b32_e32 v185, 0xffff0000, v185
	global_store_dwordx4 v[214:215], v[178:181], off offset:256
	v_pk_fma_f32 v[20:21], v[20:21], v[158:159], v[184:185]
	v_pk_fma_f32 v[18:19], v[18:19], v[156:157], v[192:193]
	v_cvt_pk_bf16_f32 v178, v22, v23
	v_cvt_pk_bf16_f32 v179, v24, v25
	v_lshlrev_b32_e32 v24, 16, v178
	v_and_b32_e32 v25, 0xffff0000, v178
	v_lshlrev_b32_e32 v22, 16, v179
	v_and_b32_e32 v23, 0xffff0000, v179
	v_cvt_pk_bf16_f32 v180, v18, v19
	v_cvt_pk_bf16_f32 v181, v20, v21
	v_pk_mul_f32 v[138:139], v[74:75], v[22:23]
	v_pk_mul_f32 v[166:167], v[72:73], v[24:25]
	global_store_dwordx4 v[216:217], v[178:181], off offset:2304
	v_lshlrev_b32_e32 v20, 16, v180
	v_and_b32_e32 v21, 0xffff0000, v180
	v_cvt_pk_bf16_f32 v178, v166, v167
	v_cvt_pk_bf16_f32 v179, v138, v139
	v_lshlrev_b32_e32 v138, 16, v134
	v_and_b32_e32 v139, 0xffff0000, v134
	v_lshlrev_b32_e32 v134, 16, v135
	v_and_b32_e32 v135, 0xffff0000, v135
	v_lshlrev_b32_e32 v166, 16, v136
	v_and_b32_e32 v167, 0xffff0000, v136
	v_lshlrev_b32_e32 v136, 16, v137
	v_and_b32_e32 v137, 0xffff0000, v137
	v_lshlrev_b32_e32 v18, 16, v181
	v_and_b32_e32 v19, 0xffff0000, v181
	v_pk_fma_f32 v[16:17], v[16:17], v[162:163], v[134:135]
	v_pk_fma_f32 v[14:15], v[14:15], v[160:161], v[138:139]
	v_pk_fma_f32 v[12:13], v[12:13], v[158:159], v[136:137]
	v_pk_fma_f32 v[10:11], v[10:11], v[156:157], v[166:167]
	v_pk_mul_f32 v[168:169], v[70:71], v[18:19]
	v_pk_mul_f32 v[180:181], v[68:69], v[20:21]
	v_cvt_pk_bf16_f32 v134, v14, v15
	v_cvt_pk_bf16_f32 v135, v16, v17
	v_cvt_pk_bf16_f32 v136, v10, v11
	v_cvt_pk_bf16_f32 v137, v12, v13
	v_cvt_pk_bf16_f32 v180, v180, v181
	v_cvt_pk_bf16_f32 v181, v168, v169
	v_lshlrev_b32_e32 v16, 16, v134
	v_and_b32_e32 v17, 0xffff0000, v134
	v_lshlrev_b32_e32 v14, 16, v135
	v_and_b32_e32 v15, 0xffff0000, v135
	v_lshlrev_b32_e32 v12, 16, v136
	v_and_b32_e32 v13, 0xffff0000, v136
	v_lshlrev_b32_e32 v10, 16, v137
	v_and_b32_e32 v11, 0xffff0000, v137
	global_store_dwordx4 v[218:219], v[178:181], off offset:256
	v_lshlrev_b32_e32 v168, 16, v186
	v_and_b32_e32 v169, 0xffff0000, v186
	v_lshlrev_b32_e32 v178, 16, v187
	v_and_b32_e32 v179, 0xffff0000, v187
	v_lshlrev_b32_e32 v180, 16, v188
	v_and_b32_e32 v181, 0xffff0000, v188
	v_lshlrev_b32_e32 v182, 16, v189
	v_and_b32_e32 v183, 0xffff0000, v189
	global_store_dwordx4 v[196:197], v[134:137], off offset:2304
	v_pk_mul_f32 v[138:139], v[70:71], v[10:11]
	v_pk_mul_f32 v[166:167], v[68:69], v[12:13]
	v_pk_mul_f32 v[136:137], v[74:75], v[14:15]
	v_pk_mul_f32 v[134:135], v[72:73], v[16:17]
	v_pk_fma_f32 v[8:9], v[8:9], v[162:163], v[178:179]
	v_cvt_pk_bf16_f32 v134, v134, v135
	v_cvt_pk_bf16_f32 v135, v136, v137
	v_cvt_pk_bf16_f32 v136, v166, v167
	v_cvt_pk_bf16_f32 v137, v138, v139
	v_pk_fma_f32 v[6:7], v[6:7], v[160:161], v[168:169]
	v_pk_fma_f32 v[4:5], v[4:5], v[158:159], v[182:183]
	v_pk_fma_f32 v[2:3], v[2:3], v[156:157], v[180:181]
	global_store_dwordx4 v[210:211], v[134:137], off offset:256
	s_nop 1
	v_cvt_pk_bf16_f32 v134, v6, v7
	v_cvt_pk_bf16_f32 v135, v8, v9
	v_cvt_pk_bf16_f32 v136, v2, v3
	v_cvt_pk_bf16_f32 v137, v4, v5
	v_lshlrev_b32_e32 v8, 16, v134
	v_and_b32_e32 v9, 0xffff0000, v134
	v_lshlrev_b32_e32 v6, 16, v135
	v_and_b32_e32 v7, 0xffff0000, v135
	v_lshlrev_b32_e32 v4, 16, v136
	v_and_b32_e32 v5, 0xffff0000, v136
	v_lshlrev_b32_e32 v2, 16, v137
	v_and_b32_e32 v3, 0xffff0000, v137
	global_store_dwordx4 v[220:221], v[134:137], off offset:2304
	v_pk_mul_f32 v[74:75], v[74:75], v[6:7]
	v_pk_mul_f32 v[72:73], v[72:73], v[8:9]
	v_pk_mul_f32 v[134:135], v[70:71], v[2:3]
	v_pk_mul_f32 v[70:71], v[68:69], v[4:5]
	v_cvt_pk_bf16_f32 v68, v72, v73
	v_cvt_pk_bf16_f32 v69, v74, v75
	v_cvt_pk_bf16_f32 v70, v70, v71
	v_cvt_pk_bf16_f32 v71, v134, v135
	global_store_dwordx4 v[132:133], v[68:71], off offset:256
	v_xor_b32_e32 v72, 32, v227
	v_mul_f32_e32 v73, v129, v129
	v_and_b32_e32 v71, 64, v227
	v_xor_b32_e32 v70, 16, v227
	v_add_u32_e32 v71, 64, v71
	v_cmp_lt_i32_e32 vcc, v70, v71
	v_fmac_f32_e32 v73, v128, v128
	v_mul_f32_e32 v74, v125, v125
	v_cndmask_b32_e32 v70, v227, v70, vcc
	v_cmp_lt_i32_e32 vcc, v72, v71
	v_fmac_f32_e32 v74, v124, v124
	v_lshlrev_b32_e32 v70, 2, v70
	v_cndmask_b32_e32 v71, v227, v72, vcc
	v_mul_f32_e32 v72, v131, v131
	v_fmac_f32_e32 v72, v130, v130
	v_add_f32_e32 v72, v72, v73
	v_mul_f32_e32 v73, v127, v127
	v_fmac_f32_e32 v73, v126, v126
	v_add_f32_e32 v73, v73, v74
	v_add_f32_e32 v72, v72, v73
	v_add_f32_e32 v64, v72, v64
	v_add_f32_e32 v60, v60, v64
	ds_bpermute_b32 v61, v70, v60
	v_lshlrev_b32_e32 v71, 2, v71
	v_lshl_add_u64 v[68:69], v[150:151], 0, s[24:25]
	s_waitcnt lgkmcnt(0)
	v_add_f32_e32 v60, v60, v61
	ds_bpermute_b32 v61, v71, v60
	s_and_saveexec_b64 s[24:25], s[38:39]
	s_cbranch_execz .LBB0_1159
	s_waitcnt lgkmcnt(0)
	v_add_f32_e32 v60, v60, v61
	global_atomic_add_f32 v[68:69], v60, off
